# v056: v054 + LDS-DMA staging loads in the GEMM K-loops use scalar base + 32-bit lane offset (no per-load 64-bit VALU add)
# speedup vs baseline: 1.0136x; 1.0136x over previous
.LBB0_339:
	ds_read_b128 v[136:139], v144
	ds_read_b128 v[140:143], v144 offset:1024
	ds_read_b128 v[150:153], v144 offset:2048
	ds_read_b128 v[154:157], v144 offset:3072
	s_add_u32 s40, s38, 0x100
	s_addc_u32 s41, s39, 0
	s_cmp_eq_u32 s67, 12
	s_cselect_b32 s46, s7, s40
	s_cselect_b32 s47, s1, s41
	s_cselect_b32 s42, s31, s65
	s_cselect_b32 s43, s29, s66
	s_add_u32 s44, s46, 0x80
	s_addc_u32 s45, s47, 0
	s_add_u32 s38, s38, 0x40080
	s_addc_u32 s39, s39, 0
	ds_read_b128 v[158:161], v145
	ds_read_b128 v[162:165], v145 offset:1024
	ds_read_b128 v[166:169], v145 offset:2048
	ds_read_b128 v[170:173], v145 offset:3072
	ds_read_b128 v[174:177], v145 offset:4096
	ds_read_b128 v[178:181], v145 offset:5120
	ds_read_b128 v[182:185], v145 offset:6144
	ds_read_b128 v[186:189], v145 offset:7168
	s_add_i32 m0, s53, 0xc000
	s_nop 0
	global_load_lds_dwordx4 v130, s[38:39]
	s_add_i32 m0, s53, 0xe000
	s_nop 0
	global_load_lds_dwordx4 v132, s[38:39]
	s_waitcnt lgkmcnt(8)
	s_barrier
	s_waitcnt lgkmcnt(0)
	s_setprio 1
	s_waitcnt lgkmcnt(0)
	v_mfma_f32_16x16x32_bf16 v[126:129], v[136:139], v[158:161], v[126:129]
	v_mfma_f32_16x16x32_bf16 v[122:125], v[150:153], v[158:161], v[122:125]
	v_mfma_f32_16x16x32_bf16 v[110:113], v[136:139], v[166:169], v[110:113]
	v_mfma_f32_16x16x32_bf16 v[106:109], v[150:153], v[166:169], v[106:109]
	v_mfma_f32_16x16x32_bf16 v[94:97], v[136:139], v[174:177], v[94:97]
	v_mfma_f32_16x16x32_bf16 v[90:93], v[150:153], v[174:177], v[90:93]
	v_mfma_f32_16x16x32_bf16 v[78:81], v[136:139], v[182:185], v[78:81]
	v_mfma_f32_16x16x32_bf16 v[74:77], v[150:153], v[182:185], v[74:77]
	v_mfma_f32_16x16x32_bf16 v[126:129], v[140:143], v[162:165], v[126:129]
	v_mfma_f32_16x16x32_bf16 v[122:125], v[154:157], v[162:165], v[122:125]
	v_mfma_f32_16x16x32_bf16 v[110:113], v[140:143], v[170:173], v[110:113]
	v_mfma_f32_16x16x32_bf16 v[106:109], v[154:157], v[170:173], v[106:109]
	v_mfma_f32_16x16x32_bf16 v[94:97], v[140:143], v[178:181], v[94:97]
	v_mfma_f32_16x16x32_bf16 v[90:93], v[154:157], v[178:181], v[90:93]
	v_mfma_f32_16x16x32_bf16 v[78:81], v[140:143], v[186:189], v[78:81]
	v_mfma_f32_16x16x32_bf16 v[74:77], v[154:157], v[186:189], v[74:77]
	s_setprio 0
	s_barrier
	s_mov_b64 s[38:39], s[42:43]
	s_add_i32 s68, s62, s52
	ds_read_b128 v[190:193], v146
	ds_read_b128 v[194:197], v146 offset:1024
	ds_read_b128 v[198:201], v146 offset:2048
	ds_read_b128 v[202:205], v146 offset:3072
	s_mov_b32 m0, s68
	s_nop 0
	global_load_lds_dwordx4 v130, s[38:39]
	s_add_i32 m0, s68, 0x2000
	s_nop 0
	global_load_lds_dwordx4 v132, s[38:39]
	s_barrier
	s_waitcnt lgkmcnt(0)
	s_setprio 1
	s_waitcnt lgkmcnt(0)
	v_mfma_f32_16x16x32_bf16 v[118:121], v[190:193], v[158:161], v[118:121]
	v_mfma_f32_16x16x32_bf16 v[114:117], v[198:201], v[158:161], v[114:117]
	v_mfma_f32_16x16x32_bf16 v[102:105], v[190:193], v[166:169], v[102:105]
	v_mfma_f32_16x16x32_bf16 v[98:101], v[198:201], v[166:169], v[98:101]
	v_mfma_f32_16x16x32_bf16 v[86:89], v[190:193], v[174:177], v[86:89]
	v_mfma_f32_16x16x32_bf16 v[82:85], v[198:201], v[174:177], v[82:85]
	v_mfma_f32_16x16x32_bf16 v[70:73], v[190:193], v[182:185], v[70:73]
	v_mfma_f32_16x16x32_bf16 v[66:69], v[198:201], v[182:185], v[66:69]
	v_mfma_f32_16x16x32_bf16 v[118:121], v[194:197], v[162:165], v[118:121]
	v_mfma_f32_16x16x32_bf16 v[114:117], v[202:205], v[162:165], v[114:117]
	v_mfma_f32_16x16x32_bf16 v[102:105], v[194:197], v[170:173], v[102:105]
	v_mfma_f32_16x16x32_bf16 v[98:101], v[202:205], v[170:173], v[98:101]
	v_mfma_f32_16x16x32_bf16 v[86:89], v[194:197], v[178:181], v[86:89]
	v_mfma_f32_16x16x32_bf16 v[82:85], v[202:205], v[178:181], v[82:85]
	v_mfma_f32_16x16x32_bf16 v[70:73], v[194:197], v[186:189], v[70:73]
	v_mfma_f32_16x16x32_bf16 v[66:69], v[202:205], v[186:189], v[66:69]
	s_setprio 0
	s_mov_b64 s[38:39], s[46:47]
	s_mov_b32 m0, s53
	s_barrier
	ds_read_b128 v[158:161], v145 offset:16384
	ds_read_b128 v[162:165], v145 offset:17408
	ds_read_b128 v[166:169], v145 offset:18432
	ds_read_b128 v[170:173], v145 offset:19456
	ds_read_b128 v[174:177], v145 offset:20480
	ds_read_b128 v[178:181], v145 offset:21504
	ds_read_b128 v[182:185], v145 offset:22528
	ds_read_b128 v[186:189], v145 offset:23552
	s_nop 0
	global_load_lds_dwordx4 v130, s[38:39]
	s_mov_b32 m0, s54
	s_nop 0
	global_load_lds_dwordx4 v132, s[38:39]
	s_barrier
	s_waitcnt lgkmcnt(0)
	s_setprio 1
	s_waitcnt lgkmcnt(0)
	v_mfma_f32_16x16x32_bf16 v[62:65], v[136:139], v[158:161], v[62:65]
	v_mfma_f32_16x16x32_bf16 v[58:61], v[150:153], v[158:161], v[58:61]
	v_mfma_f32_16x16x32_bf16 v[46:49], v[136:139], v[166:169], v[46:49]
	v_mfma_f32_16x16x32_bf16 v[42:45], v[150:153], v[166:169], v[42:45]
	v_mfma_f32_16x16x32_bf16 v[30:33], v[136:139], v[174:177], v[30:33]
	v_mfma_f32_16x16x32_bf16 v[26:29], v[150:153], v[174:177], v[26:29]
	v_mfma_f32_16x16x32_bf16 v[14:17], v[136:139], v[182:185], v[14:17]
	v_mfma_f32_16x16x32_bf16 v[10:13], v[150:153], v[182:185], v[10:13]
	v_mfma_f32_16x16x32_bf16 v[62:65], v[140:143], v[162:165], v[62:65]
	v_mfma_f32_16x16x32_bf16 v[58:61], v[154:157], v[162:165], v[58:61]
	v_mfma_f32_16x16x32_bf16 v[46:49], v[140:143], v[170:173], v[46:49]
	v_mfma_f32_16x16x32_bf16 v[42:45], v[154:157], v[170:173], v[42:45]
	v_mfma_f32_16x16x32_bf16 v[30:33], v[140:143], v[178:181], v[30:33]
	v_mfma_f32_16x16x32_bf16 v[26:29], v[154:157], v[178:181], v[26:29]
	v_mfma_f32_16x16x32_bf16 v[14:17], v[140:143], v[186:189], v[14:17]
	v_mfma_f32_16x16x32_bf16 v[10:13], v[154:157], v[186:189], v[10:13]
	s_setprio 0
	s_barrier
	s_add_u32 s38, s42, 0x40000
	s_addc_u32 s39, s43, 0
	s_add_i32 s68, s63, s52
	s_mov_b32 m0, s68
	s_nop 0
	global_load_lds_dwordx4 v130, s[38:39]
	s_add_i32 m0, s68, 0x2000
	s_nop 0
	global_load_lds_dwordx4 v132, s[38:39]
	s_waitcnt vmcnt(6)
	s_barrier
	s_setprio 1
	v_mfma_f32_16x16x32_bf16 v[54:57], v[190:193], v[158:161], v[54:57]
	v_mfma_f32_16x16x32_bf16 v[50:53], v[198:201], v[158:161], v[50:53]
	v_mfma_f32_16x16x32_bf16 v[38:41], v[190:193], v[166:169], v[38:41]
	v_mfma_f32_16x16x32_bf16 v[34:37], v[198:201], v[166:169], v[34:37]
	v_mfma_f32_16x16x32_bf16 v[22:25], v[190:193], v[174:177], v[22:25]
	v_mfma_f32_16x16x32_bf16 v[18:21], v[198:201], v[174:177], v[18:21]
	v_mfma_f32_16x16x32_bf16 v[6:9], v[190:193], v[182:185], v[6:9]
	v_mfma_f32_16x16x32_bf16 v[2:5], v[198:201], v[182:185], v[2:5]
	v_mfma_f32_16x16x32_bf16 v[54:57], v[194:197], v[162:165], v[54:57]
	v_mfma_f32_16x16x32_bf16 v[50:53], v[202:205], v[162:165], v[50:53]
	v_mfma_f32_16x16x32_bf16 v[38:41], v[194:197], v[170:173], v[38:41]
	v_mfma_f32_16x16x32_bf16 v[34:37], v[202:205], v[170:173], v[34:37]
	v_mfma_f32_16x16x32_bf16 v[22:25], v[194:197], v[178:181], v[22:25]
	v_mfma_f32_16x16x32_bf16 v[18:21], v[202:205], v[178:181], v[18:21]
	v_mfma_f32_16x16x32_bf16 v[6:9], v[194:197], v[186:189], v[6:9]
	v_mfma_f32_16x16x32_bf16 v[2:5], v[202:205], v[186:189], v[2:5]
	s_setprio 0
	s_add_i32 s68, 0, 0x18000
	v_add_u32_e32 v134, s68, v1
	s_barrier
	ds_read_b128 v[136:139], v134
	ds_read_b128 v[140:143], v134 offset:1024
	ds_read_b128 v[150:153], v134 offset:2048
	ds_read_b128 v[154:157], v134 offset:3072
	s_add_u32 s38, s46, 0x40000
	s_addc_u32 s39, s47, 0
	s_mov_b32 m0, s55
	ds_read_b128 v[158:161], v145 offset:32768
	ds_read_b128 v[162:165], v145 offset:33792
	ds_read_b128 v[166:169], v145 offset:34816
	ds_read_b128 v[170:173], v145 offset:35840
	ds_read_b128 v[174:177], v145 offset:36864
	ds_read_b128 v[178:181], v145 offset:37888
	ds_read_b128 v[182:185], v145 offset:38912
	ds_read_b128 v[186:189], v145 offset:39936
	s_nop 0
	global_load_lds_dwordx4 v130, s[38:39]
	s_mov_b32 m0, s56
	s_nop 0
	global_load_lds_dwordx4 v132, s[38:39]
	s_waitcnt lgkmcnt(8)
	s_barrier
	s_waitcnt lgkmcnt(0)
	s_setprio 1
	s_waitcnt lgkmcnt(0)
	v_mfma_f32_16x16x32_bf16 v[126:129], v[136:139], v[158:161], v[126:129]
	v_mfma_f32_16x16x32_bf16 v[122:125], v[150:153], v[158:161], v[122:125]
	v_mfma_f32_16x16x32_bf16 v[110:113], v[136:139], v[166:169], v[110:113]
	v_mfma_f32_16x16x32_bf16 v[106:109], v[150:153], v[166:169], v[106:109]
	v_mfma_f32_16x16x32_bf16 v[94:97], v[136:139], v[174:177], v[94:97]
	v_mfma_f32_16x16x32_bf16 v[90:93], v[150:153], v[174:177], v[90:93]
	v_mfma_f32_16x16x32_bf16 v[78:81], v[136:139], v[182:185], v[78:81]
	v_mfma_f32_16x16x32_bf16 v[74:77], v[150:153], v[182:185], v[74:77]
	v_mfma_f32_16x16x32_bf16 v[126:129], v[140:143], v[162:165], v[126:129]
	v_mfma_f32_16x16x32_bf16 v[122:125], v[154:157], v[162:165], v[122:125]
	v_mfma_f32_16x16x32_bf16 v[110:113], v[140:143], v[170:173], v[110:113]
	v_mfma_f32_16x16x32_bf16 v[106:109], v[154:157], v[170:173], v[106:109]
	v_mfma_f32_16x16x32_bf16 v[94:97], v[140:143], v[178:181], v[94:97]
	v_mfma_f32_16x16x32_bf16 v[90:93], v[154:157], v[178:181], v[90:93]
	v_mfma_f32_16x16x32_bf16 v[78:81], v[140:143], v[186:189], v[78:81]
	v_mfma_f32_16x16x32_bf16 v[74:77], v[154:157], v[186:189], v[74:77]
	s_setprio 0
	s_barrier
	s_add_i32 s46, 0, 0x1c000
	s_add_u32 s38, s42, 0x80
	v_add_u32_e32 v134, s46, v1
	s_addc_u32 s39, s43, 0
	s_add_i32 s47, s68, s52
	ds_read_b128 v[190:193], v134
	ds_read_b128 v[194:197], v134 offset:1024
	ds_read_b128 v[198:201], v134 offset:2048
	ds_read_b128 v[202:205], v134 offset:3072
	s_mov_b32 m0, s47
	s_nop 0
	global_load_lds_dwordx4 v130, s[38:39]
	s_add_i32 m0, s47, 0x2000
	s_nop 0
	global_load_lds_dwordx4 v132, s[38:39]
	s_barrier
	s_waitcnt lgkmcnt(0)
	s_setprio 1
	s_waitcnt lgkmcnt(0)
	v_mfma_f32_16x16x32_bf16 v[118:121], v[190:193], v[158:161], v[118:121]
	v_mfma_f32_16x16x32_bf16 v[114:117], v[198:201], v[158:161], v[114:117]
	v_mfma_f32_16x16x32_bf16 v[102:105], v[190:193], v[166:169], v[102:105]
	v_mfma_f32_16x16x32_bf16 v[98:101], v[198:201], v[166:169], v[98:101]
	v_mfma_f32_16x16x32_bf16 v[86:89], v[190:193], v[174:177], v[86:89]
	v_mfma_f32_16x16x32_bf16 v[82:85], v[198:201], v[174:177], v[82:85]
	v_mfma_f32_16x16x32_bf16 v[70:73], v[190:193], v[182:185], v[70:73]
	v_mfma_f32_16x16x32_bf16 v[66:69], v[198:201], v[182:185], v[66:69]
	v_mfma_f32_16x16x32_bf16 v[118:121], v[194:197], v[162:165], v[118:121]
	v_mfma_f32_16x16x32_bf16 v[114:117], v[202:205], v[162:165], v[114:117]
	v_mfma_f32_16x16x32_bf16 v[102:105], v[194:197], v[170:173], v[102:105]
	v_mfma_f32_16x16x32_bf16 v[98:101], v[202:205], v[170:173], v[98:101]
	v_mfma_f32_16x16x32_bf16 v[86:89], v[194:197], v[178:181], v[86:89]
	v_mfma_f32_16x16x32_bf16 v[82:85], v[202:205], v[178:181], v[82:85]
	v_mfma_f32_16x16x32_bf16 v[70:73], v[194:197], v[186:189], v[70:73]
	v_mfma_f32_16x16x32_bf16 v[66:69], v[202:205], v[186:189], v[66:69]
	s_setprio 0
	s_mov_b32 m0, s58
	s_barrier
	ds_read_b128 v[158:161], v145 offset:49152
	ds_read_b128 v[162:165], v145 offset:50176
	ds_read_b128 v[166:169], v145 offset:51200
	ds_read_b128 v[170:173], v145 offset:52224
	ds_read_b128 v[174:177], v145 offset:53248
	ds_read_b128 v[178:181], v145 offset:54272
	ds_read_b128 v[182:185], v145 offset:55296
	ds_read_b128 v[186:189], v145 offset:56320
	s_nop 0
	global_load_lds_dwordx4 v130, s[44:45]
	s_mov_b32 m0, s59
	s_nop 0
	global_load_lds_dwordx4 v132, s[44:45]
	s_barrier
	s_waitcnt lgkmcnt(0)
	s_setprio 1
	s_waitcnt lgkmcnt(0)
	v_mfma_f32_16x16x32_bf16 v[62:65], v[136:139], v[158:161], v[62:65]
	v_mfma_f32_16x16x32_bf16 v[58:61], v[150:153], v[158:161], v[58:61]
	v_mfma_f32_16x16x32_bf16 v[46:49], v[136:139], v[166:169], v[46:49]
	v_mfma_f32_16x16x32_bf16 v[42:45], v[150:153], v[166:169], v[42:45]
	v_mfma_f32_16x16x32_bf16 v[30:33], v[136:139], v[174:177], v[30:33]
	v_mfma_f32_16x16x32_bf16 v[26:29], v[150:153], v[174:177], v[26:29]
	v_mfma_f32_16x16x32_bf16 v[14:17], v[136:139], v[182:185], v[14:17]
	v_mfma_f32_16x16x32_bf16 v[10:13], v[150:153], v[182:185], v[10:13]
	v_mfma_f32_16x16x32_bf16 v[62:65], v[140:143], v[162:165], v[62:65]
	v_mfma_f32_16x16x32_bf16 v[58:61], v[154:157], v[162:165], v[58:61]
	v_mfma_f32_16x16x32_bf16 v[46:49], v[140:143], v[170:173], v[46:49]
	v_mfma_f32_16x16x32_bf16 v[42:45], v[154:157], v[170:173], v[42:45]
	v_mfma_f32_16x16x32_bf16 v[30:33], v[140:143], v[178:181], v[30:33]
	v_mfma_f32_16x16x32_bf16 v[26:29], v[154:157], v[178:181], v[26:29]
	v_mfma_f32_16x16x32_bf16 v[14:17], v[140:143], v[186:189], v[14:17]
	v_mfma_f32_16x16x32_bf16 v[10:13], v[154:157], v[186:189], v[10:13]
	s_setprio 0
	s_barrier
	s_add_u32 s38, s42, 0x40080
	s_addc_u32 s39, s43, 0
	s_add_i32 s42, s46, s52
	s_mov_b32 m0, s42
	s_nop 0
	global_load_lds_dwordx4 v130, s[38:39]
	s_add_i32 m0, s42, 0x2000
	s_nop 0
	global_load_lds_dwordx4 v132, s[38:39]
	s_waitcnt vmcnt(6)
	s_barrier
	s_setprio 1
	v_mfma_f32_16x16x32_bf16 v[54:57], v[190:193], v[158:161], v[54:57]
	v_mfma_f32_16x16x32_bf16 v[50:53], v[198:201], v[158:161], v[50:53]
	v_mfma_f32_16x16x32_bf16 v[38:41], v[190:193], v[166:169], v[38:41]
	v_mfma_f32_16x16x32_bf16 v[34:37], v[198:201], v[166:169], v[34:37]
	v_mfma_f32_16x16x32_bf16 v[22:25], v[190:193], v[174:177], v[22:25]
	v_mfma_f32_16x16x32_bf16 v[18:21], v[198:201], v[174:177], v[18:21]
	v_mfma_f32_16x16x32_bf16 v[6:9], v[190:193], v[182:185], v[6:9]
	v_mfma_f32_16x16x32_bf16 v[2:5], v[198:201], v[182:185], v[2:5]
	v_mfma_f32_16x16x32_bf16 v[54:57], v[194:197], v[162:165], v[54:57]
	v_mfma_f32_16x16x32_bf16 v[50:53], v[202:205], v[162:165], v[50:53]
	v_mfma_f32_16x16x32_bf16 v[38:41], v[194:197], v[170:173], v[38:41]
	v_mfma_f32_16x16x32_bf16 v[34:37], v[202:205], v[170:173], v[34:37]
	v_mfma_f32_16x16x32_bf16 v[22:25], v[194:197], v[178:181], v[22:25]
	v_mfma_f32_16x16x32_bf16 v[18:21], v[202:205], v[178:181], v[18:21]
	v_mfma_f32_16x16x32_bf16 v[6:9], v[194:197], v[186:189], v[6:9]
	v_mfma_f32_16x16x32_bf16 v[2:5], v[202:205], v[186:189], v[2:5]
	s_setprio 0
	s_add_i32 s67, s67, 2
	s_add_u32 s65, s65, 0x100
	s_addc_u32 s66, s66, 0
	s_cmp_gt_u32 s67, 13
	s_mov_b64 s[38:39], s[40:41]
	s_barrier
	s_cbranch_scc0 .LBB0_339
	v_mov_b32_e32 v134, v0
	s_ashr_i32 s38, s0, 1
	v_readfirstlane_b32 s1, v134
	s_and_b32 s7, s1, 0xc0
	s_ashr_i32 s1, s1, 2
	s_andn2_b32 s1, s1, 63
	v_and_or_b32 v136, v134, 15, s1
	s_ashr_i32 s39, s38, 31
	s_lshl_b64 s[40:41], s[38:39], 19
	v_lshl_add_u32 v140, s6, 8, v136
	s_or_b32 s40, s40, s7
	v_lshrrev_b32_e32 v134, 1, v134
	v_ashrrev_i32_e32 v141, 31, v140
	s_and_b32 s29, s0, 1
	v_and_b32_e32 v139, 24, v134
	v_lshlrev_b64 v[136:137], 8, v[140:141]
	s_bitcmp1_b32 s0, 0
	v_lshl_add_u64 v[142:143], v[136:137], 0, s[40:41]
	s_mov_b64 s[6:7], -1
	s_cselect_b64 s[0:1], -1, 0
	s_cmp_eq_u32 s29, 0
	v_lshlrev_b32_e32 v134, 2, v139
	v_lshlrev_b32_e32 v138, 1, v139
	v_or_b32_e32 v136, 32, v139
	s_cbranch_scc1 .LBB0_342
	v_lshl_add_u64 v[150:151], v[142:143], 2, s[16:17]
	v_lshl_add_u64 v[154:155], v[150:151], 0, v[134:135]
	v_lshl_add_u64 v[150:151], v[142:143], 1, s[20:21]
	v_mov_b32_e32 v139, v135
	v_lshl_add_u64 v[156:157], v[150:151], 0, v[138:139]
	v_cvt_pk_bf16_f32 v150, v126, v127
	v_cvt_pk_bf16_f32 v151, v128, v129
	v_cvt_pk_bf16_f32 v152, v122, v123
	v_cvt_pk_bf16_f32 v153, v124, v125
	v_mov_b32_e32 v137, v135
	s_mov_b64 s[6:7], 0
	global_store_dwordx4 v[154:155], v[126:129], off
	global_store_dwordx4 v[154:155], v[122:125], off offset:16
	global_store_dwordx4 v[156:157], v[150:153], off
	global_store_dwordx4 v[154:155], v[118:121], off offset:128

.LBB0_394:
	s_add_u32 s34, s20, s24
	s_addc_u32 s35, s21, s25
	s_add_u32 s36, s34, 0x100
	s_addc_u32 s37, s35, 0
	s_and_b64 s[30:31], s[28:29], exec
	s_cselect_b32 s39, s15, s37
	s_cselect_b32 s38, s14, s36
	s_add_u32 s24, s6, s24
	s_addc_u32 s25, s7, s25
	s_add_u32 s30, s24, 0x100
	s_addc_u32 s31, s25, 0
	s_add_u32 s24, s38, 0x80
	s_addc_u32 s25, s39, 0
	s_and_b64 s[28:29], s[28:29], exec
	s_cselect_b32 s41, s1, s31
	s_cselect_b32 s40, s13, s30
	s_add_u32 s42, s34, 0x12080
	s_addc_u32 s43, s35, 0
	s_add_i32 s78, s63, s49
	s_add_i32 m0, s50, 0xc000
	s_add_i32 s79, s50, 0xe000
	s_add_i32 s77, s78, 0x2000
	s_add_u32 s36, s40, 0x10000
	s_addc_u32 s37, s41, 0
	s_add_i32 s75, s64, s49
	s_add_i32 s73, s75, 0x2000
	s_add_i32 s72, 0, 0x18000
	s_add_u32 s34, s38, 0x12000
	ds_read_b128 v[146:149], v140
	ds_read_b128 v[150:153], v140 offset:1024
	ds_read_b128 v[154:157], v140 offset:2048
	ds_read_b128 v[158:161], v140 offset:3072
	s_addc_u32 s35, s39, 0
	s_add_i32 s70, 0, 0x1c000
	s_add_u32 s30, s40, 0x80
	s_addc_u32 s31, s41, 0
	s_add_i32 s71, s72, s49
	s_add_i32 s69, s71, 0x2000
	s_add_u32 s28, s40, 0x10080
	s_addc_u32 s29, s41, 0
	s_add_i32 s76, s70, s49
	s_add_i32 s74, s76, 0x2000
	ds_read_b128 v[162:165], v141
	ds_read_b128 v[166:169], v141 offset:1024
	ds_read_b128 v[170:173], v141 offset:2048
	ds_read_b128 v[174:177], v141 offset:3072
	ds_read_b128 v[178:181], v141 offset:4096
	ds_read_b128 v[182:185], v141 offset:5120
	ds_read_b128 v[186:189], v141 offset:6144
	ds_read_b128 v[190:193], v141 offset:7168
	s_nop 0
	global_load_lds_dwordx4 v130, s[42:43]
	s_mov_b32 m0, s79
	s_nop 0
	global_load_lds_dwordx4 v134, s[42:43]
	s_waitcnt lgkmcnt(8)
	s_barrier
	s_waitcnt lgkmcnt(0)
	s_setprio 1
	s_waitcnt lgkmcnt(0)
	v_mfma_f32_16x16x32_bf16 v[126:129], v[146:149], v[162:165], v[126:129]
	v_mfma_f32_16x16x32_bf16 v[122:125], v[154:157], v[162:165], v[122:125]
	v_mfma_f32_16x16x32_bf16 v[110:113], v[146:149], v[170:173], v[110:113]
	v_mfma_f32_16x16x32_bf16 v[106:109], v[154:157], v[170:173], v[106:109]
	v_mfma_f32_16x16x32_bf16 v[94:97], v[146:149], v[178:181], v[94:97]
	v_mfma_f32_16x16x32_bf16 v[90:93], v[154:157], v[178:181], v[90:93]
	v_mfma_f32_16x16x32_bf16 v[78:81], v[146:149], v[186:189], v[78:81]
	v_mfma_f32_16x16x32_bf16 v[74:77], v[154:157], v[186:189], v[74:77]
	v_mfma_f32_16x16x32_bf16 v[126:129], v[150:153], v[166:169], v[126:129]
	v_mfma_f32_16x16x32_bf16 v[122:125], v[158:161], v[166:169], v[122:125]
	v_mfma_f32_16x16x32_bf16 v[110:113], v[150:153], v[174:177], v[110:113]
	v_mfma_f32_16x16x32_bf16 v[106:109], v[158:161], v[174:177], v[106:109]
	v_mfma_f32_16x16x32_bf16 v[94:97], v[150:153], v[182:185], v[94:97]
	v_mfma_f32_16x16x32_bf16 v[90:93], v[158:161], v[182:185], v[90:93]
	v_mfma_f32_16x16x32_bf16 v[78:81], v[150:153], v[190:193], v[78:81]
	v_mfma_f32_16x16x32_bf16 v[74:77], v[158:161], v[190:193], v[74:77]
	s_setprio 0
	s_barrier
	s_mov_b32 m0, s78
	ds_read_b128 v[194:197], v142
	ds_read_b128 v[198:201], v142 offset:1024
	ds_read_b128 v[202:205], v142 offset:2048
	ds_read_b128 v[206:209], v142 offset:3072
	s_nop 0
	global_load_lds_dwordx4 v132, s[40:41]
	s_mov_b32 m0, s77
	s_nop 0
	global_load_lds_dwordx4 v136, s[40:41]
	s_barrier
	s_waitcnt lgkmcnt(0)
	s_setprio 1
	s_waitcnt lgkmcnt(0)
	v_mfma_f32_16x16x32_bf16 v[118:121], v[194:197], v[162:165], v[118:121]
	v_mfma_f32_16x16x32_bf16 v[114:117], v[202:205], v[162:165], v[114:117]
	v_mfma_f32_16x16x32_bf16 v[102:105], v[194:197], v[170:173], v[102:105]
	v_mfma_f32_16x16x32_bf16 v[98:101], v[202:205], v[170:173], v[98:101]
	v_mfma_f32_16x16x32_bf16 v[86:89], v[194:197], v[178:181], v[86:89]
	v_mfma_f32_16x16x32_bf16 v[82:85], v[202:205], v[178:181], v[82:85]
	v_mfma_f32_16x16x32_bf16 v[70:73], v[194:197], v[186:189], v[70:73]
	v_mfma_f32_16x16x32_bf16 v[66:69], v[202:205], v[186:189], v[66:69]
	v_mfma_f32_16x16x32_bf16 v[118:121], v[198:201], v[166:169], v[118:121]
	v_mfma_f32_16x16x32_bf16 v[114:117], v[206:209], v[166:169], v[114:117]
	v_mfma_f32_16x16x32_bf16 v[102:105], v[198:201], v[174:177], v[102:105]
	v_mfma_f32_16x16x32_bf16 v[98:101], v[206:209], v[174:177], v[98:101]
	v_mfma_f32_16x16x32_bf16 v[86:89], v[198:201], v[182:185], v[86:89]
	v_mfma_f32_16x16x32_bf16 v[82:85], v[206:209], v[182:185], v[82:85]
	v_mfma_f32_16x16x32_bf16 v[70:73], v[198:201], v[190:193], v[70:73]
	v_mfma_f32_16x16x32_bf16 v[66:69], v[206:209], v[190:193], v[66:69]
	s_setprio 0
	s_mov_b32 m0, s50
	s_barrier
	ds_read_b128 v[162:165], v141 offset:16384
	ds_read_b128 v[166:169], v141 offset:17408
	ds_read_b128 v[170:173], v141 offset:18432
	ds_read_b128 v[174:177], v141 offset:19456
	ds_read_b128 v[178:181], v141 offset:20480
	ds_read_b128 v[182:185], v141 offset:21504
	ds_read_b128 v[186:189], v141 offset:22528
	ds_read_b128 v[190:193], v141 offset:23552
	s_nop 0
	global_load_lds_dwordx4 v130, s[38:39]
	s_mov_b32 m0, s51
	s_nop 0
	global_load_lds_dwordx4 v134, s[38:39]
	s_barrier
	s_waitcnt lgkmcnt(0)
	s_setprio 1
	s_waitcnt lgkmcnt(0)
	v_mfma_f32_16x16x32_bf16 v[62:65], v[146:149], v[162:165], v[62:65]
	v_mfma_f32_16x16x32_bf16 v[58:61], v[154:157], v[162:165], v[58:61]
	v_mfma_f32_16x16x32_bf16 v[46:49], v[146:149], v[170:173], v[46:49]
	v_mfma_f32_16x16x32_bf16 v[42:45], v[154:157], v[170:173], v[42:45]
	v_mfma_f32_16x16x32_bf16 v[30:33], v[146:149], v[178:181], v[30:33]
	v_mfma_f32_16x16x32_bf16 v[26:29], v[154:157], v[178:181], v[26:29]
	v_mfma_f32_16x16x32_bf16 v[14:17], v[146:149], v[186:189], v[14:17]
	v_mfma_f32_16x16x32_bf16 v[10:13], v[154:157], v[186:189], v[10:13]
	v_mfma_f32_16x16x32_bf16 v[62:65], v[150:153], v[166:169], v[62:65]
	v_mfma_f32_16x16x32_bf16 v[58:61], v[158:161], v[166:169], v[58:61]
	v_mfma_f32_16x16x32_bf16 v[46:49], v[150:153], v[174:177], v[46:49]
	v_mfma_f32_16x16x32_bf16 v[42:45], v[158:161], v[174:177], v[42:45]
	v_mfma_f32_16x16x32_bf16 v[30:33], v[150:153], v[182:185], v[30:33]
	v_mfma_f32_16x16x32_bf16 v[26:29], v[158:161], v[182:185], v[26:29]
	v_mfma_f32_16x16x32_bf16 v[14:17], v[150:153], v[190:193], v[14:17]
	v_mfma_f32_16x16x32_bf16 v[10:13], v[158:161], v[190:193], v[10:13]
	s_setprio 0
	s_barrier
	s_mov_b32 m0, s75
	s_nop 0
	global_load_lds_dwordx4 v132, s[36:37]
	s_mov_b32 m0, s73
	s_nop 0
	global_load_lds_dwordx4 v136, s[36:37]
	s_waitcnt vmcnt(6)
	s_barrier
	s_setprio 1
	v_mfma_f32_16x16x32_bf16 v[54:57], v[194:197], v[162:165], v[54:57]
	v_mfma_f32_16x16x32_bf16 v[50:53], v[202:205], v[162:165], v[50:53]
	v_mfma_f32_16x16x32_bf16 v[38:41], v[194:197], v[170:173], v[38:41]
	v_mfma_f32_16x16x32_bf16 v[34:37], v[202:205], v[170:173], v[34:37]
	v_mfma_f32_16x16x32_bf16 v[22:25], v[194:197], v[178:181], v[22:25]
	v_mfma_f32_16x16x32_bf16 v[18:21], v[202:205], v[178:181], v[18:21]
	v_mfma_f32_16x16x32_bf16 v[6:9], v[194:197], v[186:189], v[6:9]
	v_mfma_f32_16x16x32_bf16 v[2:5], v[202:205], v[186:189], v[2:5]
	v_mfma_f32_16x16x32_bf16 v[54:57], v[198:201], v[166:169], v[54:57]
	v_mfma_f32_16x16x32_bf16 v[50:53], v[206:209], v[166:169], v[50:53]
	v_mfma_f32_16x16x32_bf16 v[38:41], v[198:201], v[174:177], v[38:41]
	v_mfma_f32_16x16x32_bf16 v[34:37], v[206:209], v[174:177], v[34:37]
	v_mfma_f32_16x16x32_bf16 v[22:25], v[198:201], v[182:185], v[22:25]
	v_mfma_f32_16x16x32_bf16 v[18:21], v[206:209], v[182:185], v[18:21]
	v_mfma_f32_16x16x32_bf16 v[6:9], v[198:201], v[190:193], v[6:9]
	v_mfma_f32_16x16x32_bf16 v[2:5], v[206:209], v[190:193], v[2:5]
	s_setprio 0
	v_add_u32_e32 v138, s72, v1
	s_barrier
	ds_read_b128 v[146:149], v138
	ds_read_b128 v[150:153], v138 offset:1024
	ds_read_b128 v[154:157], v138 offset:2048
	ds_read_b128 v[158:161], v138 offset:3072
	s_mov_b32 m0, s52
	ds_read_b128 v[162:165], v141 offset:32768
	ds_read_b128 v[166:169], v141 offset:33792
	ds_read_b128 v[170:173], v141 offset:34816
	ds_read_b128 v[174:177], v141 offset:35840
	ds_read_b128 v[178:181], v141 offset:36864
	ds_read_b128 v[182:185], v141 offset:37888
	ds_read_b128 v[186:189], v141 offset:38912
	ds_read_b128 v[190:193], v141 offset:39936
	s_nop 0
	global_load_lds_dwordx4 v130, s[34:35]
	s_mov_b32 m0, s53
	s_nop 0
	global_load_lds_dwordx4 v134, s[34:35]
	s_waitcnt lgkmcnt(8)
	s_barrier
	s_waitcnt lgkmcnt(0)
	s_setprio 1
	s_waitcnt lgkmcnt(0)
	v_mfma_f32_16x16x32_bf16 v[126:129], v[146:149], v[162:165], v[126:129]
	v_mfma_f32_16x16x32_bf16 v[122:125], v[154:157], v[162:165], v[122:125]
	v_mfma_f32_16x16x32_bf16 v[110:113], v[146:149], v[170:173], v[110:113]
	v_mfma_f32_16x16x32_bf16 v[106:109], v[154:157], v[170:173], v[106:109]
	v_mfma_f32_16x16x32_bf16 v[94:97], v[146:149], v[178:181], v[94:97]
	v_mfma_f32_16x16x32_bf16 v[90:93], v[154:157], v[178:181], v[90:93]
	v_mfma_f32_16x16x32_bf16 v[78:81], v[146:149], v[186:189], v[78:81]
	v_mfma_f32_16x16x32_bf16 v[74:77], v[154:157], v[186:189], v[74:77]
	v_mfma_f32_16x16x32_bf16 v[126:129], v[150:153], v[166:169], v[126:129]
	v_mfma_f32_16x16x32_bf16 v[122:125], v[158:161], v[166:169], v[122:125]
	v_mfma_f32_16x16x32_bf16 v[110:113], v[150:153], v[174:177], v[110:113]
	v_mfma_f32_16x16x32_bf16 v[106:109], v[158:161], v[174:177], v[106:109]
	v_mfma_f32_16x16x32_bf16 v[94:97], v[150:153], v[182:185], v[94:97]
	v_mfma_f32_16x16x32_bf16 v[90:93], v[158:161], v[182:185], v[90:93]
	v_mfma_f32_16x16x32_bf16 v[78:81], v[150:153], v[190:193], v[78:81]
	v_mfma_f32_16x16x32_bf16 v[74:77], v[158:161], v[190:193], v[74:77]
	s_setprio 0
	s_barrier
	v_add_u32_e32 v138, s70, v1
	s_mov_b32 m0, s71
	ds_read_b128 v[194:197], v138
	ds_read_b128 v[198:201], v138 offset:1024
	ds_read_b128 v[202:205], v138 offset:2048
	ds_read_b128 v[206:209], v138 offset:3072
	s_nop 0
	global_load_lds_dwordx4 v132, s[30:31]
	s_mov_b32 m0, s69
	s_nop 0
	global_load_lds_dwordx4 v136, s[30:31]
	s_barrier
	s_waitcnt lgkmcnt(0)
	s_setprio 1
	s_waitcnt lgkmcnt(0)
	v_mfma_f32_16x16x32_bf16 v[118:121], v[194:197], v[162:165], v[118:121]
	v_mfma_f32_16x16x32_bf16 v[114:117], v[202:205], v[162:165], v[114:117]
	v_mfma_f32_16x16x32_bf16 v[102:105], v[194:197], v[170:173], v[102:105]
	v_mfma_f32_16x16x32_bf16 v[98:101], v[202:205], v[170:173], v[98:101]
	v_mfma_f32_16x16x32_bf16 v[86:89], v[194:197], v[178:181], v[86:89]
	v_mfma_f32_16x16x32_bf16 v[82:85], v[202:205], v[178:181], v[82:85]
	v_mfma_f32_16x16x32_bf16 v[70:73], v[194:197], v[186:189], v[70:73]
	v_mfma_f32_16x16x32_bf16 v[66:69], v[202:205], v[186:189], v[66:69]
	v_mfma_f32_16x16x32_bf16 v[118:121], v[198:201], v[166:169], v[118:121]
	v_mfma_f32_16x16x32_bf16 v[114:117], v[206:209], v[166:169], v[114:117]
	v_mfma_f32_16x16x32_bf16 v[102:105], v[198:201], v[174:177], v[102:105]
	v_mfma_f32_16x16x32_bf16 v[98:101], v[206:209], v[174:177], v[98:101]
	v_mfma_f32_16x16x32_bf16 v[86:89], v[198:201], v[182:185], v[86:89]
	v_mfma_f32_16x16x32_bf16 v[82:85], v[206:209], v[182:185], v[82:85]
	v_mfma_f32_16x16x32_bf16 v[70:73], v[198:201], v[190:193], v[70:73]
	v_mfma_f32_16x16x32_bf16 v[66:69], v[206:209], v[190:193], v[66:69]
	s_setprio 0
	s_mov_b32 m0, s58
	s_barrier
	ds_read_b128 v[162:165], v141 offset:49152
	ds_read_b128 v[166:169], v141 offset:50176
	ds_read_b128 v[170:173], v141 offset:51200
	ds_read_b128 v[174:177], v141 offset:52224
	ds_read_b128 v[178:181], v141 offset:53248
	ds_read_b128 v[182:185], v141 offset:54272
	ds_read_b128 v[186:189], v141 offset:55296
	ds_read_b128 v[190:193], v141 offset:56320
	s_nop 0
	global_load_lds_dwordx4 v130, s[24:25]
	s_mov_b32 m0, s59
	s_nop 0
	global_load_lds_dwordx4 v134, s[24:25]
	s_barrier
	s_waitcnt lgkmcnt(0)
	s_setprio 1
	s_waitcnt lgkmcnt(0)
	v_mfma_f32_16x16x32_bf16 v[62:65], v[146:149], v[162:165], v[62:65]
	v_mfma_f32_16x16x32_bf16 v[58:61], v[154:157], v[162:165], v[58:61]
	v_mfma_f32_16x16x32_bf16 v[46:49], v[146:149], v[170:173], v[46:49]
	v_mfma_f32_16x16x32_bf16 v[42:45], v[154:157], v[170:173], v[42:45]
	v_mfma_f32_16x16x32_bf16 v[30:33], v[146:149], v[178:181], v[30:33]
	v_mfma_f32_16x16x32_bf16 v[26:29], v[154:157], v[178:181], v[26:29]
	v_mfma_f32_16x16x32_bf16 v[14:17], v[146:149], v[186:189], v[14:17]
	v_mfma_f32_16x16x32_bf16 v[10:13], v[154:157], v[186:189], v[10:13]
	v_mfma_f32_16x16x32_bf16 v[62:65], v[150:153], v[166:169], v[62:65]
	v_mfma_f32_16x16x32_bf16 v[58:61], v[158:161], v[166:169], v[58:61]
	v_mfma_f32_16x16x32_bf16 v[46:49], v[150:153], v[174:177], v[46:49]
	v_mfma_f32_16x16x32_bf16 v[42:45], v[158:161], v[174:177], v[42:45]
	v_mfma_f32_16x16x32_bf16 v[30:33], v[150:153], v[182:185], v[30:33]
	v_mfma_f32_16x16x32_bf16 v[26:29], v[158:161], v[182:185], v[26:29]
	v_mfma_f32_16x16x32_bf16 v[14:17], v[150:153], v[190:193], v[14:17]
	v_mfma_f32_16x16x32_bf16 v[10:13], v[158:161], v[190:193], v[10:13]
	s_setprio 0
	s_barrier
	s_mov_b32 m0, s76
	s_nop 0
	global_load_lds_dwordx4 v132, s[28:29]
	s_mov_b32 m0, s74
	s_nop 0
	global_load_lds_dwordx4 v136, s[28:29]
	s_waitcnt vmcnt(6)
	s_barrier
	s_setprio 1
	v_mfma_f32_16x16x32_bf16 v[54:57], v[194:197], v[162:165], v[54:57]
	v_mfma_f32_16x16x32_bf16 v[50:53], v[202:205], v[162:165], v[50:53]
	v_mfma_f32_16x16x32_bf16 v[38:41], v[194:197], v[170:173], v[38:41]
	v_mfma_f32_16x16x32_bf16 v[34:37], v[202:205], v[170:173], v[34:37]
	v_mfma_f32_16x16x32_bf16 v[22:25], v[194:197], v[178:181], v[22:25]
	v_mfma_f32_16x16x32_bf16 v[18:21], v[202:205], v[178:181], v[18:21]
	v_mfma_f32_16x16x32_bf16 v[6:9], v[194:197], v[186:189], v[6:9]
	v_mfma_f32_16x16x32_bf16 v[2:5], v[202:205], v[186:189], v[2:5]
	v_mfma_f32_16x16x32_bf16 v[54:57], v[198:201], v[166:169], v[54:57]
	v_mfma_f32_16x16x32_bf16 v[50:53], v[206:209], v[166:169], v[50:53]
	v_mfma_f32_16x16x32_bf16 v[38:41], v[198:201], v[174:177], v[38:41]
	v_mfma_f32_16x16x32_bf16 v[34:37], v[206:209], v[174:177], v[34:37]
	v_mfma_f32_16x16x32_bf16 v[22:25], v[198:201], v[182:185], v[22:25]
	v_mfma_f32_16x16x32_bf16 v[18:21], v[206:209], v[182:185], v[18:21]
	v_mfma_f32_16x16x32_bf16 v[6:9], v[198:201], v[190:193], v[6:9]
	v_mfma_f32_16x16x32_bf16 v[2:5], v[206:209], v[190:193], v[2:5]
	s_setprio 0
	s_andn2_b64 vcc, exec, s[22:23]
	s_mov_b64 s[28:29], -1
	s_mov_b64 s[22:23], 0
	s_mov_b64 s[24:25], 0x100
	s_barrier
	s_cbranch_vccz .LBB0_394
	v_mov_b32_e32 v154, v0
	s_ashr_i32 s1, s0, 31
	v_readfirstlane_b32 s6, v154
	s_bfe_u32 s13, s6, 0x20006
	s_ashr_i32 s6, s6, 2
	s_andn2_b32 s6, s6, 63
	s_ashr_i32 s7, s6, 31
	s_lshl_b64 s[20:21], s[0:1], 10
	s_add_u32 s22, s54, s20
	s_addc_u32 s23, s55, s21
	s_lshl_b64 s[20:21], s[6:7], 2
	v_and_b32_e32 v145, 15, v154
	s_add_u32 s20, s22, s20
	s_addc_u32 s21, s23, s21
	v_lshlrev_b32_e32 v138, 2, v145
	global_load_dword v153, v138, s[20:21] offset:64
	global_load_dword v152, v138, s[20:21] offset:128
	global_load_dword v151, v138, s[20:21] offset:192
	global_load_dword v150, v138, s[20:21] offset:512
	global_load_dword v149, v138, s[20:21] offset:576
	global_load_dword v148, v138, s[20:21] offset:640
	global_load_dword v147, v138, s[20:21] offset:704
	v_mul_f32_e32 v127, v127, v127
	v_mul_f32_e32 v123, v123, v123
	v_mul_f32_e32 v119, v119, v119
	v_mul_f32_e32 v115, v115, v115
	v_fmac_f32_e32 v127, v126, v126
	v_mul_f32_e32 v126, v129, v129
	v_fmac_f32_e32 v123, v122, v122
	v_mul_f32_e32 v122, v125, v125
	v_fmac_f32_e32 v119, v118, v118
	v_mul_f32_e32 v118, v121, v121
	v_fmac_f32_e32 v115, v114, v114
	v_mul_f32_e32 v114, v117, v117
	v_fmac_f32_e32 v126, v128, v128
	v_fmac_f32_e32 v122, v124, v124
	v_fmac_f32_e32 v118, v120, v120
	v_fmac_f32_e32 v114, v116, v116
	v_add_f32_e32 v126, v127, v126
	v_add_f32_e32 v122, v123, v122
	v_add_f32_e32 v118, v119, v118
	v_add_f32_e32 v114, v115, v114
	v_add_f32_e32 v122, v126, v122
	v_add_f32_e32 v114, v118, v114
	v_add_f32_e32 v115, v122, v114
	ds_swizzle_b32 v116, v115 offset:swizzle(SWAP,16)
	v_and_b32_e32 v156, 64, v143
	v_xor_b32_e32 v155, 32, v143
	v_add_u32_e32 v156, 64, v156
	v_cmp_lt_i32_e32 vcc, v155, v156
	s_lshl_b32 s22, s68, 2
	s_or_b32 s22, s13, s22
	v_cndmask_b32_e32 v114, v143, v155, vcc
	s_lshl_b64 s[0:1], s[0:1], 8
	v_lshlrev_b32_e32 v114, 2, v114
	s_waitcnt lgkmcnt(0)
	v_add_f32_e32 v115, v115, v116
	s_add_u32 s0, s0, s6
	ds_bpermute_b32 v116, v114, v115
	s_addc_u32 s1, s1, s7
	s_ashr_i32 s23, s22, 31
	v_or_b32_e32 v146, s0, v145
	v_mov_b32_e32 v145, s1
	s_lshl_b64 s[0:1], s[22:23], 2
	v_and_b32_e32 v117, 48, v154
	s_add_u32 s0, s56, s0
	v_cmp_eq_u32_e64 s[6:7], 0, v117
	s_addc_u32 s1, s57, s1
	s_and_saveexec_b64 s[22:23], s[6:7]
	s_cbranch_execz .LBB0_397
	v_lshl_add_u64 v[118:119], s[20:21], 0, v[138:139]
	global_load_dword v118, v[118:119], off
	s_waitcnt lgkmcnt(0)
	v_add_f32_e32 v115, v115, v116
	v_mad_u64_u32 v[116:117], s[20:21], v146, 48, s[0:1]
	s_waitcnt vmcnt(0)
	v_add_f32_e32 v115, v115, v118
	v_fmamk_f32 v115, v115, 0x3c2aaaab, v144
	v_mul_f32_e32 v118, 0x4b800000, v115
	v_cmp_gt_f32_e32 vcc, s65, v115
	s_nop 1
	v_cndmask_b32_e32 v115, v115, v118, vcc
	v_rsq_f32_e32 v115, v115
	v_mov_b32_e32 v118, v117
	v_mad_u64_u32 v[118:119], s[20:21], v145, 48, v[118:119]
	v_mul_f32_e32 v117, 0x45800000, v115
	v_cndmask_b32_e32 v115, v115, v117, vcc
	v_mov_b32_e32 v117, v118
	global_store_dword v[116:117], v115, off

.LBB0_505:
	s_add_u32 s18, s16, 0x100
	s_addc_u32 s19, s17, 0
	s_cmp_eq_u32 s62, 12
	s_cselect_b32 s50, s9, s18
	s_cselect_b32 s51, s1, s19
	s_cselect_b32 s20, s43, s52
	s_cselect_b32 s21, s41, s53
	s_add_u32 s48, s50, 0x80
	s_addc_u32 s49, s51, 0
	s_add_i32 s64, 0, 0x10000
	v_add_u32_e32 v150, s64, v1
	ds_read_b128 v[132:135], v150
	ds_read_b128 v[142:145], v150 offset:1024
	ds_read_b128 v[146:149], v150 offset:2048
	ds_read_b128 v[150:153], v150 offset:3072
	s_add_u32 s16, s16, 0x40080
	s_addc_u32 s17, s17, 0
	ds_read_b128 v[154:157], v3
	ds_read_b128 v[158:161], v3 offset:1024
	ds_read_b128 v[162:165], v3 offset:2048
	ds_read_b128 v[166:169], v3 offset:3072
	ds_read_b128 v[170:173], v3 offset:4096
	ds_read_b128 v[174:177], v3 offset:5120
	ds_read_b128 v[178:181], v3 offset:6144
	ds_read_b128 v[182:185], v3 offset:7168
	s_add_i32 m0, s74, 0xc000
	s_nop 0
	global_load_lds_dwordx4 v136, s[16:17]
	s_add_i32 m0, s74, 0xe000
	s_nop 0
	global_load_lds_dwordx4 v138, s[16:17]
	s_waitcnt lgkmcnt(8)
	s_barrier
	s_waitcnt lgkmcnt(0)
	s_setprio 1
	s_waitcnt lgkmcnt(0)
	v_mfma_f32_16x16x32_bf16 v[128:131], v[132:135], v[154:157], v[128:131]
	v_mfma_f32_16x16x32_bf16 v[124:127], v[146:149], v[154:157], v[124:127]
	v_mfma_f32_16x16x32_bf16 v[112:115], v[132:135], v[162:165], v[112:115]
	v_mfma_f32_16x16x32_bf16 v[108:111], v[146:149], v[162:165], v[108:111]
	v_mfma_f32_16x16x32_bf16 v[96:99], v[132:135], v[170:173], v[96:99]
	v_mfma_f32_16x16x32_bf16 v[92:95], v[146:149], v[170:173], v[92:95]
	v_mfma_f32_16x16x32_bf16 v[80:83], v[132:135], v[178:181], v[80:83]
	v_mfma_f32_16x16x32_bf16 v[76:79], v[146:149], v[178:181], v[76:79]
	v_mfma_f32_16x16x32_bf16 v[128:131], v[142:145], v[158:161], v[128:131]
	v_mfma_f32_16x16x32_bf16 v[124:127], v[150:153], v[158:161], v[124:127]
	v_mfma_f32_16x16x32_bf16 v[112:115], v[142:145], v[166:169], v[112:115]
	v_mfma_f32_16x16x32_bf16 v[108:111], v[150:153], v[166:169], v[108:111]
	v_mfma_f32_16x16x32_bf16 v[96:99], v[142:145], v[174:177], v[96:99]
	v_mfma_f32_16x16x32_bf16 v[92:95], v[150:153], v[174:177], v[92:95]
	v_mfma_f32_16x16x32_bf16 v[80:83], v[142:145], v[182:185], v[80:83]
	v_mfma_f32_16x16x32_bf16 v[76:79], v[150:153], v[182:185], v[76:79]
	s_setprio 0
	s_barrier
	s_add_i32 s65, 0, 0x14000
	v_add_u32_e32 v194, s65, v1
	s_mov_b64 s[16:17], s[20:21]
	s_add_i32 s64, s64, s73
	ds_read_b128 v[186:189], v194
	ds_read_b128 v[190:193], v194 offset:1024
	ds_read_b128 v[210:213], v194 offset:2048
	ds_read_b128 v[214:217], v194 offset:3072
	s_mov_b32 m0, s64
	s_nop 0
	global_load_lds_dwordx4 v136, s[16:17]
	s_add_i32 m0, s64, 0x2000
	s_nop 0
	global_load_lds_dwordx4 v138, s[16:17]
	s_barrier
	s_waitcnt lgkmcnt(0)
	s_setprio 1
	s_waitcnt lgkmcnt(0)
	v_mfma_f32_16x16x32_bf16 v[120:123], v[186:189], v[154:157], v[120:123]
	v_mfma_f32_16x16x32_bf16 v[116:119], v[210:213], v[154:157], v[116:119]
	v_mfma_f32_16x16x32_bf16 v[104:107], v[186:189], v[162:165], v[104:107]
	v_mfma_f32_16x16x32_bf16 v[100:103], v[210:213], v[162:165], v[100:103]
	v_mfma_f32_16x16x32_bf16 v[88:91], v[186:189], v[170:173], v[88:91]
	v_mfma_f32_16x16x32_bf16 v[84:87], v[210:213], v[170:173], v[84:87]
	v_mfma_f32_16x16x32_bf16 v[72:75], v[186:189], v[178:181], v[72:75]
	v_mfma_f32_16x16x32_bf16 v[68:71], v[210:213], v[178:181], v[68:71]
	v_mfma_f32_16x16x32_bf16 v[120:123], v[190:193], v[158:161], v[120:123]
	v_mfma_f32_16x16x32_bf16 v[116:119], v[214:217], v[158:161], v[116:119]
	v_mfma_f32_16x16x32_bf16 v[104:107], v[190:193], v[166:169], v[104:107]
	v_mfma_f32_16x16x32_bf16 v[100:103], v[214:217], v[166:169], v[100:103]
	v_mfma_f32_16x16x32_bf16 v[88:91], v[190:193], v[174:177], v[88:91]
	v_mfma_f32_16x16x32_bf16 v[84:87], v[214:217], v[174:177], v[84:87]
	v_mfma_f32_16x16x32_bf16 v[72:75], v[190:193], v[182:185], v[72:75]
	v_mfma_f32_16x16x32_bf16 v[68:71], v[214:217], v[182:185], v[68:71]
	s_setprio 0
	s_mov_b64 s[16:17], s[50:51]
	s_mov_b32 m0, s74
	s_barrier
	ds_read_b128 v[154:157], v3 offset:16384
	ds_read_b128 v[158:161], v3 offset:17408
	ds_read_b128 v[162:165], v3 offset:18432
	ds_read_b128 v[166:169], v3 offset:19456
	ds_read_b128 v[170:173], v3 offset:20480
	ds_read_b128 v[174:177], v3 offset:21504
	ds_read_b128 v[178:181], v3 offset:22528
	ds_read_b128 v[182:185], v3 offset:23552
	s_nop 0
	global_load_lds_dwordx4 v136, s[16:17]
	s_mov_b32 m0, s75
	s_nop 0
	global_load_lds_dwordx4 v138, s[16:17]
	s_barrier
	s_waitcnt lgkmcnt(0)
	s_setprio 1
	s_waitcnt lgkmcnt(0)
	v_mfma_f32_16x16x32_bf16 v[64:67], v[132:135], v[154:157], v[64:67]
	v_mfma_f32_16x16x32_bf16 v[60:63], v[146:149], v[154:157], v[60:63]
	v_mfma_f32_16x16x32_bf16 v[48:51], v[132:135], v[162:165], v[48:51]
	v_mfma_f32_16x16x32_bf16 v[44:47], v[146:149], v[162:165], v[44:47]
	v_mfma_f32_16x16x32_bf16 v[32:35], v[132:135], v[170:173], v[32:35]
	v_mfma_f32_16x16x32_bf16 v[28:31], v[146:149], v[170:173], v[28:31]
	v_mfma_f32_16x16x32_bf16 v[16:19], v[132:135], v[178:181], v[16:19]
	v_mfma_f32_16x16x32_bf16 v[12:15], v[146:149], v[178:181], v[12:15]
	v_mfma_f32_16x16x32_bf16 v[64:67], v[142:145], v[158:161], v[64:67]
	v_mfma_f32_16x16x32_bf16 v[60:63], v[150:153], v[158:161], v[60:63]
	v_mfma_f32_16x16x32_bf16 v[48:51], v[142:145], v[166:169], v[48:51]
	v_mfma_f32_16x16x32_bf16 v[44:47], v[150:153], v[166:169], v[44:47]
	v_mfma_f32_16x16x32_bf16 v[32:35], v[142:145], v[174:177], v[32:35]
	v_mfma_f32_16x16x32_bf16 v[28:31], v[150:153], v[174:177], v[28:31]
	v_mfma_f32_16x16x32_bf16 v[16:19], v[142:145], v[182:185], v[16:19]
	v_mfma_f32_16x16x32_bf16 v[12:15], v[150:153], v[182:185], v[12:15]
	s_setprio 0
	s_barrier
	s_add_u32 s16, s20, 0x40000
	s_addc_u32 s17, s21, 0
	s_add_i32 s64, s65, s73
	s_mov_b32 m0, s64
	s_nop 0
	global_load_lds_dwordx4 v136, s[16:17]
	s_add_i32 m0, s64, 0x2000
	s_nop 0
	global_load_lds_dwordx4 v138, s[16:17]
	s_waitcnt vmcnt(6)
	s_barrier
	s_setprio 1
	v_mfma_f32_16x16x32_bf16 v[56:59], v[186:189], v[154:157], v[56:59]
	v_mfma_f32_16x16x32_bf16 v[52:55], v[210:213], v[154:157], v[52:55]
	v_mfma_f32_16x16x32_bf16 v[40:43], v[186:189], v[162:165], v[40:43]
	v_mfma_f32_16x16x32_bf16 v[36:39], v[210:213], v[162:165], v[36:39]
	v_mfma_f32_16x16x32_bf16 v[24:27], v[186:189], v[170:173], v[24:27]
	v_mfma_f32_16x16x32_bf16 v[20:23], v[210:213], v[170:173], v[20:23]
	v_mfma_f32_16x16x32_bf16 v[8:11], v[186:189], v[178:181], v[8:11]
	v_mfma_f32_16x16x32_bf16 v[4:7], v[210:213], v[178:181], v[4:7]
	v_mfma_f32_16x16x32_bf16 v[56:59], v[190:193], v[158:161], v[56:59]
	v_mfma_f32_16x16x32_bf16 v[52:55], v[214:217], v[158:161], v[52:55]
	v_mfma_f32_16x16x32_bf16 v[40:43], v[190:193], v[166:169], v[40:43]
	v_mfma_f32_16x16x32_bf16 v[36:39], v[214:217], v[166:169], v[36:39]
	v_mfma_f32_16x16x32_bf16 v[24:27], v[190:193], v[174:177], v[24:27]
	v_mfma_f32_16x16x32_bf16 v[20:23], v[214:217], v[174:177], v[20:23]
	v_mfma_f32_16x16x32_bf16 v[8:11], v[190:193], v[182:185], v[8:11]
	v_mfma_f32_16x16x32_bf16 v[4:7], v[214:217], v[182:185], v[4:7]
	s_setprio 0
	s_add_i32 s64, 0, 0x18000
	v_add_u32_e32 v150, s64, v1
	s_barrier
	ds_read_b128 v[132:135], v150
	ds_read_b128 v[142:145], v150 offset:1024
	ds_read_b128 v[146:149], v150 offset:2048
	ds_read_b128 v[150:153], v150 offset:3072
	s_add_u32 s16, s50, 0x40000
	s_addc_u32 s17, s51, 0
	s_mov_b32 m0, s78
	ds_read_b128 v[154:157], v3 offset:32768
	ds_read_b128 v[158:161], v3 offset:33792
	ds_read_b128 v[162:165], v3 offset:34816
	ds_read_b128 v[166:169], v3 offset:35840
	ds_read_b128 v[170:173], v3 offset:36864
	ds_read_b128 v[174:177], v3 offset:37888
	ds_read_b128 v[178:181], v3 offset:38912
	ds_read_b128 v[182:185], v3 offset:39936
	s_nop 0
	global_load_lds_dwordx4 v136, s[16:17]
	s_mov_b32 m0, s79
	s_nop 0
	global_load_lds_dwordx4 v138, s[16:17]
	s_waitcnt lgkmcnt(8)
	s_barrier
	s_waitcnt lgkmcnt(0)
	s_setprio 1
	s_waitcnt lgkmcnt(0)
	v_mfma_f32_16x16x32_bf16 v[128:131], v[132:135], v[154:157], v[128:131]
	v_mfma_f32_16x16x32_bf16 v[124:127], v[146:149], v[154:157], v[124:127]
	v_mfma_f32_16x16x32_bf16 v[112:115], v[132:135], v[162:165], v[112:115]
	v_mfma_f32_16x16x32_bf16 v[108:111], v[146:149], v[162:165], v[108:111]
	v_mfma_f32_16x16x32_bf16 v[96:99], v[132:135], v[170:173], v[96:99]
	v_mfma_f32_16x16x32_bf16 v[92:95], v[146:149], v[170:173], v[92:95]
	v_mfma_f32_16x16x32_bf16 v[80:83], v[132:135], v[178:181], v[80:83]
	v_mfma_f32_16x16x32_bf16 v[76:79], v[146:149], v[178:181], v[76:79]
	v_mfma_f32_16x16x32_bf16 v[128:131], v[142:145], v[158:161], v[128:131]
	v_mfma_f32_16x16x32_bf16 v[124:127], v[150:153], v[158:161], v[124:127]
	v_mfma_f32_16x16x32_bf16 v[112:115], v[142:145], v[166:169], v[112:115]
	v_mfma_f32_16x16x32_bf16 v[108:111], v[150:153], v[166:169], v[108:111]
	v_mfma_f32_16x16x32_bf16 v[96:99], v[142:145], v[174:177], v[96:99]
	v_mfma_f32_16x16x32_bf16 v[92:95], v[150:153], v[174:177], v[92:95]
	v_mfma_f32_16x16x32_bf16 v[80:83], v[142:145], v[182:185], v[80:83]
	v_mfma_f32_16x16x32_bf16 v[76:79], v[150:153], v[182:185], v[76:79]
	s_setprio 0
	s_barrier
	s_add_i32 s50, 0, 0x1c000
	s_add_u32 s16, s20, 0x80
	v_add_u32_e32 v194, s50, v1
	s_addc_u32 s17, s21, 0
	s_add_i32 s51, s64, s73
	ds_read_b128 v[186:189], v194
	ds_read_b128 v[190:193], v194 offset:1024
	ds_read_b128 v[210:213], v194 offset:2048
	ds_read_b128 v[214:217], v194 offset:3072
	s_mov_b32 m0, s51
	s_nop 0
	global_load_lds_dwordx4 v136, s[16:17]
	s_add_i32 m0, s51, 0x2000
	s_nop 0
	global_load_lds_dwordx4 v138, s[16:17]
	s_barrier
	s_waitcnt lgkmcnt(0)
	s_setprio 1
	s_waitcnt lgkmcnt(0)
	v_mfma_f32_16x16x32_bf16 v[120:123], v[186:189], v[154:157], v[120:123]
	v_mfma_f32_16x16x32_bf16 v[116:119], v[210:213], v[154:157], v[116:119]
	v_mfma_f32_16x16x32_bf16 v[104:107], v[186:189], v[162:165], v[104:107]
	v_mfma_f32_16x16x32_bf16 v[100:103], v[210:213], v[162:165], v[100:103]
	v_mfma_f32_16x16x32_bf16 v[88:91], v[186:189], v[170:173], v[88:91]
	v_mfma_f32_16x16x32_bf16 v[84:87], v[210:213], v[170:173], v[84:87]
	v_mfma_f32_16x16x32_bf16 v[72:75], v[186:189], v[178:181], v[72:75]
	v_mfma_f32_16x16x32_bf16 v[68:71], v[210:213], v[178:181], v[68:71]
	v_mfma_f32_16x16x32_bf16 v[120:123], v[190:193], v[158:161], v[120:123]
	v_mfma_f32_16x16x32_bf16 v[116:119], v[214:217], v[158:161], v[116:119]
	v_mfma_f32_16x16x32_bf16 v[104:107], v[190:193], v[166:169], v[104:107]
	v_mfma_f32_16x16x32_bf16 v[100:103], v[214:217], v[166:169], v[100:103]
	v_mfma_f32_16x16x32_bf16 v[88:91], v[190:193], v[174:177], v[88:91]
	v_mfma_f32_16x16x32_bf16 v[84:87], v[214:217], v[174:177], v[84:87]
	v_mfma_f32_16x16x32_bf16 v[72:75], v[190:193], v[182:185], v[72:75]
	v_mfma_f32_16x16x32_bf16 v[68:71], v[214:217], v[182:185], v[68:71]
	s_setprio 0
	s_mov_b32 m0, s80
	s_barrier
	ds_read_b128 v[154:157], v3 offset:49152
	ds_read_b128 v[158:161], v3 offset:50176
	ds_read_b128 v[162:165], v3 offset:51200
	ds_read_b128 v[166:169], v3 offset:52224
	ds_read_b128 v[170:173], v3 offset:53248
	ds_read_b128 v[174:177], v3 offset:54272
	ds_read_b128 v[178:181], v3 offset:55296
	ds_read_b128 v[182:185], v3 offset:56320
	s_nop 0
	global_load_lds_dwordx4 v136, s[48:49]
	s_mov_b32 m0, s81
	s_nop 0
	global_load_lds_dwordx4 v138, s[48:49]
	s_barrier
	s_waitcnt lgkmcnt(0)
	s_setprio 1
	s_waitcnt lgkmcnt(0)
	v_mfma_f32_16x16x32_bf16 v[64:67], v[132:135], v[154:157], v[64:67]
	v_mfma_f32_16x16x32_bf16 v[60:63], v[146:149], v[154:157], v[60:63]
	v_mfma_f32_16x16x32_bf16 v[48:51], v[132:135], v[162:165], v[48:51]
	v_mfma_f32_16x16x32_bf16 v[44:47], v[146:149], v[162:165], v[44:47]
	v_mfma_f32_16x16x32_bf16 v[32:35], v[132:135], v[170:173], v[32:35]
	v_mfma_f32_16x16x32_bf16 v[28:31], v[146:149], v[170:173], v[28:31]
	v_mfma_f32_16x16x32_bf16 v[16:19], v[132:135], v[178:181], v[16:19]
	v_mfma_f32_16x16x32_bf16 v[12:15], v[146:149], v[178:181], v[12:15]
	v_mfma_f32_16x16x32_bf16 v[64:67], v[142:145], v[158:161], v[64:67]
	v_mfma_f32_16x16x32_bf16 v[60:63], v[150:153], v[158:161], v[60:63]
	v_mfma_f32_16x16x32_bf16 v[48:51], v[142:145], v[166:169], v[48:51]
	v_mfma_f32_16x16x32_bf16 v[44:47], v[150:153], v[166:169], v[44:47]
	v_mfma_f32_16x16x32_bf16 v[32:35], v[142:145], v[174:177], v[32:35]
	v_mfma_f32_16x16x32_bf16 v[28:31], v[150:153], v[174:177], v[28:31]
	v_mfma_f32_16x16x32_bf16 v[16:19], v[142:145], v[182:185], v[16:19]
	v_mfma_f32_16x16x32_bf16 v[12:15], v[150:153], v[182:185], v[12:15]
	s_setprio 0
	s_barrier
	s_add_u32 s16, s20, 0x40080
	s_addc_u32 s17, s21, 0
	s_add_i32 s20, s50, s73
	s_mov_b32 m0, s20
	s_nop 0
	global_load_lds_dwordx4 v136, s[16:17]
	s_add_i32 m0, s20, 0x2000
	s_nop 0
	global_load_lds_dwordx4 v138, s[16:17]
	s_waitcnt vmcnt(6)
	s_barrier
	s_setprio 1
	v_mfma_f32_16x16x32_bf16 v[56:59], v[186:189], v[154:157], v[56:59]
	v_mfma_f32_16x16x32_bf16 v[52:55], v[210:213], v[154:157], v[52:55]
	v_mfma_f32_16x16x32_bf16 v[40:43], v[186:189], v[162:165], v[40:43]
	v_mfma_f32_16x16x32_bf16 v[36:39], v[210:213], v[162:165], v[36:39]
	v_mfma_f32_16x16x32_bf16 v[24:27], v[186:189], v[170:173], v[24:27]
	v_mfma_f32_16x16x32_bf16 v[20:23], v[210:213], v[170:173], v[20:23]
	v_mfma_f32_16x16x32_bf16 v[8:11], v[186:189], v[178:181], v[8:11]
	v_mfma_f32_16x16x32_bf16 v[4:7], v[210:213], v[178:181], v[4:7]
	v_mfma_f32_16x16x32_bf16 v[56:59], v[190:193], v[158:161], v[56:59]
	v_mfma_f32_16x16x32_bf16 v[52:55], v[214:217], v[158:161], v[52:55]
	v_mfma_f32_16x16x32_bf16 v[40:43], v[190:193], v[166:169], v[40:43]
	v_mfma_f32_16x16x32_bf16 v[36:39], v[214:217], v[166:169], v[36:39]
	v_mfma_f32_16x16x32_bf16 v[24:27], v[190:193], v[174:177], v[24:27]
	v_mfma_f32_16x16x32_bf16 v[20:23], v[214:217], v[174:177], v[20:23]
	v_mfma_f32_16x16x32_bf16 v[8:11], v[190:193], v[182:185], v[8:11]
	v_mfma_f32_16x16x32_bf16 v[4:7], v[214:217], v[182:185], v[4:7]
	s_setprio 0
	s_add_i32 s62, s62, 2
	s_add_u32 s52, s52, 0x100
	s_addc_u32 s53, s53, 0
	s_cmp_gt_u32 s62, 13
	s_mov_b64 s[16:17], s[18:19]
	s_barrier
	s_cbranch_scc0 .LBB0_505
	v_mov_b32_e32 v132, v0
	s_lshl_b32 s16, s0, 2
	v_readfirstlane_b32 s1, v132
	s_bfe_u32 s9, s1, 0x20006
	s_ashr_i32 s1, s1, 2
	s_lshl_b32 s0, s8, 8
	s_andn2_b32 s1, s1, 63
	s_add_i32 s1, s1, s0
	v_and_or_b32 v142, v132, 15, s1
	v_ashrrev_i32_e32 v143, 31, v142
	v_bfe_u32 v134, v132, 4, 2
	v_lshl_add_u64 v[132:133], v[142:143], 2, s[24:25]
	global_load_dword v135, v[132:133], off
	global_load_dword v147, v[132:133], off offset:64
	global_load_dword v173, v[132:133], off offset:128
	global_load_dword v172, v[132:133], off offset:192
	global_load_dword v171, v[132:133], off offset:512
	global_load_dword v170, v[132:133], off offset:576
	global_load_dword v169, v[132:133], off offset:640
	global_load_dword v168, v[132:133], off offset:704
	s_or_b32 s17, s9, s16
	s_cmp_gt_i32 s17, 5
	s_cselect_b64 s[0:1], -1, 0
	s_cmp_gt_u32 s17, 9
	s_cselect_b64 s[8:9], -1, 0
	s_cmp_lg_u32 s17, 10
	s_cselect_b64 s[50:51], -1, 0
	s_cmp_gt_u32 s16, 11
	s_cselect_b64 s[48:49], -1, 0
	s_lshl_b32 s68, s17, 6
	s_add_i32 s16, s68, 0xfffffd00
	v_lshlrev_b32_e32 v157, 3, v134
	v_or_b32_e32 v144, s16, v157
	v_cmp_eq_u32_e64 s[16:17], 0, v134
	s_mov_b64 s[18:19], -1
	s_waitcnt vmcnt(0)
	v_fmamk_f32 v132, v135, 0x3a800000, v231
	v_cmp_gt_f32_e32 vcc, s11, v132
	v_mul_f32_e32 v133, 0x4b800000, v132
	s_nop 0
	v_cndmask_b32_e32 v132, v132, v133, vcc
	v_rsq_f32_e32 v132, v132
	s_nop 0
	v_mul_f32_e32 v133, 0x45800000, v132
	v_cndmask_b32_e32 v146, v132, v133, vcc
	s_and_b64 vcc, exec, s[0:1]
	s_cbranch_vccz .LBB0_519
	s_and_b64 vcc, exec, s[8:9]
	s_cbranch_vccz .LBB0_516
	s_and_b64 vcc, exec, s[50:51]
	s_cbranch_vccz .LBB0_512
	s_andn2_b64 vcc, exec, s[48:49]
	s_cbranch_vccnz .LBB0_511
	v_mov_b64_e32 v[148:149], s[38:39]
	s_movk_i32 s18, 0x480
	v_mad_i64_i32 v[148:149], s[18:19], v142, s18, v[148:149]
	v_mov_b32_e32 v145, v2
	v_pk_mul_f32 v[134:135], v[130:131], v[146:147] op_sel_hi:[1,0]
	v_pk_mul_f32 v[132:133], v[128:129], v[146:147] op_sel_hi:[1,0]
	v_lshl_add_u64 v[150:151], v[144:145], 2, v[148:149]
	global_store_dwordx4 v[150:151], v[132:135], off
	v_ashrrev_i32_e32 v145, 31, v144
	v_lshl_add_u64 v[148:149], v[144:145], 2, v[148:149]
	v_pk_mul_f32 v[134:135], v[126:127], v[146:147] op_sel_hi:[1,0]
	v_pk_mul_f32 v[132:133], v[124:125], v[146:147] op_sel_hi:[1,0]
	global_store_dwordx4 v[150:151], v[132:135], off offset:16
	s_nop 1
	v_pk_mul_f32 v[134:135], v[122:123], v[146:147] op_sel_hi:[1,0]
	v_pk_mul_f32 v[132:133], v[120:121], v[146:147] op_sel_hi:[1,0]
	global_store_dwordx4 v[148:149], v[132:135], off offset:128
	s_nop 1
	v_pk_mul_f32 v[134:135], v[118:119], v[146:147] op_sel_hi:[1,0]
	v_pk_mul_f32 v[132:133], v[116:117], v[146:147] op_sel_hi:[1,0]
	global_store_dwordx4 v[148:149], v[132:135], off offset:144

.LBB0_654:
	s_add_u32 s36, s14, s26
	s_addc_u32 s37, s15, s27
	s_add_u32 s38, s36, 0x100
	s_addc_u32 s39, s37, 0
	s_and_b64 s[30:31], s[28:29], exec
	s_cselect_b32 s41, s19, s39
	s_cselect_b32 s40, s18, s38
	s_add_u32 s26, s0, s26
	s_addc_u32 s27, s1, s27
	s_add_u32 s30, s26, 0x100
	s_addc_u32 s31, s27, 0
	s_add_u32 s26, s40, 0x80
	s_addc_u32 s27, s41, 0
	s_add_i32 s81, 0, 0x10000
	s_and_b64 s[28:29], s[28:29], exec
	s_cselect_b32 s43, s17, s31
	s_cselect_b32 s42, s23, s30
	s_add_u32 s44, s36, 0x12080
	s_addc_u32 s45, s37, 0
	s_add_i32 s86, s81, s51
	s_add_i32 m0, s52, 0xc000
	s_add_i32 s87, s52, 0xe000
	s_add_i32 s85, 0, 0x14000
	s_add_i32 s84, s86, 0x2000
	s_add_u32 s38, s42, 0x10000
	s_addc_u32 s39, s43, 0
	s_add_i32 s82, s85, s51
	s_add_i32 s80, s82, 0x2000
	s_add_i32 s79, 0, 0x18000
	v_add_u32_e32 v152, s81, v1
	s_add_u32 s36, s40, 0x12000
	ds_read_b128 v[140:143], v152
	ds_read_b128 v[144:147], v152 offset:1024
	ds_read_b128 v[148:151], v152 offset:2048
	ds_read_b128 v[152:155], v152 offset:3072
	s_addc_u32 s37, s41, 0
	s_add_i32 s75, 0, 0x1c000
	s_add_u32 s30, s42, 0x80
	s_addc_u32 s31, s43, 0
	s_add_i32 s78, s79, s51
	s_add_i32 s74, s78, 0x2000
	s_add_u32 s28, s42, 0x10080
	s_addc_u32 s29, s43, 0
	s_add_i32 s83, s75, s51
	s_add_i32 s81, s83, 0x2000
	ds_read_b128 v[156:159], v3
	ds_read_b128 v[160:163], v3 offset:1024
	ds_read_b128 v[164:167], v3 offset:2048
	ds_read_b128 v[168:171], v3 offset:3072
	ds_read_b128 v[172:175], v3 offset:4096
	ds_read_b128 v[176:179], v3 offset:5120
	ds_read_b128 v[180:183], v3 offset:6144
	ds_read_b128 v[184:187], v3 offset:7168
	s_nop 0
	global_load_lds_dwordx4 v132, s[44:45]
	s_mov_b32 m0, s87
	s_nop 0
	global_load_lds_dwordx4 v136, s[44:45]
	s_waitcnt lgkmcnt(8)
	s_barrier
	s_waitcnt lgkmcnt(0)
	s_setprio 1
	s_waitcnt lgkmcnt(0)
	v_mfma_f32_16x16x32_bf16 v[128:131], v[140:143], v[156:159], v[128:131]
	v_mfma_f32_16x16x32_bf16 v[124:127], v[148:151], v[156:159], v[124:127]
	v_mfma_f32_16x16x32_bf16 v[112:115], v[140:143], v[164:167], v[112:115]
	v_mfma_f32_16x16x32_bf16 v[108:111], v[148:151], v[164:167], v[108:111]
	v_mfma_f32_16x16x32_bf16 v[96:99], v[140:143], v[172:175], v[96:99]
	v_mfma_f32_16x16x32_bf16 v[92:95], v[148:151], v[172:175], v[92:95]
	v_mfma_f32_16x16x32_bf16 v[80:83], v[140:143], v[180:183], v[80:83]
	v_mfma_f32_16x16x32_bf16 v[76:79], v[148:151], v[180:183], v[76:79]
	v_mfma_f32_16x16x32_bf16 v[128:131], v[144:147], v[160:163], v[128:131]
	v_mfma_f32_16x16x32_bf16 v[124:127], v[152:155], v[160:163], v[124:127]
	v_mfma_f32_16x16x32_bf16 v[112:115], v[144:147], v[168:171], v[112:115]
	v_mfma_f32_16x16x32_bf16 v[108:111], v[152:155], v[168:171], v[108:111]
	v_mfma_f32_16x16x32_bf16 v[96:99], v[144:147], v[176:179], v[96:99]
	v_mfma_f32_16x16x32_bf16 v[92:95], v[152:155], v[176:179], v[92:95]
	v_mfma_f32_16x16x32_bf16 v[80:83], v[144:147], v[184:187], v[80:83]
	v_mfma_f32_16x16x32_bf16 v[76:79], v[152:155], v[184:187], v[76:79]
	s_setprio 0
	s_barrier
	v_add_u32_e32 v214, s85, v1
	s_mov_b32 m0, s86
	ds_read_b128 v[188:191], v214
	ds_read_b128 v[192:195], v214 offset:1024
	ds_read_b128 v[210:213], v214 offset:2048
	ds_read_b128 v[214:217], v214 offset:3072
	s_nop 0
	global_load_lds_dwordx4 v134, s[42:43]
	s_mov_b32 m0, s84
	s_nop 0
	global_load_lds_dwordx4 v138, s[42:43]
	s_barrier
	s_waitcnt lgkmcnt(0)
	s_setprio 1
	s_waitcnt lgkmcnt(0)
	v_mfma_f32_16x16x32_bf16 v[120:123], v[188:191], v[156:159], v[120:123]
	v_mfma_f32_16x16x32_bf16 v[116:119], v[210:213], v[156:159], v[116:119]
	v_mfma_f32_16x16x32_bf16 v[104:107], v[188:191], v[164:167], v[104:107]
	v_mfma_f32_16x16x32_bf16 v[100:103], v[210:213], v[164:167], v[100:103]
	v_mfma_f32_16x16x32_bf16 v[88:91], v[188:191], v[172:175], v[88:91]
	v_mfma_f32_16x16x32_bf16 v[84:87], v[210:213], v[172:175], v[84:87]
	v_mfma_f32_16x16x32_bf16 v[72:75], v[188:191], v[180:183], v[72:75]
	v_mfma_f32_16x16x32_bf16 v[68:71], v[210:213], v[180:183], v[68:71]
	v_mfma_f32_16x16x32_bf16 v[120:123], v[192:195], v[160:163], v[120:123]
	v_mfma_f32_16x16x32_bf16 v[116:119], v[214:217], v[160:163], v[116:119]
	v_mfma_f32_16x16x32_bf16 v[104:107], v[192:195], v[168:171], v[104:107]
	v_mfma_f32_16x16x32_bf16 v[100:103], v[214:217], v[168:171], v[100:103]
	v_mfma_f32_16x16x32_bf16 v[88:91], v[192:195], v[176:179], v[88:91]
	v_mfma_f32_16x16x32_bf16 v[84:87], v[214:217], v[176:179], v[84:87]
	v_mfma_f32_16x16x32_bf16 v[72:75], v[192:195], v[184:187], v[72:75]
	v_mfma_f32_16x16x32_bf16 v[68:71], v[214:217], v[184:187], v[68:71]
	s_setprio 0
	s_mov_b32 m0, s52
	s_barrier
	ds_read_b128 v[156:159], v3 offset:16384
	ds_read_b128 v[160:163], v3 offset:17408
	ds_read_b128 v[164:167], v3 offset:18432
	ds_read_b128 v[168:171], v3 offset:19456
	ds_read_b128 v[172:175], v3 offset:20480
	ds_read_b128 v[176:179], v3 offset:21504
	ds_read_b128 v[180:183], v3 offset:22528
	ds_read_b128 v[184:187], v3 offset:23552
	s_nop 0
	global_load_lds_dwordx4 v132, s[40:41]
	s_mov_b32 m0, s53
	s_nop 0
	global_load_lds_dwordx4 v136, s[40:41]
	s_barrier
	s_waitcnt lgkmcnt(0)
	s_setprio 1
	s_waitcnt lgkmcnt(0)
	v_mfma_f32_16x16x32_bf16 v[64:67], v[140:143], v[156:159], v[64:67]
	v_mfma_f32_16x16x32_bf16 v[60:63], v[148:151], v[156:159], v[60:63]
	v_mfma_f32_16x16x32_bf16 v[48:51], v[140:143], v[164:167], v[48:51]
	v_mfma_f32_16x16x32_bf16 v[44:47], v[148:151], v[164:167], v[44:47]
	v_mfma_f32_16x16x32_bf16 v[32:35], v[140:143], v[172:175], v[32:35]
	v_mfma_f32_16x16x32_bf16 v[28:31], v[148:151], v[172:175], v[28:31]
	v_mfma_f32_16x16x32_bf16 v[16:19], v[140:143], v[180:183], v[16:19]
	v_mfma_f32_16x16x32_bf16 v[12:15], v[148:151], v[180:183], v[12:15]
	v_mfma_f32_16x16x32_bf16 v[64:67], v[144:147], v[160:163], v[64:67]
	v_mfma_f32_16x16x32_bf16 v[60:63], v[152:155], v[160:163], v[60:63]
	v_mfma_f32_16x16x32_bf16 v[48:51], v[144:147], v[168:171], v[48:51]
	v_mfma_f32_16x16x32_bf16 v[44:47], v[152:155], v[168:171], v[44:47]
	v_mfma_f32_16x16x32_bf16 v[32:35], v[144:147], v[176:179], v[32:35]
	v_mfma_f32_16x16x32_bf16 v[28:31], v[152:155], v[176:179], v[28:31]
	v_mfma_f32_16x16x32_bf16 v[16:19], v[144:147], v[184:187], v[16:19]
	v_mfma_f32_16x16x32_bf16 v[12:15], v[152:155], v[184:187], v[12:15]
	s_setprio 0
	s_barrier
	s_mov_b32 m0, s82
	s_nop 0
	global_load_lds_dwordx4 v134, s[38:39]
	s_mov_b32 m0, s80
	s_nop 0
	global_load_lds_dwordx4 v138, s[38:39]
	s_waitcnt vmcnt(6)
	s_barrier
	s_setprio 1
	v_mfma_f32_16x16x32_bf16 v[56:59], v[188:191], v[156:159], v[56:59]
	v_mfma_f32_16x16x32_bf16 v[52:55], v[210:213], v[156:159], v[52:55]
	v_mfma_f32_16x16x32_bf16 v[40:43], v[188:191], v[164:167], v[40:43]
	v_mfma_f32_16x16x32_bf16 v[36:39], v[210:213], v[164:167], v[36:39]
	v_mfma_f32_16x16x32_bf16 v[24:27], v[188:191], v[172:175], v[24:27]
	v_mfma_f32_16x16x32_bf16 v[20:23], v[210:213], v[172:175], v[20:23]
	v_mfma_f32_16x16x32_bf16 v[8:11], v[188:191], v[180:183], v[8:11]
	v_mfma_f32_16x16x32_bf16 v[4:7], v[210:213], v[180:183], v[4:7]
	v_mfma_f32_16x16x32_bf16 v[56:59], v[192:195], v[160:163], v[56:59]
	v_mfma_f32_16x16x32_bf16 v[52:55], v[214:217], v[160:163], v[52:55]
	v_mfma_f32_16x16x32_bf16 v[40:43], v[192:195], v[168:171], v[40:43]
	v_mfma_f32_16x16x32_bf16 v[36:39], v[214:217], v[168:171], v[36:39]
	v_mfma_f32_16x16x32_bf16 v[24:27], v[192:195], v[176:179], v[24:27]
	v_mfma_f32_16x16x32_bf16 v[20:23], v[214:217], v[176:179], v[20:23]
	v_mfma_f32_16x16x32_bf16 v[8:11], v[192:195], v[184:187], v[8:11]
	v_mfma_f32_16x16x32_bf16 v[4:7], v[214:217], v[184:187], v[4:7]
	s_setprio 0
	v_add_u32_e32 v152, s79, v1
	s_barrier
	ds_read_b128 v[140:143], v152
	ds_read_b128 v[144:147], v152 offset:1024
	ds_read_b128 v[148:151], v152 offset:2048
	ds_read_b128 v[152:155], v152 offset:3072
	s_mov_b32 m0, s55
	ds_read_b128 v[156:159], v3 offset:32768
	ds_read_b128 v[160:163], v3 offset:33792
	ds_read_b128 v[164:167], v3 offset:34816
	ds_read_b128 v[168:171], v3 offset:35840
	ds_read_b128 v[172:175], v3 offset:36864
	ds_read_b128 v[176:179], v3 offset:37888
	ds_read_b128 v[180:183], v3 offset:38912
	ds_read_b128 v[184:187], v3 offset:39936
	s_nop 0
	global_load_lds_dwordx4 v132, s[36:37]
	s_mov_b32 m0, s56
	s_nop 0
	global_load_lds_dwordx4 v136, s[36:37]
	s_waitcnt lgkmcnt(8)
	s_barrier
	s_waitcnt lgkmcnt(0)
	s_setprio 1
	s_waitcnt lgkmcnt(0)
	v_mfma_f32_16x16x32_bf16 v[128:131], v[140:143], v[156:159], v[128:131]
	v_mfma_f32_16x16x32_bf16 v[124:127], v[148:151], v[156:159], v[124:127]
	v_mfma_f32_16x16x32_bf16 v[112:115], v[140:143], v[164:167], v[112:115]
	v_mfma_f32_16x16x32_bf16 v[108:111], v[148:151], v[164:167], v[108:111]
	v_mfma_f32_16x16x32_bf16 v[96:99], v[140:143], v[172:175], v[96:99]
	v_mfma_f32_16x16x32_bf16 v[92:95], v[148:151], v[172:175], v[92:95]
	v_mfma_f32_16x16x32_bf16 v[80:83], v[140:143], v[180:183], v[80:83]
	v_mfma_f32_16x16x32_bf16 v[76:79], v[148:151], v[180:183], v[76:79]
	v_mfma_f32_16x16x32_bf16 v[128:131], v[144:147], v[160:163], v[128:131]
	v_mfma_f32_16x16x32_bf16 v[124:127], v[152:155], v[160:163], v[124:127]
	v_mfma_f32_16x16x32_bf16 v[112:115], v[144:147], v[168:171], v[112:115]
	v_mfma_f32_16x16x32_bf16 v[108:111], v[152:155], v[168:171], v[108:111]
	v_mfma_f32_16x16x32_bf16 v[96:99], v[144:147], v[176:179], v[96:99]
	v_mfma_f32_16x16x32_bf16 v[92:95], v[152:155], v[176:179], v[92:95]
	v_mfma_f32_16x16x32_bf16 v[80:83], v[144:147], v[184:187], v[80:83]
	v_mfma_f32_16x16x32_bf16 v[76:79], v[152:155], v[184:187], v[76:79]
	s_setprio 0
	s_barrier
	v_add_u32_e32 v214, s75, v1
	s_mov_b32 m0, s78
	ds_read_b128 v[188:191], v214
	ds_read_b128 v[192:195], v214 offset:1024
	ds_read_b128 v[210:213], v214 offset:2048
	ds_read_b128 v[214:217], v214 offset:3072
	s_nop 0
	global_load_lds_dwordx4 v134, s[30:31]
	s_mov_b32 m0, s74
	s_nop 0
	global_load_lds_dwordx4 v138, s[30:31]
	s_barrier
	s_waitcnt lgkmcnt(0)
	s_setprio 1
	s_waitcnt lgkmcnt(0)
	v_mfma_f32_16x16x32_bf16 v[120:123], v[188:191], v[156:159], v[120:123]
	v_mfma_f32_16x16x32_bf16 v[116:119], v[210:213], v[156:159], v[116:119]
	v_mfma_f32_16x16x32_bf16 v[104:107], v[188:191], v[164:167], v[104:107]
	v_mfma_f32_16x16x32_bf16 v[100:103], v[210:213], v[164:167], v[100:103]
	v_mfma_f32_16x16x32_bf16 v[88:91], v[188:191], v[172:175], v[88:91]
	v_mfma_f32_16x16x32_bf16 v[84:87], v[210:213], v[172:175], v[84:87]
	v_mfma_f32_16x16x32_bf16 v[72:75], v[188:191], v[180:183], v[72:75]
	v_mfma_f32_16x16x32_bf16 v[68:71], v[210:213], v[180:183], v[68:71]
	v_mfma_f32_16x16x32_bf16 v[120:123], v[192:195], v[160:163], v[120:123]
	v_mfma_f32_16x16x32_bf16 v[116:119], v[214:217], v[160:163], v[116:119]
	v_mfma_f32_16x16x32_bf16 v[104:107], v[192:195], v[168:171], v[104:107]
	v_mfma_f32_16x16x32_bf16 v[100:103], v[214:217], v[168:171], v[100:103]
	v_mfma_f32_16x16x32_bf16 v[88:91], v[192:195], v[176:179], v[88:91]
	v_mfma_f32_16x16x32_bf16 v[84:87], v[214:217], v[176:179], v[84:87]
	v_mfma_f32_16x16x32_bf16 v[72:75], v[192:195], v[184:187], v[72:75]
	v_mfma_f32_16x16x32_bf16 v[68:71], v[214:217], v[184:187], v[68:71]
	s_setprio 0
	s_mov_b32 m0, s65
	s_barrier
	ds_read_b128 v[156:159], v3 offset:49152
	ds_read_b128 v[160:163], v3 offset:50176
	ds_read_b128 v[164:167], v3 offset:51200
	ds_read_b128 v[168:171], v3 offset:52224
	ds_read_b128 v[172:175], v3 offset:53248
	ds_read_b128 v[176:179], v3 offset:54272
	ds_read_b128 v[180:183], v3 offset:55296
	ds_read_b128 v[184:187], v3 offset:56320
	s_nop 0
	global_load_lds_dwordx4 v132, s[26:27]
	s_mov_b32 m0, s67
	s_nop 0
	global_load_lds_dwordx4 v136, s[26:27]
	s_barrier
	s_waitcnt lgkmcnt(0)
	s_setprio 1
	s_waitcnt lgkmcnt(0)
	v_mfma_f32_16x16x32_bf16 v[64:67], v[140:143], v[156:159], v[64:67]
	v_mfma_f32_16x16x32_bf16 v[60:63], v[148:151], v[156:159], v[60:63]
	v_mfma_f32_16x16x32_bf16 v[48:51], v[140:143], v[164:167], v[48:51]
	v_mfma_f32_16x16x32_bf16 v[44:47], v[148:151], v[164:167], v[44:47]
	v_mfma_f32_16x16x32_bf16 v[32:35], v[140:143], v[172:175], v[32:35]
	v_mfma_f32_16x16x32_bf16 v[28:31], v[148:151], v[172:175], v[28:31]
	v_mfma_f32_16x16x32_bf16 v[16:19], v[140:143], v[180:183], v[16:19]
	v_mfma_f32_16x16x32_bf16 v[12:15], v[148:151], v[180:183], v[12:15]
	v_mfma_f32_16x16x32_bf16 v[64:67], v[144:147], v[160:163], v[64:67]
	v_mfma_f32_16x16x32_bf16 v[60:63], v[152:155], v[160:163], v[60:63]
	v_mfma_f32_16x16x32_bf16 v[48:51], v[144:147], v[168:171], v[48:51]
	v_mfma_f32_16x16x32_bf16 v[44:47], v[152:155], v[168:171], v[44:47]
	v_mfma_f32_16x16x32_bf16 v[32:35], v[144:147], v[176:179], v[32:35]
	v_mfma_f32_16x16x32_bf16 v[28:31], v[152:155], v[176:179], v[28:31]
	v_mfma_f32_16x16x32_bf16 v[16:19], v[144:147], v[184:187], v[16:19]
	v_mfma_f32_16x16x32_bf16 v[12:15], v[152:155], v[184:187], v[12:15]
	s_setprio 0
	s_barrier
	s_mov_b32 m0, s83
	s_nop 0
	global_load_lds_dwordx4 v134, s[28:29]
	s_mov_b32 m0, s81
	s_nop 0
	global_load_lds_dwordx4 v138, s[28:29]
	s_waitcnt vmcnt(6)
	s_barrier
	s_setprio 1
	v_mfma_f32_16x16x32_bf16 v[56:59], v[188:191], v[156:159], v[56:59]
	v_mfma_f32_16x16x32_bf16 v[52:55], v[210:213], v[156:159], v[52:55]
	v_mfma_f32_16x16x32_bf16 v[40:43], v[188:191], v[164:167], v[40:43]
	v_mfma_f32_16x16x32_bf16 v[36:39], v[210:213], v[164:167], v[36:39]
	v_mfma_f32_16x16x32_bf16 v[24:27], v[188:191], v[172:175], v[24:27]
	v_mfma_f32_16x16x32_bf16 v[20:23], v[210:213], v[172:175], v[20:23]
	v_mfma_f32_16x16x32_bf16 v[8:11], v[188:191], v[180:183], v[8:11]
	v_mfma_f32_16x16x32_bf16 v[4:7], v[210:213], v[180:183], v[4:7]
	v_mfma_f32_16x16x32_bf16 v[56:59], v[192:195], v[160:163], v[56:59]
	v_mfma_f32_16x16x32_bf16 v[52:55], v[214:217], v[160:163], v[52:55]
	v_mfma_f32_16x16x32_bf16 v[40:43], v[192:195], v[168:171], v[40:43]
	v_mfma_f32_16x16x32_bf16 v[36:39], v[214:217], v[168:171], v[36:39]
	v_mfma_f32_16x16x32_bf16 v[24:27], v[192:195], v[176:179], v[24:27]
	v_mfma_f32_16x16x32_bf16 v[20:23], v[214:217], v[176:179], v[20:23]
	v_mfma_f32_16x16x32_bf16 v[8:11], v[192:195], v[184:187], v[8:11]
	v_mfma_f32_16x16x32_bf16 v[4:7], v[214:217], v[184:187], v[4:7]
	s_setprio 0
	s_andn2_b64 vcc, exec, s[24:25]
	s_mov_b64 s[28:29], -1
	s_mov_b64 s[24:25], 0
	s_mov_b64 s[26:27], 0x100
	s_barrier
	s_cbranch_vccz .LBB0_654
	v_mov_b32_e32 v141, v0
	s_ashr_i32 s23, s22, 31
	v_readfirstlane_b32 s0, v141
	s_bfe_u32 s17, s0, 0x20006
	s_ashr_i32 s0, s0, 2
	s_andn2_b32 s0, s0, 63
	s_ashr_i32 s1, s0, 31
	s_lshl_b64 s[14:15], s[22:23], 10
	s_add_u32 s24, s57, s14
	s_addc_u32 s25, s62, s15
	s_lshl_b64 s[14:15], s[0:1], 2
	v_and_b32_e32 v142, 15, v141
	s_add_u32 s24, s24, s14
	s_addc_u32 s25, s25, s15
	v_lshlrev_b32_e32 v140, 2, v142
	global_load_dword v150, v140, s[24:25] offset:64
	global_load_dword v149, v140, s[24:25] offset:128
	global_load_dword v148, v140, s[24:25] offset:192
	global_load_dword v147, v140, s[24:25] offset:512
	global_load_dword v146, v140, s[24:25] offset:576
	global_load_dword v145, v140, s[24:25] offset:640
	global_load_dword v144, v140, s[24:25] offset:704
	v_mul_f32_e32 v129, v129, v129
	v_mul_f32_e32 v125, v125, v125
	v_mul_f32_e32 v121, v121, v121
	v_mul_f32_e32 v117, v117, v117
	v_fmac_f32_e32 v129, v128, v128
	v_mul_f32_e32 v128, v131, v131
	v_fmac_f32_e32 v125, v124, v124
	v_mul_f32_e32 v124, v127, v127
	v_fmac_f32_e32 v121, v120, v120
	v_mul_f32_e32 v120, v123, v123
	v_fmac_f32_e32 v117, v116, v116
	v_mul_f32_e32 v116, v119, v119
	v_fmac_f32_e32 v128, v130, v130
	v_fmac_f32_e32 v124, v126, v126
	v_fmac_f32_e32 v120, v122, v122
	v_fmac_f32_e32 v116, v118, v118
	v_add_f32_e32 v128, v129, v128
	v_add_f32_e32 v124, v125, v124
	v_add_f32_e32 v120, v121, v120
	v_add_f32_e32 v116, v117, v116
	v_add_f32_e32 v124, v128, v124
	v_add_f32_e32 v116, v120, v116
	v_add_f32_e32 v117, v124, v116
	ds_swizzle_b32 v118, v117 offset:swizzle(SWAP,16)
	v_and_b32_e32 v152, 64, v236
	v_xor_b32_e32 v151, 32, v236
	v_add_u32_e32 v152, 64, v152
	v_cmp_lt_i32_e32 vcc, v151, v152
	s_lshl_b32 s14, s73, 2
	s_or_b32 s26, s17, s14
	v_cndmask_b32_e32 v116, v236, v151, vcc
	s_lshl_b64 s[14:15], s[22:23], 8
	v_lshlrev_b32_e32 v116, 2, v116
	s_waitcnt lgkmcnt(0)
	v_add_f32_e32 v117, v117, v118
	s_add_u32 s0, s14, s0
	ds_bpermute_b32 v118, v116, v117
	s_addc_u32 s1, s15, s1
	s_ashr_i32 s27, s26, 31
	v_or_b32_e32 v143, s0, v142
	v_mov_b32_e32 v142, s1
	s_lshl_b64 s[0:1], s[26:27], 2
	v_and_b32_e32 v119, 48, v141
	s_add_u32 s0, s63, s0
	v_cmp_eq_u32_e64 s[14:15], 0, v119
	s_addc_u32 s1, s64, s1
	s_and_saveexec_b64 s[22:23], s[14:15]
	s_cbranch_execz .LBB0_657
	v_mov_b32_e32 v141, v2
	v_lshl_add_u64 v[120:121], s[24:25], 0, v[140:141]
	global_load_dword v119, v[120:121], off
	s_waitcnt lgkmcnt(0)
	v_add_f32_e32 v117, v117, v118
	s_waitcnt vmcnt(0)
	v_add_f32_e32 v117, v117, v119
	v_fmamk_f32 v117, v117, 0x3c2aaaab, v231
	v_cmp_gt_f32_e32 vcc, s11, v117
	v_mul_f32_e32 v118, 0x4b800000, v117
	s_nop 0
	v_cndmask_b32_e32 v117, v117, v118, vcc
	v_rsq_f32_e32 v117, v117
	s_nop 0
	v_mul_f32_e32 v118, 0x45800000, v117
	v_cndmask_b32_e32 v117, v117, v118, vcc
	v_mad_u64_u32 v[118:119], s[24:25], v143, 48, s[0:1]
	v_mov_b32_e32 v120, v119
	v_mad_u64_u32 v[120:121], s[24:25], v142, 48, v[120:121]
	v_mov_b32_e32 v119, v120
	global_store_dword v[118:119], v117, off

.LBB0_769:
	s_add_u32 s0, s8, 0x100
	s_addc_u32 s1, s9, 0
	s_cmp_eq_u32 s62, 2
	s_cselect_b32 s22, s42, s0
	s_cselect_b32 s23, s43, s1
	s_cselect_b32 s18, s44, s47
	s_cselect_b32 s19, s45, s49
	s_add_u32 s20, s22, 0x80
	s_addc_u32 s21, s23, 0
	s_add_i32 s64, 0, 0x10000
	v_add_u32_e32 v144, s64, v1
	ds_read_b128 v[132:135], v144
	ds_read_b128 v[136:139], v144 offset:1024
	ds_read_b128 v[140:143], v144 offset:2048
	ds_read_b128 v[144:147], v144 offset:3072
	s_add_u32 s8, s8, 0x18080
	s_addc_u32 s9, s9, 0
	ds_read_b128 v[152:155], v3
	ds_read_b128 v[156:159], v3 offset:1024
	ds_read_b128 v[160:163], v3 offset:2048
	ds_read_b128 v[164:167], v3 offset:3072
	ds_read_b128 v[168:171], v3 offset:4096
	ds_read_b128 v[172:175], v3 offset:5120
	ds_read_b128 v[176:179], v3 offset:6144
	ds_read_b128 v[180:183], v3 offset:7168
	s_add_i32 m0, s57, 0xc000
	s_nop 0
	global_load_lds_dwordx4 v148, s[8:9]
	s_add_i32 m0, s57, 0xe000
	s_nop 0
	global_load_lds_dwordx4 v150, s[8:9]
	s_waitcnt lgkmcnt(8)
	s_barrier
	s_waitcnt lgkmcnt(0)
	s_setprio 1
	s_waitcnt lgkmcnt(0)
	v_mfma_f32_16x16x32_bf16 v[128:131], v[132:135], v[152:155], v[128:131]
	v_mfma_f32_16x16x32_bf16 v[124:127], v[140:143], v[152:155], v[124:127]
	v_mfma_f32_16x16x32_bf16 v[112:115], v[132:135], v[160:163], v[112:115]
	v_mfma_f32_16x16x32_bf16 v[108:111], v[140:143], v[160:163], v[108:111]
	v_mfma_f32_16x16x32_bf16 v[96:99], v[132:135], v[168:171], v[96:99]
	v_mfma_f32_16x16x32_bf16 v[92:95], v[140:143], v[168:171], v[92:95]
	v_mfma_f32_16x16x32_bf16 v[80:83], v[132:135], v[176:179], v[80:83]
	v_mfma_f32_16x16x32_bf16 v[76:79], v[140:143], v[176:179], v[76:79]
	v_mfma_f32_16x16x32_bf16 v[128:131], v[136:139], v[156:159], v[128:131]
	v_mfma_f32_16x16x32_bf16 v[124:127], v[144:147], v[156:159], v[124:127]
	v_mfma_f32_16x16x32_bf16 v[112:115], v[136:139], v[164:167], v[112:115]
	v_mfma_f32_16x16x32_bf16 v[108:111], v[144:147], v[164:167], v[108:111]
	v_mfma_f32_16x16x32_bf16 v[96:99], v[136:139], v[172:175], v[96:99]
	v_mfma_f32_16x16x32_bf16 v[92:95], v[144:147], v[172:175], v[92:95]
	v_mfma_f32_16x16x32_bf16 v[80:83], v[136:139], v[180:183], v[80:83]
	v_mfma_f32_16x16x32_bf16 v[76:79], v[144:147], v[180:183], v[76:79]
	s_setprio 0
	s_barrier
	s_add_i32 s65, 0, 0x14000
	v_add_u32_e32 v210, s65, v1
	s_mov_b64 s[8:9], s[18:19]
	s_add_i32 s64, s64, s56
	ds_read_b128 v[184:187], v210
	ds_read_b128 v[188:191], v210 offset:1024
	ds_read_b128 v[192:195], v210 offset:2048
	ds_read_b128 v[210:213], v210 offset:3072
	s_mov_b32 m0, s64
	s_nop 0
	global_load_lds_dwordx4 v148, s[8:9]
	s_add_i32 m0, s64, 0x2000
	s_nop 0
	global_load_lds_dwordx4 v150, s[8:9]
	s_barrier
	s_waitcnt lgkmcnt(0)
	s_setprio 1
	s_waitcnt lgkmcnt(0)
	v_mfma_f32_16x16x32_bf16 v[120:123], v[184:187], v[152:155], v[120:123]
	v_mfma_f32_16x16x32_bf16 v[116:119], v[192:195], v[152:155], v[116:119]
	v_mfma_f32_16x16x32_bf16 v[104:107], v[184:187], v[160:163], v[104:107]
	v_mfma_f32_16x16x32_bf16 v[100:103], v[192:195], v[160:163], v[100:103]
	v_mfma_f32_16x16x32_bf16 v[88:91], v[184:187], v[168:171], v[88:91]
	v_mfma_f32_16x16x32_bf16 v[84:87], v[192:195], v[168:171], v[84:87]
	v_mfma_f32_16x16x32_bf16 v[72:75], v[184:187], v[176:179], v[72:75]
	v_mfma_f32_16x16x32_bf16 v[68:71], v[192:195], v[176:179], v[68:71]
	v_mfma_f32_16x16x32_bf16 v[120:123], v[188:191], v[156:159], v[120:123]
	v_mfma_f32_16x16x32_bf16 v[116:119], v[210:213], v[156:159], v[116:119]
	v_mfma_f32_16x16x32_bf16 v[104:107], v[188:191], v[164:167], v[104:107]
	v_mfma_f32_16x16x32_bf16 v[100:103], v[210:213], v[164:167], v[100:103]
	v_mfma_f32_16x16x32_bf16 v[88:91], v[188:191], v[172:175], v[88:91]
	v_mfma_f32_16x16x32_bf16 v[84:87], v[210:213], v[172:175], v[84:87]
	v_mfma_f32_16x16x32_bf16 v[72:75], v[188:191], v[180:183], v[72:75]
	v_mfma_f32_16x16x32_bf16 v[68:71], v[210:213], v[180:183], v[68:71]
	s_setprio 0
	s_mov_b64 s[8:9], s[22:23]
	s_mov_b32 m0, s57
	s_barrier
	ds_read_b128 v[152:155], v3 offset:16384
	ds_read_b128 v[156:159], v3 offset:17408
	ds_read_b128 v[160:163], v3 offset:18432
	ds_read_b128 v[164:167], v3 offset:19456
	ds_read_b128 v[168:171], v3 offset:20480
	ds_read_b128 v[172:175], v3 offset:21504
	ds_read_b128 v[176:179], v3 offset:22528
	ds_read_b128 v[180:183], v3 offset:23552
	s_nop 0
	global_load_lds_dwordx4 v148, s[8:9]
	s_mov_b32 m0, s63
	s_nop 0
	global_load_lds_dwordx4 v150, s[8:9]
	s_barrier
	s_waitcnt lgkmcnt(0)
	s_setprio 1
	s_waitcnt lgkmcnt(0)
	v_mfma_f32_16x16x32_bf16 v[64:67], v[132:135], v[152:155], v[64:67]
	v_mfma_f32_16x16x32_bf16 v[60:63], v[140:143], v[152:155], v[60:63]
	v_mfma_f32_16x16x32_bf16 v[48:51], v[132:135], v[160:163], v[48:51]
	v_mfma_f32_16x16x32_bf16 v[44:47], v[140:143], v[160:163], v[44:47]
	v_mfma_f32_16x16x32_bf16 v[32:35], v[132:135], v[168:171], v[32:35]
	v_mfma_f32_16x16x32_bf16 v[28:31], v[140:143], v[168:171], v[28:31]
	v_mfma_f32_16x16x32_bf16 v[16:19], v[132:135], v[176:179], v[16:19]
	v_mfma_f32_16x16x32_bf16 v[12:15], v[140:143], v[176:179], v[12:15]
	v_mfma_f32_16x16x32_bf16 v[64:67], v[136:139], v[156:159], v[64:67]
	v_mfma_f32_16x16x32_bf16 v[60:63], v[144:147], v[156:159], v[60:63]
	v_mfma_f32_16x16x32_bf16 v[48:51], v[136:139], v[164:167], v[48:51]
	v_mfma_f32_16x16x32_bf16 v[44:47], v[144:147], v[164:167], v[44:47]
	v_mfma_f32_16x16x32_bf16 v[32:35], v[136:139], v[172:175], v[32:35]
	v_mfma_f32_16x16x32_bf16 v[28:31], v[144:147], v[172:175], v[28:31]
	v_mfma_f32_16x16x32_bf16 v[16:19], v[136:139], v[180:183], v[16:19]
	v_mfma_f32_16x16x32_bf16 v[12:15], v[144:147], v[180:183], v[12:15]
	s_setprio 0
	s_barrier
	s_add_u32 s8, s18, 0x18000
	s_addc_u32 s9, s19, 0
	s_add_i32 s64, s65, s56
	s_mov_b32 m0, s64
	s_nop 0
	global_load_lds_dwordx4 v148, s[8:9]
	s_add_i32 m0, s64, 0x2000
	s_nop 0
	global_load_lds_dwordx4 v150, s[8:9]
	s_waitcnt vmcnt(6)
	s_barrier
	s_setprio 1
	v_mfma_f32_16x16x32_bf16 v[56:59], v[184:187], v[152:155], v[56:59]
	v_mfma_f32_16x16x32_bf16 v[52:55], v[192:195], v[152:155], v[52:55]
	v_mfma_f32_16x16x32_bf16 v[40:43], v[184:187], v[160:163], v[40:43]
	v_mfma_f32_16x16x32_bf16 v[36:39], v[192:195], v[160:163], v[36:39]
	v_mfma_f32_16x16x32_bf16 v[24:27], v[184:187], v[168:171], v[24:27]
	v_mfma_f32_16x16x32_bf16 v[20:23], v[192:195], v[168:171], v[20:23]
	v_mfma_f32_16x16x32_bf16 v[8:11], v[184:187], v[176:179], v[8:11]
	v_mfma_f32_16x16x32_bf16 v[4:7], v[192:195], v[176:179], v[4:7]
	v_mfma_f32_16x16x32_bf16 v[56:59], v[188:191], v[156:159], v[56:59]
	v_mfma_f32_16x16x32_bf16 v[52:55], v[210:213], v[156:159], v[52:55]
	v_mfma_f32_16x16x32_bf16 v[40:43], v[188:191], v[164:167], v[40:43]
	v_mfma_f32_16x16x32_bf16 v[36:39], v[210:213], v[164:167], v[36:39]
	v_mfma_f32_16x16x32_bf16 v[24:27], v[188:191], v[172:175], v[24:27]
	v_mfma_f32_16x16x32_bf16 v[20:23], v[210:213], v[172:175], v[20:23]
	v_mfma_f32_16x16x32_bf16 v[8:11], v[188:191], v[180:183], v[8:11]
	v_mfma_f32_16x16x32_bf16 v[4:7], v[210:213], v[180:183], v[4:7]
	s_setprio 0
	s_add_i32 s64, 0, 0x18000
	v_add_u32_e32 v144, s64, v1
	s_barrier
	ds_read_b128 v[132:135], v144
	ds_read_b128 v[136:139], v144 offset:1024
	ds_read_b128 v[140:143], v144 offset:2048
	ds_read_b128 v[144:147], v144 offset:3072
	s_add_u32 s8, s22, 0x18000
	s_addc_u32 s9, s23, 0
	s_mov_b32 m0, s72
	ds_read_b128 v[152:155], v3 offset:32768
	ds_read_b128 v[156:159], v3 offset:33792
	ds_read_b128 v[160:163], v3 offset:34816
	ds_read_b128 v[164:167], v3 offset:35840
	ds_read_b128 v[168:171], v3 offset:36864
	ds_read_b128 v[172:175], v3 offset:37888
	ds_read_b128 v[176:179], v3 offset:38912
	ds_read_b128 v[180:183], v3 offset:39936
	s_nop 0
	global_load_lds_dwordx4 v148, s[8:9]
	s_mov_b32 m0, s73
	s_nop 0
	global_load_lds_dwordx4 v150, s[8:9]
	s_waitcnt lgkmcnt(8)
	s_barrier
	s_waitcnt lgkmcnt(0)
	s_setprio 1
	s_waitcnt lgkmcnt(0)
	v_mfma_f32_16x16x32_bf16 v[128:131], v[132:135], v[152:155], v[128:131]
	v_mfma_f32_16x16x32_bf16 v[124:127], v[140:143], v[152:155], v[124:127]
	v_mfma_f32_16x16x32_bf16 v[112:115], v[132:135], v[160:163], v[112:115]
	v_mfma_f32_16x16x32_bf16 v[108:111], v[140:143], v[160:163], v[108:111]
	v_mfma_f32_16x16x32_bf16 v[96:99], v[132:135], v[168:171], v[96:99]
	v_mfma_f32_16x16x32_bf16 v[92:95], v[140:143], v[168:171], v[92:95]
	v_mfma_f32_16x16x32_bf16 v[80:83], v[132:135], v[176:179], v[80:83]
	v_mfma_f32_16x16x32_bf16 v[76:79], v[140:143], v[176:179], v[76:79]
	v_mfma_f32_16x16x32_bf16 v[128:131], v[136:139], v[156:159], v[128:131]
	v_mfma_f32_16x16x32_bf16 v[124:127], v[144:147], v[156:159], v[124:127]
	v_mfma_f32_16x16x32_bf16 v[112:115], v[136:139], v[164:167], v[112:115]
	v_mfma_f32_16x16x32_bf16 v[108:111], v[144:147], v[164:167], v[108:111]
	v_mfma_f32_16x16x32_bf16 v[96:99], v[136:139], v[172:175], v[96:99]
	v_mfma_f32_16x16x32_bf16 v[92:95], v[144:147], v[172:175], v[92:95]
	v_mfma_f32_16x16x32_bf16 v[80:83], v[136:139], v[180:183], v[80:83]
	v_mfma_f32_16x16x32_bf16 v[76:79], v[144:147], v[180:183], v[76:79]
	s_setprio 0
	s_barrier
	s_add_i32 s22, 0, 0x1c000
	s_add_u32 s8, s18, 0x80
	v_add_u32_e32 v210, s22, v1
	s_addc_u32 s9, s19, 0
	s_add_i32 s23, s64, s56
	ds_read_b128 v[184:187], v210
	ds_read_b128 v[188:191], v210 offset:1024
	ds_read_b128 v[192:195], v210 offset:2048
	ds_read_b128 v[210:213], v210 offset:3072
	s_mov_b32 m0, s23
	s_nop 0
	global_load_lds_dwordx4 v148, s[8:9]
	s_add_i32 m0, s23, 0x2000
	s_nop 0
	global_load_lds_dwordx4 v150, s[8:9]
	s_barrier
	s_waitcnt lgkmcnt(0)
	s_setprio 1
	s_waitcnt lgkmcnt(0)
	v_mfma_f32_16x16x32_bf16 v[120:123], v[184:187], v[152:155], v[120:123]
	v_mfma_f32_16x16x32_bf16 v[116:119], v[192:195], v[152:155], v[116:119]
	v_mfma_f32_16x16x32_bf16 v[104:107], v[184:187], v[160:163], v[104:107]
	v_mfma_f32_16x16x32_bf16 v[100:103], v[192:195], v[160:163], v[100:103]
	v_mfma_f32_16x16x32_bf16 v[88:91], v[184:187], v[168:171], v[88:91]
	v_mfma_f32_16x16x32_bf16 v[84:87], v[192:195], v[168:171], v[84:87]
	v_mfma_f32_16x16x32_bf16 v[72:75], v[184:187], v[176:179], v[72:75]
	v_mfma_f32_16x16x32_bf16 v[68:71], v[192:195], v[176:179], v[68:71]
	v_mfma_f32_16x16x32_bf16 v[120:123], v[188:191], v[156:159], v[120:123]
	v_mfma_f32_16x16x32_bf16 v[116:119], v[210:213], v[156:159], v[116:119]
	v_mfma_f32_16x16x32_bf16 v[104:107], v[188:191], v[164:167], v[104:107]
	v_mfma_f32_16x16x32_bf16 v[100:103], v[210:213], v[164:167], v[100:103]
	v_mfma_f32_16x16x32_bf16 v[88:91], v[188:191], v[172:175], v[88:91]
	v_mfma_f32_16x16x32_bf16 v[84:87], v[210:213], v[172:175], v[84:87]
	v_mfma_f32_16x16x32_bf16 v[72:75], v[188:191], v[180:183], v[72:75]
	v_mfma_f32_16x16x32_bf16 v[68:71], v[210:213], v[180:183], v[68:71]
	s_setprio 0
	s_mov_b32 m0, s68
	s_barrier
	ds_read_b128 v[152:155], v3 offset:49152
	ds_read_b128 v[156:159], v3 offset:50176
	ds_read_b128 v[160:163], v3 offset:51200
	ds_read_b128 v[164:167], v3 offset:52224
	ds_read_b128 v[168:171], v3 offset:53248
	ds_read_b128 v[172:175], v3 offset:54272
	ds_read_b128 v[176:179], v3 offset:55296
	ds_read_b128 v[180:183], v3 offset:56320
	s_nop 0
	global_load_lds_dwordx4 v148, s[20:21]
	s_mov_b32 m0, s74
	s_nop 0
	global_load_lds_dwordx4 v150, s[20:21]
	s_barrier
	s_waitcnt lgkmcnt(0)
	s_setprio 1
	s_waitcnt lgkmcnt(0)
	v_mfma_f32_16x16x32_bf16 v[64:67], v[132:135], v[152:155], v[64:67]
	v_mfma_f32_16x16x32_bf16 v[60:63], v[140:143], v[152:155], v[60:63]
	v_mfma_f32_16x16x32_bf16 v[48:51], v[132:135], v[160:163], v[48:51]
	v_mfma_f32_16x16x32_bf16 v[44:47], v[140:143], v[160:163], v[44:47]
	v_mfma_f32_16x16x32_bf16 v[32:35], v[132:135], v[168:171], v[32:35]
	v_mfma_f32_16x16x32_bf16 v[28:31], v[140:143], v[168:171], v[28:31]
	v_mfma_f32_16x16x32_bf16 v[16:19], v[132:135], v[176:179], v[16:19]
	v_mfma_f32_16x16x32_bf16 v[12:15], v[140:143], v[176:179], v[12:15]
	v_mfma_f32_16x16x32_bf16 v[64:67], v[136:139], v[156:159], v[64:67]
	v_mfma_f32_16x16x32_bf16 v[60:63], v[144:147], v[156:159], v[60:63]
	v_mfma_f32_16x16x32_bf16 v[48:51], v[136:139], v[164:167], v[48:51]
	v_mfma_f32_16x16x32_bf16 v[44:47], v[144:147], v[164:167], v[44:47]
	v_mfma_f32_16x16x32_bf16 v[32:35], v[136:139], v[172:175], v[32:35]
	v_mfma_f32_16x16x32_bf16 v[28:31], v[144:147], v[172:175], v[28:31]
	v_mfma_f32_16x16x32_bf16 v[16:19], v[136:139], v[180:183], v[16:19]
	v_mfma_f32_16x16x32_bf16 v[12:15], v[144:147], v[180:183], v[12:15]
	s_setprio 0
	s_barrier
	s_add_u32 s8, s18, 0x18080
	s_addc_u32 s9, s19, 0
	s_add_i32 s18, s22, s56
	s_mov_b32 m0, s18
	s_nop 0
	global_load_lds_dwordx4 v148, s[8:9]
	s_add_i32 m0, s18, 0x2000
	s_nop 0
	global_load_lds_dwordx4 v150, s[8:9]
	s_waitcnt vmcnt(6)
	s_barrier
	s_setprio 1
	v_mfma_f32_16x16x32_bf16 v[56:59], v[184:187], v[152:155], v[56:59]
	v_mfma_f32_16x16x32_bf16 v[52:55], v[192:195], v[152:155], v[52:55]
	v_mfma_f32_16x16x32_bf16 v[40:43], v[184:187], v[160:163], v[40:43]
	v_mfma_f32_16x16x32_bf16 v[36:39], v[192:195], v[160:163], v[36:39]
	v_mfma_f32_16x16x32_bf16 v[24:27], v[184:187], v[168:171], v[24:27]
	v_mfma_f32_16x16x32_bf16 v[20:23], v[192:195], v[168:171], v[20:23]
	v_mfma_f32_16x16x32_bf16 v[8:11], v[184:187], v[176:179], v[8:11]
	v_mfma_f32_16x16x32_bf16 v[4:7], v[192:195], v[176:179], v[4:7]
	v_mfma_f32_16x16x32_bf16 v[56:59], v[188:191], v[156:159], v[56:59]
	v_mfma_f32_16x16x32_bf16 v[52:55], v[210:213], v[156:159], v[52:55]
	v_mfma_f32_16x16x32_bf16 v[40:43], v[188:191], v[164:167], v[40:43]
	v_mfma_f32_16x16x32_bf16 v[36:39], v[210:213], v[164:167], v[36:39]
	v_mfma_f32_16x16x32_bf16 v[24:27], v[188:191], v[172:175], v[24:27]
	v_mfma_f32_16x16x32_bf16 v[20:23], v[210:213], v[172:175], v[20:23]
	v_mfma_f32_16x16x32_bf16 v[8:11], v[188:191], v[180:183], v[8:11]
	v_mfma_f32_16x16x32_bf16 v[4:7], v[210:213], v[180:183], v[4:7]
	s_setprio 0
	s_add_i32 s62, s62, 2
	s_add_u32 s47, s47, 0x100
	s_addc_u32 s49, s49, 0
	s_cmp_gt_u32 s62, 3
	s_mov_b64 s[8:9], s[0:1]
	s_barrier
	s_cbranch_scc0 .LBB0_769
	v_mov_b32_e32 v132, v0
	s_nop 0
	v_readfirstlane_b32 s0, v132
	s_lshr_b32 s1, s0, 6
	s_and_b32 s49, s1, 3
	s_cmp_eq_u32 s48, 4
	s_cselect_b64 s[8:9], -1, 0
	s_cmp_gt_u32 s49, 1
	s_cselect_b64 s[18:19], -1, 0
	s_and_b64 s[8:9], s[8:9], s[18:19]
	s_and_b64 vcc, exec, s[8:9]
	s_cbranch_vccnz .LBB0_757
	s_ashr_i32 s0, s0, 2
	s_lshl_b32 s1, s46, 8
	s_andn2_b32 s0, s0, 63
	s_add_i32 s0, s0, s1
	v_and_or_b32 v152, v132, 15, s0
	v_ashrrev_i32_e32 v153, 31, v152
	v_bfe_u32 v134, v132, 4, 2
	v_lshl_add_u64 v[132:133], v[152:153], 2, s[6:7]
	global_load_dword v135, v[132:133], off
	global_load_dword v178, v[132:133], off offset:64
	global_load_dword v177, v[132:133], off offset:128
	global_load_dword v176, v[132:133], off offset:192
	global_load_dword v175, v[132:133], off offset:512
	global_load_dword v174, v[132:133], off offset:576
	global_load_dword v173, v[132:133], off offset:640
	global_load_dword v172, v[132:133], off offset:704
	s_cmp_gt_i32 s48, 2
	s_cselect_b64 s[0:1], -1, 0
	v_lshlrev_b32_e32 v179, 3, v134
	s_lshl_b32 s8, s48, 3
	s_lshl_b32 s9, s49, 1
	s_or_b32 s8, s8, s9
	s_sub_i32 s46, s8, 24
	v_cmp_eq_u32_e64 s[18:19], 0, v134
	v_cmp_ne_u32_e64 s[20:21], 0, v134
	s_mov_b64 s[8:9], -1
	v_lshlrev_b32_e32 v154, 2, v179
	s_waitcnt vmcnt(0)
	v_fmamk_f32 v132, v135, 0x3b2aaaab, v231
	v_cmp_gt_f32_e32 vcc, s11, v132
	v_mul_f32_e32 v133, 0x4b800000, v132
	s_nop 0
	v_cndmask_b32_e32 v132, v132, v133, vcc
	v_rsq_f32_e32 v132, v132
	s_nop 0
	v_mul_f32_e32 v133, 0x45800000, v132
	v_cndmask_b32_e32 v158, v132, v133, vcc
	v_and_b32_e32 v132, 8, v179
	v_mov_b32_e32 v159, v158
	s_and_b64 vcc, exec, s[0:1]
	v_lshlrev_b32_e32 v156, 2, v132
	v_pk_mul_f32 v[128:129], v[128:129], v[158:159]
	v_pk_mul_f32 v[124:125], v[124:125], v[158:159]
	s_cbranch_vccz .LBB0_781
	v_and_b32_e32 v133, 64, v236
	v_xor_b32_e32 v132, 32, v236
	v_add_u32_e32 v133, 64, v133
	v_cmp_lt_i32_e32 vcc, v132, v133
	v_mov_b32_e32 v162, v158
	v_mov_b32_e32 v163, v158
	v_cndmask_b32_e32 v132, v236, v132, vcc
	v_pk_mul_f32 v[160:161], v[130:131], v[162:163]
	v_lshlrev_b32_e32 v170, 2, v132
	v_mul_f32_e32 v132, v129, v129
	v_mul_f32_e32 v133, v161, v161
	v_fmac_f32_e32 v132, v128, v128
	v_fmac_f32_e32 v133, v160, v160
	v_add_f32_e32 v155, v132, v133
	global_load_dwordx4 v[136:139], v154, s[40:41] offset:272
	global_load_dwordx4 v[144:147], v154, s[40:41] offset:256
	global_load_dwordx4 v[132:135], v156, s[26:27] offset:16
	global_load_dwordx4 v[140:143], v156, s[26:27]
	v_pk_mul_f32 v[162:163], v[126:127], v[162:163]
	v_mul_f32_e32 v157, v125, v125
	v_mul_f32_e32 v164, v163, v163
	v_fmac_f32_e32 v157, v124, v124
	v_fmac_f32_e32 v164, v162, v162
	v_add_f32_e32 v157, v157, v164
	v_add_f32_e32 v155, v155, v157
	ds_swizzle_b32 v157, v155 offset:swizzle(SWAP,16)
	s_waitcnt lgkmcnt(0)
	v_add_f32_e32 v155, v155, v157
	ds_bpermute_b32 v157, v170, v155
	s_and_saveexec_b64 s[8:9], s[20:21]
	s_xor_b64 s[8:9], exec, s[8:9]
	s_ashr_i32 s47, s46, 31
	s_or_saveexec_b64 s[8:9], s[8:9]
	v_mov_b64_e32 v[164:165], s[46:47]
	s_xor_b64 exec, exec, s[8:9]
	s_cbranch_execz .LBB0_776
	s_ashr_i32 s47, s46, 31
	s_mul_i32 s22, s46, 0x10400
	s_mul_hi_i32 s23, s46, 0x10400
	s_add_u32 s22, s35, s22
	s_addc_u32 s23, s54, s23
	s_waitcnt lgkmcnt(0)
	v_add_f32_e32 v155, v155, v157
	v_lshl_add_u64 v[164:165], v[152:153], 2, s[22:23]
	global_atomic_add_f32 v[164:165], v155, off
	v_mov_b64_e32 v[164:165], s[46:47]

.LBB0_1012:
	s_add_u32 s29, s20, s36
	s_addc_u32 s42, s21, s37
	s_add_u32 s43, s29, 0x100
	s_addc_u32 s44, s42, 0
	s_and_b64 s[40:41], s[38:39], exec
	s_cselect_b32 s47, s31, s44
	s_cselect_b32 s46, s30, s43
	s_add_u32 s36, s0, s36
	s_addc_u32 s37, s1, s37
	s_add_u32 s40, s36, 0x100
	s_addc_u32 s41, s37, 0
	s_add_u32 s36, s46, 0x80
	s_addc_u32 s37, s47, 0
	s_add_i32 s78, 0, 0x10000
	s_and_b64 s[38:39], s[38:39], exec
	s_cselect_b32 s49, s9, s41
	s_cselect_b32 s48, s19, s40
	s_add_u32 s50, s29, 0x12080
	s_addc_u32 s51, s42, 0
	s_add_i32 s83, s78, s55
	s_add_i32 m0, s56, 0xc000
	s_add_i32 s84, s56, 0xe000
	s_add_i32 s82, 0, 0x14000
	s_add_i32 s81, s83, 0x2000
	s_add_u32 s44, s48, 0x10000
	s_addc_u32 s45, s49, 0
	s_add_i32 s79, s82, s55
	s_add_i32 s75, s79, 0x2000
	s_add_i32 s74, 0, 0x18000
	v_add_u32_e32 v128, s78, v1
	s_add_u32 s42, s46, 0x12000
	ds_read_b128 v[68:71], v128
	ds_read_b128 v[88:91], v128 offset:1024
	ds_read_b128 v[108:111], v128 offset:2048
	ds_read_b128 v[128:131], v128 offset:3072
	s_addc_u32 s43, s47, 0
	s_add_i32 s67, 0, 0x1c000
	s_add_u32 s40, s48, 0x80
	s_addc_u32 s41, s49, 0
	s_add_i32 s68, s74, s55
	s_add_i32 s29, s68, 0x2000
	s_add_u32 s38, s48, 0x10080
	s_addc_u32 s39, s49, 0
	s_add_i32 s80, s67, s55
	s_add_i32 s78, s80, 0x2000
	ds_read_b128 v[148:151], v3
	ds_read_b128 v[152:155], v3 offset:1024
	ds_read_b128 v[156:159], v3 offset:2048
	ds_read_b128 v[160:163], v3 offset:3072
	ds_read_b128 v[172:175], v3 offset:4096
	ds_read_b128 v[176:179], v3 offset:5120
	ds_read_b128 v[180:183], v3 offset:6144
	ds_read_b128 v[184:187], v3 offset:7168
	s_nop 0
	global_load_lds_dwordx4 v164, s[50:51]
	s_mov_b32 m0, s84
	s_nop 0
	global_load_lds_dwordx4 v168, s[50:51]
	s_waitcnt lgkmcnt(8)
	s_barrier
	s_waitcnt lgkmcnt(0)
	s_setprio 1
	s_waitcnt lgkmcnt(0)
	v_mfma_f32_16x16x32_bf16 v[144:147], v[68:71], v[148:151], v[144:147]
	v_mfma_f32_16x16x32_bf16 v[140:143], v[108:111], v[148:151], v[140:143]
	v_mfma_f32_16x16x32_bf16 v[124:127], v[68:71], v[156:159], v[124:127]
	v_mfma_f32_16x16x32_bf16 v[120:123], v[108:111], v[156:159], v[120:123]
	v_mfma_f32_16x16x32_bf16 v[104:107], v[68:71], v[172:175], v[104:107]
	v_mfma_f32_16x16x32_bf16 v[100:103], v[108:111], v[172:175], v[100:103]
	v_mfma_f32_16x16x32_bf16 v[84:87], v[68:71], v[180:183], v[84:87]
	v_mfma_f32_16x16x32_bf16 v[80:83], v[108:111], v[180:183], v[80:83]
	v_mfma_f32_16x16x32_bf16 v[144:147], v[88:91], v[152:155], v[144:147]
	v_mfma_f32_16x16x32_bf16 v[140:143], v[128:131], v[152:155], v[140:143]
	v_mfma_f32_16x16x32_bf16 v[124:127], v[88:91], v[160:163], v[124:127]
	v_mfma_f32_16x16x32_bf16 v[120:123], v[128:131], v[160:163], v[120:123]
	v_mfma_f32_16x16x32_bf16 v[104:107], v[88:91], v[176:179], v[104:107]
	v_mfma_f32_16x16x32_bf16 v[100:103], v[128:131], v[176:179], v[100:103]
	v_mfma_f32_16x16x32_bf16 v[84:87], v[88:91], v[184:187], v[84:87]
	v_mfma_f32_16x16x32_bf16 v[80:83], v[128:131], v[184:187], v[80:83]
	s_setprio 0
	s_barrier
	v_add_u32_e32 v214, s82, v1
	s_mov_b32 m0, s83
	ds_read_b128 v[188:191], v214
	ds_read_b128 v[192:195], v214 offset:1024
	ds_read_b128 v[210:213], v214 offset:2048
	ds_read_b128 v[214:217], v214 offset:3072
	s_nop 0
	global_load_lds_dwordx4 v166, s[48:49]
	s_mov_b32 m0, s81
	s_nop 0
	global_load_lds_dwordx4 v170, s[48:49]
	s_barrier
	s_waitcnt lgkmcnt(0)
	s_setprio 1
	s_waitcnt lgkmcnt(0)
	v_mfma_f32_16x16x32_bf16 v[136:139], v[188:191], v[148:151], v[136:139]
	v_mfma_f32_16x16x32_bf16 v[132:135], v[210:213], v[148:151], v[132:135]
	v_mfma_f32_16x16x32_bf16 v[116:119], v[188:191], v[156:159], v[116:119]
	v_mfma_f32_16x16x32_bf16 v[112:115], v[210:213], v[156:159], v[112:115]
	v_mfma_f32_16x16x32_bf16 v[96:99], v[188:191], v[172:175], v[96:99]
	v_mfma_f32_16x16x32_bf16 v[92:95], v[210:213], v[172:175], v[92:95]
	v_mfma_f32_16x16x32_bf16 v[76:79], v[188:191], v[180:183], v[76:79]
	v_mfma_f32_16x16x32_bf16 v[72:75], v[210:213], v[180:183], v[72:75]
	v_mfma_f32_16x16x32_bf16 v[136:139], v[192:195], v[152:155], v[136:139]
	v_mfma_f32_16x16x32_bf16 v[132:135], v[214:217], v[152:155], v[132:135]
	v_mfma_f32_16x16x32_bf16 v[116:119], v[192:195], v[160:163], v[116:119]
	v_mfma_f32_16x16x32_bf16 v[112:115], v[214:217], v[160:163], v[112:115]
	v_mfma_f32_16x16x32_bf16 v[96:99], v[192:195], v[176:179], v[96:99]
	v_mfma_f32_16x16x32_bf16 v[92:95], v[214:217], v[176:179], v[92:95]
	v_mfma_f32_16x16x32_bf16 v[76:79], v[192:195], v[184:187], v[76:79]
	v_mfma_f32_16x16x32_bf16 v[72:75], v[214:217], v[184:187], v[72:75]
	s_setprio 0
	s_mov_b32 m0, s56
	s_barrier
	ds_read_b128 v[148:151], v3 offset:16384
	ds_read_b128 v[152:155], v3 offset:17408
	ds_read_b128 v[156:159], v3 offset:18432
	ds_read_b128 v[160:163], v3 offset:19456
	ds_read_b128 v[172:175], v3 offset:20480
	ds_read_b128 v[176:179], v3 offset:21504
	ds_read_b128 v[180:183], v3 offset:22528
	ds_read_b128 v[184:187], v3 offset:23552
	s_nop 0
	global_load_lds_dwordx4 v164, s[46:47]
	s_mov_b32 m0, s57
	s_nop 0
	global_load_lds_dwordx4 v168, s[46:47]
	s_barrier
	s_waitcnt lgkmcnt(0)
	s_setprio 1
	s_waitcnt lgkmcnt(0)
	v_mfma_f32_16x16x32_bf16 v[64:67], v[68:71], v[148:151], v[64:67]
	v_mfma_f32_16x16x32_bf16 v[60:63], v[108:111], v[148:151], v[60:63]
	v_mfma_f32_16x16x32_bf16 v[48:51], v[68:71], v[156:159], v[48:51]
	v_mfma_f32_16x16x32_bf16 v[44:47], v[108:111], v[156:159], v[44:47]
	v_mfma_f32_16x16x32_bf16 v[32:35], v[68:71], v[172:175], v[32:35]
	v_mfma_f32_16x16x32_bf16 v[28:31], v[108:111], v[172:175], v[28:31]
	v_mfma_f32_16x16x32_bf16 v[16:19], v[68:71], v[180:183], v[16:19]
	v_mfma_f32_16x16x32_bf16 v[12:15], v[108:111], v[180:183], v[12:15]
	v_mfma_f32_16x16x32_bf16 v[64:67], v[88:91], v[152:155], v[64:67]
	v_mfma_f32_16x16x32_bf16 v[60:63], v[128:131], v[152:155], v[60:63]
	v_mfma_f32_16x16x32_bf16 v[48:51], v[88:91], v[160:163], v[48:51]
	v_mfma_f32_16x16x32_bf16 v[44:47], v[128:131], v[160:163], v[44:47]
	v_mfma_f32_16x16x32_bf16 v[32:35], v[88:91], v[176:179], v[32:35]
	v_mfma_f32_16x16x32_bf16 v[28:31], v[128:131], v[176:179], v[28:31]
	v_mfma_f32_16x16x32_bf16 v[16:19], v[88:91], v[184:187], v[16:19]
	v_mfma_f32_16x16x32_bf16 v[12:15], v[128:131], v[184:187], v[12:15]
	s_setprio 0
	s_barrier
	s_mov_b32 m0, s79
	s_nop 0
	global_load_lds_dwordx4 v166, s[44:45]
	s_mov_b32 m0, s75
	s_nop 0
	global_load_lds_dwordx4 v170, s[44:45]
	s_waitcnt vmcnt(6)
	s_barrier
	s_setprio 1
	v_mfma_f32_16x16x32_bf16 v[56:59], v[188:191], v[148:151], v[56:59]
	v_mfma_f32_16x16x32_bf16 v[52:55], v[210:213], v[148:151], v[52:55]
	v_mfma_f32_16x16x32_bf16 v[40:43], v[188:191], v[156:159], v[40:43]
	v_mfma_f32_16x16x32_bf16 v[36:39], v[210:213], v[156:159], v[36:39]
	v_mfma_f32_16x16x32_bf16 v[24:27], v[188:191], v[172:175], v[24:27]
	v_mfma_f32_16x16x32_bf16 v[20:23], v[210:213], v[172:175], v[20:23]
	v_mfma_f32_16x16x32_bf16 v[8:11], v[188:191], v[180:183], v[8:11]
	v_mfma_f32_16x16x32_bf16 v[4:7], v[210:213], v[180:183], v[4:7]
	v_mfma_f32_16x16x32_bf16 v[56:59], v[192:195], v[152:155], v[56:59]
	v_mfma_f32_16x16x32_bf16 v[52:55], v[214:217], v[152:155], v[52:55]
	v_mfma_f32_16x16x32_bf16 v[40:43], v[192:195], v[160:163], v[40:43]
	v_mfma_f32_16x16x32_bf16 v[36:39], v[214:217], v[160:163], v[36:39]
	v_mfma_f32_16x16x32_bf16 v[24:27], v[192:195], v[176:179], v[24:27]
	v_mfma_f32_16x16x32_bf16 v[20:23], v[214:217], v[176:179], v[20:23]
	v_mfma_f32_16x16x32_bf16 v[8:11], v[192:195], v[184:187], v[8:11]
	v_mfma_f32_16x16x32_bf16 v[4:7], v[214:217], v[184:187], v[4:7]
	s_setprio 0
	v_add_u32_e32 v128, s74, v1
	s_barrier
	ds_read_b128 v[68:71], v128
	ds_read_b128 v[88:91], v128 offset:1024
	ds_read_b128 v[108:111], v128 offset:2048
	ds_read_b128 v[128:131], v128 offset:3072
	s_mov_b32 m0, s62
	ds_read_b128 v[148:151], v3 offset:32768
	ds_read_b128 v[152:155], v3 offset:33792
	ds_read_b128 v[156:159], v3 offset:34816
	ds_read_b128 v[160:163], v3 offset:35840
	ds_read_b128 v[172:175], v3 offset:36864
	ds_read_b128 v[176:179], v3 offset:37888
	ds_read_b128 v[180:183], v3 offset:38912
	ds_read_b128 v[184:187], v3 offset:39936
	s_nop 0
	global_load_lds_dwordx4 v164, s[42:43]
	s_mov_b32 m0, s63
	s_nop 0
	global_load_lds_dwordx4 v168, s[42:43]
	s_waitcnt lgkmcnt(8)
	s_barrier
	s_waitcnt lgkmcnt(0)
	s_setprio 1
	s_waitcnt lgkmcnt(0)
	v_mfma_f32_16x16x32_bf16 v[144:147], v[68:71], v[148:151], v[144:147]
	v_mfma_f32_16x16x32_bf16 v[140:143], v[108:111], v[148:151], v[140:143]
	v_mfma_f32_16x16x32_bf16 v[124:127], v[68:71], v[156:159], v[124:127]
	v_mfma_f32_16x16x32_bf16 v[120:123], v[108:111], v[156:159], v[120:123]
	v_mfma_f32_16x16x32_bf16 v[104:107], v[68:71], v[172:175], v[104:107]
	v_mfma_f32_16x16x32_bf16 v[100:103], v[108:111], v[172:175], v[100:103]
	v_mfma_f32_16x16x32_bf16 v[84:87], v[68:71], v[180:183], v[84:87]
	v_mfma_f32_16x16x32_bf16 v[80:83], v[108:111], v[180:183], v[80:83]
	v_mfma_f32_16x16x32_bf16 v[144:147], v[88:91], v[152:155], v[144:147]
	v_mfma_f32_16x16x32_bf16 v[140:143], v[128:131], v[152:155], v[140:143]
	v_mfma_f32_16x16x32_bf16 v[124:127], v[88:91], v[160:163], v[124:127]
	v_mfma_f32_16x16x32_bf16 v[120:123], v[128:131], v[160:163], v[120:123]
	v_mfma_f32_16x16x32_bf16 v[104:107], v[88:91], v[176:179], v[104:107]
	v_mfma_f32_16x16x32_bf16 v[100:103], v[128:131], v[176:179], v[100:103]
	v_mfma_f32_16x16x32_bf16 v[84:87], v[88:91], v[184:187], v[84:87]
	v_mfma_f32_16x16x32_bf16 v[80:83], v[128:131], v[184:187], v[80:83]
	s_setprio 0
	s_barrier
	v_add_u32_e32 v214, s67, v1
	s_mov_b32 m0, s68
	ds_read_b128 v[188:191], v214
	ds_read_b128 v[192:195], v214 offset:1024
	ds_read_b128 v[210:213], v214 offset:2048
	ds_read_b128 v[214:217], v214 offset:3072
	s_nop 0
	global_load_lds_dwordx4 v166, s[40:41]
	s_mov_b32 m0, s29
	s_nop 0
	global_load_lds_dwordx4 v170, s[40:41]
	s_barrier
	s_waitcnt lgkmcnt(0)
	s_setprio 1
	s_waitcnt lgkmcnt(0)
	v_mfma_f32_16x16x32_bf16 v[136:139], v[188:191], v[148:151], v[136:139]
	v_mfma_f32_16x16x32_bf16 v[132:135], v[210:213], v[148:151], v[132:135]
	v_mfma_f32_16x16x32_bf16 v[116:119], v[188:191], v[156:159], v[116:119]
	v_mfma_f32_16x16x32_bf16 v[112:115], v[210:213], v[156:159], v[112:115]
	v_mfma_f32_16x16x32_bf16 v[96:99], v[188:191], v[172:175], v[96:99]
	v_mfma_f32_16x16x32_bf16 v[92:95], v[210:213], v[172:175], v[92:95]
	v_mfma_f32_16x16x32_bf16 v[76:79], v[188:191], v[180:183], v[76:79]
	v_mfma_f32_16x16x32_bf16 v[72:75], v[210:213], v[180:183], v[72:75]
	v_mfma_f32_16x16x32_bf16 v[136:139], v[192:195], v[152:155], v[136:139]
	v_mfma_f32_16x16x32_bf16 v[132:135], v[214:217], v[152:155], v[132:135]
	v_mfma_f32_16x16x32_bf16 v[116:119], v[192:195], v[160:163], v[116:119]
	v_mfma_f32_16x16x32_bf16 v[112:115], v[214:217], v[160:163], v[112:115]
	v_mfma_f32_16x16x32_bf16 v[96:99], v[192:195], v[176:179], v[96:99]
	v_mfma_f32_16x16x32_bf16 v[92:95], v[214:217], v[176:179], v[92:95]
	v_mfma_f32_16x16x32_bf16 v[76:79], v[192:195], v[184:187], v[76:79]
	v_mfma_f32_16x16x32_bf16 v[72:75], v[214:217], v[184:187], v[72:75]
	s_setprio 0
	s_mov_b32 m0, s64
	s_barrier
	ds_read_b128 v[148:151], v3 offset:49152
	ds_read_b128 v[152:155], v3 offset:50176
	ds_read_b128 v[156:159], v3 offset:51200
	ds_read_b128 v[160:163], v3 offset:52224
	ds_read_b128 v[172:175], v3 offset:53248
	ds_read_b128 v[176:179], v3 offset:54272
	ds_read_b128 v[180:183], v3 offset:55296
	ds_read_b128 v[184:187], v3 offset:56320
	s_nop 0
	global_load_lds_dwordx4 v164, s[36:37]
	s_mov_b32 m0, s65
	s_nop 0
	global_load_lds_dwordx4 v168, s[36:37]
	s_barrier
	s_waitcnt lgkmcnt(0)
	s_setprio 1
	s_waitcnt lgkmcnt(0)
	v_mfma_f32_16x16x32_bf16 v[64:67], v[68:71], v[148:151], v[64:67]
	v_mfma_f32_16x16x32_bf16 v[60:63], v[108:111], v[148:151], v[60:63]
	v_mfma_f32_16x16x32_bf16 v[48:51], v[68:71], v[156:159], v[48:51]
	v_mfma_f32_16x16x32_bf16 v[44:47], v[108:111], v[156:159], v[44:47]
	v_mfma_f32_16x16x32_bf16 v[32:35], v[68:71], v[172:175], v[32:35]
	v_mfma_f32_16x16x32_bf16 v[28:31], v[108:111], v[172:175], v[28:31]
	v_mfma_f32_16x16x32_bf16 v[16:19], v[68:71], v[180:183], v[16:19]
	v_mfma_f32_16x16x32_bf16 v[12:15], v[108:111], v[180:183], v[12:15]
	v_mfma_f32_16x16x32_bf16 v[64:67], v[88:91], v[152:155], v[64:67]
	v_mfma_f32_16x16x32_bf16 v[60:63], v[128:131], v[152:155], v[60:63]
	v_mfma_f32_16x16x32_bf16 v[48:51], v[88:91], v[160:163], v[48:51]
	v_mfma_f32_16x16x32_bf16 v[44:47], v[128:131], v[160:163], v[44:47]
	v_mfma_f32_16x16x32_bf16 v[32:35], v[88:91], v[176:179], v[32:35]
	v_mfma_f32_16x16x32_bf16 v[28:31], v[128:131], v[176:179], v[28:31]
	v_mfma_f32_16x16x32_bf16 v[16:19], v[88:91], v[184:187], v[16:19]
	v_mfma_f32_16x16x32_bf16 v[12:15], v[128:131], v[184:187], v[12:15]
	s_setprio 0
	s_barrier
	s_mov_b32 m0, s80
	s_nop 0
	global_load_lds_dwordx4 v166, s[38:39]
	s_mov_b32 m0, s78
	s_nop 0
	global_load_lds_dwordx4 v170, s[38:39]
	s_waitcnt vmcnt(6)
	s_barrier
	s_setprio 1
	v_mfma_f32_16x16x32_bf16 v[56:59], v[188:191], v[148:151], v[56:59]
	v_mfma_f32_16x16x32_bf16 v[52:55], v[210:213], v[148:151], v[52:55]
	v_mfma_f32_16x16x32_bf16 v[40:43], v[188:191], v[156:159], v[40:43]
	v_mfma_f32_16x16x32_bf16 v[36:39], v[210:213], v[156:159], v[36:39]
	v_mfma_f32_16x16x32_bf16 v[24:27], v[188:191], v[172:175], v[24:27]
	v_mfma_f32_16x16x32_bf16 v[20:23], v[210:213], v[172:175], v[20:23]
	v_mfma_f32_16x16x32_bf16 v[8:11], v[188:191], v[180:183], v[8:11]
	v_mfma_f32_16x16x32_bf16 v[4:7], v[210:213], v[180:183], v[4:7]
	v_mfma_f32_16x16x32_bf16 v[56:59], v[192:195], v[152:155], v[56:59]
	v_mfma_f32_16x16x32_bf16 v[52:55], v[214:217], v[152:155], v[52:55]
	v_mfma_f32_16x16x32_bf16 v[40:43], v[192:195], v[160:163], v[40:43]
	v_mfma_f32_16x16x32_bf16 v[36:39], v[214:217], v[160:163], v[36:39]
	v_mfma_f32_16x16x32_bf16 v[24:27], v[192:195], v[176:179], v[24:27]
	v_mfma_f32_16x16x32_bf16 v[20:23], v[214:217], v[176:179], v[20:23]
	v_mfma_f32_16x16x32_bf16 v[8:11], v[192:195], v[184:187], v[8:11]
	v_mfma_f32_16x16x32_bf16 v[4:7], v[214:217], v[184:187], v[4:7]
	s_setprio 0
	s_andn2_b64 vcc, exec, s[16:17]
	s_mov_b64 s[38:39], -1
	s_mov_b64 s[16:17], 0
	s_mov_b64 s[36:37], 0x100
	s_barrier
	s_cbranch_vccz .LBB0_1012
	v_mov_b32_e32 v68, v0
	s_cmp_gt_i32 s8, 2
	s_cselect_b64 s[0:1], -1, 0
	v_readfirstlane_b32 s9, v68
	s_ashr_i32 s19, s18, 31
	s_lshl_b64 s[16:17], s[18:19], 8
	s_ashr_i32 s18, s9, 2
	s_andn2_b32 s18, s18, 63
	s_ashr_i32 s19, s18, 31
	s_add_u32 s18, s16, s18
	v_bfe_u32 v174, v68, 4, 2
	s_addc_u32 s19, s17, s19
	v_and_or_b32 v172, v68, 15, s18
	v_mov_b32_e32 v173, s19
	v_lshlrev_b32_e32 v179, 3, v174
	s_and_b64 vcc, exec, s[0:1]
	s_cbranch_vccnz .LBB0_1015
	v_mov_b64_e32 v[68:69], s[6:7]
	s_movk_i32 s20, 0x240
	v_mad_u64_u32 v[68:69], s[16:17], v172, s20, v[68:69]
	v_mov_b32_e32 v70, v69
	v_mad_u64_u32 v[70:71], s[16:17], v173, s20, v[70:71]
	v_mov_b32_e32 v69, v70
	v_lshlrev_b32_e32 v70, 1, v179
	v_mov_b32_e32 v71, v2
	v_lshl_add_u64 v[68:69], v[68:69], 0, v[70:71]
	v_add_co_u32_e32 v70, vcc, 0x2000, v68
	s_movk_i32 s16, 0x4000
	s_nop 0
	v_addc_co_u32_e32 v71, vcc, 0, v69, vcc
	global_load_dwordx4 v[160:163], v[68:69], off offset:512
	global_load_dwordx4 v[156:159], v[70:71], off offset:1536
	v_add_co_u32_e32 v70, vcc, s16, v68
	s_nop 1
	v_addc_co_u32_e32 v71, vcc, 0, v69, vcc
	v_add_co_u32_e32 v88, vcc, 0x6000, v68
	s_nop 1
	v_addc_co_u32_e32 v89, vcc, 0, v69, vcc
	global_load_dwordx4 v[152:155], v[70:71], off offset:2560
	global_load_dwordx4 v[148:151], v[88:89], off offset:3584
	v_add_co_u32_e32 v70, vcc, 0x12000, v68
	s_nop 1
	v_addc_co_u32_e32 v71, vcc, 0, v69, vcc
	v_add_co_u32_e32 v88, vcc, 0x14000, v68
	s_nop 1
	v_addc_co_u32_e32 v89, vcc, 0, v69, vcc
	global_load_dwordx4 v[128:131], v[70:71], off offset:512
	global_load_dwordx4 v[108:111], v[88:89], off offset:1536
	v_add_co_u32_e32 v70, vcc, 0x16000, v68
	s_nop 1
	v_addc_co_u32_e32 v71, vcc, 0, v69, vcc
	v_add_co_u32_e32 v68, vcc, 0x18000, v68
	s_nop 1
	v_addc_co_u32_e32 v69, vcc, 0, v69, vcc
	global_load_dwordx4 v[88:91], v[70:71], off offset:2560
	s_nop 0
	global_load_dwordx4 v[68:71], v[68:69], off offset:3584

.LBB0_1765:
	s_add_u32 s8, s0, 0x100
	s_addc_u32 s9, s1, 0
	s_cmp_eq_u32 s80, 12
	s_cselect_b32 s46, s65, s8
	s_cselect_b32 s47, s41, s9
	s_cselect_b32 s14, s67, s68
	s_cselect_b32 s15, s39, s79
	s_add_u32 s18, s46, 0x80
	s_addc_u32 s19, s47, 0
	s_add_i32 s81, 0, 0x10000
	v_add_u32_e32 v148, s81, v1
	ds_read_b128 v[132:135], v148
	ds_read_b128 v[140:143], v148 offset:1024
	ds_read_b128 v[144:147], v148 offset:2048
	ds_read_b128 v[148:151], v148 offset:3072
	s_add_u32 s0, s0, 0x40080
	s_addc_u32 s1, s1, 0
	ds_read_b128 v[152:155], v3
	ds_read_b128 v[156:159], v3 offset:1024
	ds_read_b128 v[160:163], v3 offset:2048
	ds_read_b128 v[164:167], v3 offset:3072
	ds_read_b128 v[168:171], v3 offset:4096
	ds_read_b128 v[172:175], v3 offset:5120
	ds_read_b128 v[176:179], v3 offset:6144
	ds_read_b128 v[180:183], v3 offset:7168
	s_add_i32 m0, s57, 0xc000
	s_nop 0
	global_load_lds_dwordx4 v138, s[0:1]
	s_add_i32 m0, s57, 0xe000
	s_nop 0
	global_load_lds_dwordx4 v136, s[0:1]
	s_waitcnt lgkmcnt(8)
	s_barrier
	s_waitcnt lgkmcnt(0)
	s_setprio 1
	s_waitcnt lgkmcnt(0)
	v_mfma_f32_16x16x32_bf16 v[128:131], v[132:135], v[152:155], v[128:131]
	v_mfma_f32_16x16x32_bf16 v[124:127], v[144:147], v[152:155], v[124:127]
	v_mfma_f32_16x16x32_bf16 v[112:115], v[132:135], v[160:163], v[112:115]
	v_mfma_f32_16x16x32_bf16 v[108:111], v[144:147], v[160:163], v[108:111]
	v_mfma_f32_16x16x32_bf16 v[96:99], v[132:135], v[168:171], v[96:99]
	v_mfma_f32_16x16x32_bf16 v[92:95], v[144:147], v[168:171], v[92:95]
	v_mfma_f32_16x16x32_bf16 v[80:83], v[132:135], v[176:179], v[80:83]
	v_mfma_f32_16x16x32_bf16 v[76:79], v[144:147], v[176:179], v[76:79]
	v_mfma_f32_16x16x32_bf16 v[128:131], v[140:143], v[156:159], v[128:131]
	v_mfma_f32_16x16x32_bf16 v[124:127], v[148:151], v[156:159], v[124:127]
	v_mfma_f32_16x16x32_bf16 v[112:115], v[140:143], v[164:167], v[112:115]
	v_mfma_f32_16x16x32_bf16 v[108:111], v[148:151], v[164:167], v[108:111]
	v_mfma_f32_16x16x32_bf16 v[96:99], v[140:143], v[172:175], v[96:99]
	v_mfma_f32_16x16x32_bf16 v[92:95], v[148:151], v[172:175], v[92:95]
	v_mfma_f32_16x16x32_bf16 v[80:83], v[140:143], v[180:183], v[80:83]
	v_mfma_f32_16x16x32_bf16 v[76:79], v[148:151], v[180:183], v[76:79]
	s_setprio 0
	s_barrier
	s_add_i32 s82, 0, 0x14000
	v_add_u32_e32 v210, s82, v1
	s_mov_b64 s[0:1], s[14:15]
	s_add_i32 s81, s81, s56
	ds_read_b128 v[184:187], v210
	ds_read_b128 v[188:191], v210 offset:1024
	ds_read_b128 v[192:195], v210 offset:2048
	ds_read_b128 v[210:213], v210 offset:3072
	s_mov_b32 m0, s81
	s_nop 0
	global_load_lds_dwordx4 v138, s[0:1]
	s_add_i32 m0, s81, 0x2000
	s_nop 0
	global_load_lds_dwordx4 v136, s[0:1]
	s_barrier
	s_waitcnt lgkmcnt(0)
	s_setprio 1
	s_waitcnt lgkmcnt(0)
	v_mfma_f32_16x16x32_bf16 v[120:123], v[184:187], v[152:155], v[120:123]
	v_mfma_f32_16x16x32_bf16 v[116:119], v[192:195], v[152:155], v[116:119]
	v_mfma_f32_16x16x32_bf16 v[104:107], v[184:187], v[160:163], v[104:107]
	v_mfma_f32_16x16x32_bf16 v[100:103], v[192:195], v[160:163], v[100:103]
	v_mfma_f32_16x16x32_bf16 v[88:91], v[184:187], v[168:171], v[88:91]
	v_mfma_f32_16x16x32_bf16 v[84:87], v[192:195], v[168:171], v[84:87]
	v_mfma_f32_16x16x32_bf16 v[72:75], v[184:187], v[176:179], v[72:75]
	v_mfma_f32_16x16x32_bf16 v[68:71], v[192:195], v[176:179], v[68:71]
	v_mfma_f32_16x16x32_bf16 v[120:123], v[188:191], v[156:159], v[120:123]
	v_mfma_f32_16x16x32_bf16 v[116:119], v[210:213], v[156:159], v[116:119]
	v_mfma_f32_16x16x32_bf16 v[104:107], v[188:191], v[164:167], v[104:107]
	v_mfma_f32_16x16x32_bf16 v[100:103], v[210:213], v[164:167], v[100:103]
	v_mfma_f32_16x16x32_bf16 v[88:91], v[188:191], v[172:175], v[88:91]
	v_mfma_f32_16x16x32_bf16 v[84:87], v[210:213], v[172:175], v[84:87]
	v_mfma_f32_16x16x32_bf16 v[72:75], v[188:191], v[180:183], v[72:75]
	v_mfma_f32_16x16x32_bf16 v[68:71], v[210:213], v[180:183], v[68:71]
	s_setprio 0
	s_mov_b64 s[0:1], s[46:47]
	s_mov_b32 m0, s57
	s_barrier
	ds_read_b128 v[152:155], v3 offset:16384
	ds_read_b128 v[156:159], v3 offset:17408
	ds_read_b128 v[160:163], v3 offset:18432
	ds_read_b128 v[164:167], v3 offset:19456
	ds_read_b128 v[168:171], v3 offset:20480
	ds_read_b128 v[172:175], v3 offset:21504
	ds_read_b128 v[176:179], v3 offset:22528
	ds_read_b128 v[180:183], v3 offset:23552
	s_nop 0
	global_load_lds_dwordx4 v138, s[0:1]
	s_mov_b32 m0, s62
	s_nop 0
	global_load_lds_dwordx4 v136, s[0:1]
	s_barrier
	s_waitcnt lgkmcnt(0)
	s_setprio 1
	s_waitcnt lgkmcnt(0)
	v_mfma_f32_16x16x32_bf16 v[64:67], v[132:135], v[152:155], v[64:67]
	v_mfma_f32_16x16x32_bf16 v[60:63], v[144:147], v[152:155], v[60:63]
	v_mfma_f32_16x16x32_bf16 v[48:51], v[132:135], v[160:163], v[48:51]
	v_mfma_f32_16x16x32_bf16 v[44:47], v[144:147], v[160:163], v[44:47]
	v_mfma_f32_16x16x32_bf16 v[32:35], v[132:135], v[168:171], v[32:35]
	v_mfma_f32_16x16x32_bf16 v[28:31], v[144:147], v[168:171], v[28:31]
	v_mfma_f32_16x16x32_bf16 v[16:19], v[132:135], v[176:179], v[16:19]
	v_mfma_f32_16x16x32_bf16 v[12:15], v[144:147], v[176:179], v[12:15]
	v_mfma_f32_16x16x32_bf16 v[64:67], v[140:143], v[156:159], v[64:67]
	v_mfma_f32_16x16x32_bf16 v[60:63], v[148:151], v[156:159], v[60:63]
	v_mfma_f32_16x16x32_bf16 v[48:51], v[140:143], v[164:167], v[48:51]
	v_mfma_f32_16x16x32_bf16 v[44:47], v[148:151], v[164:167], v[44:47]
	v_mfma_f32_16x16x32_bf16 v[32:35], v[140:143], v[172:175], v[32:35]
	v_mfma_f32_16x16x32_bf16 v[28:31], v[148:151], v[172:175], v[28:31]
	v_mfma_f32_16x16x32_bf16 v[16:19], v[140:143], v[180:183], v[16:19]
	v_mfma_f32_16x16x32_bf16 v[12:15], v[148:151], v[180:183], v[12:15]
	s_setprio 0
	s_barrier
	s_add_u32 s0, s14, 0x40000
	s_addc_u32 s1, s15, 0
	s_add_i32 s81, s82, s56
	s_mov_b32 m0, s81
	s_nop 0
	global_load_lds_dwordx4 v138, s[0:1]
	s_add_i32 m0, s81, 0x2000
	s_nop 0
	global_load_lds_dwordx4 v136, s[0:1]
	s_waitcnt vmcnt(6)
	s_barrier
	s_setprio 1
	v_mfma_f32_16x16x32_bf16 v[56:59], v[184:187], v[152:155], v[56:59]
	v_mfma_f32_16x16x32_bf16 v[52:55], v[192:195], v[152:155], v[52:55]
	v_mfma_f32_16x16x32_bf16 v[40:43], v[184:187], v[160:163], v[40:43]
	v_mfma_f32_16x16x32_bf16 v[36:39], v[192:195], v[160:163], v[36:39]
	v_mfma_f32_16x16x32_bf16 v[24:27], v[184:187], v[168:171], v[24:27]
	v_mfma_f32_16x16x32_bf16 v[20:23], v[192:195], v[168:171], v[20:23]
	v_mfma_f32_16x16x32_bf16 v[8:11], v[184:187], v[176:179], v[8:11]
	v_mfma_f32_16x16x32_bf16 v[4:7], v[192:195], v[176:179], v[4:7]
	v_mfma_f32_16x16x32_bf16 v[56:59], v[188:191], v[156:159], v[56:59]
	v_mfma_f32_16x16x32_bf16 v[52:55], v[210:213], v[156:159], v[52:55]
	v_mfma_f32_16x16x32_bf16 v[40:43], v[188:191], v[164:167], v[40:43]
	v_mfma_f32_16x16x32_bf16 v[36:39], v[210:213], v[164:167], v[36:39]
	v_mfma_f32_16x16x32_bf16 v[24:27], v[188:191], v[172:175], v[24:27]
	v_mfma_f32_16x16x32_bf16 v[20:23], v[210:213], v[172:175], v[20:23]
	v_mfma_f32_16x16x32_bf16 v[8:11], v[188:191], v[180:183], v[8:11]
	v_mfma_f32_16x16x32_bf16 v[4:7], v[210:213], v[180:183], v[4:7]
	s_setprio 0
	s_add_i32 s81, 0, 0x18000
	v_add_u32_e32 v148, s81, v1
	s_barrier
	ds_read_b128 v[132:135], v148
	ds_read_b128 v[140:143], v148 offset:1024
	ds_read_b128 v[144:147], v148 offset:2048
	ds_read_b128 v[148:151], v148 offset:3072
	s_add_u32 s0, s46, 0x40000
	s_addc_u32 s1, s47, 0
	s_mov_b32 m0, s63
	ds_read_b128 v[152:155], v3 offset:32768
	ds_read_b128 v[156:159], v3 offset:33792
	ds_read_b128 v[160:163], v3 offset:34816
	ds_read_b128 v[164:167], v3 offset:35840
	ds_read_b128 v[168:171], v3 offset:36864
	ds_read_b128 v[172:175], v3 offset:37888
	ds_read_b128 v[176:179], v3 offset:38912
	ds_read_b128 v[180:183], v3 offset:39936
	s_nop 0
	global_load_lds_dwordx4 v138, s[0:1]
	s_mov_b32 m0, s72
	s_nop 0
	global_load_lds_dwordx4 v136, s[0:1]
	s_waitcnt lgkmcnt(8)
	s_barrier
	s_waitcnt lgkmcnt(0)
	s_setprio 1
	s_waitcnt lgkmcnt(0)
	v_mfma_f32_16x16x32_bf16 v[128:131], v[132:135], v[152:155], v[128:131]
	v_mfma_f32_16x16x32_bf16 v[124:127], v[144:147], v[152:155], v[124:127]
	v_mfma_f32_16x16x32_bf16 v[112:115], v[132:135], v[160:163], v[112:115]
	v_mfma_f32_16x16x32_bf16 v[108:111], v[144:147], v[160:163], v[108:111]
	v_mfma_f32_16x16x32_bf16 v[96:99], v[132:135], v[168:171], v[96:99]
	v_mfma_f32_16x16x32_bf16 v[92:95], v[144:147], v[168:171], v[92:95]
	v_mfma_f32_16x16x32_bf16 v[80:83], v[132:135], v[176:179], v[80:83]
	v_mfma_f32_16x16x32_bf16 v[76:79], v[144:147], v[176:179], v[76:79]
	v_mfma_f32_16x16x32_bf16 v[128:131], v[140:143], v[156:159], v[128:131]
	v_mfma_f32_16x16x32_bf16 v[124:127], v[148:151], v[156:159], v[124:127]
	v_mfma_f32_16x16x32_bf16 v[112:115], v[140:143], v[164:167], v[112:115]
	v_mfma_f32_16x16x32_bf16 v[108:111], v[148:151], v[164:167], v[108:111]
	v_mfma_f32_16x16x32_bf16 v[96:99], v[140:143], v[172:175], v[96:99]
	v_mfma_f32_16x16x32_bf16 v[92:95], v[148:151], v[172:175], v[92:95]
	v_mfma_f32_16x16x32_bf16 v[80:83], v[140:143], v[180:183], v[80:83]
	v_mfma_f32_16x16x32_bf16 v[76:79], v[148:151], v[180:183], v[76:79]
	s_setprio 0
	s_barrier
	s_add_i32 s46, 0, 0x1c000
	s_add_u32 s0, s14, 0x80
	v_add_u32_e32 v210, s46, v1
	s_addc_u32 s1, s15, 0
	s_add_i32 s47, s81, s56
	ds_read_b128 v[184:187], v210
	ds_read_b128 v[188:191], v210 offset:1024
	ds_read_b128 v[192:195], v210 offset:2048
	ds_read_b128 v[210:213], v210 offset:3072
	s_mov_b32 m0, s47
	s_nop 0
	global_load_lds_dwordx4 v138, s[0:1]
	s_add_i32 m0, s47, 0x2000
	s_nop 0
	global_load_lds_dwordx4 v136, s[0:1]
	s_barrier
	s_waitcnt lgkmcnt(0)
	s_setprio 1
	s_waitcnt lgkmcnt(0)
	v_mfma_f32_16x16x32_bf16 v[120:123], v[184:187], v[152:155], v[120:123]
	v_mfma_f32_16x16x32_bf16 v[116:119], v[192:195], v[152:155], v[116:119]
	v_mfma_f32_16x16x32_bf16 v[104:107], v[184:187], v[160:163], v[104:107]
	v_mfma_f32_16x16x32_bf16 v[100:103], v[192:195], v[160:163], v[100:103]
	v_mfma_f32_16x16x32_bf16 v[88:91], v[184:187], v[168:171], v[88:91]
	v_mfma_f32_16x16x32_bf16 v[84:87], v[192:195], v[168:171], v[84:87]
	v_mfma_f32_16x16x32_bf16 v[72:75], v[184:187], v[176:179], v[72:75]
	v_mfma_f32_16x16x32_bf16 v[68:71], v[192:195], v[176:179], v[68:71]
	v_mfma_f32_16x16x32_bf16 v[120:123], v[188:191], v[156:159], v[120:123]
	v_mfma_f32_16x16x32_bf16 v[116:119], v[210:213], v[156:159], v[116:119]
	v_mfma_f32_16x16x32_bf16 v[104:107], v[188:191], v[164:167], v[104:107]
	v_mfma_f32_16x16x32_bf16 v[100:103], v[210:213], v[164:167], v[100:103]
	v_mfma_f32_16x16x32_bf16 v[88:91], v[188:191], v[172:175], v[88:91]
	v_mfma_f32_16x16x32_bf16 v[84:87], v[210:213], v[172:175], v[84:87]
	v_mfma_f32_16x16x32_bf16 v[72:75], v[188:191], v[180:183], v[72:75]
	v_mfma_f32_16x16x32_bf16 v[68:71], v[210:213], v[180:183], v[68:71]
	s_setprio 0
	s_mov_b32 m0, s73
	s_barrier
	ds_read_b128 v[152:155], v3 offset:49152
	ds_read_b128 v[156:159], v3 offset:50176
	ds_read_b128 v[160:163], v3 offset:51200
	ds_read_b128 v[164:167], v3 offset:52224
	ds_read_b128 v[168:171], v3 offset:53248
	ds_read_b128 v[172:175], v3 offset:54272
	ds_read_b128 v[176:179], v3 offset:55296
	ds_read_b128 v[180:183], v3 offset:56320
	s_nop 0
	global_load_lds_dwordx4 v138, s[18:19]
	s_mov_b32 m0, s74
	s_nop 0
	global_load_lds_dwordx4 v136, s[18:19]
	s_barrier
	s_waitcnt lgkmcnt(0)
	s_setprio 1
	s_waitcnt lgkmcnt(0)
	v_mfma_f32_16x16x32_bf16 v[64:67], v[132:135], v[152:155], v[64:67]
	v_mfma_f32_16x16x32_bf16 v[60:63], v[144:147], v[152:155], v[60:63]
	v_mfma_f32_16x16x32_bf16 v[48:51], v[132:135], v[160:163], v[48:51]
	v_mfma_f32_16x16x32_bf16 v[44:47], v[144:147], v[160:163], v[44:47]
	v_mfma_f32_16x16x32_bf16 v[32:35], v[132:135], v[168:171], v[32:35]
	v_mfma_f32_16x16x32_bf16 v[28:31], v[144:147], v[168:171], v[28:31]
	v_mfma_f32_16x16x32_bf16 v[16:19], v[132:135], v[176:179], v[16:19]
	v_mfma_f32_16x16x32_bf16 v[12:15], v[144:147], v[176:179], v[12:15]
	v_mfma_f32_16x16x32_bf16 v[64:67], v[140:143], v[156:159], v[64:67]
	v_mfma_f32_16x16x32_bf16 v[60:63], v[148:151], v[156:159], v[60:63]
	v_mfma_f32_16x16x32_bf16 v[48:51], v[140:143], v[164:167], v[48:51]
	v_mfma_f32_16x16x32_bf16 v[44:47], v[148:151], v[164:167], v[44:47]
	v_mfma_f32_16x16x32_bf16 v[32:35], v[140:143], v[172:175], v[32:35]
	v_mfma_f32_16x16x32_bf16 v[28:31], v[148:151], v[172:175], v[28:31]
	v_mfma_f32_16x16x32_bf16 v[16:19], v[140:143], v[180:183], v[16:19]
	v_mfma_f32_16x16x32_bf16 v[12:15], v[148:151], v[180:183], v[12:15]
	s_setprio 0
	s_barrier
	s_add_u32 s0, s14, 0x40080
	s_addc_u32 s1, s15, 0
	s_add_i32 s14, s46, s56
	s_mov_b32 m0, s14
	s_nop 0
	global_load_lds_dwordx4 v138, s[0:1]
	s_add_i32 m0, s14, 0x2000
	s_nop 0
	global_load_lds_dwordx4 v136, s[0:1]
	s_waitcnt vmcnt(6)
	s_barrier
	s_setprio 1
	v_mfma_f32_16x16x32_bf16 v[56:59], v[184:187], v[152:155], v[56:59]
	v_mfma_f32_16x16x32_bf16 v[52:55], v[192:195], v[152:155], v[52:55]
	v_mfma_f32_16x16x32_bf16 v[40:43], v[184:187], v[160:163], v[40:43]
	v_mfma_f32_16x16x32_bf16 v[36:39], v[192:195], v[160:163], v[36:39]
	v_mfma_f32_16x16x32_bf16 v[24:27], v[184:187], v[168:171], v[24:27]
	v_mfma_f32_16x16x32_bf16 v[20:23], v[192:195], v[168:171], v[20:23]
	v_mfma_f32_16x16x32_bf16 v[8:11], v[184:187], v[176:179], v[8:11]
	v_mfma_f32_16x16x32_bf16 v[4:7], v[192:195], v[176:179], v[4:7]
	v_mfma_f32_16x16x32_bf16 v[56:59], v[188:191], v[156:159], v[56:59]
	v_mfma_f32_16x16x32_bf16 v[52:55], v[210:213], v[156:159], v[52:55]
	v_mfma_f32_16x16x32_bf16 v[40:43], v[188:191], v[164:167], v[40:43]
	v_mfma_f32_16x16x32_bf16 v[36:39], v[210:213], v[164:167], v[36:39]
	v_mfma_f32_16x16x32_bf16 v[24:27], v[188:191], v[172:175], v[24:27]
	v_mfma_f32_16x16x32_bf16 v[20:23], v[210:213], v[172:175], v[20:23]
	v_mfma_f32_16x16x32_bf16 v[8:11], v[188:191], v[180:183], v[8:11]
	v_mfma_f32_16x16x32_bf16 v[4:7], v[210:213], v[180:183], v[4:7]
	s_setprio 0
	s_add_i32 s80, s80, 2
	s_add_u32 s68, s68, 0x100
	s_addc_u32 s79, s79, 0
	s_cmp_gt_u32 s80, 13
	s_mov_b64 s[0:1], s[8:9]
	s_barrier
	s_cbranch_scc0 .LBB0_1765
	v_mov_b32_e32 v145, v0
	s_lshl_b32 s1, s64, 8
	v_readfirstlane_b32 s0, v145
	s_and_b32 s14, s0, 0xc0
	s_ashr_i32 s0, s0, 2
	v_and_b32_e32 v170, 15, v145
	s_and_b32 s15, s0, 0xffffffc0
	v_or_b32_e32 v132, s15, v170
	v_add_u32_e32 v132, s1, v132
	v_ashrrev_i32_e32 v133, 31, v132
	v_lshl_add_u64 v[132:133], v[132:133], 2, s[20:21]
	global_load_dword v134, v[132:133], off
	global_load_dword v174, v[132:133], off offset:64
	global_load_dword v173, v[132:133], off offset:128
	global_load_dword v172, v[132:133], off offset:192
	global_load_dword v171, v[132:133], off offset:512
	global_load_dword v169, v[132:133], off offset:576
	global_load_dword v168, v[132:133], off offset:640
	global_load_dword v167, v[132:133], off offset:704
	s_add_i32 s15, s15, s1
	s_cmp_gt_i32 s78, 2
	s_cselect_b64 s[0:1], -1, 0
	v_or_b32_e32 v142, s15, v170
	s_mov_b64 s[8:9], -1
	s_waitcnt vmcnt(0)
	v_fmamk_f32 v132, v134, 0x3a800000, v231
	v_cmp_gt_f32_e32 vcc, s11, v132
	v_mul_f32_e32 v133, 0x4b800000, v132
	s_nop 0
	v_cndmask_b32_e32 v132, v132, v133, vcc
	v_rsq_f32_e32 v132, v132
	s_nop 0
	v_mul_f32_e32 v133, 0x45800000, v132
	v_cndmask_b32_e32 v144, v132, v133, vcc
	v_lshrrev_b32_e32 v132, 1, v145
	v_and_b32_e32 v155, 24, v132
	s_and_b64 vcc, exec, s[0:1]
	v_lshlrev_b32_e32 v166, 2, v155
	v_lshlrev_b32_e32 v140, 1, v155
	s_cbranch_vccz .LBB0_1768
	v_ashrrev_i32_e32 v143, 31, v142
	v_lshlrev_b64 v[132:133], 9, v[142:143]
	v_lshl_add_u64 v[132:133], s[24:25], 0, v[132:133]
	s_lshl_b32 s68, s14, 1
	v_pk_mul_f32 v[160:161], v[130:131], v[144:145] op_sel_hi:[1,0]
	v_pk_mul_f32 v[162:163], v[128:129], v[144:145] op_sel_hi:[1,0]
	v_lshl_add_u64 v[164:165], v[132:133], 0, s[68:69]
	v_pk_mul_f32 v[132:133], v[160:161], v[160:161]
	v_pk_mul_f32 v[134:135], v[162:163], v[162:163]
	v_pk_mul_f32 v[156:157], v[126:127], v[144:145] op_sel_hi:[1,0]
	v_pk_mov_b32 v[146:147], v[134:135], v[132:133] op_sel:[1,0]
	v_mov_b32_e32 v135, v133
	v_pk_add_f32 v[132:133], v[146:147], v[134:135]
	v_pk_mul_f32 v[158:159], v[124:125], v[144:145] op_sel_hi:[1,0]
	v_pk_add_f32 v[132:133], v[132:133], v[132:133] op_sel_hi:[0,1]
	v_pk_mul_f32 v[134:135], v[156:157], v[156:157]
	v_pk_mul_f32 v[146:147], v[158:159], v[158:159]
	v_pk_mul_f32 v[152:153], v[120:121], v[144:145] op_sel_hi:[1,0]
	v_pk_mov_b32 v[148:149], v[146:147], v[134:135] op_sel:[1,0]
	v_mov_b32_e32 v147, v135
	v_pk_mul_f32 v[150:151], v[122:123], v[144:145] op_sel_hi:[1,0]
	v_mul_f32_e32 v132, v152, v152
	v_pk_add_f32 v[134:135], v[148:149], v[146:147]
	v_pk_fma_f32 v[176:177], v[152:153], v[152:153], v[132:133] op_sel_hi:[1,1,0]
	v_mul_f32_e32 v132, v150, v150
	v_pk_add_f32 v[134:135], v[134:135], v[134:135] op_sel_hi:[0,1]
	v_pk_fma_f32 v[178:179], v[150:151], v[150:151], v[132:133] op_sel_hi:[1,1,0]
	v_pk_mul_f32 v[146:147], v[118:119], v[144:145] op_sel_hi:[1,0]
	v_pk_mul_f32 v[148:149], v[116:117], v[144:145] op_sel_hi:[1,0]
	v_mul_f32_e32 v132, v146, v146
	v_mul_f32_e32 v176, v148, v148
	v_mul_f32_e32 v178, v149, v149
	v_mul_f32_e32 v134, v147, v147
	v_pk_add_f32 v[176:177], v[176:177], v[178:179]
	v_pk_add_f32 v[132:133], v[132:133], v[134:135]
	v_and_b32_e32 v134, 64, v236
	v_pk_add_f32 v[132:133], v[176:177], v[132:133]
	v_add_u32_e32 v134, 64, v134
	v_add_f32_e32 v132, v132, v133
	ds_swizzle_b32 v133, v132 offset:swizzle(SWAP,16)
	v_mov_b32_e32 v141, v2
	v_lshl_add_u64 v[164:165], v[164:165], 0, v[140:141]
	s_mov_b64 s[8:9], 0
	s_waitcnt lgkmcnt(0)
	v_add_f32_e32 v132, v132, v133
	v_xor_b32_e32 v133, 32, v236
	v_cmp_lt_i32_e32 vcc, v133, v134
	s_nop 1
	v_cndmask_b32_e32 v133, v236, v133, vcc
	v_lshlrev_b32_e32 v133, 2, v133
	ds_bpermute_b32 v133, v133, v132
	s_waitcnt lgkmcnt(0)
	v_add_f32_e32 v132, v132, v133
	v_fmamk_f32 v132, v132, 0x3c800000, v231
	v_cmp_gt_f32_e32 vcc, s11, v132
	v_mul_f32_e32 v133, 0x4b800000, v132
	s_nop 0
	v_cndmask_b32_e32 v132, v132, v133, vcc
	v_rsq_f32_e32 v132, v132
	s_nop 0
	v_mul_f32_e32 v133, 0x45800000, v132
	v_cndmask_b32_e32 v132, v132, v133, vcc
	v_mul_f32_e32 v154, 0x3e38aa3b, v132
	global_load_dwordx4 v[132:135], v166, s[26:27] offset:16
	global_load_dwordx4 v[176:179], v166, s[26:27]
	v_pk_mul_f32 v[162:163], v[162:163], v[154:155] op_sel_hi:[1,0]
	v_pk_mul_f32 v[160:161], v[160:161], v[154:155] op_sel_hi:[1,0]
	v_pk_mul_f32 v[158:159], v[158:159], v[154:155] op_sel_hi:[1,0]
	v_pk_mul_f32 v[156:157], v[156:157], v[154:155] op_sel_hi:[1,0]
	v_pk_mul_f32 v[152:153], v[152:153], v[154:155] op_sel_hi:[1,0]
	v_pk_mul_f32 v[150:151], v[150:151], v[154:155] op_sel_hi:[1,0]
	v_pk_mul_f32 v[148:149], v[148:149], v[154:155] op_sel_hi:[1,0]
	v_pk_mul_f32 v[146:147], v[146:147], v[154:155] op_sel_hi:[1,0]
	s_waitcnt vmcnt(1)
	v_pk_mul_f32 v[156:157], v[134:135], v[156:157]
	s_waitcnt vmcnt(0)
	v_pk_mul_f32 v[160:161], v[178:179], v[160:161]
	v_pk_mul_f32 v[162:163], v[176:177], v[162:163]
	v_pk_mul_f32 v[134:135], v[132:133], v[158:159]
	v_cvt_pk_bf16_f32 v132, v162, v163
	v_cvt_pk_bf16_f32 v133, v160, v161
	v_cvt_pk_bf16_f32 v134, v134, v135
	v_cvt_pk_bf16_f32 v135, v156, v157
	global_store_dwordx4 v[164:165], v[132:135], off
	global_load_dwordx4 v[132:135], v166, s[26:27] offset:144
	s_nop 0
	global_load_dwordx4 v[156:159], v166, s[26:27] offset:128
	s_waitcnt vmcnt(1)
	v_pk_mul_f32 v[146:147], v[134:135], v[146:147]
	s_waitcnt vmcnt(0)
	v_pk_mul_f32 v[150:151], v[158:159], v[150:151]
	v_pk_mul_f32 v[152:153], v[156:157], v[152:153]
	v_pk_mul_f32 v[134:135], v[132:133], v[148:149]
	v_cvt_pk_bf16_f32 v132, v152, v153
	v_cvt_pk_bf16_f32 v133, v150, v151
	v_cvt_pk_bf16_f32 v134, v134, v135
	v_cvt_pk_bf16_f32 v135, v146, v147
	global_store_dwordx4 v[164:165], v[132:135], off offset:64

.LBB0_1912:
	s_add_u32 s18, s16, s56
	s_addc_u32 s19, s17, s57
	s_add_u32 s26, s16, 0x7bfdd00
	s_addc_u32 s27, s17, 0
	s_cmp_eq_u32 s51, 12
	s_cselect_b32 s18, s14, s18
	s_cselect_b32 s19, s15, s19
	s_cselect_b32 s38, s8, s26
	s_cselect_b32 s39, s9, s27
	s_add_u32 s28, s18, 0x80
	s_addc_u32 s29, s19, 0
	s_add_u32 s26, s38, 0x80
	s_addc_u32 s27, s39, 0
	s_add_i32 s54, 0, 0x10000
	v_add_u32_e32 v148, s54, v1
	ds_read_b128 v[136:139], v148
	ds_read_b128 v[140:143], v148 offset:1024
	ds_read_b128 v[144:147], v148 offset:2048
	ds_read_b128 v[148:151], v148 offset:3072
	s_add_u32 s52, s16, 0x7c3dc80
	s_addc_u32 s53, s17, 0
	ds_read_b128 v[152:155], v3
	ds_read_b128 v[156:159], v3 offset:1024
	ds_read_b128 v[160:163], v3 offset:2048
	ds_read_b128 v[164:167], v3 offset:3072
	ds_read_b128 v[168:171], v3 offset:4096
	ds_read_b128 v[172:175], v3 offset:5120
	ds_read_b128 v[176:179], v3 offset:6144
	ds_read_b128 v[180:183], v3 offset:7168
	s_add_i32 m0, s42, 0xc000
	s_nop 0
	global_load_lds_dwordx4 v132, s[52:53]
	s_add_i32 m0, s42, 0xe000
	s_nop 0
	global_load_lds_dwordx4 v134, s[52:53]
	s_waitcnt lgkmcnt(8)
	s_barrier
	s_waitcnt lgkmcnt(0)
	s_setprio 1
	s_waitcnt lgkmcnt(0)
	v_mfma_f32_16x16x32_bf16 v[128:131], v[136:139], v[152:155], v[128:131]
	v_mfma_f32_16x16x32_bf16 v[124:127], v[144:147], v[152:155], v[124:127]
	v_mfma_f32_16x16x32_bf16 v[112:115], v[136:139], v[160:163], v[112:115]
	v_mfma_f32_16x16x32_bf16 v[108:111], v[144:147], v[160:163], v[108:111]
	v_mfma_f32_16x16x32_bf16 v[96:99], v[136:139], v[168:171], v[96:99]
	v_mfma_f32_16x16x32_bf16 v[92:95], v[144:147], v[168:171], v[92:95]
	v_mfma_f32_16x16x32_bf16 v[80:83], v[136:139], v[176:179], v[80:83]
	v_mfma_f32_16x16x32_bf16 v[76:79], v[144:147], v[176:179], v[76:79]
	v_mfma_f32_16x16x32_bf16 v[128:131], v[140:143], v[156:159], v[128:131]
	v_mfma_f32_16x16x32_bf16 v[124:127], v[148:151], v[156:159], v[124:127]
	v_mfma_f32_16x16x32_bf16 v[112:115], v[140:143], v[164:167], v[112:115]
	v_mfma_f32_16x16x32_bf16 v[108:111], v[148:151], v[164:167], v[108:111]
	v_mfma_f32_16x16x32_bf16 v[96:99], v[140:143], v[172:175], v[96:99]
	v_mfma_f32_16x16x32_bf16 v[92:95], v[148:151], v[172:175], v[92:95]
	v_mfma_f32_16x16x32_bf16 v[80:83], v[140:143], v[180:183], v[80:83]
	v_mfma_f32_16x16x32_bf16 v[76:79], v[148:151], v[180:183], v[76:79]
	s_setprio 0
	s_barrier
	s_add_i32 s55, 0, 0x14000
	v_add_u32_e32 v210, s55, v1
	s_mov_b64 s[52:53], s[18:19]
	s_add_i32 s54, s54, s41
	ds_read_b128 v[184:187], v210
	ds_read_b128 v[188:191], v210 offset:1024
	ds_read_b128 v[192:195], v210 offset:2048
	ds_read_b128 v[210:213], v210 offset:3072
	s_mov_b32 m0, s54
	s_nop 0
	global_load_lds_dwordx4 v132, s[52:53]
	s_add_i32 m0, s54, 0x2000
	s_nop 0
	global_load_lds_dwordx4 v134, s[52:53]
	s_barrier
	s_waitcnt lgkmcnt(0)
	s_setprio 1
	s_waitcnt lgkmcnt(0)
	v_mfma_f32_16x16x32_bf16 v[120:123], v[184:187], v[152:155], v[120:123]
	v_mfma_f32_16x16x32_bf16 v[116:119], v[192:195], v[152:155], v[116:119]
	v_mfma_f32_16x16x32_bf16 v[104:107], v[184:187], v[160:163], v[104:107]
	v_mfma_f32_16x16x32_bf16 v[100:103], v[192:195], v[160:163], v[100:103]
	v_mfma_f32_16x16x32_bf16 v[88:91], v[184:187], v[168:171], v[88:91]
	v_mfma_f32_16x16x32_bf16 v[84:87], v[192:195], v[168:171], v[84:87]
	v_mfma_f32_16x16x32_bf16 v[72:75], v[184:187], v[176:179], v[72:75]
	v_mfma_f32_16x16x32_bf16 v[68:71], v[192:195], v[176:179], v[68:71]
	v_mfma_f32_16x16x32_bf16 v[120:123], v[188:191], v[156:159], v[120:123]
	v_mfma_f32_16x16x32_bf16 v[116:119], v[210:213], v[156:159], v[116:119]
	v_mfma_f32_16x16x32_bf16 v[104:107], v[188:191], v[164:167], v[104:107]
	v_mfma_f32_16x16x32_bf16 v[100:103], v[210:213], v[164:167], v[100:103]
	v_mfma_f32_16x16x32_bf16 v[88:91], v[188:191], v[172:175], v[88:91]
	v_mfma_f32_16x16x32_bf16 v[84:87], v[210:213], v[172:175], v[84:87]
	v_mfma_f32_16x16x32_bf16 v[72:75], v[188:191], v[180:183], v[72:75]
	v_mfma_f32_16x16x32_bf16 v[68:71], v[210:213], v[180:183], v[68:71]
	s_setprio 0
	s_mov_b64 s[52:53], s[38:39]
	s_mov_b32 m0, s42
	s_barrier
	ds_read_b128 v[152:155], v3 offset:16384
	ds_read_b128 v[156:159], v3 offset:17408
	ds_read_b128 v[160:163], v3 offset:18432
	ds_read_b128 v[164:167], v3 offset:19456
	ds_read_b128 v[168:171], v3 offset:20480
	ds_read_b128 v[172:175], v3 offset:21504
	ds_read_b128 v[176:179], v3 offset:22528
	ds_read_b128 v[180:183], v3 offset:23552
	s_nop 0
	global_load_lds_dwordx4 v132, s[52:53]
	s_mov_b32 m0, s43
	s_nop 0
	global_load_lds_dwordx4 v134, s[52:53]
	s_barrier
	s_waitcnt lgkmcnt(0)
	s_setprio 1
	s_waitcnt lgkmcnt(0)
	v_mfma_f32_16x16x32_bf16 v[64:67], v[136:139], v[152:155], v[64:67]
	v_mfma_f32_16x16x32_bf16 v[60:63], v[144:147], v[152:155], v[60:63]
	v_mfma_f32_16x16x32_bf16 v[48:51], v[136:139], v[160:163], v[48:51]
	v_mfma_f32_16x16x32_bf16 v[44:47], v[144:147], v[160:163], v[44:47]
	v_mfma_f32_16x16x32_bf16 v[32:35], v[136:139], v[168:171], v[32:35]
	v_mfma_f32_16x16x32_bf16 v[28:31], v[144:147], v[168:171], v[28:31]
	v_mfma_f32_16x16x32_bf16 v[16:19], v[136:139], v[176:179], v[16:19]
	v_mfma_f32_16x16x32_bf16 v[12:15], v[144:147], v[176:179], v[12:15]
	v_mfma_f32_16x16x32_bf16 v[64:67], v[140:143], v[156:159], v[64:67]
	v_mfma_f32_16x16x32_bf16 v[60:63], v[148:151], v[156:159], v[60:63]
	v_mfma_f32_16x16x32_bf16 v[48:51], v[140:143], v[164:167], v[48:51]
	v_mfma_f32_16x16x32_bf16 v[44:47], v[148:151], v[164:167], v[44:47]
	v_mfma_f32_16x16x32_bf16 v[32:35], v[140:143], v[172:175], v[32:35]
	v_mfma_f32_16x16x32_bf16 v[28:31], v[148:151], v[172:175], v[28:31]
	v_mfma_f32_16x16x32_bf16 v[16:19], v[140:143], v[180:183], v[16:19]
	v_mfma_f32_16x16x32_bf16 v[12:15], v[148:151], v[180:183], v[12:15]
	s_setprio 0
	s_barrier
	s_add_u32 s52, s18, 0x40000
	s_addc_u32 s53, s19, 0
	s_add_i32 s54, s55, s41
	s_mov_b32 m0, s54
	s_nop 0
	global_load_lds_dwordx4 v132, s[52:53]
	s_add_i32 m0, s54, 0x2000
	s_nop 0
	global_load_lds_dwordx4 v134, s[52:53]
	s_waitcnt vmcnt(6)
	s_barrier
	s_setprio 1
	v_mfma_f32_16x16x32_bf16 v[56:59], v[184:187], v[152:155], v[56:59]
	v_mfma_f32_16x16x32_bf16 v[52:55], v[192:195], v[152:155], v[52:55]
	v_mfma_f32_16x16x32_bf16 v[40:43], v[184:187], v[160:163], v[40:43]
	v_mfma_f32_16x16x32_bf16 v[36:39], v[192:195], v[160:163], v[36:39]
	v_mfma_f32_16x16x32_bf16 v[24:27], v[184:187], v[168:171], v[24:27]
	v_mfma_f32_16x16x32_bf16 v[20:23], v[192:195], v[168:171], v[20:23]
	v_mfma_f32_16x16x32_bf16 v[8:11], v[184:187], v[176:179], v[8:11]
	v_mfma_f32_16x16x32_bf16 v[4:7], v[192:195], v[176:179], v[4:7]
	v_mfma_f32_16x16x32_bf16 v[56:59], v[188:191], v[156:159], v[56:59]
	v_mfma_f32_16x16x32_bf16 v[52:55], v[210:213], v[156:159], v[52:55]
	v_mfma_f32_16x16x32_bf16 v[40:43], v[188:191], v[164:167], v[40:43]
	v_mfma_f32_16x16x32_bf16 v[36:39], v[210:213], v[164:167], v[36:39]
	v_mfma_f32_16x16x32_bf16 v[24:27], v[188:191], v[172:175], v[24:27]
	v_mfma_f32_16x16x32_bf16 v[20:23], v[210:213], v[172:175], v[20:23]
	v_mfma_f32_16x16x32_bf16 v[8:11], v[188:191], v[180:183], v[8:11]
	v_mfma_f32_16x16x32_bf16 v[4:7], v[210:213], v[180:183], v[4:7]
	s_setprio 0
	s_add_i32 s52, 0, 0x18000
	v_add_u32_e32 v148, s52, v1
	s_barrier
	ds_read_b128 v[136:139], v148
	ds_read_b128 v[140:143], v148 offset:1024
	ds_read_b128 v[144:147], v148 offset:2048
	ds_read_b128 v[148:151], v148 offset:3072
	s_add_u32 s38, s38, 0x40000
	s_addc_u32 s39, s39, 0
	s_mov_b32 m0, s44
	ds_read_b128 v[152:155], v3 offset:32768
	ds_read_b128 v[156:159], v3 offset:33792
	ds_read_b128 v[160:163], v3 offset:34816
	ds_read_b128 v[164:167], v3 offset:35840
	ds_read_b128 v[168:171], v3 offset:36864
	ds_read_b128 v[172:175], v3 offset:37888
	ds_read_b128 v[176:179], v3 offset:38912
	ds_read_b128 v[180:183], v3 offset:39936
	s_nop 0
	global_load_lds_dwordx4 v132, s[38:39]
	s_mov_b32 m0, s45
	s_nop 0
	global_load_lds_dwordx4 v134, s[38:39]
	s_waitcnt lgkmcnt(8)
	s_barrier
	s_waitcnt lgkmcnt(0)
	s_setprio 1
	s_waitcnt lgkmcnt(0)
	v_mfma_f32_16x16x32_bf16 v[128:131], v[136:139], v[152:155], v[128:131]
	v_mfma_f32_16x16x32_bf16 v[124:127], v[144:147], v[152:155], v[124:127]
	v_mfma_f32_16x16x32_bf16 v[112:115], v[136:139], v[160:163], v[112:115]
	v_mfma_f32_16x16x32_bf16 v[108:111], v[144:147], v[160:163], v[108:111]
	v_mfma_f32_16x16x32_bf16 v[96:99], v[136:139], v[168:171], v[96:99]
	v_mfma_f32_16x16x32_bf16 v[92:95], v[144:147], v[168:171], v[92:95]
	v_mfma_f32_16x16x32_bf16 v[80:83], v[136:139], v[176:179], v[80:83]
	v_mfma_f32_16x16x32_bf16 v[76:79], v[144:147], v[176:179], v[76:79]
	v_mfma_f32_16x16x32_bf16 v[128:131], v[140:143], v[156:159], v[128:131]
	v_mfma_f32_16x16x32_bf16 v[124:127], v[148:151], v[156:159], v[124:127]
	v_mfma_f32_16x16x32_bf16 v[112:115], v[140:143], v[164:167], v[112:115]
	v_mfma_f32_16x16x32_bf16 v[108:111], v[148:151], v[164:167], v[108:111]
	v_mfma_f32_16x16x32_bf16 v[96:99], v[140:143], v[172:175], v[96:99]
	v_mfma_f32_16x16x32_bf16 v[92:95], v[148:151], v[172:175], v[92:95]
	v_mfma_f32_16x16x32_bf16 v[80:83], v[140:143], v[180:183], v[80:83]
	v_mfma_f32_16x16x32_bf16 v[76:79], v[148:151], v[180:183], v[76:79]
	s_setprio 0
	s_barrier
	s_add_i32 s38, 0, 0x1c000
	v_add_u32_e32 v210, s38, v1
	s_add_i32 s39, s52, s41
	ds_read_b128 v[184:187], v210
	ds_read_b128 v[188:191], v210 offset:1024
	ds_read_b128 v[192:195], v210 offset:2048
	ds_read_b128 v[210:213], v210 offset:3072
	s_mov_b32 m0, s39
	s_nop 0
	global_load_lds_dwordx4 v132, s[28:29]
	s_add_i32 m0, s39, 0x2000
	s_nop 0
	global_load_lds_dwordx4 v134, s[28:29]
	s_barrier
	s_waitcnt lgkmcnt(0)
	s_setprio 1
	s_waitcnt lgkmcnt(0)
	v_mfma_f32_16x16x32_bf16 v[120:123], v[184:187], v[152:155], v[120:123]
	v_mfma_f32_16x16x32_bf16 v[116:119], v[192:195], v[152:155], v[116:119]
	v_mfma_f32_16x16x32_bf16 v[104:107], v[184:187], v[160:163], v[104:107]
	v_mfma_f32_16x16x32_bf16 v[100:103], v[192:195], v[160:163], v[100:103]
	v_mfma_f32_16x16x32_bf16 v[88:91], v[184:187], v[168:171], v[88:91]
	v_mfma_f32_16x16x32_bf16 v[84:87], v[192:195], v[168:171], v[84:87]
	v_mfma_f32_16x16x32_bf16 v[72:75], v[184:187], v[176:179], v[72:75]
	v_mfma_f32_16x16x32_bf16 v[68:71], v[192:195], v[176:179], v[68:71]
	v_mfma_f32_16x16x32_bf16 v[120:123], v[188:191], v[156:159], v[120:123]
	v_mfma_f32_16x16x32_bf16 v[116:119], v[210:213], v[156:159], v[116:119]
	v_mfma_f32_16x16x32_bf16 v[104:107], v[188:191], v[164:167], v[104:107]
	v_mfma_f32_16x16x32_bf16 v[100:103], v[210:213], v[164:167], v[100:103]
	v_mfma_f32_16x16x32_bf16 v[88:91], v[188:191], v[172:175], v[88:91]
	v_mfma_f32_16x16x32_bf16 v[84:87], v[210:213], v[172:175], v[84:87]
	v_mfma_f32_16x16x32_bf16 v[72:75], v[188:191], v[180:183], v[72:75]
	v_mfma_f32_16x16x32_bf16 v[68:71], v[210:213], v[180:183], v[68:71]
	s_setprio 0
	s_mov_b32 m0, s46
	s_barrier
	ds_read_b128 v[152:155], v3 offset:49152
	ds_read_b128 v[156:159], v3 offset:50176
	ds_read_b128 v[160:163], v3 offset:51200
	ds_read_b128 v[164:167], v3 offset:52224
	ds_read_b128 v[168:171], v3 offset:53248
	ds_read_b128 v[172:175], v3 offset:54272
	ds_read_b128 v[176:179], v3 offset:55296
	ds_read_b128 v[180:183], v3 offset:56320
	s_nop 0
	global_load_lds_dwordx4 v132, s[26:27]
	s_mov_b32 m0, s47
	s_nop 0
	global_load_lds_dwordx4 v134, s[26:27]
	s_barrier
	s_waitcnt lgkmcnt(0)
	s_setprio 1
	s_waitcnt lgkmcnt(0)
	v_mfma_f32_16x16x32_bf16 v[64:67], v[136:139], v[152:155], v[64:67]
	v_mfma_f32_16x16x32_bf16 v[60:63], v[144:147], v[152:155], v[60:63]
	v_mfma_f32_16x16x32_bf16 v[48:51], v[136:139], v[160:163], v[48:51]
	v_mfma_f32_16x16x32_bf16 v[44:47], v[144:147], v[160:163], v[44:47]
	v_mfma_f32_16x16x32_bf16 v[32:35], v[136:139], v[168:171], v[32:35]
	v_mfma_f32_16x16x32_bf16 v[28:31], v[144:147], v[168:171], v[28:31]
	v_mfma_f32_16x16x32_bf16 v[16:19], v[136:139], v[176:179], v[16:19]
	v_mfma_f32_16x16x32_bf16 v[12:15], v[144:147], v[176:179], v[12:15]
	v_mfma_f32_16x16x32_bf16 v[64:67], v[140:143], v[156:159], v[64:67]
	v_mfma_f32_16x16x32_bf16 v[60:63], v[148:151], v[156:159], v[60:63]
	v_mfma_f32_16x16x32_bf16 v[48:51], v[140:143], v[164:167], v[48:51]
	v_mfma_f32_16x16x32_bf16 v[44:47], v[148:151], v[164:167], v[44:47]
	v_mfma_f32_16x16x32_bf16 v[32:35], v[140:143], v[172:175], v[32:35]
	v_mfma_f32_16x16x32_bf16 v[28:31], v[148:151], v[172:175], v[28:31]
	v_mfma_f32_16x16x32_bf16 v[16:19], v[140:143], v[180:183], v[16:19]
	v_mfma_f32_16x16x32_bf16 v[12:15], v[148:151], v[180:183], v[12:15]
	s_setprio 0
	s_barrier
	s_add_u32 s18, s18, 0x40080
	s_addc_u32 s19, s19, 0
	s_add_i32 s26, s38, s41
	s_mov_b32 m0, s26
	s_nop 0
	global_load_lds_dwordx4 v132, s[18:19]
	s_add_i32 m0, s26, 0x2000
	s_nop 0
	global_load_lds_dwordx4 v134, s[18:19]
	s_waitcnt vmcnt(6)
	s_barrier
	s_setprio 1
	v_mfma_f32_16x16x32_bf16 v[56:59], v[184:187], v[152:155], v[56:59]
	v_mfma_f32_16x16x32_bf16 v[52:55], v[192:195], v[152:155], v[52:55]
	v_mfma_f32_16x16x32_bf16 v[40:43], v[184:187], v[160:163], v[40:43]
	v_mfma_f32_16x16x32_bf16 v[36:39], v[192:195], v[160:163], v[36:39]
	v_mfma_f32_16x16x32_bf16 v[24:27], v[184:187], v[168:171], v[24:27]
	v_mfma_f32_16x16x32_bf16 v[20:23], v[192:195], v[168:171], v[20:23]
	v_mfma_f32_16x16x32_bf16 v[8:11], v[184:187], v[176:179], v[8:11]
	v_mfma_f32_16x16x32_bf16 v[4:7], v[192:195], v[176:179], v[4:7]
	v_mfma_f32_16x16x32_bf16 v[56:59], v[188:191], v[156:159], v[56:59]
	v_mfma_f32_16x16x32_bf16 v[52:55], v[210:213], v[156:159], v[52:55]
	v_mfma_f32_16x16x32_bf16 v[40:43], v[188:191], v[164:167], v[40:43]
	v_mfma_f32_16x16x32_bf16 v[36:39], v[210:213], v[164:167], v[36:39]
	v_mfma_f32_16x16x32_bf16 v[24:27], v[188:191], v[172:175], v[24:27]
	v_mfma_f32_16x16x32_bf16 v[20:23], v[210:213], v[172:175], v[20:23]
	v_mfma_f32_16x16x32_bf16 v[8:11], v[188:191], v[180:183], v[8:11]
	v_mfma_f32_16x16x32_bf16 v[4:7], v[210:213], v[180:183], v[4:7]
	s_setprio 0
	s_add_i32 s51, s51, 2
	s_add_u32 s16, s16, 0x100
	s_addc_u32 s17, s17, 0
	s_cmp_gt_u32 s51, 13
	s_barrier
	s_cbranch_scc0 .LBB0_1912
	s_add_u32 s8, s24, s50
	s_addc_u32 s9, s25, 0
	s_add_u32 s18, s24, 0x7c7dc00
	s_addc_u32 s19, s25, 0
	s_add_u32 s28, s24, 0x94ddc00
	s_addc_u32 s29, s25, 0
	s_lshl_b64 s[6:7], s[6:7], 2
	s_add_u32 s26, s0, s6
	s_addc_u32 s27, s1, s7
	s_add_u32 s0, s30, s49
	s_addc_u32 s1, s31, s48
	v_mov_b32_e32 v141, v0
	s_add_u32 s6, s0, 0x53fc000
	s_addc_u32 s7, s1, 0
	v_readfirstlane_b32 s0, v141
	s_ashr_i32 s15, s0, 2
	v_and_b32_e32 v164, 15, v141
	s_andn2_b32 s15, s15, 63
	v_or_b32_e32 v132, s15, v164
	v_ashrrev_i32_e32 v133, 31, v132
	s_and_b32 s14, s0, 0xc0
	v_lshl_add_u64 v[132:133], v[132:133], 2, s[8:9]
	s_mov_b32 s0, 0x15000
	v_add_co_u32_e32 v132, vcc, s0, v132
	v_readlane_b32 s8, v253, 54
	s_nop 0
	v_addc_co_u32_e32 v133, vcc, 0, v133, vcc
	global_load_dword v1, v[132:133], off
	global_load_dword v168, v[132:133], off offset:64
	global_load_dword v167, v[132:133], off offset:128
	global_load_dword v166, v[132:133], off offset:192
	global_load_dword v165, v[132:133], off offset:512
	global_load_dword v163, v[132:133], off offset:576
	global_load_dword v162, v[132:133], off offset:640
	global_load_dword v151, v[132:133], off offset:704
	s_add_i32 s38, s15, 0x4000
	v_readlane_b32 s9, v253, 55
	v_or_b32_e32 v138, s38, v164
	s_mov_b64 s[0:1], -1
	s_waitcnt vmcnt(0)
	v_fmamk_f32 v1, v1, 0x3a800000, v231
	v_cmp_gt_f32_e32 vcc, s11, v1
	v_mul_f32_e32 v3, 0x4b800000, v1
	s_nop 0
	v_cndmask_b32_e32 v1, v1, v3, vcc
	v_rsq_f32_e32 v1, v1
	s_nop 0
	v_mul_f32_e32 v3, 0x45800000, v1
	v_cndmask_b32_e32 v140, v1, v3, vcc
	v_lshrrev_b32_e32 v1, 1, v141
	v_and_b32_e32 v1, 24, v1
	s_and_b64 vcc, exec, s[8:9]
	v_lshlrev_b32_e32 v3, 2, v1
	v_lshlrev_b32_e32 v136, 1, v1
	s_cbranch_vccz .LBB0_1915
	v_ashrrev_i32_e32 v139, 31, v138
	v_lshlrev_b64 v[132:133], 9, v[138:139]
	v_lshl_add_u64 v[132:133], s[28:29], 0, v[132:133]
	s_lshl_b32 s68, s14, 1
	v_pk_mul_f32 v[156:157], v[130:131], v[140:141] op_sel_hi:[1,0]
	v_pk_mul_f32 v[158:159], v[128:129], v[140:141] op_sel_hi:[1,0]
	v_lshl_add_u64 v[160:161], v[132:133], 0, s[68:69]
	v_pk_mul_f32 v[132:133], v[156:157], v[156:157]
	v_pk_mul_f32 v[134:135], v[158:159], v[158:159]
	v_pk_mul_f32 v[152:153], v[126:127], v[140:141] op_sel_hi:[1,0]
	v_pk_mov_b32 v[142:143], v[134:135], v[132:133] op_sel:[1,0]
	v_mov_b32_e32 v135, v133
	v_pk_add_f32 v[132:133], v[142:143], v[134:135]
	v_pk_mul_f32 v[154:155], v[124:125], v[140:141] op_sel_hi:[1,0]
	v_pk_add_f32 v[132:133], v[132:133], v[132:133] op_sel_hi:[0,1]
	v_pk_mul_f32 v[134:135], v[152:153], v[152:153]
	v_pk_mul_f32 v[142:143], v[154:155], v[154:155]
	v_pk_mul_f32 v[148:149], v[120:121], v[140:141] op_sel_hi:[1,0]
	v_pk_mov_b32 v[144:145], v[142:143], v[134:135] op_sel:[1,0]
	v_mov_b32_e32 v143, v135
	v_pk_mul_f32 v[146:147], v[122:123], v[140:141] op_sel_hi:[1,0]
	v_mul_f32_e32 v132, v148, v148
	v_pk_add_f32 v[134:135], v[144:145], v[142:143]
	v_pk_fma_f32 v[170:171], v[148:149], v[148:149], v[132:133] op_sel_hi:[1,1,0]
	v_mul_f32_e32 v132, v146, v146
	v_pk_add_f32 v[134:135], v[134:135], v[134:135] op_sel_hi:[0,1]
	v_pk_fma_f32 v[172:173], v[146:147], v[146:147], v[132:133] op_sel_hi:[1,1,0]
	v_pk_mul_f32 v[142:143], v[118:119], v[140:141] op_sel_hi:[1,0]
	v_pk_mul_f32 v[144:145], v[116:117], v[140:141] op_sel_hi:[1,0]
	v_mul_f32_e32 v132, v142, v142
	v_mul_f32_e32 v170, v144, v144
	v_mul_f32_e32 v172, v145, v145
	v_mul_f32_e32 v134, v143, v143
	v_pk_add_f32 v[170:171], v[170:171], v[172:173]
	v_pk_add_f32 v[132:133], v[132:133], v[134:135]
	v_and_b32_e32 v134, 64, v236
	v_pk_add_f32 v[132:133], v[170:171], v[132:133]
	v_add_u32_e32 v134, 64, v134
	v_add_f32_e32 v132, v132, v133
	ds_swizzle_b32 v133, v132 offset:swizzle(SWAP,16)
	v_mov_b32_e32 v137, v2
	v_lshl_add_u64 v[160:161], v[160:161], 0, v[136:137]
	s_mov_b64 s[0:1], 0
	s_waitcnt lgkmcnt(0)
	v_add_f32_e32 v132, v132, v133
	v_xor_b32_e32 v133, 32, v236
	v_cmp_lt_i32_e32 vcc, v133, v134
	s_nop 1
	v_cndmask_b32_e32 v133, v236, v133, vcc
	v_lshlrev_b32_e32 v133, 2, v133
	ds_bpermute_b32 v133, v133, v132
	s_waitcnt lgkmcnt(0)
	v_add_f32_e32 v132, v132, v133
	v_fmamk_f32 v132, v132, 0x3c800000, v231
	v_cmp_gt_f32_e32 vcc, s11, v132
	v_mul_f32_e32 v133, 0x4b800000, v132
	s_nop 0
	v_cndmask_b32_e32 v132, v132, v133, vcc
	v_rsq_f32_e32 v132, v132
	s_nop 0
	v_mul_f32_e32 v133, 0x45800000, v132
	v_cndmask_b32_e32 v132, v132, v133, vcc
	v_mul_f32_e32 v150, 0x3e38aa3b, v132
	global_load_dwordx4 v[132:135], v3, s[26:27] offset:16
	global_load_dwordx4 v[170:173], v3, s[26:27]
	v_pk_mul_f32 v[158:159], v[158:159], v[150:151] op_sel_hi:[1,0]
	v_pk_mul_f32 v[156:157], v[156:157], v[150:151] op_sel_hi:[1,0]
	v_pk_mul_f32 v[154:155], v[154:155], v[150:151] op_sel_hi:[1,0]
	v_pk_mul_f32 v[152:153], v[152:153], v[150:151] op_sel_hi:[1,0]
	v_pk_mul_f32 v[148:149], v[148:149], v[150:151] op_sel_hi:[1,0]
	v_pk_mul_f32 v[146:147], v[146:147], v[150:151] op_sel_hi:[1,0]
	v_pk_mul_f32 v[144:145], v[144:145], v[150:151] op_sel_hi:[1,0]
	v_pk_mul_f32 v[142:143], v[142:143], v[150:151] op_sel_hi:[1,0]
	s_waitcnt vmcnt(1)
	v_pk_mul_f32 v[152:153], v[134:135], v[152:153]
	s_waitcnt vmcnt(0)
	v_pk_mul_f32 v[156:157], v[172:173], v[156:157]
	v_pk_mul_f32 v[158:159], v[170:171], v[158:159]
	v_pk_mul_f32 v[134:135], v[132:133], v[154:155]
	v_cvt_pk_bf16_f32 v132, v158, v159
	v_cvt_pk_bf16_f32 v133, v156, v157
	v_cvt_pk_bf16_f32 v134, v134, v135
	v_cvt_pk_bf16_f32 v135, v152, v153
	global_store_dwordx4 v[160:161], v[132:135], off
	global_load_dwordx4 v[132:135], v3, s[26:27] offset:144
	s_nop 0
	global_load_dwordx4 v[152:155], v3, s[26:27] offset:128
	s_waitcnt vmcnt(1)
	v_pk_mul_f32 v[142:143], v[134:135], v[142:143]
	s_waitcnt vmcnt(0)
	v_pk_mul_f32 v[146:147], v[154:155], v[146:147]
	v_pk_mul_f32 v[148:149], v[152:153], v[148:149]
	v_pk_mul_f32 v[134:135], v[132:133], v[144:145]
	v_cvt_pk_bf16_f32 v132, v148, v149
	v_cvt_pk_bf16_f32 v133, v146, v147
	v_cvt_pk_bf16_f32 v134, v134, v135
	v_cvt_pk_bf16_f32 v135, v142, v143
	global_store_dwordx4 v[160:161], v[132:135], off offset:64

.LBB0_2213:
	s_add_u32 s15, s20, s24
	s_addc_u32 s30, s21, s25
	s_add_u32 s31, s15, 0x100
	s_addc_u32 s38, s30, 0
	s_and_b64 s[28:29], s[26:27], exec
	s_cselect_b32 s41, s9, s38
	s_cselect_b32 s40, s8, s31
	s_add_u32 s24, s16, s24
	s_addc_u32 s25, s17, s25
	s_add_u32 s28, s24, 0x100
	s_addc_u32 s29, s25, 0
	s_add_u32 s24, s40, 0x80
	s_addc_u32 s25, s41, 0
	s_add_i32 s79, 0, 0x10000
	s_and_b64 s[26:27], s[26:27], exec
	s_cselect_b32 s43, s1, s29
	s_cselect_b32 s42, s7, s28
	s_add_u32 s44, s15, 0x12080
	s_addc_u32 s45, s30, 0
	s_add_i32 s84, s79, s51
	s_add_i32 m0, s52, 0xc000
	s_add_i32 s85, s52, 0xe000
	s_add_i32 s83, 0, 0x14000
	s_add_i32 s82, s84, 0x2000
	s_add_u32 s38, s42, 0x10000
	s_addc_u32 s39, s43, 0
	s_add_i32 s80, s83, s51
	s_add_i32 s78, s80, 0x2000
	s_add_i32 s75, 0, 0x18000
	v_add_u32_e32 v152, s79, v1
	s_add_u32 s30, s40, 0x12000
	ds_read_b128 v[140:143], v152
	ds_read_b128 v[144:147], v152 offset:1024
	ds_read_b128 v[148:151], v152 offset:2048
	ds_read_b128 v[152:155], v152 offset:3072
	s_addc_u32 s31, s41, 0
	s_add_i32 s73, 0, 0x1c000
	s_add_u32 s28, s42, 0x80
	s_addc_u32 s29, s43, 0
	s_add_i32 s74, s75, s51
	s_add_i32 s15, s74, 0x2000
	s_add_u32 s26, s42, 0x10080
	s_addc_u32 s27, s43, 0
	s_add_i32 s81, s73, s51
	s_add_i32 s79, s81, 0x2000
	ds_read_b128 v[156:159], v3
	ds_read_b128 v[160:163], v3 offset:1024
	ds_read_b128 v[164:167], v3 offset:2048
	ds_read_b128 v[168:171], v3 offset:3072
	ds_read_b128 v[172:175], v3 offset:4096
	ds_read_b128 v[176:179], v3 offset:5120
	ds_read_b128 v[180:183], v3 offset:6144
	ds_read_b128 v[184:187], v3 offset:7168
	s_nop 0
	global_load_lds_dwordx4 v132, s[44:45]
	s_mov_b32 m0, s85
	s_nop 0
	global_load_lds_dwordx4 v136, s[44:45]
	s_waitcnt lgkmcnt(8)
	s_barrier
	s_waitcnt lgkmcnt(0)
	s_setprio 1
	s_waitcnt lgkmcnt(0)
	v_mfma_f32_16x16x32_bf16 v[128:131], v[140:143], v[156:159], v[128:131]
	v_mfma_f32_16x16x32_bf16 v[124:127], v[148:151], v[156:159], v[124:127]
	v_mfma_f32_16x16x32_bf16 v[112:115], v[140:143], v[164:167], v[112:115]
	v_mfma_f32_16x16x32_bf16 v[108:111], v[148:151], v[164:167], v[108:111]
	v_mfma_f32_16x16x32_bf16 v[96:99], v[140:143], v[172:175], v[96:99]
	v_mfma_f32_16x16x32_bf16 v[92:95], v[148:151], v[172:175], v[92:95]
	v_mfma_f32_16x16x32_bf16 v[80:83], v[140:143], v[180:183], v[80:83]
	v_mfma_f32_16x16x32_bf16 v[76:79], v[148:151], v[180:183], v[76:79]
	v_mfma_f32_16x16x32_bf16 v[128:131], v[144:147], v[160:163], v[128:131]
	v_mfma_f32_16x16x32_bf16 v[124:127], v[152:155], v[160:163], v[124:127]
	v_mfma_f32_16x16x32_bf16 v[112:115], v[144:147], v[168:171], v[112:115]
	v_mfma_f32_16x16x32_bf16 v[108:111], v[152:155], v[168:171], v[108:111]
	v_mfma_f32_16x16x32_bf16 v[96:99], v[144:147], v[176:179], v[96:99]
	v_mfma_f32_16x16x32_bf16 v[92:95], v[152:155], v[176:179], v[92:95]
	v_mfma_f32_16x16x32_bf16 v[80:83], v[144:147], v[184:187], v[80:83]
	v_mfma_f32_16x16x32_bf16 v[76:79], v[152:155], v[184:187], v[76:79]
	s_setprio 0
	s_barrier
	v_add_u32_e32 v214, s83, v1
	s_mov_b32 m0, s84
	ds_read_b128 v[188:191], v214
	ds_read_b128 v[192:195], v214 offset:1024
	ds_read_b128 v[210:213], v214 offset:2048
	ds_read_b128 v[214:217], v214 offset:3072
	s_nop 0
	global_load_lds_dwordx4 v134, s[42:43]
	s_mov_b32 m0, s82
	s_nop 0
	global_load_lds_dwordx4 v138, s[42:43]
	s_barrier
	s_waitcnt lgkmcnt(0)
	s_setprio 1
	s_waitcnt lgkmcnt(0)
	v_mfma_f32_16x16x32_bf16 v[120:123], v[188:191], v[156:159], v[120:123]
	v_mfma_f32_16x16x32_bf16 v[116:119], v[210:213], v[156:159], v[116:119]
	v_mfma_f32_16x16x32_bf16 v[104:107], v[188:191], v[164:167], v[104:107]
	v_mfma_f32_16x16x32_bf16 v[100:103], v[210:213], v[164:167], v[100:103]
	v_mfma_f32_16x16x32_bf16 v[88:91], v[188:191], v[172:175], v[88:91]
	v_mfma_f32_16x16x32_bf16 v[84:87], v[210:213], v[172:175], v[84:87]
	v_mfma_f32_16x16x32_bf16 v[72:75], v[188:191], v[180:183], v[72:75]
	v_mfma_f32_16x16x32_bf16 v[68:71], v[210:213], v[180:183], v[68:71]
	v_mfma_f32_16x16x32_bf16 v[120:123], v[192:195], v[160:163], v[120:123]
	v_mfma_f32_16x16x32_bf16 v[116:119], v[214:217], v[160:163], v[116:119]
	v_mfma_f32_16x16x32_bf16 v[104:107], v[192:195], v[168:171], v[104:107]
	v_mfma_f32_16x16x32_bf16 v[100:103], v[214:217], v[168:171], v[100:103]
	v_mfma_f32_16x16x32_bf16 v[88:91], v[192:195], v[176:179], v[88:91]
	v_mfma_f32_16x16x32_bf16 v[84:87], v[214:217], v[176:179], v[84:87]
	v_mfma_f32_16x16x32_bf16 v[72:75], v[192:195], v[184:187], v[72:75]
	v_mfma_f32_16x16x32_bf16 v[68:71], v[214:217], v[184:187], v[68:71]
	s_setprio 0
	s_mov_b32 m0, s52
	s_barrier
	ds_read_b128 v[156:159], v3 offset:16384
	ds_read_b128 v[160:163], v3 offset:17408
	ds_read_b128 v[164:167], v3 offset:18432
	ds_read_b128 v[168:171], v3 offset:19456
	ds_read_b128 v[172:175], v3 offset:20480
	ds_read_b128 v[176:179], v3 offset:21504
	ds_read_b128 v[180:183], v3 offset:22528
	ds_read_b128 v[184:187], v3 offset:23552
	s_nop 0
	global_load_lds_dwordx4 v132, s[40:41]
	s_mov_b32 m0, s53
	s_nop 0
	global_load_lds_dwordx4 v136, s[40:41]
	s_barrier
	s_waitcnt lgkmcnt(0)
	s_setprio 1
	s_waitcnt lgkmcnt(0)
	v_mfma_f32_16x16x32_bf16 v[64:67], v[140:143], v[156:159], v[64:67]
	v_mfma_f32_16x16x32_bf16 v[60:63], v[148:151], v[156:159], v[60:63]
	v_mfma_f32_16x16x32_bf16 v[48:51], v[140:143], v[164:167], v[48:51]
	v_mfma_f32_16x16x32_bf16 v[44:47], v[148:151], v[164:167], v[44:47]
	v_mfma_f32_16x16x32_bf16 v[32:35], v[140:143], v[172:175], v[32:35]
	v_mfma_f32_16x16x32_bf16 v[28:31], v[148:151], v[172:175], v[28:31]
	v_mfma_f32_16x16x32_bf16 v[16:19], v[140:143], v[180:183], v[16:19]
	v_mfma_f32_16x16x32_bf16 v[12:15], v[148:151], v[180:183], v[12:15]
	v_mfma_f32_16x16x32_bf16 v[64:67], v[144:147], v[160:163], v[64:67]
	v_mfma_f32_16x16x32_bf16 v[60:63], v[152:155], v[160:163], v[60:63]
	v_mfma_f32_16x16x32_bf16 v[48:51], v[144:147], v[168:171], v[48:51]
	v_mfma_f32_16x16x32_bf16 v[44:47], v[152:155], v[168:171], v[44:47]
	v_mfma_f32_16x16x32_bf16 v[32:35], v[144:147], v[176:179], v[32:35]
	v_mfma_f32_16x16x32_bf16 v[28:31], v[152:155], v[176:179], v[28:31]
	v_mfma_f32_16x16x32_bf16 v[16:19], v[144:147], v[184:187], v[16:19]
	v_mfma_f32_16x16x32_bf16 v[12:15], v[152:155], v[184:187], v[12:15]
	s_setprio 0
	s_barrier
	s_mov_b32 m0, s80
	s_nop 0
	global_load_lds_dwordx4 v134, s[38:39]
	s_mov_b32 m0, s78
	s_nop 0
	global_load_lds_dwordx4 v138, s[38:39]
	s_waitcnt vmcnt(6)
	s_barrier
	s_setprio 1
	v_mfma_f32_16x16x32_bf16 v[56:59], v[188:191], v[156:159], v[56:59]
	v_mfma_f32_16x16x32_bf16 v[52:55], v[210:213], v[156:159], v[52:55]
	v_mfma_f32_16x16x32_bf16 v[40:43], v[188:191], v[164:167], v[40:43]
	v_mfma_f32_16x16x32_bf16 v[36:39], v[210:213], v[164:167], v[36:39]
	v_mfma_f32_16x16x32_bf16 v[24:27], v[188:191], v[172:175], v[24:27]
	v_mfma_f32_16x16x32_bf16 v[20:23], v[210:213], v[172:175], v[20:23]
	v_mfma_f32_16x16x32_bf16 v[8:11], v[188:191], v[180:183], v[8:11]
	v_mfma_f32_16x16x32_bf16 v[4:7], v[210:213], v[180:183], v[4:7]
	v_mfma_f32_16x16x32_bf16 v[56:59], v[192:195], v[160:163], v[56:59]
	v_mfma_f32_16x16x32_bf16 v[52:55], v[214:217], v[160:163], v[52:55]
	v_mfma_f32_16x16x32_bf16 v[40:43], v[192:195], v[168:171], v[40:43]
	v_mfma_f32_16x16x32_bf16 v[36:39], v[214:217], v[168:171], v[36:39]
	v_mfma_f32_16x16x32_bf16 v[24:27], v[192:195], v[176:179], v[24:27]
	v_mfma_f32_16x16x32_bf16 v[20:23], v[214:217], v[176:179], v[20:23]
	v_mfma_f32_16x16x32_bf16 v[8:11], v[192:195], v[184:187], v[8:11]
	v_mfma_f32_16x16x32_bf16 v[4:7], v[214:217], v[184:187], v[4:7]
	s_setprio 0
	v_add_u32_e32 v152, s75, v1
	s_barrier
	ds_read_b128 v[140:143], v152
	ds_read_b128 v[144:147], v152 offset:1024
	ds_read_b128 v[148:151], v152 offset:2048
	ds_read_b128 v[152:155], v152 offset:3072
	s_mov_b32 m0, s54
	ds_read_b128 v[156:159], v3 offset:32768
	ds_read_b128 v[160:163], v3 offset:33792
	ds_read_b128 v[164:167], v3 offset:34816
	ds_read_b128 v[168:171], v3 offset:35840
	ds_read_b128 v[172:175], v3 offset:36864
	ds_read_b128 v[176:179], v3 offset:37888
	ds_read_b128 v[180:183], v3 offset:38912
	ds_read_b128 v[184:187], v3 offset:39936
	s_nop 0
	global_load_lds_dwordx4 v132, s[30:31]
	s_mov_b32 m0, s55
	s_nop 0
	global_load_lds_dwordx4 v136, s[30:31]
	s_waitcnt lgkmcnt(8)
	s_barrier
	s_waitcnt lgkmcnt(0)
	s_setprio 1
	s_waitcnt lgkmcnt(0)
	v_mfma_f32_16x16x32_bf16 v[128:131], v[140:143], v[156:159], v[128:131]
	v_mfma_f32_16x16x32_bf16 v[124:127], v[148:151], v[156:159], v[124:127]
	v_mfma_f32_16x16x32_bf16 v[112:115], v[140:143], v[164:167], v[112:115]
	v_mfma_f32_16x16x32_bf16 v[108:111], v[148:151], v[164:167], v[108:111]
	v_mfma_f32_16x16x32_bf16 v[96:99], v[140:143], v[172:175], v[96:99]
	v_mfma_f32_16x16x32_bf16 v[92:95], v[148:151], v[172:175], v[92:95]
	v_mfma_f32_16x16x32_bf16 v[80:83], v[140:143], v[180:183], v[80:83]
	v_mfma_f32_16x16x32_bf16 v[76:79], v[148:151], v[180:183], v[76:79]
	v_mfma_f32_16x16x32_bf16 v[128:131], v[144:147], v[160:163], v[128:131]
	v_mfma_f32_16x16x32_bf16 v[124:127], v[152:155], v[160:163], v[124:127]
	v_mfma_f32_16x16x32_bf16 v[112:115], v[144:147], v[168:171], v[112:115]
	v_mfma_f32_16x16x32_bf16 v[108:111], v[152:155], v[168:171], v[108:111]
	v_mfma_f32_16x16x32_bf16 v[96:99], v[144:147], v[176:179], v[96:99]
	v_mfma_f32_16x16x32_bf16 v[92:95], v[152:155], v[176:179], v[92:95]
	v_mfma_f32_16x16x32_bf16 v[80:83], v[144:147], v[184:187], v[80:83]
	v_mfma_f32_16x16x32_bf16 v[76:79], v[152:155], v[184:187], v[76:79]
	s_setprio 0
	s_barrier
	v_add_u32_e32 v214, s73, v1
	s_mov_b32 m0, s74
	ds_read_b128 v[188:191], v214
	ds_read_b128 v[192:195], v214 offset:1024
	ds_read_b128 v[210:213], v214 offset:2048
	ds_read_b128 v[214:217], v214 offset:3072
	s_nop 0
	global_load_lds_dwordx4 v134, s[28:29]
	s_mov_b32 m0, s15
	s_nop 0
	global_load_lds_dwordx4 v138, s[28:29]
	s_barrier
	s_waitcnt lgkmcnt(0)
	s_setprio 1
	s_waitcnt lgkmcnt(0)
	v_mfma_f32_16x16x32_bf16 v[120:123], v[188:191], v[156:159], v[120:123]
	v_mfma_f32_16x16x32_bf16 v[116:119], v[210:213], v[156:159], v[116:119]
	v_mfma_f32_16x16x32_bf16 v[104:107], v[188:191], v[164:167], v[104:107]
	v_mfma_f32_16x16x32_bf16 v[100:103], v[210:213], v[164:167], v[100:103]
	v_mfma_f32_16x16x32_bf16 v[88:91], v[188:191], v[172:175], v[88:91]
	v_mfma_f32_16x16x32_bf16 v[84:87], v[210:213], v[172:175], v[84:87]
	v_mfma_f32_16x16x32_bf16 v[72:75], v[188:191], v[180:183], v[72:75]
	v_mfma_f32_16x16x32_bf16 v[68:71], v[210:213], v[180:183], v[68:71]
	v_mfma_f32_16x16x32_bf16 v[120:123], v[192:195], v[160:163], v[120:123]
	v_mfma_f32_16x16x32_bf16 v[116:119], v[214:217], v[160:163], v[116:119]
	v_mfma_f32_16x16x32_bf16 v[104:107], v[192:195], v[168:171], v[104:107]
	v_mfma_f32_16x16x32_bf16 v[100:103], v[214:217], v[168:171], v[100:103]
	v_mfma_f32_16x16x32_bf16 v[88:91], v[192:195], v[176:179], v[88:91]
	v_mfma_f32_16x16x32_bf16 v[84:87], v[214:217], v[176:179], v[84:87]
	v_mfma_f32_16x16x32_bf16 v[72:75], v[192:195], v[184:187], v[72:75]
	v_mfma_f32_16x16x32_bf16 v[68:71], v[214:217], v[184:187], v[68:71]
	s_setprio 0
	s_mov_b32 m0, s64
	s_barrier
	ds_read_b128 v[156:159], v3 offset:49152
	ds_read_b128 v[160:163], v3 offset:50176
	ds_read_b128 v[164:167], v3 offset:51200
	ds_read_b128 v[168:171], v3 offset:52224
	ds_read_b128 v[172:175], v3 offset:53248
	ds_read_b128 v[176:179], v3 offset:54272
	ds_read_b128 v[180:183], v3 offset:55296
	ds_read_b128 v[184:187], v3 offset:56320
	s_nop 0
	global_load_lds_dwordx4 v132, s[24:25]
	s_mov_b32 m0, s65
	s_nop 0
	global_load_lds_dwordx4 v136, s[24:25]
	s_barrier
	s_waitcnt lgkmcnt(0)
	s_setprio 1
	s_waitcnt lgkmcnt(0)
	v_mfma_f32_16x16x32_bf16 v[64:67], v[140:143], v[156:159], v[64:67]
	v_mfma_f32_16x16x32_bf16 v[60:63], v[148:151], v[156:159], v[60:63]
	v_mfma_f32_16x16x32_bf16 v[48:51], v[140:143], v[164:167], v[48:51]
	v_mfma_f32_16x16x32_bf16 v[44:47], v[148:151], v[164:167], v[44:47]
	v_mfma_f32_16x16x32_bf16 v[32:35], v[140:143], v[172:175], v[32:35]
	v_mfma_f32_16x16x32_bf16 v[28:31], v[148:151], v[172:175], v[28:31]
	v_mfma_f32_16x16x32_bf16 v[16:19], v[140:143], v[180:183], v[16:19]
	v_mfma_f32_16x16x32_bf16 v[12:15], v[148:151], v[180:183], v[12:15]
	v_mfma_f32_16x16x32_bf16 v[64:67], v[144:147], v[160:163], v[64:67]
	v_mfma_f32_16x16x32_bf16 v[60:63], v[152:155], v[160:163], v[60:63]
	v_mfma_f32_16x16x32_bf16 v[48:51], v[144:147], v[168:171], v[48:51]
	v_mfma_f32_16x16x32_bf16 v[44:47], v[152:155], v[168:171], v[44:47]
	v_mfma_f32_16x16x32_bf16 v[32:35], v[144:147], v[176:179], v[32:35]
	v_mfma_f32_16x16x32_bf16 v[28:31], v[152:155], v[176:179], v[28:31]
	v_mfma_f32_16x16x32_bf16 v[16:19], v[144:147], v[184:187], v[16:19]
	v_mfma_f32_16x16x32_bf16 v[12:15], v[152:155], v[184:187], v[12:15]
	s_setprio 0
	s_barrier
	s_mov_b32 m0, s81
	s_nop 0
	global_load_lds_dwordx4 v134, s[26:27]
	s_mov_b32 m0, s79
	s_nop 0
	global_load_lds_dwordx4 v138, s[26:27]
	s_waitcnt vmcnt(6)
	s_barrier
	s_setprio 1
	v_mfma_f32_16x16x32_bf16 v[56:59], v[188:191], v[156:159], v[56:59]
	v_mfma_f32_16x16x32_bf16 v[52:55], v[210:213], v[156:159], v[52:55]
	v_mfma_f32_16x16x32_bf16 v[40:43], v[188:191], v[164:167], v[40:43]
	v_mfma_f32_16x16x32_bf16 v[36:39], v[210:213], v[164:167], v[36:39]
	v_mfma_f32_16x16x32_bf16 v[24:27], v[188:191], v[172:175], v[24:27]
	v_mfma_f32_16x16x32_bf16 v[20:23], v[210:213], v[172:175], v[20:23]
	v_mfma_f32_16x16x32_bf16 v[8:11], v[188:191], v[180:183], v[8:11]
	v_mfma_f32_16x16x32_bf16 v[4:7], v[210:213], v[180:183], v[4:7]
	v_mfma_f32_16x16x32_bf16 v[56:59], v[192:195], v[160:163], v[56:59]
	v_mfma_f32_16x16x32_bf16 v[52:55], v[214:217], v[160:163], v[52:55]
	v_mfma_f32_16x16x32_bf16 v[40:43], v[192:195], v[168:171], v[40:43]
	v_mfma_f32_16x16x32_bf16 v[36:39], v[214:217], v[168:171], v[36:39]
	v_mfma_f32_16x16x32_bf16 v[24:27], v[192:195], v[176:179], v[24:27]
	v_mfma_f32_16x16x32_bf16 v[20:23], v[214:217], v[176:179], v[20:23]
	v_mfma_f32_16x16x32_bf16 v[8:11], v[192:195], v[184:187], v[8:11]
	v_mfma_f32_16x16x32_bf16 v[4:7], v[214:217], v[184:187], v[4:7]
	s_setprio 0
	s_andn2_b64 vcc, exec, s[22:23]
	s_mov_b64 s[26:27], -1
	s_mov_b64 s[22:23], 0
	s_mov_b64 s[24:25], 0x100
	s_barrier
	s_cbranch_vccz .LBB0_2213
	v_mov_b32_e32 v141, v0
	s_ashr_i32 s15, s14, 31
	v_readfirstlane_b32 s1, v141
	s_bfe_u32 s7, s1, 0x20006
	s_ashr_i32 s1, s1, 2
	s_and_b32 s16, s1, 0xffffffc0
	s_ashr_i32 s17, s16, 31
	s_lshl_b64 s[20:21], s[14:15], 10
	s_add_u32 s1, s56, s20
	s_addc_u32 s22, s57, s21
	s_lshl_b64 s[20:21], s[16:17], 2
	v_and_b32_e32 v142, 15, v141
	s_add_u32 s20, s1, s20
	s_addc_u32 s21, s22, s21
	v_lshlrev_b32_e32 v140, 2, v142
	global_load_dword v150, v140, s[20:21] offset:64
	global_load_dword v149, v140, s[20:21] offset:128
	global_load_dword v148, v140, s[20:21] offset:192
	global_load_dword v147, v140, s[20:21] offset:512
	global_load_dword v146, v140, s[20:21] offset:576
	global_load_dword v145, v140, s[20:21] offset:640
	global_load_dword v144, v140, s[20:21] offset:704
	v_mul_f32_e32 v129, v129, v129
	v_mul_f32_e32 v125, v125, v125
	v_mul_f32_e32 v121, v121, v121
	v_mul_f32_e32 v117, v117, v117
	v_fmac_f32_e32 v129, v128, v128
	v_mul_f32_e32 v128, v131, v131
	v_fmac_f32_e32 v125, v124, v124
	v_mul_f32_e32 v124, v127, v127
	v_fmac_f32_e32 v121, v120, v120
	v_mul_f32_e32 v120, v123, v123
	v_fmac_f32_e32 v117, v116, v116
	v_mul_f32_e32 v116, v119, v119
	v_fmac_f32_e32 v128, v130, v130
	v_fmac_f32_e32 v124, v126, v126
	v_fmac_f32_e32 v120, v122, v122
	v_fmac_f32_e32 v116, v118, v118
	v_add_f32_e32 v128, v129, v128
	v_add_f32_e32 v124, v125, v124
	v_add_f32_e32 v120, v121, v120
	v_add_f32_e32 v116, v117, v116
	v_add_f32_e32 v124, v128, v124
	v_add_f32_e32 v116, v120, v116
	v_add_f32_e32 v117, v124, v116
	ds_swizzle_b32 v118, v117 offset:swizzle(SWAP,16)
	v_and_b32_e32 v152, 64, v236
	v_xor_b32_e32 v151, 32, v236
	v_add_u32_e32 v152, 64, v152
	v_cmp_lt_i32_e32 vcc, v151, v152
	s_lshl_b32 s0, s0, 2
	s_or_b32 s0, s7, s0
	v_cndmask_b32_e32 v116, v236, v151, vcc
	s_lshl_b64 s[14:15], s[14:15], 8
	v_lshlrev_b32_e32 v116, 2, v116
	s_waitcnt lgkmcnt(0)
	v_add_f32_e32 v117, v117, v118
	s_add_u32 s1, s14, s16
	ds_bpermute_b32 v118, v116, v117
	s_addc_u32 s7, s15, s17
	v_or_b32_e32 v143, s1, v142
	s_ashr_i32 s1, s0, 31
	s_lshl_b64 s[0:1], s[0:1], 2
	v_and_b32_e32 v119, 48, v141
	s_add_u32 s0, s62, s0
	v_mov_b32_e32 v142, s7
	v_cmp_eq_u32_e64 s[16:17], 0, v119
	s_addc_u32 s1, s63, s1
	s_and_saveexec_b64 s[14:15], s[16:17]
	s_cbranch_execz .LBB0_2216
	v_mov_b32_e32 v141, v2
	v_lshl_add_u64 v[120:121], s[20:21], 0, v[140:141]
	global_load_dword v119, v[120:121], off
	s_waitcnt lgkmcnt(0)
	v_add_f32_e32 v117, v117, v118
	s_waitcnt vmcnt(0)
	v_add_f32_e32 v117, v117, v119
	v_fmamk_f32 v117, v117, 0x3c2aaaab, v231
	v_cmp_gt_f32_e32 vcc, s11, v117
	v_mul_f32_e32 v118, 0x4b800000, v117
	s_nop 0
	v_cndmask_b32_e32 v117, v117, v118, vcc
	v_rsq_f32_e32 v117, v117
	s_nop 0
	v_mul_f32_e32 v118, 0x45800000, v117
	v_cndmask_b32_e32 v117, v117, v118, vcc
	v_mad_u64_u32 v[118:119], s[20:21], v143, 48, s[0:1]
	v_mov_b32_e32 v120, v119
	v_mad_u64_u32 v[120:121], s[20:21], v142, 48, v[120:121]
	v_mov_b32_e32 v119, v120
	global_store_dword v[118:119], v117, off

.LBB0_2603:
	s_add_u32 s18, s14, 0x100
	s_addc_u32 s19, s15, 0
	s_cmp_eq_u32 s49, 2
	s_cselect_b32 s24, s6, s18
	s_cselect_b32 s25, s7, s19
	s_cselect_b32 s20, s8, s47
	s_cselect_b32 s21, s9, s48
	s_add_u32 s22, s24, 0x80
	s_addc_u32 s23, s25, 0
	s_add_i32 s50, 0, 0x10000
	v_add_u32_e32 v152, s50, v1
	ds_read_b128 v[140:143], v152
	ds_read_b128 v[144:147], v152 offset:1024
	ds_read_b128 v[148:151], v152 offset:2048
	ds_read_b128 v[152:155], v152 offset:3072
	s_add_u32 s14, s14, 0x30080
	s_addc_u32 s15, s15, 0
	ds_read_b128 v[156:159], v3
	ds_read_b128 v[160:163], v3 offset:1024
	ds_read_b128 v[164:167], v3 offset:2048
	ds_read_b128 v[168:171], v3 offset:3072
	ds_read_b128 v[172:175], v3 offset:4096
	ds_read_b128 v[176:179], v3 offset:5120
	ds_read_b128 v[180:183], v3 offset:6144
	ds_read_b128 v[184:187], v3 offset:7168
	s_add_i32 m0, s38, 0xc000
	s_nop 0
	global_load_lds_dwordx4 v132, s[14:15]
	s_add_i32 m0, s38, 0xe000
	s_nop 0
	global_load_lds_dwordx4 v136, s[14:15]
	s_waitcnt lgkmcnt(8)
	s_barrier
	s_waitcnt lgkmcnt(0)
	s_setprio 1
	s_waitcnt lgkmcnt(0)
	v_mfma_f32_16x16x32_bf16 v[128:131], v[140:143], v[156:159], v[128:131]
	v_mfma_f32_16x16x32_bf16 v[124:127], v[148:151], v[156:159], v[124:127]
	v_mfma_f32_16x16x32_bf16 v[120:123], v[140:143], v[164:167], v[120:123]
	v_mfma_f32_16x16x32_bf16 v[112:115], v[148:151], v[164:167], v[112:115]
	v_mfma_f32_16x16x32_bf16 v[104:107], v[140:143], v[172:175], v[104:107]
	v_mfma_f32_16x16x32_bf16 v[96:99], v[148:151], v[172:175], v[96:99]
	v_mfma_f32_16x16x32_bf16 v[88:91], v[140:143], v[180:183], v[88:91]
	v_mfma_f32_16x16x32_bf16 v[80:83], v[148:151], v[180:183], v[80:83]
	v_mfma_f32_16x16x32_bf16 v[128:131], v[144:147], v[160:163], v[128:131]
	v_mfma_f32_16x16x32_bf16 v[124:127], v[152:155], v[160:163], v[124:127]
	v_mfma_f32_16x16x32_bf16 v[120:123], v[144:147], v[168:171], v[120:123]
	v_mfma_f32_16x16x32_bf16 v[112:115], v[152:155], v[168:171], v[112:115]
	v_mfma_f32_16x16x32_bf16 v[104:107], v[144:147], v[176:179], v[104:107]
	v_mfma_f32_16x16x32_bf16 v[96:99], v[152:155], v[176:179], v[96:99]
	v_mfma_f32_16x16x32_bf16 v[88:91], v[144:147], v[184:187], v[88:91]
	v_mfma_f32_16x16x32_bf16 v[80:83], v[152:155], v[184:187], v[80:83]
	s_setprio 0
	s_barrier
	s_add_i32 s51, 0, 0x14000
	v_add_u32_e32 v214, s51, v1
	s_mov_b64 s[14:15], s[20:21]
	s_add_i32 s50, s50, s37
	ds_read_b128 v[188:191], v214
	ds_read_b128 v[192:195], v214 offset:1024
	ds_read_b128 v[210:213], v214 offset:2048
	ds_read_b128 v[214:217], v214 offset:3072
	s_mov_b32 m0, s50
	s_nop 0
	global_load_lds_dwordx4 v134, s[14:15]
	s_add_i32 m0, s50, 0x2000
	s_nop 0
	global_load_lds_dwordx4 v138, s[14:15]
	s_barrier
	s_waitcnt lgkmcnt(0)
	s_setprio 1
	s_waitcnt lgkmcnt(0)
	v_mfma_f32_16x16x32_bf16 v[116:119], v[188:191], v[156:159], v[116:119]
	v_mfma_f32_16x16x32_bf16 v[108:111], v[210:213], v[156:159], v[108:111]
	v_mfma_f32_16x16x32_bf16 v[100:103], v[188:191], v[164:167], v[100:103]
	v_mfma_f32_16x16x32_bf16 v[92:95], v[210:213], v[164:167], v[92:95]
	v_mfma_f32_16x16x32_bf16 v[84:87], v[188:191], v[172:175], v[84:87]
	v_mfma_f32_16x16x32_bf16 v[76:79], v[210:213], v[172:175], v[76:79]
	v_mfma_f32_16x16x32_bf16 v[72:75], v[188:191], v[180:183], v[72:75]
	v_mfma_f32_16x16x32_bf16 v[68:71], v[210:213], v[180:183], v[68:71]
	v_mfma_f32_16x16x32_bf16 v[116:119], v[192:195], v[160:163], v[116:119]
	v_mfma_f32_16x16x32_bf16 v[108:111], v[214:217], v[160:163], v[108:111]
	v_mfma_f32_16x16x32_bf16 v[100:103], v[192:195], v[168:171], v[100:103]
	v_mfma_f32_16x16x32_bf16 v[92:95], v[214:217], v[168:171], v[92:95]
	v_mfma_f32_16x16x32_bf16 v[84:87], v[192:195], v[176:179], v[84:87]
	v_mfma_f32_16x16x32_bf16 v[76:79], v[214:217], v[176:179], v[76:79]
	v_mfma_f32_16x16x32_bf16 v[72:75], v[192:195], v[184:187], v[72:75]
	v_mfma_f32_16x16x32_bf16 v[68:71], v[214:217], v[184:187], v[68:71]
	s_setprio 0
	s_mov_b64 s[14:15], s[24:25]
	s_mov_b32 m0, s38
	s_barrier
	ds_read_b128 v[156:159], v3 offset:16384
	ds_read_b128 v[160:163], v3 offset:17408
	ds_read_b128 v[164:167], v3 offset:18432
	ds_read_b128 v[168:171], v3 offset:19456
	ds_read_b128 v[172:175], v3 offset:20480
	ds_read_b128 v[176:179], v3 offset:21504
	ds_read_b128 v[180:183], v3 offset:22528
	ds_read_b128 v[184:187], v3 offset:23552
	s_nop 0
	global_load_lds_dwordx4 v132, s[14:15]
	s_mov_b32 m0, s39
	s_nop 0
	global_load_lds_dwordx4 v136, s[14:15]
	s_barrier
	s_waitcnt lgkmcnt(0)
	s_setprio 1
	s_waitcnt lgkmcnt(0)
	v_mfma_f32_16x16x32_bf16 v[64:67], v[140:143], v[156:159], v[64:67]
	v_mfma_f32_16x16x32_bf16 v[60:63], v[148:151], v[156:159], v[60:63]
	v_mfma_f32_16x16x32_bf16 v[56:59], v[140:143], v[164:167], v[56:59]
	v_mfma_f32_16x16x32_bf16 v[52:55], v[148:151], v[164:167], v[52:55]
	v_mfma_f32_16x16x32_bf16 v[40:43], v[140:143], v[172:175], v[40:43]
	v_mfma_f32_16x16x32_bf16 v[36:39], v[148:151], v[172:175], v[36:39]
	v_mfma_f32_16x16x32_bf16 v[24:27], v[140:143], v[180:183], v[24:27]
	v_mfma_f32_16x16x32_bf16 v[20:23], v[148:151], v[180:183], v[20:23]
	v_mfma_f32_16x16x32_bf16 v[64:67], v[144:147], v[160:163], v[64:67]
	v_mfma_f32_16x16x32_bf16 v[60:63], v[152:155], v[160:163], v[60:63]
	v_mfma_f32_16x16x32_bf16 v[56:59], v[144:147], v[168:171], v[56:59]
	v_mfma_f32_16x16x32_bf16 v[52:55], v[152:155], v[168:171], v[52:55]
	v_mfma_f32_16x16x32_bf16 v[40:43], v[144:147], v[176:179], v[40:43]
	v_mfma_f32_16x16x32_bf16 v[36:39], v[152:155], v[176:179], v[36:39]
	v_mfma_f32_16x16x32_bf16 v[24:27], v[144:147], v[184:187], v[24:27]
	v_mfma_f32_16x16x32_bf16 v[20:23], v[152:155], v[184:187], v[20:23]
	s_setprio 0
	s_barrier
	s_add_u32 s14, s20, 0x18000
	s_addc_u32 s15, s21, 0
	s_add_i32 s50, s51, s37
	s_mov_b32 m0, s50
	s_nop 0
	global_load_lds_dwordx4 v134, s[14:15]
	s_add_i32 m0, s50, 0x2000
	s_nop 0
	global_load_lds_dwordx4 v138, s[14:15]
	s_waitcnt vmcnt(6)
	s_barrier
	s_setprio 1
	v_mfma_f32_16x16x32_bf16 v[48:51], v[188:191], v[156:159], v[48:51]
	v_mfma_f32_16x16x32_bf16 v[44:47], v[210:213], v[156:159], v[44:47]
	v_mfma_f32_16x16x32_bf16 v[32:35], v[188:191], v[164:167], v[32:35]
	v_mfma_f32_16x16x32_bf16 v[28:31], v[210:213], v[164:167], v[28:31]
	v_mfma_f32_16x16x32_bf16 v[16:19], v[188:191], v[172:175], v[16:19]
	v_mfma_f32_16x16x32_bf16 v[12:15], v[210:213], v[172:175], v[12:15]
	v_mfma_f32_16x16x32_bf16 v[8:11], v[188:191], v[180:183], v[8:11]
	v_mfma_f32_16x16x32_bf16 v[4:7], v[210:213], v[180:183], v[4:7]
	v_mfma_f32_16x16x32_bf16 v[48:51], v[192:195], v[160:163], v[48:51]
	v_mfma_f32_16x16x32_bf16 v[44:47], v[214:217], v[160:163], v[44:47]
	v_mfma_f32_16x16x32_bf16 v[32:35], v[192:195], v[168:171], v[32:35]
	v_mfma_f32_16x16x32_bf16 v[28:31], v[214:217], v[168:171], v[28:31]
	v_mfma_f32_16x16x32_bf16 v[16:19], v[192:195], v[176:179], v[16:19]
	v_mfma_f32_16x16x32_bf16 v[12:15], v[214:217], v[176:179], v[12:15]
	v_mfma_f32_16x16x32_bf16 v[8:11], v[192:195], v[184:187], v[8:11]
	v_mfma_f32_16x16x32_bf16 v[4:7], v[214:217], v[184:187], v[4:7]
	s_setprio 0
	s_add_i32 s50, 0, 0x18000
	v_add_u32_e32 v152, s50, v1
	s_barrier
	ds_read_b128 v[140:143], v152
	ds_read_b128 v[144:147], v152 offset:1024
	ds_read_b128 v[148:151], v152 offset:2048
	ds_read_b128 v[152:155], v152 offset:3072
	s_add_u32 s14, s24, 0x30000
	s_addc_u32 s15, s25, 0
	s_mov_b32 m0, s40
	ds_read_b128 v[156:159], v3 offset:32768
	ds_read_b128 v[160:163], v3 offset:33792
	ds_read_b128 v[164:167], v3 offset:34816
	ds_read_b128 v[168:171], v3 offset:35840
	ds_read_b128 v[172:175], v3 offset:36864
	ds_read_b128 v[176:179], v3 offset:37888
	ds_read_b128 v[180:183], v3 offset:38912
	ds_read_b128 v[184:187], v3 offset:39936
	s_nop 0
	global_load_lds_dwordx4 v132, s[14:15]
	s_mov_b32 m0, s41
	s_nop 0
	global_load_lds_dwordx4 v136, s[14:15]
	s_waitcnt lgkmcnt(8)
	s_barrier
	s_waitcnt lgkmcnt(0)
	s_setprio 1
	s_waitcnt lgkmcnt(0)
	v_mfma_f32_16x16x32_bf16 v[128:131], v[140:143], v[156:159], v[128:131]
	v_mfma_f32_16x16x32_bf16 v[124:127], v[148:151], v[156:159], v[124:127]
	v_mfma_f32_16x16x32_bf16 v[120:123], v[140:143], v[164:167], v[120:123]
	v_mfma_f32_16x16x32_bf16 v[112:115], v[148:151], v[164:167], v[112:115]
	v_mfma_f32_16x16x32_bf16 v[104:107], v[140:143], v[172:175], v[104:107]
	v_mfma_f32_16x16x32_bf16 v[96:99], v[148:151], v[172:175], v[96:99]
	v_mfma_f32_16x16x32_bf16 v[88:91], v[140:143], v[180:183], v[88:91]
	v_mfma_f32_16x16x32_bf16 v[80:83], v[148:151], v[180:183], v[80:83]
	v_mfma_f32_16x16x32_bf16 v[128:131], v[144:147], v[160:163], v[128:131]
	v_mfma_f32_16x16x32_bf16 v[124:127], v[152:155], v[160:163], v[124:127]
	v_mfma_f32_16x16x32_bf16 v[120:123], v[144:147], v[168:171], v[120:123]
	v_mfma_f32_16x16x32_bf16 v[112:115], v[152:155], v[168:171], v[112:115]
	v_mfma_f32_16x16x32_bf16 v[104:107], v[144:147], v[176:179], v[104:107]
	v_mfma_f32_16x16x32_bf16 v[96:99], v[152:155], v[176:179], v[96:99]
	v_mfma_f32_16x16x32_bf16 v[88:91], v[144:147], v[184:187], v[88:91]
	v_mfma_f32_16x16x32_bf16 v[80:83], v[152:155], v[184:187], v[80:83]
	s_setprio 0
	s_barrier
	s_add_i32 s24, 0, 0x1c000
	s_add_u32 s14, s20, 0x80
	v_add_u32_e32 v214, s24, v1
	s_addc_u32 s15, s21, 0
	s_add_i32 s25, s50, s37
	ds_read_b128 v[188:191], v214
	ds_read_b128 v[192:195], v214 offset:1024
	ds_read_b128 v[210:213], v214 offset:2048
	ds_read_b128 v[214:217], v214 offset:3072
	s_mov_b32 m0, s25
	s_nop 0
	global_load_lds_dwordx4 v134, s[14:15]
	s_add_i32 m0, s25, 0x2000
	s_nop 0
	global_load_lds_dwordx4 v138, s[14:15]
	s_barrier
	s_waitcnt lgkmcnt(0)
	s_setprio 1
	s_waitcnt lgkmcnt(0)
	v_mfma_f32_16x16x32_bf16 v[116:119], v[188:191], v[156:159], v[116:119]
	v_mfma_f32_16x16x32_bf16 v[108:111], v[210:213], v[156:159], v[108:111]
	v_mfma_f32_16x16x32_bf16 v[100:103], v[188:191], v[164:167], v[100:103]
	v_mfma_f32_16x16x32_bf16 v[92:95], v[210:213], v[164:167], v[92:95]
	v_mfma_f32_16x16x32_bf16 v[84:87], v[188:191], v[172:175], v[84:87]
	v_mfma_f32_16x16x32_bf16 v[76:79], v[210:213], v[172:175], v[76:79]
	v_mfma_f32_16x16x32_bf16 v[72:75], v[188:191], v[180:183], v[72:75]
	v_mfma_f32_16x16x32_bf16 v[68:71], v[210:213], v[180:183], v[68:71]
	v_mfma_f32_16x16x32_bf16 v[116:119], v[192:195], v[160:163], v[116:119]
	v_mfma_f32_16x16x32_bf16 v[108:111], v[214:217], v[160:163], v[108:111]
	v_mfma_f32_16x16x32_bf16 v[100:103], v[192:195], v[168:171], v[100:103]
	v_mfma_f32_16x16x32_bf16 v[92:95], v[214:217], v[168:171], v[92:95]
	v_mfma_f32_16x16x32_bf16 v[84:87], v[192:195], v[176:179], v[84:87]
	v_mfma_f32_16x16x32_bf16 v[76:79], v[214:217], v[176:179], v[76:79]
	v_mfma_f32_16x16x32_bf16 v[72:75], v[192:195], v[184:187], v[72:75]
	v_mfma_f32_16x16x32_bf16 v[68:71], v[214:217], v[184:187], v[68:71]
	s_setprio 0
	s_mov_b32 m0, s26
	s_barrier
	ds_read_b128 v[156:159], v3 offset:49152
	ds_read_b128 v[160:163], v3 offset:50176
	ds_read_b128 v[164:167], v3 offset:51200
	ds_read_b128 v[168:171], v3 offset:52224
	ds_read_b128 v[172:175], v3 offset:53248
	ds_read_b128 v[176:179], v3 offset:54272
	ds_read_b128 v[180:183], v3 offset:55296
	ds_read_b128 v[184:187], v3 offset:56320
	s_nop 0
	global_load_lds_dwordx4 v132, s[22:23]
	s_mov_b32 m0, s27
	s_nop 0
	global_load_lds_dwordx4 v136, s[22:23]
	s_barrier
	s_waitcnt lgkmcnt(0)
	s_setprio 1
	s_waitcnt lgkmcnt(0)
	v_mfma_f32_16x16x32_bf16 v[64:67], v[140:143], v[156:159], v[64:67]
	v_mfma_f32_16x16x32_bf16 v[60:63], v[148:151], v[156:159], v[60:63]
	v_mfma_f32_16x16x32_bf16 v[56:59], v[140:143], v[164:167], v[56:59]
	v_mfma_f32_16x16x32_bf16 v[52:55], v[148:151], v[164:167], v[52:55]
	v_mfma_f32_16x16x32_bf16 v[40:43], v[140:143], v[172:175], v[40:43]
	v_mfma_f32_16x16x32_bf16 v[36:39], v[148:151], v[172:175], v[36:39]
	v_mfma_f32_16x16x32_bf16 v[24:27], v[140:143], v[180:183], v[24:27]
	v_mfma_f32_16x16x32_bf16 v[20:23], v[148:151], v[180:183], v[20:23]
	v_mfma_f32_16x16x32_bf16 v[64:67], v[144:147], v[160:163], v[64:67]
	v_mfma_f32_16x16x32_bf16 v[60:63], v[152:155], v[160:163], v[60:63]
	v_mfma_f32_16x16x32_bf16 v[56:59], v[144:147], v[168:171], v[56:59]
	v_mfma_f32_16x16x32_bf16 v[52:55], v[152:155], v[168:171], v[52:55]
	v_mfma_f32_16x16x32_bf16 v[40:43], v[144:147], v[176:179], v[40:43]
	v_mfma_f32_16x16x32_bf16 v[36:39], v[152:155], v[176:179], v[36:39]
	v_mfma_f32_16x16x32_bf16 v[24:27], v[144:147], v[184:187], v[24:27]
	v_mfma_f32_16x16x32_bf16 v[20:23], v[152:155], v[184:187], v[20:23]
	s_setprio 0
	s_barrier
	s_add_u32 s14, s20, 0x18080
	s_addc_u32 s15, s21, 0
	s_add_i32 s20, s24, s37
	s_mov_b32 m0, s20
	s_nop 0
	global_load_lds_dwordx4 v134, s[14:15]
	s_add_i32 m0, s20, 0x2000
	s_nop 0
	global_load_lds_dwordx4 v138, s[14:15]
	s_waitcnt vmcnt(6)
	s_barrier
	s_setprio 1
	v_mfma_f32_16x16x32_bf16 v[48:51], v[188:191], v[156:159], v[48:51]
	v_mfma_f32_16x16x32_bf16 v[44:47], v[210:213], v[156:159], v[44:47]
	v_mfma_f32_16x16x32_bf16 v[32:35], v[188:191], v[164:167], v[32:35]
	v_mfma_f32_16x16x32_bf16 v[28:31], v[210:213], v[164:167], v[28:31]
	v_mfma_f32_16x16x32_bf16 v[16:19], v[188:191], v[172:175], v[16:19]
	v_mfma_f32_16x16x32_bf16 v[12:15], v[210:213], v[172:175], v[12:15]
	v_mfma_f32_16x16x32_bf16 v[8:11], v[188:191], v[180:183], v[8:11]
	v_mfma_f32_16x16x32_bf16 v[4:7], v[210:213], v[180:183], v[4:7]
	v_mfma_f32_16x16x32_bf16 v[48:51], v[192:195], v[160:163], v[48:51]
	v_mfma_f32_16x16x32_bf16 v[44:47], v[214:217], v[160:163], v[44:47]
	v_mfma_f32_16x16x32_bf16 v[32:35], v[192:195], v[168:171], v[32:35]
	v_mfma_f32_16x16x32_bf16 v[28:31], v[214:217], v[168:171], v[28:31]
	v_mfma_f32_16x16x32_bf16 v[16:19], v[192:195], v[176:179], v[16:19]
	v_mfma_f32_16x16x32_bf16 v[12:15], v[214:217], v[176:179], v[12:15]
	v_mfma_f32_16x16x32_bf16 v[8:11], v[192:195], v[184:187], v[8:11]
	v_mfma_f32_16x16x32_bf16 v[4:7], v[214:217], v[184:187], v[4:7]
	s_setprio 0
	s_add_i32 s49, s49, 2
	s_add_u32 s47, s47, 0x100
	s_addc_u32 s48, s48, 0
	s_cmp_gt_u32 s49, 3
	s_mov_b64 s[14:15], s[18:19]
	s_barrier
	s_cbranch_scc0 .LBB0_2603
	v_mov_b32_e32 v141, v0
	s_lshl_b32 s18, s46, 8
	v_readfirstlane_b32 s14, v141
	s_and_b32 s15, s14, 0xc0
	s_ashr_i32 s14, s14, 2
	s_andn2_b32 s14, s14, 63
	s_add_i32 s14, s14, s18
	v_and_or_b32 v140, v141, 15, s14
	s_lshl_b32 s14, s45, 8
	s_or_b32 s14, s15, s14
	v_lshrrev_b32_e32 v141, 1, v141
	v_cvt_pk_bf16_f32 v72, v72, v73
	v_cvt_pk_bf16_f32 v73, v74, v75
	v_cvt_pk_bf16_f32 v74, v68, v69
	v_add_u32_e32 v68, 0x80, v140
	v_and_or_b32 v142, v141, 24, s14
	v_ashrrev_i32_e32 v141, 31, v140
	v_cvt_pk_bf16_f32 v116, v116, v117
	v_cvt_pk_bf16_f32 v117, v118, v119
	v_cvt_pk_bf16_f32 v118, v108, v109
	v_or_b32_e32 v108, 16, v140
	v_ashrrev_i32_e32 v69, 31, v68
	v_cvt_pk_bf16_f32 v48, v48, v49
	v_cvt_pk_bf16_f32 v49, v50, v51
	v_cvt_pk_bf16_f32 v50, v44, v45
	v_add_u32_e32 v44, 0x90, v140
	v_lshlrev_b64 v[144:145], 11, v[140:141]
	v_ashrrev_i32_e32 v143, 31, v142
	v_ashrrev_i32_e32 v109, 31, v108
	v_cvt_pk_bf16_f32 v100, v100, v101
	v_cvt_pk_bf16_f32 v101, v102, v103
	v_cvt_pk_bf16_f32 v102, v92, v93
	v_or_b32_e32 v92, 32, v140
	v_lshlrev_b64 v[68:69], 11, v[68:69]
	v_ashrrev_i32_e32 v45, 31, v44
	v_cvt_pk_bf16_f32 v32, v32, v33
	v_cvt_pk_bf16_f32 v33, v34, v35
	v_cvt_pk_bf16_f32 v34, v28, v29
	v_add_u32_e32 v28, 0xa0, v140
	v_lshl_add_u64 v[144:145], s[0:1], 0, v[144:145]
	v_lshlrev_b64 v[142:143], 1, v[142:143]
	v_lshlrev_b64 v[108:109], 11, v[108:109]
	v_ashrrev_i32_e32 v93, 31, v92
	v_cvt_pk_bf16_f32 v84, v84, v85
	v_cvt_pk_bf16_f32 v85, v86, v87
	v_cvt_pk_bf16_f32 v86, v76, v77
	v_or_b32_e32 v76, 48, v140
	v_lshl_add_u64 v[68:69], s[0:1], 0, v[68:69]
	v_lshlrev_b64 v[44:45], 11, v[44:45]
	v_ashrrev_i32_e32 v29, 31, v28
	v_cvt_pk_bf16_f32 v16, v16, v17
	v_cvt_pk_bf16_f32 v17, v18, v19
	v_cvt_pk_bf16_f32 v18, v12, v13
	v_add_u32_e32 v12, 0xb0, v140
	v_lshl_add_u64 v[144:145], v[144:145], 0, v[142:143]
	v_cvt_pk_bf16_f32 v119, v110, v111
	v_lshl_add_u64 v[108:109], s[0:1], 0, v[108:109]
	v_lshlrev_b64 v[92:93], 11, v[92:93]
	v_ashrrev_i32_e32 v77, 31, v76
	v_lshl_add_u64 v[68:69], v[68:69], 0, v[142:143]
	v_cvt_pk_bf16_f32 v51, v46, v47
	v_lshl_add_u64 v[44:45], s[0:1], 0, v[44:45]
	v_lshlrev_b64 v[28:29], 11, v[28:29]
	v_ashrrev_i32_e32 v13, 31, v12
	global_store_dwordx4 v[144:145], v[116:119], off offset:64
	v_cvt_pk_bf16_f32 v103, v94, v95
	v_lshl_add_u64 v[92:93], s[0:1], 0, v[92:93]
	v_lshl_add_u64 v[116:117], v[108:109], 0, v[142:143]
	v_lshlrev_b64 v[76:77], 11, v[76:77]
	global_store_dwordx4 v[68:69], v[48:51], off offset:64
	v_cvt_pk_bf16_f32 v35, v30, v31
	v_lshl_add_u64 v[28:29], s[0:1], 0, v[28:29]
	v_lshl_add_u64 v[48:49], v[44:45], 0, v[142:143]
	v_lshlrev_b64 v[12:13], 11, v[12:13]
	global_store_dwordx4 v[116:117], v[100:103], off offset:64
	v_cvt_pk_bf16_f32 v87, v78, v79
	v_lshl_add_u64 v[76:77], s[0:1], 0, v[76:77]
	v_lshl_add_u64 v[100:101], v[92:93], 0, v[142:143]
	global_store_dwordx4 v[48:49], v[32:35], off offset:64
	v_cvt_pk_bf16_f32 v19, v14, v15
	v_lshl_add_u64 v[12:13], s[0:1], 0, v[12:13]
	v_lshl_add_u64 v[32:33], v[28:29], 0, v[142:143]
	v_cvt_pk_bf16_f32 v128, v128, v129
	v_cvt_pk_bf16_f32 v129, v130, v131
	v_cvt_pk_bf16_f32 v130, v124, v125
	v_cvt_pk_bf16_f32 v131, v126, v127
	v_cvt_pk_bf16_f32 v108, v120, v121
	v_cvt_pk_bf16_f32 v109, v122, v123
	v_cvt_pk_bf16_f32 v110, v112, v113
	v_cvt_pk_bf16_f32 v111, v114, v115
	v_cvt_pk_bf16_f32 v92, v104, v105
	v_cvt_pk_bf16_f32 v93, v106, v107
	v_cvt_pk_bf16_f32 v94, v96, v97
	v_cvt_pk_bf16_f32 v95, v98, v99
	global_store_dwordx4 v[100:101], v[84:87], off offset:64
	v_cvt_pk_bf16_f32 v78, v80, v81
	v_cvt_pk_bf16_f32 v79, v82, v83
	v_lshl_add_u64 v[84:85], v[76:77], 0, v[142:143]
	v_cvt_pk_bf16_f32 v76, v88, v89
	v_cvt_pk_bf16_f32 v77, v90, v91
	v_cvt_pk_bf16_f32 v75, v70, v71
	v_cvt_pk_bf16_f32 v64, v64, v65
	v_cvt_pk_bf16_f32 v65, v66, v67
	v_cvt_pk_bf16_f32 v66, v60, v61
	v_cvt_pk_bf16_f32 v67, v62, v63
	v_cvt_pk_bf16_f32 v44, v56, v57
	v_cvt_pk_bf16_f32 v45, v58, v59
	v_cvt_pk_bf16_f32 v46, v52, v53
	v_cvt_pk_bf16_f32 v47, v54, v55
	v_cvt_pk_bf16_f32 v28, v40, v41
	v_cvt_pk_bf16_f32 v29, v42, v43
	v_cvt_pk_bf16_f32 v30, v36, v37
	v_cvt_pk_bf16_f32 v31, v38, v39
	global_store_dwordx4 v[32:33], v[16:19], off offset:64
	v_cvt_pk_bf16_f32 v14, v20, v21
	v_cvt_pk_bf16_f32 v15, v22, v23
	v_lshl_add_u64 v[16:17], v[12:13], 0, v[142:143]
	v_cvt_pk_bf16_f32 v12, v24, v25
	v_cvt_pk_bf16_f32 v13, v26, v27
	v_cvt_pk_bf16_f32 v8, v8, v9
	v_cvt_pk_bf16_f32 v9, v10, v11
	v_cvt_pk_bf16_f32 v10, v4, v5
	v_cvt_pk_bf16_f32 v11, v6, v7
	s_and_b64 vcc, exec, s[16:17]
	s_mov_b32 s45, s43
	s_mov_b32 s46, s44
	s_mov_b64 s[22:23], s[8:9]
	s_mov_b64 s[14:15], s[6:7]
	global_store_dwordx4 v[144:145], v[128:131], off
	global_store_dwordx4 v[116:117], v[108:111], off
	global_store_dwordx4 v[100:101], v[92:95], off
	global_store_dwordx4 v[84:85], v[76:79], off
	global_store_dwordx4 v[84:85], v[72:75], off offset:64
	global_store_dwordx4 v[68:69], v[64:67], off
	global_store_dwordx4 v[48:49], v[44:47], off
	global_store_dwordx4 v[32:33], v[28:31], off
	global_store_dwordx4 v[16:17], v[12:15], off
	global_store_dwordx4 v[16:17], v[8:11], off offset:64
	s_cbranch_vccz .LBB0_2596
	s_waitcnt vmcnt(0)
	s_cmpk_gt_u32 s36, 0xff
	s_cbranch_scc1 .LBB0_2607
	s_barrier

.LBB0_2674:
	s_add_u32 s8, s0, 0x100
	s_addc_u32 s9, s1, 0
	s_cmp_eq_u32 s75, 12
	s_cselect_b32 s42, s68, s8
	s_cselect_b32 s43, s31, s9
	s_cselect_b32 s40, s72, s73
	s_cselect_b32 s41, s29, s74
	s_add_u32 s14, s42, 0x80
	s_addc_u32 s15, s43, 0
	s_add_i32 s78, 0, 0x10000
	s_add_i32 s79, 0, 0x14000
	v_add_u32_e32 v144, s78, v1
	v_add_u32_e32 v160, s79, v1
	ds_read_b128 v[132:135], v144
	ds_read_b128 v[136:139], v144 offset:1024
	ds_read_b128 v[140:143], v144 offset:2048
	ds_read_b128 v[144:147], v144 offset:3072
	ds_read_b128 v[148:151], v160
	ds_read_b128 v[152:155], v160 offset:1024
	ds_read_b128 v[156:159], v160 offset:2048
	ds_read_b128 v[160:163], v160 offset:3072
	s_add_u32 s0, s0, 0x40080
	s_addc_u32 s1, s1, 0
	ds_read_b128 v[164:167], v3
	ds_read_b128 v[168:171], v3 offset:1024
	ds_read_b128 v[172:175], v3 offset:2048
	ds_read_b128 v[176:179], v3 offset:3072
	ds_read_b128 v[180:183], v3 offset:4096
	ds_read_b128 v[184:187], v3 offset:5120
	ds_read_b128 v[192:195], v3 offset:6144
	ds_read_b128 v[210:213], v3 offset:7168
	s_add_i32 m0, s50, 0xc000
	s_nop 0
	global_load_lds_dwordx4 v190, s[0:1]
	s_add_i32 m0, s50, 0xe000
	s_nop 0
	global_load_lds_dwordx4 v188, s[0:1]
	s_waitcnt vmcnt(8)
	s_waitcnt lgkmcnt(0)
	s_barrier
	s_setprio 1
	s_waitcnt lgkmcnt(0)
	v_mfma_f32_16x16x32_bf16 v[128:131], v[132:135], v[164:167], v[128:131]
	v_mfma_f32_16x16x32_bf16 v[124:127], v[140:143], v[164:167], v[124:127]
	v_mfma_f32_16x16x32_bf16 v[112:115], v[132:135], v[172:175], v[112:115]
	v_mfma_f32_16x16x32_bf16 v[108:111], v[140:143], v[172:175], v[108:111]
	v_mfma_f32_16x16x32_bf16 v[96:99], v[132:135], v[180:183], v[96:99]
	v_mfma_f32_16x16x32_bf16 v[92:95], v[140:143], v[180:183], v[92:95]
	v_mfma_f32_16x16x32_bf16 v[80:83], v[132:135], v[192:195], v[80:83]
	v_mfma_f32_16x16x32_bf16 v[76:79], v[140:143], v[192:195], v[76:79]
	v_mfma_f32_16x16x32_bf16 v[128:131], v[136:139], v[168:171], v[128:131]
	v_mfma_f32_16x16x32_bf16 v[124:127], v[144:147], v[168:171], v[124:127]
	v_mfma_f32_16x16x32_bf16 v[112:115], v[136:139], v[176:179], v[112:115]
	v_mfma_f32_16x16x32_bf16 v[108:111], v[144:147], v[176:179], v[108:111]
	v_mfma_f32_16x16x32_bf16 v[96:99], v[136:139], v[184:187], v[96:99]
	v_mfma_f32_16x16x32_bf16 v[92:95], v[144:147], v[184:187], v[92:95]
	v_mfma_f32_16x16x32_bf16 v[80:83], v[136:139], v[210:213], v[80:83]
	v_mfma_f32_16x16x32_bf16 v[76:79], v[144:147], v[210:213], v[76:79]
	s_setprio 0
	s_setprio 1
	v_mfma_f32_16x16x32_bf16 v[120:123], v[148:151], v[164:167], v[120:123]
	v_mfma_f32_16x16x32_bf16 v[116:119], v[156:159], v[164:167], v[116:119]
	v_mfma_f32_16x16x32_bf16 v[104:107], v[148:151], v[172:175], v[104:107]
	v_mfma_f32_16x16x32_bf16 v[100:103], v[156:159], v[172:175], v[100:103]
	v_mfma_f32_16x16x32_bf16 v[88:91], v[148:151], v[180:183], v[88:91]
	v_mfma_f32_16x16x32_bf16 v[84:87], v[156:159], v[180:183], v[84:87]
	v_mfma_f32_16x16x32_bf16 v[72:75], v[148:151], v[192:195], v[72:75]
	v_mfma_f32_16x16x32_bf16 v[68:71], v[156:159], v[192:195], v[68:71]
	v_mfma_f32_16x16x32_bf16 v[120:123], v[152:155], v[168:171], v[120:123]
	v_mfma_f32_16x16x32_bf16 v[116:119], v[160:163], v[168:171], v[116:119]
	v_mfma_f32_16x16x32_bf16 v[104:107], v[152:155], v[176:179], v[104:107]
	v_mfma_f32_16x16x32_bf16 v[100:103], v[160:163], v[176:179], v[100:103]
	v_mfma_f32_16x16x32_bf16 v[88:91], v[152:155], v[184:187], v[88:91]
	v_mfma_f32_16x16x32_bf16 v[84:87], v[160:163], v[184:187], v[84:87]
	v_mfma_f32_16x16x32_bf16 v[72:75], v[152:155], v[210:213], v[72:75]
	v_mfma_f32_16x16x32_bf16 v[68:71], v[160:163], v[210:213], v[68:71]
	s_setprio 0
	s_barrier
	s_mov_b64 s[0:1], s[40:41]
	s_add_i32 s78, s78, s49
	ds_read_b128 v[164:167], v3 offset:16384
	ds_read_b128 v[168:171], v3 offset:17408
	ds_read_b128 v[172:175], v3 offset:18432
	ds_read_b128 v[176:179], v3 offset:19456
	ds_read_b128 v[180:183], v3 offset:20480
	ds_read_b128 v[184:187], v3 offset:21504
	ds_read_b128 v[192:195], v3 offset:22528
	ds_read_b128 v[210:213], v3 offset:23552
	s_mov_b32 m0, s78
	s_nop 0
	global_load_lds_dwordx4 v190, s[0:1]
	s_add_i32 m0, s78, 0x2000
	s_nop 0
	global_load_lds_dwordx4 v188, s[0:1]
	s_add_u32 s0, s40, 0x40000
	s_addc_u32 s1, s41, 0
	s_add_i32 s78, s79, s49
	s_mov_b32 m0, s78
	s_nop 0
	global_load_lds_dwordx4 v190, s[0:1]
	s_add_i32 m0, s78, 0x2000
	s_nop 0
	global_load_lds_dwordx4 v188, s[0:1]
	s_mov_b64 s[0:1], s[42:43]
	s_mov_b32 m0, s50
	s_nop 0
	global_load_lds_dwordx4 v190, s[0:1]
	s_mov_b32 m0, s51
	s_nop 0
	global_load_lds_dwordx4 v188, s[0:1]
	s_waitcnt vmcnt(8)
	s_waitcnt lgkmcnt(0)
	s_barrier
	s_setprio 1
	s_waitcnt lgkmcnt(0)
	v_mfma_f32_16x16x32_bf16 v[64:67], v[132:135], v[164:167], v[64:67]
	v_mfma_f32_16x16x32_bf16 v[60:63], v[140:143], v[164:167], v[60:63]
	v_mfma_f32_16x16x32_bf16 v[56:59], v[132:135], v[172:175], v[56:59]
	v_mfma_f32_16x16x32_bf16 v[52:55], v[140:143], v[172:175], v[52:55]
	v_mfma_f32_16x16x32_bf16 v[32:35], v[132:135], v[180:183], v[32:35]
	v_mfma_f32_16x16x32_bf16 v[28:31], v[140:143], v[180:183], v[28:31]
	v_mfma_f32_16x16x32_bf16 v[16:19], v[132:135], v[192:195], v[16:19]
	v_mfma_f32_16x16x32_bf16 v[12:15], v[140:143], v[192:195], v[12:15]
	v_mfma_f32_16x16x32_bf16 v[64:67], v[136:139], v[168:171], v[64:67]
	v_mfma_f32_16x16x32_bf16 v[60:63], v[144:147], v[168:171], v[60:63]
	v_mfma_f32_16x16x32_bf16 v[56:59], v[136:139], v[176:179], v[56:59]
	v_mfma_f32_16x16x32_bf16 v[52:55], v[144:147], v[176:179], v[52:55]
	v_mfma_f32_16x16x32_bf16 v[32:35], v[136:139], v[184:187], v[32:35]
	v_mfma_f32_16x16x32_bf16 v[28:31], v[144:147], v[184:187], v[28:31]
	v_mfma_f32_16x16x32_bf16 v[16:19], v[136:139], v[210:213], v[16:19]
	v_mfma_f32_16x16x32_bf16 v[12:15], v[144:147], v[210:213], v[12:15]
	s_setprio 0
	s_setprio 1
	v_mfma_f32_16x16x32_bf16 v[48:51], v[148:151], v[164:167], v[48:51]
	v_mfma_f32_16x16x32_bf16 v[44:47], v[156:159], v[164:167], v[44:47]
	v_mfma_f32_16x16x32_bf16 v[40:43], v[148:151], v[172:175], v[40:43]
	v_mfma_f32_16x16x32_bf16 v[36:39], v[156:159], v[172:175], v[36:39]
	v_mfma_f32_16x16x32_bf16 v[24:27], v[148:151], v[180:183], v[24:27]
	v_mfma_f32_16x16x32_bf16 v[20:23], v[156:159], v[180:183], v[20:23]
	v_mfma_f32_16x16x32_bf16 v[8:11], v[148:151], v[192:195], v[8:11]
	v_mfma_f32_16x16x32_bf16 v[4:7], v[156:159], v[192:195], v[4:7]
	v_mfma_f32_16x16x32_bf16 v[48:51], v[152:155], v[168:171], v[48:51]
	v_mfma_f32_16x16x32_bf16 v[44:47], v[160:163], v[168:171], v[44:47]
	v_mfma_f32_16x16x32_bf16 v[40:43], v[152:155], v[176:179], v[40:43]
	v_mfma_f32_16x16x32_bf16 v[36:39], v[160:163], v[176:179], v[36:39]
	v_mfma_f32_16x16x32_bf16 v[24:27], v[152:155], v[184:187], v[24:27]
	v_mfma_f32_16x16x32_bf16 v[20:23], v[160:163], v[184:187], v[20:23]
	v_mfma_f32_16x16x32_bf16 v[8:11], v[152:155], v[210:213], v[8:11]
	v_mfma_f32_16x16x32_bf16 v[4:7], v[160:163], v[210:213], v[4:7]
	s_setprio 0
	s_barrier
	s_add_i32 s78, 0, 0x18000
	s_add_i32 s79, 0, 0x1c000
	v_add_u32_e32 v144, s78, v1
	v_add_u32_e32 v160, s79, v1
	ds_read_b128 v[132:135], v144
	ds_read_b128 v[136:139], v144 offset:1024
	ds_read_b128 v[140:143], v144 offset:2048
	ds_read_b128 v[144:147], v144 offset:3072
	ds_read_b128 v[148:151], v160
	ds_read_b128 v[152:155], v160 offset:1024
	ds_read_b128 v[156:159], v160 offset:2048
	ds_read_b128 v[160:163], v160 offset:3072
	s_add_u32 s0, s42, 0x40000
	s_addc_u32 s1, s43, 0
	s_mov_b32 m0, s52
	ds_read_b128 v[164:167], v3 offset:32768
	ds_read_b128 v[168:171], v3 offset:33792
	ds_read_b128 v[172:175], v3 offset:34816
	ds_read_b128 v[176:179], v3 offset:35840
	ds_read_b128 v[180:183], v3 offset:36864
	ds_read_b128 v[184:187], v3 offset:37888
	ds_read_b128 v[192:195], v3 offset:38912
	ds_read_b128 v[210:213], v3 offset:39936
	s_nop 0
	global_load_lds_dwordx4 v190, s[0:1]
	s_mov_b32 m0, s53
	s_nop 0
	global_load_lds_dwordx4 v188, s[0:1]
	s_waitcnt vmcnt(8)
	s_waitcnt lgkmcnt(0)
	s_barrier
	s_setprio 1
	s_waitcnt lgkmcnt(0)
	v_mfma_f32_16x16x32_bf16 v[128:131], v[132:135], v[164:167], v[128:131]
	v_mfma_f32_16x16x32_bf16 v[124:127], v[140:143], v[164:167], v[124:127]
	v_mfma_f32_16x16x32_bf16 v[112:115], v[132:135], v[172:175], v[112:115]
	v_mfma_f32_16x16x32_bf16 v[108:111], v[140:143], v[172:175], v[108:111]
	v_mfma_f32_16x16x32_bf16 v[96:99], v[132:135], v[180:183], v[96:99]
	v_mfma_f32_16x16x32_bf16 v[92:95], v[140:143], v[180:183], v[92:95]
	v_mfma_f32_16x16x32_bf16 v[80:83], v[132:135], v[192:195], v[80:83]
	v_mfma_f32_16x16x32_bf16 v[76:79], v[140:143], v[192:195], v[76:79]
	v_mfma_f32_16x16x32_bf16 v[128:131], v[136:139], v[168:171], v[128:131]
	v_mfma_f32_16x16x32_bf16 v[124:127], v[144:147], v[168:171], v[124:127]
	v_mfma_f32_16x16x32_bf16 v[112:115], v[136:139], v[176:179], v[112:115]
	v_mfma_f32_16x16x32_bf16 v[108:111], v[144:147], v[176:179], v[108:111]
	v_mfma_f32_16x16x32_bf16 v[96:99], v[136:139], v[184:187], v[96:99]
	v_mfma_f32_16x16x32_bf16 v[92:95], v[144:147], v[184:187], v[92:95]
	v_mfma_f32_16x16x32_bf16 v[80:83], v[136:139], v[210:213], v[80:83]
	v_mfma_f32_16x16x32_bf16 v[76:79], v[144:147], v[210:213], v[76:79]
	s_setprio 0
	s_setprio 1
	v_mfma_f32_16x16x32_bf16 v[120:123], v[148:151], v[164:167], v[120:123]
	v_mfma_f32_16x16x32_bf16 v[116:119], v[156:159], v[164:167], v[116:119]
	v_mfma_f32_16x16x32_bf16 v[104:107], v[148:151], v[172:175], v[104:107]
	v_mfma_f32_16x16x32_bf16 v[100:103], v[156:159], v[172:175], v[100:103]
	v_mfma_f32_16x16x32_bf16 v[88:91], v[148:151], v[180:183], v[88:91]
	v_mfma_f32_16x16x32_bf16 v[84:87], v[156:159], v[180:183], v[84:87]
	v_mfma_f32_16x16x32_bf16 v[72:75], v[148:151], v[192:195], v[72:75]
	v_mfma_f32_16x16x32_bf16 v[68:71], v[156:159], v[192:195], v[68:71]
	v_mfma_f32_16x16x32_bf16 v[120:123], v[152:155], v[168:171], v[120:123]
	v_mfma_f32_16x16x32_bf16 v[116:119], v[160:163], v[168:171], v[116:119]
	v_mfma_f32_16x16x32_bf16 v[104:107], v[152:155], v[176:179], v[104:107]
	v_mfma_f32_16x16x32_bf16 v[100:103], v[160:163], v[176:179], v[100:103]
	v_mfma_f32_16x16x32_bf16 v[88:91], v[152:155], v[184:187], v[88:91]
	v_mfma_f32_16x16x32_bf16 v[84:87], v[160:163], v[184:187], v[84:87]
	v_mfma_f32_16x16x32_bf16 v[72:75], v[152:155], v[210:213], v[72:75]
	v_mfma_f32_16x16x32_bf16 v[68:71], v[160:163], v[210:213], v[68:71]
	s_setprio 0
	s_barrier
	s_add_u32 s0, s40, 0x80
	s_addc_u32 s1, s41, 0
	s_add_i32 s42, s78, s49
	ds_read_b128 v[164:167], v3 offset:49152
	ds_read_b128 v[168:171], v3 offset:50176
	ds_read_b128 v[172:175], v3 offset:51200
	ds_read_b128 v[176:179], v3 offset:52224
	ds_read_b128 v[180:183], v3 offset:53248
	ds_read_b128 v[184:187], v3 offset:54272
	ds_read_b128 v[192:195], v3 offset:55296
	ds_read_b128 v[210:213], v3 offset:56320
	s_mov_b32 m0, s42
	s_nop 0
	global_load_lds_dwordx4 v190, s[0:1]
	s_add_i32 m0, s42, 0x2000
	s_nop 0
	global_load_lds_dwordx4 v188, s[0:1]
	s_add_u32 s0, s40, 0x40080
	s_addc_u32 s1, s41, 0
	s_add_i32 s40, s79, s49
	s_mov_b32 m0, s40
	s_nop 0
	global_load_lds_dwordx4 v190, s[0:1]
	s_add_i32 m0, s40, 0x2000
	s_nop 0
	global_load_lds_dwordx4 v188, s[0:1]
	s_mov_b32 m0, s56
	s_nop 0
	global_load_lds_dwordx4 v190, s[14:15]
	s_mov_b32 m0, s57
	s_nop 0
	global_load_lds_dwordx4 v188, s[14:15]
	s_waitcnt vmcnt(8)
	s_waitcnt lgkmcnt(0)
	s_barrier
	s_setprio 1
	s_waitcnt lgkmcnt(0)
	v_mfma_f32_16x16x32_bf16 v[64:67], v[132:135], v[164:167], v[64:67]
	v_mfma_f32_16x16x32_bf16 v[60:63], v[140:143], v[164:167], v[60:63]
	v_mfma_f32_16x16x32_bf16 v[56:59], v[132:135], v[172:175], v[56:59]
	v_mfma_f32_16x16x32_bf16 v[52:55], v[140:143], v[172:175], v[52:55]
	v_mfma_f32_16x16x32_bf16 v[32:35], v[132:135], v[180:183], v[32:35]
	v_mfma_f32_16x16x32_bf16 v[28:31], v[140:143], v[180:183], v[28:31]
	v_mfma_f32_16x16x32_bf16 v[16:19], v[132:135], v[192:195], v[16:19]
	v_mfma_f32_16x16x32_bf16 v[12:15], v[140:143], v[192:195], v[12:15]
	v_mfma_f32_16x16x32_bf16 v[64:67], v[136:139], v[168:171], v[64:67]
	v_mfma_f32_16x16x32_bf16 v[60:63], v[144:147], v[168:171], v[60:63]
	v_mfma_f32_16x16x32_bf16 v[56:59], v[136:139], v[176:179], v[56:59]
	v_mfma_f32_16x16x32_bf16 v[52:55], v[144:147], v[176:179], v[52:55]
	v_mfma_f32_16x16x32_bf16 v[32:35], v[136:139], v[184:187], v[32:35]
	v_mfma_f32_16x16x32_bf16 v[28:31], v[144:147], v[184:187], v[28:31]
	v_mfma_f32_16x16x32_bf16 v[16:19], v[136:139], v[210:213], v[16:19]
	v_mfma_f32_16x16x32_bf16 v[12:15], v[144:147], v[210:213], v[12:15]
	s_setprio 0
	s_setprio 1
	v_mfma_f32_16x16x32_bf16 v[48:51], v[148:151], v[164:167], v[48:51]
	v_mfma_f32_16x16x32_bf16 v[44:47], v[156:159], v[164:167], v[44:47]
	v_mfma_f32_16x16x32_bf16 v[40:43], v[148:151], v[172:175], v[40:43]
	v_mfma_f32_16x16x32_bf16 v[36:39], v[156:159], v[172:175], v[36:39]
	v_mfma_f32_16x16x32_bf16 v[24:27], v[148:151], v[180:183], v[24:27]
	v_mfma_f32_16x16x32_bf16 v[20:23], v[156:159], v[180:183], v[20:23]
	v_mfma_f32_16x16x32_bf16 v[8:11], v[148:151], v[192:195], v[8:11]
	v_mfma_f32_16x16x32_bf16 v[4:7], v[156:159], v[192:195], v[4:7]
	v_mfma_f32_16x16x32_bf16 v[48:51], v[152:155], v[168:171], v[48:51]
	v_mfma_f32_16x16x32_bf16 v[44:47], v[160:163], v[168:171], v[44:47]
	v_mfma_f32_16x16x32_bf16 v[40:43], v[152:155], v[176:179], v[40:43]
	v_mfma_f32_16x16x32_bf16 v[36:39], v[160:163], v[176:179], v[36:39]
	v_mfma_f32_16x16x32_bf16 v[24:27], v[152:155], v[184:187], v[24:27]
	v_mfma_f32_16x16x32_bf16 v[20:23], v[160:163], v[184:187], v[20:23]
	v_mfma_f32_16x16x32_bf16 v[8:11], v[152:155], v[210:213], v[8:11]
	v_mfma_f32_16x16x32_bf16 v[4:7], v[160:163], v[210:213], v[4:7]
	s_setprio 0
	s_barrier
	s_add_i32 s75, s75, 2
	s_add_u32 s73, s73, 0x100
	s_addc_u32 s74, s74, 0
	s_cmp_gt_u32 s75, 13
	s_mov_b64 s[0:1], s[8:9]
	s_cbranch_scc0 .LBB0_2674
	s_and_b64 vcc, exec, s[26:27]
	s_cbranch_vccz .LBB0_2677
	s_barrier

.LBB0_2741:
	s_add_u32 s20, s18, 0x100
	s_addc_u32 s21, s19, 0
	s_cmp_eq_u32 s65, 2
	s_cselect_b32 s22, s14, s51
	s_cselect_b32 s23, s15, s64
	s_cselect_b32 s56, s0, s20
	s_cselect_b32 s57, s1, s21
	s_add_u32 s54, s22, 0x80
	s_addc_u32 s55, s23, 0
	s_add_u32 s52, s56, 0x80
	s_addc_u32 s53, s57, 0
	s_add_i32 s67, 0, 0x10000
	v_add_u32_e32 v152, s67, v1
	ds_read_b128 v[140:143], v152
	ds_read_b128 v[144:147], v152 offset:1024
	ds_read_b128 v[148:151], v152 offset:2048
	ds_read_b128 v[152:155], v152 offset:3072
	s_add_u32 s18, s18, 0x30080
	s_addc_u32 s19, s19, 0
	ds_read_b128 v[156:159], v3
	ds_read_b128 v[160:163], v3 offset:1024
	ds_read_b128 v[164:167], v3 offset:2048
	ds_read_b128 v[168:171], v3 offset:3072
	ds_read_b128 v[172:175], v3 offset:4096
	ds_read_b128 v[176:179], v3 offset:5120
	ds_read_b128 v[180:183], v3 offset:6144
	ds_read_b128 v[184:187], v3 offset:7168
	s_add_i32 m0, s42, 0xc000
	s_nop 0
	global_load_lds_dwordx4 v132, s[18:19]
	s_add_i32 m0, s42, 0xe000
	s_nop 0
	global_load_lds_dwordx4 v136, s[18:19]
	s_waitcnt lgkmcnt(8)
	s_barrier
	s_waitcnt lgkmcnt(0)
	s_setprio 1
	s_waitcnt lgkmcnt(0)
	v_mfma_f32_16x16x32_bf16 v[128:131], v[140:143], v[156:159], v[128:131]
	v_mfma_f32_16x16x32_bf16 v[124:127], v[148:151], v[156:159], v[124:127]
	v_mfma_f32_16x16x32_bf16 v[120:123], v[140:143], v[164:167], v[120:123]
	v_mfma_f32_16x16x32_bf16 v[116:119], v[148:151], v[164:167], v[116:119]
	v_mfma_f32_16x16x32_bf16 v[104:107], v[140:143], v[172:175], v[104:107]
	v_mfma_f32_16x16x32_bf16 v[100:103], v[148:151], v[172:175], v[100:103]
	v_mfma_f32_16x16x32_bf16 v[88:91], v[140:143], v[180:183], v[88:91]
	v_mfma_f32_16x16x32_bf16 v[84:87], v[148:151], v[180:183], v[84:87]
	v_mfma_f32_16x16x32_bf16 v[128:131], v[144:147], v[160:163], v[128:131]
	v_mfma_f32_16x16x32_bf16 v[124:127], v[152:155], v[160:163], v[124:127]
	v_mfma_f32_16x16x32_bf16 v[120:123], v[144:147], v[168:171], v[120:123]
	v_mfma_f32_16x16x32_bf16 v[116:119], v[152:155], v[168:171], v[116:119]
	v_mfma_f32_16x16x32_bf16 v[104:107], v[144:147], v[176:179], v[104:107]
	v_mfma_f32_16x16x32_bf16 v[100:103], v[152:155], v[176:179], v[100:103]
	v_mfma_f32_16x16x32_bf16 v[88:91], v[144:147], v[184:187], v[88:91]
	v_mfma_f32_16x16x32_bf16 v[84:87], v[152:155], v[184:187], v[84:87]
	s_setprio 0
	s_barrier
	s_add_i32 s68, 0, 0x14000
	v_add_u32_e32 v196, s68, v1
	s_mov_b64 s[18:19], s[22:23]
	s_add_i32 s67, s67, s41
	ds_read_b128 v[188:191], v196
	ds_read_b128 v[192:195], v196 offset:1024
	ds_read_b128 v[210:213], v196 offset:2048
	ds_read_b128 v[214:217], v196 offset:3072
	s_mov_b32 m0, s67
	s_nop 0
	global_load_lds_dwordx4 v134, s[18:19]
	s_add_i32 m0, s67, 0x2000
	s_nop 0
	global_load_lds_dwordx4 v138, s[18:19]
	s_barrier
	s_waitcnt lgkmcnt(0)
	s_setprio 1
	s_waitcnt lgkmcnt(0)
	v_mfma_f32_16x16x32_bf16 v[112:115], v[188:191], v[156:159], v[112:115]
	v_mfma_f32_16x16x32_bf16 v[108:111], v[210:213], v[156:159], v[108:111]
	v_mfma_f32_16x16x32_bf16 v[96:99], v[188:191], v[164:167], v[96:99]
	v_mfma_f32_16x16x32_bf16 v[92:95], v[210:213], v[164:167], v[92:95]
	v_mfma_f32_16x16x32_bf16 v[80:83], v[188:191], v[172:175], v[80:83]
	v_mfma_f32_16x16x32_bf16 v[76:79], v[210:213], v[172:175], v[76:79]
	v_mfma_f32_16x16x32_bf16 v[72:75], v[188:191], v[180:183], v[72:75]
	v_mfma_f32_16x16x32_bf16 v[68:71], v[210:213], v[180:183], v[68:71]
	v_mfma_f32_16x16x32_bf16 v[112:115], v[192:195], v[160:163], v[112:115]
	v_mfma_f32_16x16x32_bf16 v[108:111], v[214:217], v[160:163], v[108:111]
	v_mfma_f32_16x16x32_bf16 v[96:99], v[192:195], v[168:171], v[96:99]
	v_mfma_f32_16x16x32_bf16 v[92:95], v[214:217], v[168:171], v[92:95]
	v_mfma_f32_16x16x32_bf16 v[80:83], v[192:195], v[176:179], v[80:83]
	v_mfma_f32_16x16x32_bf16 v[76:79], v[214:217], v[176:179], v[76:79]
	v_mfma_f32_16x16x32_bf16 v[72:75], v[192:195], v[184:187], v[72:75]
	v_mfma_f32_16x16x32_bf16 v[68:71], v[214:217], v[184:187], v[68:71]
	s_setprio 0
	s_mov_b64 s[18:19], s[56:57]
	s_mov_b32 m0, s42
	s_barrier
	ds_read_b128 v[156:159], v3 offset:16384
	ds_read_b128 v[160:163], v3 offset:17408
	ds_read_b128 v[164:167], v3 offset:18432
	ds_read_b128 v[168:171], v3 offset:19456
	ds_read_b128 v[172:175], v3 offset:20480
	ds_read_b128 v[176:179], v3 offset:21504
	ds_read_b128 v[180:183], v3 offset:22528
	ds_read_b128 v[184:187], v3 offset:23552
	s_nop 0
	global_load_lds_dwordx4 v132, s[18:19]
	s_mov_b32 m0, s43
	s_nop 0
	global_load_lds_dwordx4 v136, s[18:19]
	s_barrier
	s_waitcnt lgkmcnt(0)
	s_setprio 1
	s_waitcnt lgkmcnt(0)
	v_mfma_f32_16x16x32_bf16 v[64:67], v[140:143], v[156:159], v[64:67]
	v_mfma_f32_16x16x32_bf16 v[60:63], v[148:151], v[156:159], v[60:63]
	v_mfma_f32_16x16x32_bf16 v[56:59], v[140:143], v[164:167], v[56:59]
	v_mfma_f32_16x16x32_bf16 v[52:55], v[148:151], v[164:167], v[52:55]
	v_mfma_f32_16x16x32_bf16 v[40:43], v[140:143], v[172:175], v[40:43]
	v_mfma_f32_16x16x32_bf16 v[36:39], v[148:151], v[172:175], v[36:39]
	v_mfma_f32_16x16x32_bf16 v[24:27], v[140:143], v[180:183], v[24:27]
	v_mfma_f32_16x16x32_bf16 v[20:23], v[148:151], v[180:183], v[20:23]
	v_mfma_f32_16x16x32_bf16 v[64:67], v[144:147], v[160:163], v[64:67]
	v_mfma_f32_16x16x32_bf16 v[60:63], v[152:155], v[160:163], v[60:63]
	v_mfma_f32_16x16x32_bf16 v[56:59], v[144:147], v[168:171], v[56:59]
	v_mfma_f32_16x16x32_bf16 v[52:55], v[152:155], v[168:171], v[52:55]
	v_mfma_f32_16x16x32_bf16 v[40:43], v[144:147], v[176:179], v[40:43]
	v_mfma_f32_16x16x32_bf16 v[36:39], v[152:155], v[176:179], v[36:39]
	v_mfma_f32_16x16x32_bf16 v[24:27], v[144:147], v[184:187], v[24:27]
	v_mfma_f32_16x16x32_bf16 v[20:23], v[152:155], v[184:187], v[20:23]
	s_setprio 0
	s_barrier
	s_add_u32 s18, s22, 0x18000
	s_addc_u32 s19, s23, 0
	s_add_i32 s67, s68, s41
	s_mov_b32 m0, s67
	s_nop 0
	global_load_lds_dwordx4 v134, s[18:19]
	s_add_i32 m0, s67, 0x2000
	s_nop 0
	global_load_lds_dwordx4 v138, s[18:19]
	s_waitcnt vmcnt(6)
	s_barrier
	s_setprio 1
	v_mfma_f32_16x16x32_bf16 v[48:51], v[188:191], v[156:159], v[48:51]
	v_mfma_f32_16x16x32_bf16 v[44:47], v[210:213], v[156:159], v[44:47]
	v_mfma_f32_16x16x32_bf16 v[32:35], v[188:191], v[164:167], v[32:35]
	v_mfma_f32_16x16x32_bf16 v[28:31], v[210:213], v[164:167], v[28:31]
	v_mfma_f32_16x16x32_bf16 v[16:19], v[188:191], v[172:175], v[16:19]
	v_mfma_f32_16x16x32_bf16 v[12:15], v[210:213], v[172:175], v[12:15]
	v_mfma_f32_16x16x32_bf16 v[8:11], v[188:191], v[180:183], v[8:11]
	v_mfma_f32_16x16x32_bf16 v[4:7], v[210:213], v[180:183], v[4:7]
	v_mfma_f32_16x16x32_bf16 v[48:51], v[192:195], v[160:163], v[48:51]
	v_mfma_f32_16x16x32_bf16 v[44:47], v[214:217], v[160:163], v[44:47]
	v_mfma_f32_16x16x32_bf16 v[32:35], v[192:195], v[168:171], v[32:35]
	v_mfma_f32_16x16x32_bf16 v[28:31], v[214:217], v[168:171], v[28:31]
	v_mfma_f32_16x16x32_bf16 v[16:19], v[192:195], v[176:179], v[16:19]
	v_mfma_f32_16x16x32_bf16 v[12:15], v[214:217], v[176:179], v[12:15]
	v_mfma_f32_16x16x32_bf16 v[8:11], v[192:195], v[184:187], v[8:11]
	v_mfma_f32_16x16x32_bf16 v[4:7], v[214:217], v[184:187], v[4:7]
	s_setprio 0
	s_add_i32 s67, 0, 0x18000
	v_add_u32_e32 v152, s67, v1
	s_barrier
	ds_read_b128 v[140:143], v152
	ds_read_b128 v[144:147], v152 offset:1024
	ds_read_b128 v[148:151], v152 offset:2048
	ds_read_b128 v[152:155], v152 offset:3072
	s_add_u32 s18, s56, 0x30000
	s_addc_u32 s19, s57, 0
	s_mov_b32 m0, s45
	ds_read_b128 v[156:159], v3 offset:32768
	ds_read_b128 v[160:163], v3 offset:33792
	ds_read_b128 v[164:167], v3 offset:34816
	ds_read_b128 v[168:171], v3 offset:35840
	ds_read_b128 v[172:175], v3 offset:36864
	ds_read_b128 v[176:179], v3 offset:37888
	ds_read_b128 v[180:183], v3 offset:38912
	ds_read_b128 v[184:187], v3 offset:39936
	s_nop 0
	global_load_lds_dwordx4 v132, s[18:19]
	s_mov_b32 m0, s46
	s_nop 0
	global_load_lds_dwordx4 v136, s[18:19]
	s_waitcnt lgkmcnt(8)
	s_barrier
	s_waitcnt lgkmcnt(0)
	s_setprio 1
	s_waitcnt lgkmcnt(0)
	v_mfma_f32_16x16x32_bf16 v[128:131], v[140:143], v[156:159], v[128:131]
	v_mfma_f32_16x16x32_bf16 v[124:127], v[148:151], v[156:159], v[124:127]
	v_mfma_f32_16x16x32_bf16 v[120:123], v[140:143], v[164:167], v[120:123]
	v_mfma_f32_16x16x32_bf16 v[116:119], v[148:151], v[164:167], v[116:119]
	v_mfma_f32_16x16x32_bf16 v[104:107], v[140:143], v[172:175], v[104:107]
	v_mfma_f32_16x16x32_bf16 v[100:103], v[148:151], v[172:175], v[100:103]
	v_mfma_f32_16x16x32_bf16 v[88:91], v[140:143], v[180:183], v[88:91]
	v_mfma_f32_16x16x32_bf16 v[84:87], v[148:151], v[180:183], v[84:87]
	v_mfma_f32_16x16x32_bf16 v[128:131], v[144:147], v[160:163], v[128:131]
	v_mfma_f32_16x16x32_bf16 v[124:127], v[152:155], v[160:163], v[124:127]
	v_mfma_f32_16x16x32_bf16 v[120:123], v[144:147], v[168:171], v[120:123]
	v_mfma_f32_16x16x32_bf16 v[116:119], v[152:155], v[168:171], v[116:119]
	v_mfma_f32_16x16x32_bf16 v[104:107], v[144:147], v[176:179], v[104:107]
	v_mfma_f32_16x16x32_bf16 v[100:103], v[152:155], v[176:179], v[100:103]
	v_mfma_f32_16x16x32_bf16 v[88:91], v[144:147], v[184:187], v[88:91]
	v_mfma_f32_16x16x32_bf16 v[84:87], v[152:155], v[184:187], v[84:87]
	s_setprio 0
	s_barrier
	s_add_i32 s56, 0, 0x1c000
	v_add_u32_e32 v196, s56, v1
	s_add_i32 s18, s67, s41
	ds_read_b128 v[188:191], v196
	ds_read_b128 v[192:195], v196 offset:1024
	ds_read_b128 v[210:213], v196 offset:2048
	ds_read_b128 v[214:217], v196 offset:3072
	s_mov_b32 m0, s18
	s_nop 0
	global_load_lds_dwordx4 v134, s[54:55]
	s_add_i32 m0, s18, 0x2000
	s_nop 0
	global_load_lds_dwordx4 v138, s[54:55]
	s_barrier
	s_waitcnt lgkmcnt(0)
	s_setprio 1
	s_waitcnt lgkmcnt(0)
	v_mfma_f32_16x16x32_bf16 v[112:115], v[188:191], v[156:159], v[112:115]
	v_mfma_f32_16x16x32_bf16 v[108:111], v[210:213], v[156:159], v[108:111]
	v_mfma_f32_16x16x32_bf16 v[96:99], v[188:191], v[164:167], v[96:99]
	v_mfma_f32_16x16x32_bf16 v[92:95], v[210:213], v[164:167], v[92:95]
	v_mfma_f32_16x16x32_bf16 v[80:83], v[188:191], v[172:175], v[80:83]
	v_mfma_f32_16x16x32_bf16 v[76:79], v[210:213], v[172:175], v[76:79]
	v_mfma_f32_16x16x32_bf16 v[72:75], v[188:191], v[180:183], v[72:75]
	v_mfma_f32_16x16x32_bf16 v[68:71], v[210:213], v[180:183], v[68:71]
	v_mfma_f32_16x16x32_bf16 v[112:115], v[192:195], v[160:163], v[112:115]
	v_mfma_f32_16x16x32_bf16 v[108:111], v[214:217], v[160:163], v[108:111]
	v_mfma_f32_16x16x32_bf16 v[96:99], v[192:195], v[168:171], v[96:99]
	v_mfma_f32_16x16x32_bf16 v[92:95], v[214:217], v[168:171], v[92:95]
	v_mfma_f32_16x16x32_bf16 v[80:83], v[192:195], v[176:179], v[80:83]
	v_mfma_f32_16x16x32_bf16 v[76:79], v[214:217], v[176:179], v[76:79]
	v_mfma_f32_16x16x32_bf16 v[72:75], v[192:195], v[184:187], v[72:75]
	v_mfma_f32_16x16x32_bf16 v[68:71], v[214:217], v[184:187], v[68:71]
	s_setprio 0
	s_mov_b32 m0, s47
	s_barrier
	ds_read_b128 v[156:159], v3 offset:49152
	ds_read_b128 v[160:163], v3 offset:50176
	ds_read_b128 v[164:167], v3 offset:51200
	ds_read_b128 v[168:171], v3 offset:52224
	ds_read_b128 v[172:175], v3 offset:53248
	ds_read_b128 v[176:179], v3 offset:54272
	ds_read_b128 v[180:183], v3 offset:55296
	ds_read_b128 v[184:187], v3 offset:56320
	s_nop 0
	global_load_lds_dwordx4 v132, s[52:53]
	s_mov_b32 m0, s50
	s_nop 0
	global_load_lds_dwordx4 v136, s[52:53]
	s_barrier
	s_waitcnt lgkmcnt(0)
	s_setprio 1
	s_waitcnt lgkmcnt(0)
	v_mfma_f32_16x16x32_bf16 v[64:67], v[140:143], v[156:159], v[64:67]
	v_mfma_f32_16x16x32_bf16 v[60:63], v[148:151], v[156:159], v[60:63]
	v_mfma_f32_16x16x32_bf16 v[56:59], v[140:143], v[164:167], v[56:59]
	v_mfma_f32_16x16x32_bf16 v[52:55], v[148:151], v[164:167], v[52:55]
	v_mfma_f32_16x16x32_bf16 v[40:43], v[140:143], v[172:175], v[40:43]
	v_mfma_f32_16x16x32_bf16 v[36:39], v[148:151], v[172:175], v[36:39]
	v_mfma_f32_16x16x32_bf16 v[24:27], v[140:143], v[180:183], v[24:27]
	v_mfma_f32_16x16x32_bf16 v[20:23], v[148:151], v[180:183], v[20:23]
	v_mfma_f32_16x16x32_bf16 v[64:67], v[144:147], v[160:163], v[64:67]
	v_mfma_f32_16x16x32_bf16 v[60:63], v[152:155], v[160:163], v[60:63]
	v_mfma_f32_16x16x32_bf16 v[56:59], v[144:147], v[168:171], v[56:59]
	v_mfma_f32_16x16x32_bf16 v[52:55], v[152:155], v[168:171], v[52:55]
	v_mfma_f32_16x16x32_bf16 v[40:43], v[144:147], v[176:179], v[40:43]
	v_mfma_f32_16x16x32_bf16 v[36:39], v[152:155], v[176:179], v[36:39]
	v_mfma_f32_16x16x32_bf16 v[24:27], v[144:147], v[184:187], v[24:27]
	v_mfma_f32_16x16x32_bf16 v[20:23], v[152:155], v[184:187], v[20:23]
	s_setprio 0
	s_barrier
	s_add_u32 s18, s22, 0x18080
	s_addc_u32 s19, s23, 0
	s_add_i32 s22, s56, s41
	s_mov_b32 m0, s22
	s_nop 0
	global_load_lds_dwordx4 v134, s[18:19]
	s_add_i32 m0, s22, 0x2000
	s_nop 0
	global_load_lds_dwordx4 v138, s[18:19]
	s_waitcnt vmcnt(6)
	s_barrier
	s_setprio 1
	v_mfma_f32_16x16x32_bf16 v[48:51], v[188:191], v[156:159], v[48:51]
	v_mfma_f32_16x16x32_bf16 v[44:47], v[210:213], v[156:159], v[44:47]
	v_mfma_f32_16x16x32_bf16 v[32:35], v[188:191], v[164:167], v[32:35]
	v_mfma_f32_16x16x32_bf16 v[28:31], v[210:213], v[164:167], v[28:31]
	v_mfma_f32_16x16x32_bf16 v[16:19], v[188:191], v[172:175], v[16:19]
	v_mfma_f32_16x16x32_bf16 v[12:15], v[210:213], v[172:175], v[12:15]
	v_mfma_f32_16x16x32_bf16 v[8:11], v[188:191], v[180:183], v[8:11]
	v_mfma_f32_16x16x32_bf16 v[4:7], v[210:213], v[180:183], v[4:7]
	v_mfma_f32_16x16x32_bf16 v[48:51], v[192:195], v[160:163], v[48:51]
	v_mfma_f32_16x16x32_bf16 v[44:47], v[214:217], v[160:163], v[44:47]
	v_mfma_f32_16x16x32_bf16 v[32:35], v[192:195], v[168:171], v[32:35]
	v_mfma_f32_16x16x32_bf16 v[28:31], v[214:217], v[168:171], v[28:31]
	v_mfma_f32_16x16x32_bf16 v[16:19], v[192:195], v[176:179], v[16:19]
	v_mfma_f32_16x16x32_bf16 v[12:15], v[214:217], v[176:179], v[12:15]
	v_mfma_f32_16x16x32_bf16 v[8:11], v[192:195], v[184:187], v[8:11]
	v_mfma_f32_16x16x32_bf16 v[4:7], v[214:217], v[184:187], v[4:7]
	s_setprio 0
	s_add_i32 s65, s65, 2
	s_add_u32 s51, s51, 0x100
	s_addc_u32 s64, s64, 0
	s_cmp_gt_u32 s65, 3
	s_mov_b64 s[18:19], s[20:21]
	s_barrier
	s_cbranch_scc0 .LBB0_2741
	v_mov_b32_e32 v1, v0
	s_add_u32 s0, s38, 0xb55ec00
	s_addc_u32 s1, s39, 0
	v_readfirstlane_b32 s14, v1
	s_and_b32 s15, s14, 0xc0
	s_ashr_i32 s14, s14, 2
	s_andn2_b32 s14, s14, 63
	s_addk_i32 s14, 0x4000
	v_and_or_b32 v132, v1, 15, s14
	v_lshrrev_b32_e32 v1, 1, v1
	v_and_or_b32 v1, v1, 24, s15
	v_readlane_b32 s14, v255, 15
	v_ashrrev_i32_e32 v133, 31, v132
	v_lshlrev_b64 v[136:137], 11, v[132:133]
	v_or_b32_e32 v134, s14, v1
	v_ashrrev_i32_e32 v135, 31, v134
	v_cvt_pk_bf16_f32 v112, v112, v113
	v_cvt_pk_bf16_f32 v113, v114, v115
	v_cvt_pk_bf16_f32 v114, v108, v109
	v_or_b32_e32 v108, 16, v132
	v_lshl_add_u64 v[136:137], s[0:1], 0, v[136:137]
	v_lshlrev_b64 v[134:135], 1, v[134:135]
	v_ashrrev_i32_e32 v109, 31, v108
	v_lshl_add_u64 v[136:137], v[136:137], 0, v[134:135]
	v_cvt_pk_bf16_f32 v128, v128, v129
	v_cvt_pk_bf16_f32 v129, v130, v131
	v_cvt_pk_bf16_f32 v130, v124, v125
	v_cvt_pk_bf16_f32 v131, v126, v127
	global_store_dwordx4 v[136:137], v[128:131], off sc1
	s_nop 1
	v_lshlrev_b64 v[108:109], 11, v[108:109]
	v_cvt_pk_bf16_f32 v96, v96, v97
	v_cvt_pk_bf16_f32 v97, v98, v99
	v_cvt_pk_bf16_f32 v98, v92, v93
	v_or_b32_e32 v92, 32, v132
	v_lshl_add_u64 v[124:125], v[136:137], 0, 64
	v_cvt_pk_bf16_f32 v115, v110, v111
	global_store_dwordx4 v[124:125], v[112:115], off sc1
	s_nop 1
	v_lshl_add_u64 v[108:109], s[0:1], 0, v[108:109]
	v_ashrrev_i32_e32 v93, 31, v92
	v_lshl_add_u64 v[112:113], v[108:109], 0, v[134:135]
	v_cvt_pk_bf16_f32 v108, v120, v121
	v_cvt_pk_bf16_f32 v109, v122, v123
	v_cvt_pk_bf16_f32 v110, v116, v117
	v_cvt_pk_bf16_f32 v111, v118, v119
	global_store_dwordx4 v[112:113], v[108:111], off sc1
	s_nop 1
	v_lshlrev_b64 v[92:93], 11, v[92:93]
	v_cvt_pk_bf16_f32 v80, v80, v81
	v_cvt_pk_bf16_f32 v81, v82, v83
	v_cvt_pk_bf16_f32 v82, v76, v77
	v_or_b32_e32 v76, 48, v132
	v_lshl_add_u64 v[108:109], v[112:113], 0, 64
	v_cvt_pk_bf16_f32 v99, v94, v95
	global_store_dwordx4 v[108:109], v[96:99], off sc1
	s_nop 1
	v_lshl_add_u64 v[92:93], s[0:1], 0, v[92:93]
	v_ashrrev_i32_e32 v77, 31, v76
	v_lshl_add_u64 v[96:97], v[92:93], 0, v[134:135]
	v_cvt_pk_bf16_f32 v92, v104, v105
	v_cvt_pk_bf16_f32 v93, v106, v107
	v_cvt_pk_bf16_f32 v94, v100, v101
	v_cvt_pk_bf16_f32 v95, v102, v103
	global_store_dwordx4 v[96:97], v[92:95], off sc1
	s_nop 1
	v_lshlrev_b64 v[76:77], 11, v[76:77]
	v_lshl_add_u64 v[92:93], v[96:97], 0, 64
	v_cvt_pk_bf16_f32 v83, v78, v79
	global_store_dwordx4 v[92:93], v[80:83], off sc1
	s_nop 1
	v_lshl_add_u64 v[76:77], s[0:1], 0, v[76:77]
	v_lshl_add_u64 v[80:81], v[76:77], 0, v[134:135]
	v_cvt_pk_bf16_f32 v76, v88, v89
	v_cvt_pk_bf16_f32 v77, v90, v91
	v_cvt_pk_bf16_f32 v78, v84, v85
	v_cvt_pk_bf16_f32 v79, v86, v87
	global_store_dwordx4 v[80:81], v[76:79], off sc1
	s_nop 1
	v_lshl_add_u64 v[76:77], v[80:81], 0, 64
	v_cvt_pk_bf16_f32 v72, v72, v73
	v_cvt_pk_bf16_f32 v73, v74, v75
	v_cvt_pk_bf16_f32 v74, v68, v69
	v_cvt_pk_bf16_f32 v75, v70, v71
	global_store_dwordx4 v[76:77], v[72:75], off sc1
	s_nop 1
	s_mov_b64 s[0:1], 0x40000
	v_lshl_add_u64 v[68:69], v[136:137], 0, s[0:1]
	v_cvt_pk_bf16_f32 v64, v64, v65
	v_cvt_pk_bf16_f32 v65, v66, v67
	v_cvt_pk_bf16_f32 v66, v60, v61
	v_cvt_pk_bf16_f32 v67, v62, v63
	global_store_dwordx4 v[68:69], v[64:67], off sc1
	s_nop 1
	s_mov_b64 s[0:1], 0x40040
	v_lshl_add_u64 v[60:61], v[136:137], 0, s[0:1]
	v_cvt_pk_bf16_f32 v48, v48, v49
	v_cvt_pk_bf16_f32 v49, v50, v51
	v_cvt_pk_bf16_f32 v50, v44, v45
	v_cvt_pk_bf16_f32 v51, v46, v47
	global_store_dwordx4 v[60:61], v[48:51], off sc1
	s_nop 1
	s_mov_b64 s[0:1], 0x48000
	v_lshl_add_u64 v[48:49], v[136:137], 0, s[0:1]
	v_cvt_pk_bf16_f32 v44, v56, v57
	v_cvt_pk_bf16_f32 v45, v58, v59
	v_cvt_pk_bf16_f32 v46, v52, v53
	v_cvt_pk_bf16_f32 v47, v54, v55
	global_store_dwordx4 v[48:49], v[44:47], off sc1
	s_nop 1
	s_mov_b64 s[0:1], 0x48040
	v_lshl_add_u64 v[44:45], v[136:137], 0, s[0:1]
	v_cvt_pk_bf16_f32 v32, v32, v33
	v_cvt_pk_bf16_f32 v33, v34, v35
	v_cvt_pk_bf16_f32 v34, v28, v29
	v_cvt_pk_bf16_f32 v35, v30, v31
	global_store_dwordx4 v[44:45], v[32:35], off sc1
	s_nop 1
	s_mov_b64 s[0:1], 0x50000
	v_lshl_add_u64 v[32:33], v[136:137], 0, s[0:1]
	v_cvt_pk_bf16_f32 v28, v40, v41
	v_cvt_pk_bf16_f32 v29, v42, v43
	v_cvt_pk_bf16_f32 v30, v36, v37
	v_cvt_pk_bf16_f32 v31, v38, v39
	global_store_dwordx4 v[32:33], v[28:31], off sc1
	s_nop 1
	s_mov_b64 s[0:1], 0x50040
	v_lshl_add_u64 v[28:29], v[136:137], 0, s[0:1]
	v_cvt_pk_bf16_f32 v16, v16, v17
	v_cvt_pk_bf16_f32 v17, v18, v19
	v_cvt_pk_bf16_f32 v18, v12, v13
	v_cvt_pk_bf16_f32 v19, v14, v15
	global_store_dwordx4 v[28:29], v[16:19], off sc1
	s_nop 1
	s_mov_b64 s[0:1], 0x58000
	v_lshl_add_u64 v[16:17], v[136:137], 0, s[0:1]
	v_cvt_pk_bf16_f32 v12, v24, v25
	v_cvt_pk_bf16_f32 v13, v26, v27
	v_cvt_pk_bf16_f32 v14, v20, v21
	v_cvt_pk_bf16_f32 v15, v22, v23
	global_store_dwordx4 v[16:17], v[12:15], off sc1
	s_nop 1
	s_mov_b64 s[0:1], 0x58040
	v_lshl_add_u64 v[12:13], v[136:137], 0, s[0:1]
	v_cvt_pk_bf16_f32 v8, v8, v9
	v_cvt_pk_bf16_f32 v9, v10, v11
	v_cvt_pk_bf16_f32 v10, v4, v5
	v_cvt_pk_bf16_f32 v11, v6, v7
	global_store_dwordx4 v[12:13], v[8:11], off sc1
	s_nop 1
	s_waitcnt vmcnt(0)
	v_readlane_b32 s15, v255, 16
	s_mov_b64 s[0:1], exec
	v_readlane_b32 s14, v253, 23
	v_readlane_b32 s15, v253, 24
	s_and_b64 s[14:15], s[0:1], s[14:15]
	s_mov_b64 exec, s[14:15]
	s_cbranch_execz .LBB0_2745
	s_mov_b64 s[14:15], exec
	v_mbcnt_lo_u32_b32 v1, s14, 0
	v_mbcnt_hi_u32_b32 v1, s15, v1
	v_cmp_eq_u32_e32 vcc, 0, v1
	s_and_b64 s[18:19], exec, vcc
	s_mov_b64 exec, s[18:19]
	s_cbranch_execz .LBB0_2745
	s_bcnt1_i32_b64 s14, s[14:15]
	v_mov_b32_e32 v1, s14
	global_atomic_add v2, v1, s[8:9]

.LBB0_2766:
	s_add_u32 s20, s14, s50
	s_addc_u32 s21, s15, s51
	s_add_u32 s22, s20, 0xf30df100
	s_addc_u32 s23, s21, -1
	s_add_u32 s20, s14, 0x100
	s_addc_u32 s21, s15, 0
	s_cmp_eq_u32 s56, 12
	s_cselect_b32 s34, s8, s22
	s_cselect_b32 s35, s9, s23
	s_cselect_b32 s54, s0, s20
	s_cselect_b32 s55, s1, s21
	s_add_u32 s52, s34, 0x80
	s_addc_u32 s53, s35, 0
	s_add_u32 s22, s54, 0x80
	s_addc_u32 s23, s55, 0
	s_add_i32 s57, 0, 0x10000
	s_add_i32 s64, 0, 0x14000
	v_add_u32_e32 v148, s57, v1
	v_add_u32_e32 v164, s64, v1
	ds_read_b128 v[136:139], v148
	ds_read_b128 v[140:143], v148 offset:1024
	ds_read_b128 v[144:147], v148 offset:2048
	ds_read_b128 v[148:151], v148 offset:3072
	ds_read_b128 v[152:155], v164
	ds_read_b128 v[156:159], v164 offset:1024
	ds_read_b128 v[160:163], v164 offset:2048
	ds_read_b128 v[164:167], v164 offset:3072
	s_add_u32 s14, s14, 0x40080
	s_addc_u32 s15, s15, 0
	ds_read_b128 v[168:171], v3
	ds_read_b128 v[172:175], v3 offset:1024
	ds_read_b128 v[176:179], v3 offset:2048
	ds_read_b128 v[180:183], v3 offset:3072
	ds_read_b128 v[184:187], v3 offset:4096
	ds_read_b128 v[188:191], v3 offset:5120
	ds_read_b128 v[192:195], v3 offset:6144
	ds_read_b128 v[210:213], v3 offset:7168
	s_add_i32 m0, s42, 0xc000
	s_nop 0
	global_load_lds_dwordx4 v132, s[14:15]
	s_add_i32 m0, s42, 0xe000
	s_nop 0
	global_load_lds_dwordx4 v134, s[14:15]
	s_waitcnt vmcnt(8)
	s_waitcnt lgkmcnt(0)
	s_barrier
	s_setprio 1
	s_waitcnt lgkmcnt(0)
	v_mfma_f32_16x16x32_bf16 v[128:131], v[136:139], v[168:171], v[128:131]
	v_mfma_f32_16x16x32_bf16 v[124:127], v[144:147], v[168:171], v[124:127]
	v_mfma_f32_16x16x32_bf16 v[112:115], v[136:139], v[176:179], v[112:115]
	v_mfma_f32_16x16x32_bf16 v[108:111], v[144:147], v[176:179], v[108:111]
	v_mfma_f32_16x16x32_bf16 v[96:99], v[136:139], v[184:187], v[96:99]
	v_mfma_f32_16x16x32_bf16 v[92:95], v[144:147], v[184:187], v[92:95]
	v_mfma_f32_16x16x32_bf16 v[80:83], v[136:139], v[192:195], v[80:83]
	v_mfma_f32_16x16x32_bf16 v[76:79], v[144:147], v[192:195], v[76:79]
	v_mfma_f32_16x16x32_bf16 v[128:131], v[140:143], v[172:175], v[128:131]
	v_mfma_f32_16x16x32_bf16 v[124:127], v[148:151], v[172:175], v[124:127]
	v_mfma_f32_16x16x32_bf16 v[112:115], v[140:143], v[180:183], v[112:115]
	v_mfma_f32_16x16x32_bf16 v[108:111], v[148:151], v[180:183], v[108:111]
	v_mfma_f32_16x16x32_bf16 v[96:99], v[140:143], v[188:191], v[96:99]
	v_mfma_f32_16x16x32_bf16 v[92:95], v[148:151], v[188:191], v[92:95]
	v_mfma_f32_16x16x32_bf16 v[80:83], v[140:143], v[210:213], v[80:83]
	v_mfma_f32_16x16x32_bf16 v[76:79], v[148:151], v[210:213], v[76:79]
	s_setprio 0
	s_setprio 1
	v_mfma_f32_16x16x32_bf16 v[120:123], v[152:155], v[168:171], v[120:123]
	v_mfma_f32_16x16x32_bf16 v[116:119], v[160:163], v[168:171], v[116:119]
	v_mfma_f32_16x16x32_bf16 v[104:107], v[152:155], v[176:179], v[104:107]
	v_mfma_f32_16x16x32_bf16 v[100:103], v[160:163], v[176:179], v[100:103]
	v_mfma_f32_16x16x32_bf16 v[88:91], v[152:155], v[184:187], v[88:91]
	v_mfma_f32_16x16x32_bf16 v[84:87], v[160:163], v[184:187], v[84:87]
	v_mfma_f32_16x16x32_bf16 v[72:75], v[152:155], v[192:195], v[72:75]
	v_mfma_f32_16x16x32_bf16 v[68:71], v[160:163], v[192:195], v[68:71]
	v_mfma_f32_16x16x32_bf16 v[120:123], v[156:159], v[172:175], v[120:123]
	v_mfma_f32_16x16x32_bf16 v[116:119], v[164:167], v[172:175], v[116:119]
	v_mfma_f32_16x16x32_bf16 v[104:107], v[156:159], v[180:183], v[104:107]
	v_mfma_f32_16x16x32_bf16 v[100:103], v[164:167], v[180:183], v[100:103]
	v_mfma_f32_16x16x32_bf16 v[88:91], v[156:159], v[188:191], v[88:91]
	v_mfma_f32_16x16x32_bf16 v[84:87], v[164:167], v[188:191], v[84:87]
	v_mfma_f32_16x16x32_bf16 v[72:75], v[156:159], v[210:213], v[72:75]
	v_mfma_f32_16x16x32_bf16 v[68:71], v[164:167], v[210:213], v[68:71]
	s_setprio 0
	s_barrier
	s_mov_b64 s[14:15], s[34:35]
	s_add_i32 s57, s57, s41
	ds_read_b128 v[168:171], v3 offset:16384
	ds_read_b128 v[172:175], v3 offset:17408
	ds_read_b128 v[176:179], v3 offset:18432
	ds_read_b128 v[180:183], v3 offset:19456
	ds_read_b128 v[184:187], v3 offset:20480
	ds_read_b128 v[188:191], v3 offset:21504
	ds_read_b128 v[192:195], v3 offset:22528
	ds_read_b128 v[210:213], v3 offset:23552
	s_mov_b32 m0, s57
	s_nop 0
	global_load_lds_dwordx4 v132, s[14:15]
	s_add_i32 m0, s57, 0x2000
	s_nop 0
	global_load_lds_dwordx4 v134, s[14:15]
	s_add_u32 s14, s34, 0x40000
	s_addc_u32 s15, s35, 0
	s_add_i32 s57, s64, s41
	s_mov_b32 m0, s57
	s_nop 0
	global_load_lds_dwordx4 v132, s[14:15]
	s_add_i32 m0, s57, 0x2000
	s_nop 0
	global_load_lds_dwordx4 v134, s[14:15]
	s_mov_b64 s[14:15], s[54:55]
	s_mov_b32 m0, s42
	s_nop 0
	global_load_lds_dwordx4 v132, s[14:15]
	s_mov_b32 m0, s43
	s_nop 0
	global_load_lds_dwordx4 v134, s[14:15]
	s_waitcnt vmcnt(8)
	s_waitcnt lgkmcnt(0)
	s_barrier
	s_setprio 1
	s_waitcnt lgkmcnt(0)
	v_mfma_f32_16x16x32_bf16 v[64:67], v[136:139], v[168:171], v[64:67]
	v_mfma_f32_16x16x32_bf16 v[60:63], v[144:147], v[168:171], v[60:63]
	v_mfma_f32_16x16x32_bf16 v[48:51], v[136:139], v[176:179], v[48:51]
	v_mfma_f32_16x16x32_bf16 v[44:47], v[144:147], v[176:179], v[44:47]
	v_mfma_f32_16x16x32_bf16 v[32:35], v[136:139], v[184:187], v[32:35]
	v_mfma_f32_16x16x32_bf16 v[28:31], v[144:147], v[184:187], v[28:31]
	v_mfma_f32_16x16x32_bf16 v[16:19], v[136:139], v[192:195], v[16:19]
	v_mfma_f32_16x16x32_bf16 v[12:15], v[144:147], v[192:195], v[12:15]
	v_mfma_f32_16x16x32_bf16 v[64:67], v[140:143], v[172:175], v[64:67]
	v_mfma_f32_16x16x32_bf16 v[60:63], v[148:151], v[172:175], v[60:63]
	v_mfma_f32_16x16x32_bf16 v[48:51], v[140:143], v[180:183], v[48:51]
	v_mfma_f32_16x16x32_bf16 v[44:47], v[148:151], v[180:183], v[44:47]
	v_mfma_f32_16x16x32_bf16 v[32:35], v[140:143], v[188:191], v[32:35]
	v_mfma_f32_16x16x32_bf16 v[28:31], v[148:151], v[188:191], v[28:31]
	v_mfma_f32_16x16x32_bf16 v[16:19], v[140:143], v[210:213], v[16:19]
	v_mfma_f32_16x16x32_bf16 v[12:15], v[148:151], v[210:213], v[12:15]
	s_setprio 0
	s_setprio 1
	v_mfma_f32_16x16x32_bf16 v[56:59], v[152:155], v[168:171], v[56:59]
	v_mfma_f32_16x16x32_bf16 v[52:55], v[160:163], v[168:171], v[52:55]
	v_mfma_f32_16x16x32_bf16 v[40:43], v[152:155], v[176:179], v[40:43]
	v_mfma_f32_16x16x32_bf16 v[36:39], v[160:163], v[176:179], v[36:39]
	v_mfma_f32_16x16x32_bf16 v[24:27], v[152:155], v[184:187], v[24:27]
	v_mfma_f32_16x16x32_bf16 v[20:23], v[160:163], v[184:187], v[20:23]
	v_mfma_f32_16x16x32_bf16 v[8:11], v[152:155], v[192:195], v[8:11]
	v_mfma_f32_16x16x32_bf16 v[4:7], v[160:163], v[192:195], v[4:7]
	v_mfma_f32_16x16x32_bf16 v[56:59], v[156:159], v[172:175], v[56:59]
	v_mfma_f32_16x16x32_bf16 v[52:55], v[164:167], v[172:175], v[52:55]
	v_mfma_f32_16x16x32_bf16 v[40:43], v[156:159], v[180:183], v[40:43]
	v_mfma_f32_16x16x32_bf16 v[36:39], v[164:167], v[180:183], v[36:39]
	v_mfma_f32_16x16x32_bf16 v[24:27], v[156:159], v[188:191], v[24:27]
	v_mfma_f32_16x16x32_bf16 v[20:23], v[164:167], v[188:191], v[20:23]
	v_mfma_f32_16x16x32_bf16 v[8:11], v[156:159], v[210:213], v[8:11]
	v_mfma_f32_16x16x32_bf16 v[4:7], v[164:167], v[210:213], v[4:7]
	s_setprio 0
	s_barrier
	s_add_i32 s57, 0, 0x18000
	s_add_i32 s64, 0, 0x1c000
	v_add_u32_e32 v148, s57, v1
	v_add_u32_e32 v164, s64, v1
	ds_read_b128 v[136:139], v148
	ds_read_b128 v[140:143], v148 offset:1024
	ds_read_b128 v[144:147], v148 offset:2048
	ds_read_b128 v[148:151], v148 offset:3072
	ds_read_b128 v[152:155], v164
	ds_read_b128 v[156:159], v164 offset:1024
	ds_read_b128 v[160:163], v164 offset:2048
	ds_read_b128 v[164:167], v164 offset:3072
	s_add_u32 s14, s54, 0x40000
	s_addc_u32 s15, s55, 0
	s_mov_b32 m0, s44
	ds_read_b128 v[168:171], v3 offset:32768
	ds_read_b128 v[172:175], v3 offset:33792
	ds_read_b128 v[176:179], v3 offset:34816
	ds_read_b128 v[180:183], v3 offset:35840
	ds_read_b128 v[184:187], v3 offset:36864
	ds_read_b128 v[188:191], v3 offset:37888
	ds_read_b128 v[192:195], v3 offset:38912
	ds_read_b128 v[210:213], v3 offset:39936
	s_nop 0
	global_load_lds_dwordx4 v132, s[14:15]
	s_mov_b32 m0, s45
	s_nop 0
	global_load_lds_dwordx4 v134, s[14:15]
	s_waitcnt vmcnt(8)
	s_waitcnt lgkmcnt(0)
	s_barrier
	s_setprio 1
	s_waitcnt lgkmcnt(0)
	v_mfma_f32_16x16x32_bf16 v[128:131], v[136:139], v[168:171], v[128:131]
	v_mfma_f32_16x16x32_bf16 v[124:127], v[144:147], v[168:171], v[124:127]
	v_mfma_f32_16x16x32_bf16 v[112:115], v[136:139], v[176:179], v[112:115]
	v_mfma_f32_16x16x32_bf16 v[108:111], v[144:147], v[176:179], v[108:111]
	v_mfma_f32_16x16x32_bf16 v[96:99], v[136:139], v[184:187], v[96:99]
	v_mfma_f32_16x16x32_bf16 v[92:95], v[144:147], v[184:187], v[92:95]
	v_mfma_f32_16x16x32_bf16 v[80:83], v[136:139], v[192:195], v[80:83]
	v_mfma_f32_16x16x32_bf16 v[76:79], v[144:147], v[192:195], v[76:79]
	v_mfma_f32_16x16x32_bf16 v[128:131], v[140:143], v[172:175], v[128:131]
	v_mfma_f32_16x16x32_bf16 v[124:127], v[148:151], v[172:175], v[124:127]
	v_mfma_f32_16x16x32_bf16 v[112:115], v[140:143], v[180:183], v[112:115]
	v_mfma_f32_16x16x32_bf16 v[108:111], v[148:151], v[180:183], v[108:111]
	v_mfma_f32_16x16x32_bf16 v[96:99], v[140:143], v[188:191], v[96:99]
	v_mfma_f32_16x16x32_bf16 v[92:95], v[148:151], v[188:191], v[92:95]
	v_mfma_f32_16x16x32_bf16 v[80:83], v[140:143], v[210:213], v[80:83]
	v_mfma_f32_16x16x32_bf16 v[76:79], v[148:151], v[210:213], v[76:79]
	s_setprio 0
	s_setprio 1
	v_mfma_f32_16x16x32_bf16 v[120:123], v[152:155], v[168:171], v[120:123]
	v_mfma_f32_16x16x32_bf16 v[116:119], v[160:163], v[168:171], v[116:119]
	v_mfma_f32_16x16x32_bf16 v[104:107], v[152:155], v[176:179], v[104:107]
	v_mfma_f32_16x16x32_bf16 v[100:103], v[160:163], v[176:179], v[100:103]
	v_mfma_f32_16x16x32_bf16 v[88:91], v[152:155], v[184:187], v[88:91]
	v_mfma_f32_16x16x32_bf16 v[84:87], v[160:163], v[184:187], v[84:87]
	v_mfma_f32_16x16x32_bf16 v[72:75], v[152:155], v[192:195], v[72:75]
	v_mfma_f32_16x16x32_bf16 v[68:71], v[160:163], v[192:195], v[68:71]
	v_mfma_f32_16x16x32_bf16 v[120:123], v[156:159], v[172:175], v[120:123]
	v_mfma_f32_16x16x32_bf16 v[116:119], v[164:167], v[172:175], v[116:119]
	v_mfma_f32_16x16x32_bf16 v[104:107], v[156:159], v[180:183], v[104:107]
	v_mfma_f32_16x16x32_bf16 v[100:103], v[164:167], v[180:183], v[100:103]
	v_mfma_f32_16x16x32_bf16 v[88:91], v[156:159], v[188:191], v[88:91]
	v_mfma_f32_16x16x32_bf16 v[84:87], v[164:167], v[188:191], v[84:87]
	v_mfma_f32_16x16x32_bf16 v[72:75], v[156:159], v[210:213], v[72:75]
	v_mfma_f32_16x16x32_bf16 v[68:71], v[164:167], v[210:213], v[68:71]
	s_setprio 0
	s_barrier
	s_add_i32 s14, s57, s41
	ds_read_b128 v[168:171], v3 offset:49152
	ds_read_b128 v[172:175], v3 offset:50176
	ds_read_b128 v[176:179], v3 offset:51200
	ds_read_b128 v[180:183], v3 offset:52224
	ds_read_b128 v[184:187], v3 offset:53248
	ds_read_b128 v[188:191], v3 offset:54272
	ds_read_b128 v[192:195], v3 offset:55296
	ds_read_b128 v[210:213], v3 offset:56320
	s_mov_b32 m0, s14
	s_nop 0
	global_load_lds_dwordx4 v132, s[52:53]
	s_add_i32 m0, s14, 0x2000
	s_add_u32 s14, s34, 0x40080
	s_addc_u32 s15, s35, 0
	s_add_i32 s34, s64, s41
	global_load_lds_dwordx4 v134, s[52:53]
	s_mov_b32 m0, s34
	s_nop 0
	global_load_lds_dwordx4 v132, s[14:15]
	s_add_i32 m0, s34, 0x2000
	s_nop 0
	global_load_lds_dwordx4 v134, s[14:15]
	s_mov_b32 m0, s46
	s_nop 0
	global_load_lds_dwordx4 v132, s[22:23]
	s_mov_b32 m0, s47
	s_nop 0
	global_load_lds_dwordx4 v134, s[22:23]
	s_waitcnt vmcnt(8)
	s_waitcnt lgkmcnt(0)
	s_barrier
	s_setprio 1
	s_waitcnt lgkmcnt(0)
	v_mfma_f32_16x16x32_bf16 v[64:67], v[136:139], v[168:171], v[64:67]
	v_mfma_f32_16x16x32_bf16 v[60:63], v[144:147], v[168:171], v[60:63]
	v_mfma_f32_16x16x32_bf16 v[48:51], v[136:139], v[176:179], v[48:51]
	v_mfma_f32_16x16x32_bf16 v[44:47], v[144:147], v[176:179], v[44:47]
	v_mfma_f32_16x16x32_bf16 v[32:35], v[136:139], v[184:187], v[32:35]
	v_mfma_f32_16x16x32_bf16 v[28:31], v[144:147], v[184:187], v[28:31]
	v_mfma_f32_16x16x32_bf16 v[16:19], v[136:139], v[192:195], v[16:19]
	v_mfma_f32_16x16x32_bf16 v[12:15], v[144:147], v[192:195], v[12:15]
	v_mfma_f32_16x16x32_bf16 v[64:67], v[140:143], v[172:175], v[64:67]
	v_mfma_f32_16x16x32_bf16 v[60:63], v[148:151], v[172:175], v[60:63]
	v_mfma_f32_16x16x32_bf16 v[48:51], v[140:143], v[180:183], v[48:51]
	v_mfma_f32_16x16x32_bf16 v[44:47], v[148:151], v[180:183], v[44:47]
	v_mfma_f32_16x16x32_bf16 v[32:35], v[140:143], v[188:191], v[32:35]
	v_mfma_f32_16x16x32_bf16 v[28:31], v[148:151], v[188:191], v[28:31]
	v_mfma_f32_16x16x32_bf16 v[16:19], v[140:143], v[210:213], v[16:19]
	v_mfma_f32_16x16x32_bf16 v[12:15], v[148:151], v[210:213], v[12:15]
	s_setprio 0
	s_setprio 1
	v_mfma_f32_16x16x32_bf16 v[56:59], v[152:155], v[168:171], v[56:59]
	v_mfma_f32_16x16x32_bf16 v[52:55], v[160:163], v[168:171], v[52:55]
	v_mfma_f32_16x16x32_bf16 v[40:43], v[152:155], v[176:179], v[40:43]
	v_mfma_f32_16x16x32_bf16 v[36:39], v[160:163], v[176:179], v[36:39]
	v_mfma_f32_16x16x32_bf16 v[24:27], v[152:155], v[184:187], v[24:27]
	v_mfma_f32_16x16x32_bf16 v[20:23], v[160:163], v[184:187], v[20:23]
	v_mfma_f32_16x16x32_bf16 v[8:11], v[152:155], v[192:195], v[8:11]
	v_mfma_f32_16x16x32_bf16 v[4:7], v[160:163], v[192:195], v[4:7]
	v_mfma_f32_16x16x32_bf16 v[56:59], v[156:159], v[172:175], v[56:59]
	v_mfma_f32_16x16x32_bf16 v[52:55], v[164:167], v[172:175], v[52:55]
	v_mfma_f32_16x16x32_bf16 v[40:43], v[156:159], v[180:183], v[40:43]
	v_mfma_f32_16x16x32_bf16 v[36:39], v[164:167], v[180:183], v[36:39]
	v_mfma_f32_16x16x32_bf16 v[24:27], v[156:159], v[188:191], v[24:27]
	v_mfma_f32_16x16x32_bf16 v[20:23], v[164:167], v[188:191], v[20:23]
	v_mfma_f32_16x16x32_bf16 v[8:11], v[156:159], v[210:213], v[8:11]
	v_mfma_f32_16x16x32_bf16 v[4:7], v[164:167], v[210:213], v[4:7]
	s_setprio 0
	s_barrier
	s_add_i32 s56, s56, 2
	s_cmp_gt_u32 s56, 13
	s_mov_b64 s[14:15], s[20:21]
	s_cbranch_scc0 .LBB0_2766
	s_cmpk_lt_u32 s40, 0x100
	s_cbranch_scc0 .LBB0_2769
	s_barrier

.Lffn1_pf_skip:
	s_lshl_b32 s78, s75, 7
	s_add_u32 s88, s8, s78
	s_addc_u32 s89, s9, 0
	s_add_u32 s79, s88, 0x100
	s_addc_u32 s84, s89, 0
	s_and_b64 s[72:73], s[52:53], exec
	s_cselect_b32 s91, s84, s64
	s_cselect_b32 s90, s79, s65
	s_add_u32 s72, s16, s78
	s_addc_u32 s73, s17, 0
	s_add_u32 s72, s72, 0x100
	s_addc_u32 s73, s73, 0
	s_and_b64 s[52:53], s[52:53], exec
	s_cselect_b32 s73, s73, s63
	s_cselect_b32 s72, s72, s67
	s_add_u32 s52, s90, 0x80
	s_addc_u32 s53, s91, 0
	s_add_u32 s78, s72, 0x80
	s_addc_u32 s79, s73, 0
	s_add_i32 s84, 0, 0x10000
	s_add_i32 s85, 0, 0x14000
	v_add_u32_e32 v148, s84, v1
	v_add_u32_e32 v164, s85, v1
	ds_read_b128 v[136:139], v148
	ds_read_b128 v[140:143], v148 offset:1024
	ds_read_b128 v[144:147], v148 offset:2048
	ds_read_b128 v[148:151], v148 offset:3072
	ds_read_b128 v[152:155], v164
	ds_read_b128 v[156:159], v164 offset:1024
	ds_read_b128 v[160:163], v164 offset:2048
	ds_read_b128 v[164:167], v164 offset:3072
	s_add_u32 s88, s88, 0x40080
	s_addc_u32 s89, s89, 0
	ds_read_b128 v[168:171], v3
	ds_read_b128 v[172:175], v3 offset:1024
	ds_read_b128 v[176:179], v3 offset:2048
	ds_read_b128 v[180:183], v3 offset:3072
	ds_read_b128 v[184:187], v3 offset:4096
	ds_read_b128 v[188:191], v3 offset:5120
	ds_read_b128 v[192:195], v3 offset:6144
	ds_read_b128 v[210:213], v3 offset:7168
	s_add_i32 m0, s95, 0xc000
	s_nop 0
	global_load_lds_dwordx4 v132, s[88:89]
	s_add_i32 m0, s95, 0xe000
	s_nop 0
	global_load_lds_dwordx4 v134, s[88:89]
	s_waitcnt vmcnt(8)
	s_waitcnt lgkmcnt(0)
	s_barrier
	s_setprio 1
	s_waitcnt lgkmcnt(0)
	v_mfma_f32_16x16x32_bf16 v[128:131], v[136:139], v[168:171], v[128:131]
	v_mfma_f32_16x16x32_bf16 v[124:127], v[144:147], v[168:171], v[124:127]
	v_mfma_f32_16x16x32_bf16 v[112:115], v[136:139], v[176:179], v[112:115]
	v_mfma_f32_16x16x32_bf16 v[104:107], v[144:147], v[176:179], v[104:107]
	v_mfma_f32_16x16x32_bf16 v[96:99], v[136:139], v[184:187], v[96:99]
	v_mfma_f32_16x16x32_bf16 v[88:91], v[144:147], v[184:187], v[88:91]
	v_mfma_f32_16x16x32_bf16 v[80:83], v[136:139], v[192:195], v[80:83]
	v_mfma_f32_16x16x32_bf16 v[72:75], v[144:147], v[192:195], v[72:75]
	v_mfma_f32_16x16x32_bf16 v[128:131], v[140:143], v[172:175], v[128:131]
	v_mfma_f32_16x16x32_bf16 v[124:127], v[148:151], v[172:175], v[124:127]
	v_mfma_f32_16x16x32_bf16 v[112:115], v[140:143], v[180:183], v[112:115]
	v_mfma_f32_16x16x32_bf16 v[104:107], v[148:151], v[180:183], v[104:107]
	v_mfma_f32_16x16x32_bf16 v[96:99], v[140:143], v[188:191], v[96:99]
	v_mfma_f32_16x16x32_bf16 v[88:91], v[148:151], v[188:191], v[88:91]
	v_mfma_f32_16x16x32_bf16 v[80:83], v[140:143], v[210:213], v[80:83]
	v_mfma_f32_16x16x32_bf16 v[72:75], v[148:151], v[210:213], v[72:75]
	s_setprio 0
	s_setprio 1
	v_mfma_f32_16x16x32_bf16 v[120:123], v[152:155], v[168:171], v[120:123]
	v_mfma_f32_16x16x32_bf16 v[116:119], v[160:163], v[168:171], v[116:119]
	v_mfma_f32_16x16x32_bf16 v[108:111], v[152:155], v[176:179], v[108:111]
	v_mfma_f32_16x16x32_bf16 v[100:103], v[160:163], v[176:179], v[100:103]
	v_mfma_f32_16x16x32_bf16 v[92:95], v[152:155], v[184:187], v[92:95]
	v_mfma_f32_16x16x32_bf16 v[84:87], v[160:163], v[184:187], v[84:87]
	v_mfma_f32_16x16x32_bf16 v[76:79], v[152:155], v[192:195], v[76:79]
	v_mfma_f32_16x16x32_bf16 v[68:71], v[160:163], v[192:195], v[68:71]
	v_mfma_f32_16x16x32_bf16 v[120:123], v[156:159], v[172:175], v[120:123]
	v_mfma_f32_16x16x32_bf16 v[116:119], v[164:167], v[172:175], v[116:119]
	v_mfma_f32_16x16x32_bf16 v[108:111], v[156:159], v[180:183], v[108:111]
	v_mfma_f32_16x16x32_bf16 v[100:103], v[164:167], v[180:183], v[100:103]
	v_mfma_f32_16x16x32_bf16 v[92:95], v[156:159], v[188:191], v[92:95]
	v_mfma_f32_16x16x32_bf16 v[84:87], v[164:167], v[188:191], v[84:87]
	v_mfma_f32_16x16x32_bf16 v[76:79], v[156:159], v[210:213], v[76:79]
	v_mfma_f32_16x16x32_bf16 v[68:71], v[164:167], v[210:213], v[68:71]
	s_setprio 0
	s_barrier
	s_mov_b64 s[88:89], s[72:73]
	s_add_i32 s92, s84, s94
	ds_read_b128 v[168:171], v3 offset:16384
	ds_read_b128 v[172:175], v3 offset:17408
	ds_read_b128 v[176:179], v3 offset:18432
	ds_read_b128 v[180:183], v3 offset:19456
	ds_read_b128 v[184:187], v3 offset:20480
	ds_read_b128 v[188:191], v3 offset:21504
	ds_read_b128 v[192:195], v3 offset:22528
	ds_read_b128 v[210:213], v3 offset:23552
	s_mov_b32 m0, s92
	s_nop 0
	global_load_lds_dwordx4 v132, s[88:89]
	s_add_i32 m0, s92, 0x2000
	s_nop 0
	global_load_lds_dwordx4 v134, s[88:89]
	s_add_u32 s88, s72, 0x40000
	s_addc_u32 s89, s73, 0
	s_add_i32 s92, s85, s94
	s_mov_b32 m0, s92
	s_nop 0
	global_load_lds_dwordx4 v132, s[88:89]
	s_add_i32 m0, s92, 0x2000
	s_nop 0
	global_load_lds_dwordx4 v134, s[88:89]
	s_mov_b64 s[88:89], s[90:91]
	s_mov_b32 m0, s95
	s_nop 0
	global_load_lds_dwordx4 v132, s[88:89]
	s_mov_b32 m0, s40
	s_nop 0
	global_load_lds_dwordx4 v134, s[88:89]
	s_waitcnt vmcnt(8)
	s_waitcnt lgkmcnt(0)
	s_barrier
	s_setprio 1
	s_waitcnt lgkmcnt(0)
	v_mfma_f32_16x16x32_bf16 v[64:67], v[136:139], v[168:171], v[64:67]
	v_mfma_f32_16x16x32_bf16 v[56:59], v[144:147], v[168:171], v[56:59]
	v_mfma_f32_16x16x32_bf16 v[48:51], v[136:139], v[176:179], v[48:51]
	v_mfma_f32_16x16x32_bf16 v[40:43], v[144:147], v[176:179], v[40:43]
	v_mfma_f32_16x16x32_bf16 v[32:35], v[136:139], v[184:187], v[32:35]
	v_mfma_f32_16x16x32_bf16 v[24:27], v[144:147], v[184:187], v[24:27]
	v_mfma_f32_16x16x32_bf16 v[16:19], v[136:139], v[192:195], v[16:19]
	v_mfma_f32_16x16x32_bf16 v[8:11], v[144:147], v[192:195], v[8:11]
	v_mfma_f32_16x16x32_bf16 v[64:67], v[140:143], v[172:175], v[64:67]
	v_mfma_f32_16x16x32_bf16 v[56:59], v[148:151], v[172:175], v[56:59]
	v_mfma_f32_16x16x32_bf16 v[48:51], v[140:143], v[180:183], v[48:51]
	v_mfma_f32_16x16x32_bf16 v[40:43], v[148:151], v[180:183], v[40:43]
	v_mfma_f32_16x16x32_bf16 v[32:35], v[140:143], v[188:191], v[32:35]
	v_mfma_f32_16x16x32_bf16 v[24:27], v[148:151], v[188:191], v[24:27]
	v_mfma_f32_16x16x32_bf16 v[16:19], v[140:143], v[210:213], v[16:19]
	v_mfma_f32_16x16x32_bf16 v[8:11], v[148:151], v[210:213], v[8:11]
	s_setprio 0
	s_setprio 1
	v_mfma_f32_16x16x32_bf16 v[60:63], v[152:155], v[168:171], v[60:63]
	v_mfma_f32_16x16x32_bf16 v[52:55], v[160:163], v[168:171], v[52:55]
	v_mfma_f32_16x16x32_bf16 v[44:47], v[152:155], v[176:179], v[44:47]
	v_mfma_f32_16x16x32_bf16 v[36:39], v[160:163], v[176:179], v[36:39]
	v_mfma_f32_16x16x32_bf16 v[28:31], v[152:155], v[184:187], v[28:31]
	v_mfma_f32_16x16x32_bf16 v[20:23], v[160:163], v[184:187], v[20:23]
	v_mfma_f32_16x16x32_bf16 v[12:15], v[152:155], v[192:195], v[12:15]
	v_mfma_f32_16x16x32_bf16 v[4:7], v[160:163], v[192:195], v[4:7]
	v_mfma_f32_16x16x32_bf16 v[60:63], v[156:159], v[172:175], v[60:63]
	v_mfma_f32_16x16x32_bf16 v[52:55], v[164:167], v[172:175], v[52:55]
	v_mfma_f32_16x16x32_bf16 v[44:47], v[156:159], v[180:183], v[44:47]
	v_mfma_f32_16x16x32_bf16 v[36:39], v[164:167], v[180:183], v[36:39]
	v_mfma_f32_16x16x32_bf16 v[28:31], v[156:159], v[188:191], v[28:31]
	v_mfma_f32_16x16x32_bf16 v[20:23], v[164:167], v[188:191], v[20:23]
	v_mfma_f32_16x16x32_bf16 v[12:15], v[156:159], v[210:213], v[12:15]
	v_mfma_f32_16x16x32_bf16 v[4:7], v[164:167], v[210:213], v[4:7]
	s_setprio 0
	s_barrier
	s_add_i32 s88, 0, 0x18000
	s_add_i32 s89, 0, 0x1c000
	v_add_u32_e32 v148, s88, v1
	v_add_u32_e32 v164, s89, v1
	ds_read_b128 v[136:139], v148
	ds_read_b128 v[140:143], v148 offset:1024
	ds_read_b128 v[144:147], v148 offset:2048
	ds_read_b128 v[148:151], v148 offset:3072
	ds_read_b128 v[152:155], v164
	ds_read_b128 v[156:159], v164 offset:1024
	ds_read_b128 v[160:163], v164 offset:2048
	ds_read_b128 v[164:167], v164 offset:3072
	s_add_u32 s90, s90, 0x40000
	s_addc_u32 s91, s91, 0
	s_mov_b32 m0, s41
	ds_read_b128 v[168:171], v3 offset:32768
	ds_read_b128 v[172:175], v3 offset:33792
	ds_read_b128 v[176:179], v3 offset:34816
	ds_read_b128 v[180:183], v3 offset:35840
	ds_read_b128 v[184:187], v3 offset:36864
	ds_read_b128 v[188:191], v3 offset:37888
	ds_read_b128 v[192:195], v3 offset:38912
	ds_read_b128 v[210:213], v3 offset:39936
	s_nop 0
	global_load_lds_dwordx4 v132, s[90:91]
	s_mov_b32 m0, s42
	s_nop 0
	global_load_lds_dwordx4 v134, s[90:91]
	s_waitcnt vmcnt(8)
	s_waitcnt lgkmcnt(0)
	s_barrier
	s_setprio 1
	s_waitcnt lgkmcnt(0)
	v_mfma_f32_16x16x32_bf16 v[128:131], v[136:139], v[168:171], v[128:131]
	v_mfma_f32_16x16x32_bf16 v[124:127], v[144:147], v[168:171], v[124:127]
	v_mfma_f32_16x16x32_bf16 v[112:115], v[136:139], v[176:179], v[112:115]
	v_mfma_f32_16x16x32_bf16 v[104:107], v[144:147], v[176:179], v[104:107]
	v_mfma_f32_16x16x32_bf16 v[96:99], v[136:139], v[184:187], v[96:99]
	v_mfma_f32_16x16x32_bf16 v[88:91], v[144:147], v[184:187], v[88:91]
	v_mfma_f32_16x16x32_bf16 v[80:83], v[136:139], v[192:195], v[80:83]
	v_mfma_f32_16x16x32_bf16 v[72:75], v[144:147], v[192:195], v[72:75]
	v_mfma_f32_16x16x32_bf16 v[128:131], v[140:143], v[172:175], v[128:131]
	v_mfma_f32_16x16x32_bf16 v[124:127], v[148:151], v[172:175], v[124:127]
	v_mfma_f32_16x16x32_bf16 v[112:115], v[140:143], v[180:183], v[112:115]
	v_mfma_f32_16x16x32_bf16 v[104:107], v[148:151], v[180:183], v[104:107]
	v_mfma_f32_16x16x32_bf16 v[96:99], v[140:143], v[188:191], v[96:99]
	v_mfma_f32_16x16x32_bf16 v[88:91], v[148:151], v[188:191], v[88:91]
	v_mfma_f32_16x16x32_bf16 v[80:83], v[140:143], v[210:213], v[80:83]
	v_mfma_f32_16x16x32_bf16 v[72:75], v[148:151], v[210:213], v[72:75]
	s_setprio 0
	s_setprio 1
	v_mfma_f32_16x16x32_bf16 v[120:123], v[152:155], v[168:171], v[120:123]
	v_mfma_f32_16x16x32_bf16 v[116:119], v[160:163], v[168:171], v[116:119]
	v_mfma_f32_16x16x32_bf16 v[108:111], v[152:155], v[176:179], v[108:111]
	v_mfma_f32_16x16x32_bf16 v[100:103], v[160:163], v[176:179], v[100:103]
	v_mfma_f32_16x16x32_bf16 v[92:95], v[152:155], v[184:187], v[92:95]
	v_mfma_f32_16x16x32_bf16 v[84:87], v[160:163], v[184:187], v[84:87]
	v_mfma_f32_16x16x32_bf16 v[76:79], v[152:155], v[192:195], v[76:79]
	v_mfma_f32_16x16x32_bf16 v[68:71], v[160:163], v[192:195], v[68:71]
	v_mfma_f32_16x16x32_bf16 v[120:123], v[156:159], v[172:175], v[120:123]
	v_mfma_f32_16x16x32_bf16 v[116:119], v[164:167], v[172:175], v[116:119]
	v_mfma_f32_16x16x32_bf16 v[108:111], v[156:159], v[180:183], v[108:111]
	v_mfma_f32_16x16x32_bf16 v[100:103], v[164:167], v[180:183], v[100:103]
	v_mfma_f32_16x16x32_bf16 v[92:95], v[156:159], v[188:191], v[92:95]
	v_mfma_f32_16x16x32_bf16 v[84:87], v[164:167], v[188:191], v[84:87]
	v_mfma_f32_16x16x32_bf16 v[76:79], v[156:159], v[210:213], v[76:79]
	v_mfma_f32_16x16x32_bf16 v[68:71], v[164:167], v[210:213], v[68:71]
	s_setprio 0
	s_barrier
	s_add_i32 s90, s88, s94
	ds_read_b128 v[168:171], v3 offset:49152
	ds_read_b128 v[172:175], v3 offset:50176
	ds_read_b128 v[176:179], v3 offset:51200
	ds_read_b128 v[180:183], v3 offset:52224
	ds_read_b128 v[184:187], v3 offset:53248
	ds_read_b128 v[188:191], v3 offset:54272
	ds_read_b128 v[192:195], v3 offset:55296
	ds_read_b128 v[210:213], v3 offset:56320
	s_mov_b32 m0, s90
	s_nop 0
	global_load_lds_dwordx4 v132, s[78:79]
	s_add_i32 m0, s90, 0x2000
	s_add_u32 s72, s72, 0x40080
	s_addc_u32 s73, s73, 0
	global_load_lds_dwordx4 v134, s[78:79]
	s_add_i32 s78, s89, s94
	s_mov_b32 m0, s78
	s_nop 0
	global_load_lds_dwordx4 v132, s[72:73]
	s_add_i32 m0, s78, 0x2000
	s_nop 0
	global_load_lds_dwordx4 v134, s[72:73]
	s_mov_b32 m0, s43
	s_nop 0
	global_load_lds_dwordx4 v132, s[52:53]
	s_mov_b32 m0, s97
	s_nop 0
	global_load_lds_dwordx4 v134, s[52:53]
	s_waitcnt vmcnt(8)
	s_waitcnt lgkmcnt(0)
	s_barrier
	s_setprio 1
	s_waitcnt lgkmcnt(0)
	v_mfma_f32_16x16x32_bf16 v[64:67], v[136:139], v[168:171], v[64:67]
	v_mfma_f32_16x16x32_bf16 v[56:59], v[144:147], v[168:171], v[56:59]
	v_mfma_f32_16x16x32_bf16 v[48:51], v[136:139], v[176:179], v[48:51]
	v_mfma_f32_16x16x32_bf16 v[40:43], v[144:147], v[176:179], v[40:43]
	v_mfma_f32_16x16x32_bf16 v[32:35], v[136:139], v[184:187], v[32:35]
	v_mfma_f32_16x16x32_bf16 v[24:27], v[144:147], v[184:187], v[24:27]
	v_mfma_f32_16x16x32_bf16 v[16:19], v[136:139], v[192:195], v[16:19]
	v_mfma_f32_16x16x32_bf16 v[8:11], v[144:147], v[192:195], v[8:11]
	v_mfma_f32_16x16x32_bf16 v[64:67], v[140:143], v[172:175], v[64:67]
	v_mfma_f32_16x16x32_bf16 v[56:59], v[148:151], v[172:175], v[56:59]
	v_mfma_f32_16x16x32_bf16 v[48:51], v[140:143], v[180:183], v[48:51]
	v_mfma_f32_16x16x32_bf16 v[40:43], v[148:151], v[180:183], v[40:43]
	v_mfma_f32_16x16x32_bf16 v[32:35], v[140:143], v[188:191], v[32:35]
	v_mfma_f32_16x16x32_bf16 v[24:27], v[148:151], v[188:191], v[24:27]
	v_mfma_f32_16x16x32_bf16 v[16:19], v[140:143], v[210:213], v[16:19]
	v_mfma_f32_16x16x32_bf16 v[8:11], v[148:151], v[210:213], v[8:11]
	s_setprio 0
	s_setprio 1
	v_mfma_f32_16x16x32_bf16 v[60:63], v[152:155], v[168:171], v[60:63]
	v_mfma_f32_16x16x32_bf16 v[52:55], v[160:163], v[168:171], v[52:55]
	v_mfma_f32_16x16x32_bf16 v[44:47], v[152:155], v[176:179], v[44:47]
	v_mfma_f32_16x16x32_bf16 v[36:39], v[160:163], v[176:179], v[36:39]
	v_mfma_f32_16x16x32_bf16 v[28:31], v[152:155], v[184:187], v[28:31]
	v_mfma_f32_16x16x32_bf16 v[20:23], v[160:163], v[184:187], v[20:23]
	v_mfma_f32_16x16x32_bf16 v[12:15], v[152:155], v[192:195], v[12:15]
	v_mfma_f32_16x16x32_bf16 v[4:7], v[160:163], v[192:195], v[4:7]
	v_mfma_f32_16x16x32_bf16 v[60:63], v[156:159], v[172:175], v[60:63]
	v_mfma_f32_16x16x32_bf16 v[52:55], v[164:167], v[172:175], v[52:55]
	v_mfma_f32_16x16x32_bf16 v[44:47], v[156:159], v[180:183], v[44:47]
	v_mfma_f32_16x16x32_bf16 v[36:39], v[164:167], v[180:183], v[36:39]
	v_mfma_f32_16x16x32_bf16 v[28:31], v[156:159], v[188:191], v[28:31]
	v_mfma_f32_16x16x32_bf16 v[20:23], v[164:167], v[188:191], v[20:23]
	v_mfma_f32_16x16x32_bf16 v[12:15], v[156:159], v[210:213], v[12:15]
	v_mfma_f32_16x16x32_bf16 v[4:7], v[164:167], v[210:213], v[4:7]
	s_setprio 0
	s_barrier
	s_add_i32 s52, s75, 2
	s_cmp_gt_u32 s75, 13
	s_mov_b32 s75, s52
	s_cbranch_scc1 .LBB0_2848

.LBB0_3050:
	s_add_u32 s30, s22, s24
	s_addc_u32 s31, s23, s25
	s_add_u32 s40, s30, 0x100
	s_addc_u32 s41, s31, 0
	s_and_b64 s[28:29], s[26:27], exec
	s_cselect_b32 s43, s19, s41
	s_cselect_b32 s42, s18, s40
	s_add_u32 s24, s14, s24
	s_addc_u32 s25, s15, s25
	s_add_u32 s28, s24, 0x100
	s_addc_u32 s29, s25, 0
	s_add_u32 s24, s42, 0x80
	s_addc_u32 s25, s43, 0
	s_and_b64 s[26:27], s[26:27], exec
	s_cselect_b32 s45, s1, s29
	s_cselect_b32 s44, s9, s28
	s_add_u32 s46, s30, 0x12080
	s_addc_u32 s47, s31, 0
	s_add_i32 s95, s84, s57
	s_add_i32 m0, s63, 0xc000
	s_add_i32 s97, s63, 0xe000
	s_add_i32 s94, s95, 0x2000
	s_add_u32 s40, s44, 0x10000
	s_addc_u32 s41, s45, 0
	s_add_i32 s93, s85, s57
	s_add_i32 s92, s93, 0x2000
	v_add_u32_e32 v152, s84, v1
	s_add_u32 s30, s42, 0x12000
	ds_read_b128 v[140:143], v152
	ds_read_b128 v[144:147], v152 offset:1024
	ds_read_b128 v[148:151], v152 offset:2048
	ds_read_b128 v[152:155], v152 offset:3072
	s_addc_u32 s31, s43, 0
	s_add_u32 s28, s44, 0x80
	s_addc_u32 s29, s45, 0
	s_add_i32 s91, s88, s57
	s_add_i32 s90, s91, 0x2000
	s_add_u32 s26, s44, 0x10080
	s_addc_u32 s27, s45, 0
	s_add_i32 s87, s89, s57
	s_add_i32 s86, s87, 0x2000
	ds_read_b128 v[156:159], v3
	ds_read_b128 v[160:163], v3 offset:1024
	ds_read_b128 v[164:167], v3 offset:2048
	ds_read_b128 v[168:171], v3 offset:3072
	ds_read_b128 v[172:175], v3 offset:4096
	ds_read_b128 v[176:179], v3 offset:5120
	ds_read_b128 v[180:183], v3 offset:6144
	ds_read_b128 v[184:187], v3 offset:7168
	s_nop 0
	global_load_lds_dwordx4 v132, s[46:47]
	s_mov_b32 m0, s97
	s_nop 0
	global_load_lds_dwordx4 v136, s[46:47]
	s_waitcnt lgkmcnt(8)
	s_barrier
	s_waitcnt lgkmcnt(0)
	s_setprio 1
	s_waitcnt lgkmcnt(0)
	v_mfma_f32_16x16x32_bf16 v[128:131], v[140:143], v[156:159], v[128:131]
	v_mfma_f32_16x16x32_bf16 v[124:127], v[148:151], v[156:159], v[124:127]
	v_mfma_f32_16x16x32_bf16 v[112:115], v[140:143], v[164:167], v[112:115]
	v_mfma_f32_16x16x32_bf16 v[108:111], v[148:151], v[164:167], v[108:111]
	v_mfma_f32_16x16x32_bf16 v[96:99], v[140:143], v[172:175], v[96:99]
	v_mfma_f32_16x16x32_bf16 v[92:95], v[148:151], v[172:175], v[92:95]
	v_mfma_f32_16x16x32_bf16 v[80:83], v[140:143], v[180:183], v[80:83]
	v_mfma_f32_16x16x32_bf16 v[76:79], v[148:151], v[180:183], v[76:79]
	v_mfma_f32_16x16x32_bf16 v[128:131], v[144:147], v[160:163], v[128:131]
	v_mfma_f32_16x16x32_bf16 v[124:127], v[152:155], v[160:163], v[124:127]
	v_mfma_f32_16x16x32_bf16 v[112:115], v[144:147], v[168:171], v[112:115]
	v_mfma_f32_16x16x32_bf16 v[108:111], v[152:155], v[168:171], v[108:111]
	v_mfma_f32_16x16x32_bf16 v[96:99], v[144:147], v[176:179], v[96:99]
	v_mfma_f32_16x16x32_bf16 v[92:95], v[152:155], v[176:179], v[92:95]
	v_mfma_f32_16x16x32_bf16 v[80:83], v[144:147], v[184:187], v[80:83]
	v_mfma_f32_16x16x32_bf16 v[76:79], v[152:155], v[184:187], v[76:79]
	s_setprio 0
	s_barrier
	v_add_u32_e32 v196, s85, v1
	s_mov_b32 m0, s95
	ds_read_b128 v[188:191], v196
	ds_read_b128 v[192:195], v196 offset:1024
	ds_read_b128 v[210:213], v196 offset:2048
	ds_read_b128 v[214:217], v196 offset:3072
	s_nop 0
	global_load_lds_dwordx4 v134, s[44:45]
	s_mov_b32 m0, s94
	s_nop 0
	global_load_lds_dwordx4 v138, s[44:45]
	s_barrier
	s_waitcnt lgkmcnt(0)
	s_setprio 1
	s_waitcnt lgkmcnt(0)
	v_mfma_f32_16x16x32_bf16 v[120:123], v[188:191], v[156:159], v[120:123]
	v_mfma_f32_16x16x32_bf16 v[116:119], v[210:213], v[156:159], v[116:119]
	v_mfma_f32_16x16x32_bf16 v[104:107], v[188:191], v[164:167], v[104:107]
	v_mfma_f32_16x16x32_bf16 v[100:103], v[210:213], v[164:167], v[100:103]
	v_mfma_f32_16x16x32_bf16 v[88:91], v[188:191], v[172:175], v[88:91]
	v_mfma_f32_16x16x32_bf16 v[84:87], v[210:213], v[172:175], v[84:87]
	v_mfma_f32_16x16x32_bf16 v[72:75], v[188:191], v[180:183], v[72:75]
	v_mfma_f32_16x16x32_bf16 v[68:71], v[210:213], v[180:183], v[68:71]
	v_mfma_f32_16x16x32_bf16 v[120:123], v[192:195], v[160:163], v[120:123]
	v_mfma_f32_16x16x32_bf16 v[116:119], v[214:217], v[160:163], v[116:119]
	v_mfma_f32_16x16x32_bf16 v[104:107], v[192:195], v[168:171], v[104:107]
	v_mfma_f32_16x16x32_bf16 v[100:103], v[214:217], v[168:171], v[100:103]
	v_mfma_f32_16x16x32_bf16 v[88:91], v[192:195], v[176:179], v[88:91]
	v_mfma_f32_16x16x32_bf16 v[84:87], v[214:217], v[176:179], v[84:87]
	v_mfma_f32_16x16x32_bf16 v[72:75], v[192:195], v[184:187], v[72:75]
	v_mfma_f32_16x16x32_bf16 v[68:71], v[214:217], v[184:187], v[68:71]
	s_setprio 0
	s_mov_b32 m0, s63
	s_barrier
	ds_read_b128 v[156:159], v3 offset:16384
	ds_read_b128 v[160:163], v3 offset:17408
	ds_read_b128 v[164:167], v3 offset:18432
	ds_read_b128 v[168:171], v3 offset:19456
	ds_read_b128 v[172:175], v3 offset:20480
	ds_read_b128 v[176:179], v3 offset:21504
	ds_read_b128 v[180:183], v3 offset:22528
	ds_read_b128 v[184:187], v3 offset:23552
	s_nop 0
	global_load_lds_dwordx4 v132, s[42:43]
	s_mov_b32 m0, s64
	s_nop 0
	global_load_lds_dwordx4 v136, s[42:43]
	s_barrier
	s_waitcnt lgkmcnt(0)
	s_setprio 1
	s_waitcnt lgkmcnt(0)
	v_mfma_f32_16x16x32_bf16 v[64:67], v[140:143], v[156:159], v[64:67]
	v_mfma_f32_16x16x32_bf16 v[60:63], v[148:151], v[156:159], v[60:63]
	v_mfma_f32_16x16x32_bf16 v[48:51], v[140:143], v[164:167], v[48:51]
	v_mfma_f32_16x16x32_bf16 v[44:47], v[148:151], v[164:167], v[44:47]
	v_mfma_f32_16x16x32_bf16 v[32:35], v[140:143], v[172:175], v[32:35]
	v_mfma_f32_16x16x32_bf16 v[28:31], v[148:151], v[172:175], v[28:31]
	v_mfma_f32_16x16x32_bf16 v[16:19], v[140:143], v[180:183], v[16:19]
	v_mfma_f32_16x16x32_bf16 v[12:15], v[148:151], v[180:183], v[12:15]
	v_mfma_f32_16x16x32_bf16 v[64:67], v[144:147], v[160:163], v[64:67]
	v_mfma_f32_16x16x32_bf16 v[60:63], v[152:155], v[160:163], v[60:63]
	v_mfma_f32_16x16x32_bf16 v[48:51], v[144:147], v[168:171], v[48:51]
	v_mfma_f32_16x16x32_bf16 v[44:47], v[152:155], v[168:171], v[44:47]
	v_mfma_f32_16x16x32_bf16 v[32:35], v[144:147], v[176:179], v[32:35]
	v_mfma_f32_16x16x32_bf16 v[28:31], v[152:155], v[176:179], v[28:31]
	v_mfma_f32_16x16x32_bf16 v[16:19], v[144:147], v[184:187], v[16:19]
	v_mfma_f32_16x16x32_bf16 v[12:15], v[152:155], v[184:187], v[12:15]
	s_setprio 0
	s_barrier
	s_mov_b32 m0, s93
	s_nop 0
	global_load_lds_dwordx4 v134, s[40:41]
	s_mov_b32 m0, s92
	s_nop 0
	global_load_lds_dwordx4 v138, s[40:41]
	s_waitcnt vmcnt(6)
	s_barrier
	s_setprio 1
	v_mfma_f32_16x16x32_bf16 v[56:59], v[188:191], v[156:159], v[56:59]
	v_mfma_f32_16x16x32_bf16 v[52:55], v[210:213], v[156:159], v[52:55]
	v_mfma_f32_16x16x32_bf16 v[40:43], v[188:191], v[164:167], v[40:43]
	v_mfma_f32_16x16x32_bf16 v[36:39], v[210:213], v[164:167], v[36:39]
	v_mfma_f32_16x16x32_bf16 v[24:27], v[188:191], v[172:175], v[24:27]
	v_mfma_f32_16x16x32_bf16 v[20:23], v[210:213], v[172:175], v[20:23]
	v_mfma_f32_16x16x32_bf16 v[8:11], v[188:191], v[180:183], v[8:11]
	v_mfma_f32_16x16x32_bf16 v[4:7], v[210:213], v[180:183], v[4:7]
	v_mfma_f32_16x16x32_bf16 v[56:59], v[192:195], v[160:163], v[56:59]
	v_mfma_f32_16x16x32_bf16 v[52:55], v[214:217], v[160:163], v[52:55]
	v_mfma_f32_16x16x32_bf16 v[40:43], v[192:195], v[168:171], v[40:43]
	v_mfma_f32_16x16x32_bf16 v[36:39], v[214:217], v[168:171], v[36:39]
	v_mfma_f32_16x16x32_bf16 v[24:27], v[192:195], v[176:179], v[24:27]
	v_mfma_f32_16x16x32_bf16 v[20:23], v[214:217], v[176:179], v[20:23]
	v_mfma_f32_16x16x32_bf16 v[8:11], v[192:195], v[184:187], v[8:11]
	v_mfma_f32_16x16x32_bf16 v[4:7], v[214:217], v[184:187], v[4:7]
	s_setprio 0
	v_add_u32_e32 v152, s88, v1
	s_barrier
	ds_read_b128 v[140:143], v152
	ds_read_b128 v[144:147], v152 offset:1024
	ds_read_b128 v[148:151], v152 offset:2048
	ds_read_b128 v[152:155], v152 offset:3072
	s_mov_b32 m0, s65
	ds_read_b128 v[156:159], v3 offset:32768
	ds_read_b128 v[160:163], v3 offset:33792
	ds_read_b128 v[164:167], v3 offset:34816
	ds_read_b128 v[168:171], v3 offset:35840
	ds_read_b128 v[172:175], v3 offset:36864
	ds_read_b128 v[176:179], v3 offset:37888
	ds_read_b128 v[180:183], v3 offset:38912
	ds_read_b128 v[184:187], v3 offset:39936
	s_nop 0
	global_load_lds_dwordx4 v132, s[30:31]
	s_mov_b32 m0, s67
	s_nop 0
	global_load_lds_dwordx4 v136, s[30:31]
	s_waitcnt lgkmcnt(8)
	s_barrier
	s_waitcnt lgkmcnt(0)
	s_setprio 1
	s_waitcnt lgkmcnt(0)
	v_mfma_f32_16x16x32_bf16 v[128:131], v[140:143], v[156:159], v[128:131]
	v_mfma_f32_16x16x32_bf16 v[124:127], v[148:151], v[156:159], v[124:127]
	v_mfma_f32_16x16x32_bf16 v[112:115], v[140:143], v[164:167], v[112:115]
	v_mfma_f32_16x16x32_bf16 v[108:111], v[148:151], v[164:167], v[108:111]
	v_mfma_f32_16x16x32_bf16 v[96:99], v[140:143], v[172:175], v[96:99]
	v_mfma_f32_16x16x32_bf16 v[92:95], v[148:151], v[172:175], v[92:95]
	v_mfma_f32_16x16x32_bf16 v[80:83], v[140:143], v[180:183], v[80:83]
	v_mfma_f32_16x16x32_bf16 v[76:79], v[148:151], v[180:183], v[76:79]
	v_mfma_f32_16x16x32_bf16 v[128:131], v[144:147], v[160:163], v[128:131]
	v_mfma_f32_16x16x32_bf16 v[124:127], v[152:155], v[160:163], v[124:127]
	v_mfma_f32_16x16x32_bf16 v[112:115], v[144:147], v[168:171], v[112:115]
	v_mfma_f32_16x16x32_bf16 v[108:111], v[152:155], v[168:171], v[108:111]
	v_mfma_f32_16x16x32_bf16 v[96:99], v[144:147], v[176:179], v[96:99]
	v_mfma_f32_16x16x32_bf16 v[92:95], v[152:155], v[176:179], v[92:95]
	v_mfma_f32_16x16x32_bf16 v[80:83], v[144:147], v[184:187], v[80:83]
	v_mfma_f32_16x16x32_bf16 v[76:79], v[152:155], v[184:187], v[76:79]
	s_setprio 0
	s_barrier
	v_add_u32_e32 v196, s89, v1
	s_mov_b32 m0, s91
	ds_read_b128 v[188:191], v196
	ds_read_b128 v[192:195], v196 offset:1024
	ds_read_b128 v[210:213], v196 offset:2048
	ds_read_b128 v[214:217], v196 offset:3072
	s_nop 0
	global_load_lds_dwordx4 v134, s[28:29]
	s_mov_b32 m0, s90
	s_nop 0
	global_load_lds_dwordx4 v138, s[28:29]
	s_barrier
	s_waitcnt lgkmcnt(0)
	s_setprio 1
	s_waitcnt lgkmcnt(0)
	v_mfma_f32_16x16x32_bf16 v[120:123], v[188:191], v[156:159], v[120:123]
	v_mfma_f32_16x16x32_bf16 v[116:119], v[210:213], v[156:159], v[116:119]
	v_mfma_f32_16x16x32_bf16 v[104:107], v[188:191], v[164:167], v[104:107]
	v_mfma_f32_16x16x32_bf16 v[100:103], v[210:213], v[164:167], v[100:103]
	v_mfma_f32_16x16x32_bf16 v[88:91], v[188:191], v[172:175], v[88:91]
	v_mfma_f32_16x16x32_bf16 v[84:87], v[210:213], v[172:175], v[84:87]
	v_mfma_f32_16x16x32_bf16 v[72:75], v[188:191], v[180:183], v[72:75]
	v_mfma_f32_16x16x32_bf16 v[68:71], v[210:213], v[180:183], v[68:71]
	v_mfma_f32_16x16x32_bf16 v[120:123], v[192:195], v[160:163], v[120:123]
	v_mfma_f32_16x16x32_bf16 v[116:119], v[214:217], v[160:163], v[116:119]
	v_mfma_f32_16x16x32_bf16 v[104:107], v[192:195], v[168:171], v[104:107]
	v_mfma_f32_16x16x32_bf16 v[100:103], v[214:217], v[168:171], v[100:103]
	v_mfma_f32_16x16x32_bf16 v[88:91], v[192:195], v[176:179], v[88:91]
	v_mfma_f32_16x16x32_bf16 v[84:87], v[214:217], v[176:179], v[84:87]
	v_mfma_f32_16x16x32_bf16 v[72:75], v[192:195], v[184:187], v[72:75]
	v_mfma_f32_16x16x32_bf16 v[68:71], v[214:217], v[184:187], v[68:71]
	s_setprio 0
	s_mov_b32 m0, s75
	s_barrier
	ds_read_b128 v[156:159], v3 offset:49152
	ds_read_b128 v[160:163], v3 offset:50176
	ds_read_b128 v[164:167], v3 offset:51200
	ds_read_b128 v[168:171], v3 offset:52224
	ds_read_b128 v[172:175], v3 offset:53248
	ds_read_b128 v[176:179], v3 offset:54272
	ds_read_b128 v[180:183], v3 offset:55296
	ds_read_b128 v[184:187], v3 offset:56320
	s_nop 0
	global_load_lds_dwordx4 v132, s[24:25]
	s_mov_b32 m0, s78
	s_nop 0
	global_load_lds_dwordx4 v136, s[24:25]
	s_barrier
	s_waitcnt lgkmcnt(0)
	s_setprio 1
	s_waitcnt lgkmcnt(0)
	v_mfma_f32_16x16x32_bf16 v[64:67], v[140:143], v[156:159], v[64:67]
	v_mfma_f32_16x16x32_bf16 v[60:63], v[148:151], v[156:159], v[60:63]
	v_mfma_f32_16x16x32_bf16 v[48:51], v[140:143], v[164:167], v[48:51]
	v_mfma_f32_16x16x32_bf16 v[44:47], v[148:151], v[164:167], v[44:47]
	v_mfma_f32_16x16x32_bf16 v[32:35], v[140:143], v[172:175], v[32:35]
	v_mfma_f32_16x16x32_bf16 v[28:31], v[148:151], v[172:175], v[28:31]
	v_mfma_f32_16x16x32_bf16 v[16:19], v[140:143], v[180:183], v[16:19]
	v_mfma_f32_16x16x32_bf16 v[12:15], v[148:151], v[180:183], v[12:15]
	v_mfma_f32_16x16x32_bf16 v[64:67], v[144:147], v[160:163], v[64:67]
	v_mfma_f32_16x16x32_bf16 v[60:63], v[152:155], v[160:163], v[60:63]
	v_mfma_f32_16x16x32_bf16 v[48:51], v[144:147], v[168:171], v[48:51]
	v_mfma_f32_16x16x32_bf16 v[44:47], v[152:155], v[168:171], v[44:47]
	v_mfma_f32_16x16x32_bf16 v[32:35], v[144:147], v[176:179], v[32:35]
	v_mfma_f32_16x16x32_bf16 v[28:31], v[152:155], v[176:179], v[28:31]
	v_mfma_f32_16x16x32_bf16 v[16:19], v[144:147], v[184:187], v[16:19]
	v_mfma_f32_16x16x32_bf16 v[12:15], v[152:155], v[184:187], v[12:15]
	s_setprio 0
	s_barrier
	s_mov_b32 m0, s87
	s_nop 0
	global_load_lds_dwordx4 v134, s[26:27]
	s_mov_b32 m0, s86
	s_nop 0
	global_load_lds_dwordx4 v138, s[26:27]
	s_waitcnt vmcnt(6)
	s_barrier
	s_setprio 1
	v_mfma_f32_16x16x32_bf16 v[56:59], v[188:191], v[156:159], v[56:59]
	v_mfma_f32_16x16x32_bf16 v[52:55], v[210:213], v[156:159], v[52:55]
	v_mfma_f32_16x16x32_bf16 v[40:43], v[188:191], v[164:167], v[40:43]
	v_mfma_f32_16x16x32_bf16 v[36:39], v[210:213], v[164:167], v[36:39]
	v_mfma_f32_16x16x32_bf16 v[24:27], v[188:191], v[172:175], v[24:27]
	v_mfma_f32_16x16x32_bf16 v[20:23], v[210:213], v[172:175], v[20:23]
	v_mfma_f32_16x16x32_bf16 v[8:11], v[188:191], v[180:183], v[8:11]
	v_mfma_f32_16x16x32_bf16 v[4:7], v[210:213], v[180:183], v[4:7]
	v_mfma_f32_16x16x32_bf16 v[56:59], v[192:195], v[160:163], v[56:59]
	v_mfma_f32_16x16x32_bf16 v[52:55], v[214:217], v[160:163], v[52:55]
	v_mfma_f32_16x16x32_bf16 v[40:43], v[192:195], v[168:171], v[40:43]
	v_mfma_f32_16x16x32_bf16 v[36:39], v[214:217], v[168:171], v[36:39]
	v_mfma_f32_16x16x32_bf16 v[24:27], v[192:195], v[176:179], v[24:27]
	v_mfma_f32_16x16x32_bf16 v[20:23], v[214:217], v[176:179], v[20:23]
	v_mfma_f32_16x16x32_bf16 v[8:11], v[192:195], v[184:187], v[8:11]
	v_mfma_f32_16x16x32_bf16 v[4:7], v[214:217], v[184:187], v[4:7]
	s_setprio 0
	s_andn2_b64 vcc, exec, s[16:17]
	s_mov_b64 s[26:27], -1
	s_mov_b64 s[16:17], 0
	s_mov_b64 s[24:25], 0x100
	s_barrier
	s_cbranch_vccz .LBB0_3050
	v_mov_b32_e32 v141, v0
	s_ashr_i32 s1, s0, 31
	v_readfirstlane_b32 s9, v141
	s_bfe_u32 s24, s9, 0x20006
	s_ashr_i32 s9, s9, 2
	s_and_b32 s14, s9, 0xffffffc0
	s_ashr_i32 s15, s14, 31
	s_lshl_b64 s[16:17], s[0:1], 10
	s_add_u32 s9, s68, s16
	s_addc_u32 s23, s72, s17
	s_lshl_b64 s[16:17], s[14:15], 2
	v_and_b32_e32 v142, 15, v141
	s_add_u32 s22, s9, s16
	s_addc_u32 s23, s23, s17
	v_lshlrev_b32_e32 v140, 2, v142
	global_load_dword v150, v140, s[22:23] offset:64
	global_load_dword v149, v140, s[22:23] offset:128
	global_load_dword v148, v140, s[22:23] offset:192
	global_load_dword v147, v140, s[22:23] offset:512
	global_load_dword v146, v140, s[22:23] offset:576
	global_load_dword v145, v140, s[22:23] offset:640
	global_load_dword v144, v140, s[22:23] offset:704
	v_mul_f32_e32 v129, v129, v129
	v_mul_f32_e32 v125, v125, v125
	v_mul_f32_e32 v121, v121, v121
	v_mul_f32_e32 v117, v117, v117
	v_fmac_f32_e32 v129, v128, v128
	v_mul_f32_e32 v128, v131, v131
	v_fmac_f32_e32 v125, v124, v124
	v_mul_f32_e32 v124, v127, v127
	v_fmac_f32_e32 v121, v120, v120
	v_mul_f32_e32 v120, v123, v123
	v_fmac_f32_e32 v117, v116, v116
	v_mul_f32_e32 v116, v119, v119
	v_fmac_f32_e32 v128, v130, v130
	v_fmac_f32_e32 v124, v126, v126
	v_fmac_f32_e32 v120, v122, v122
	v_fmac_f32_e32 v116, v118, v118
	v_add_f32_e32 v128, v129, v128
	v_add_f32_e32 v124, v125, v124
	v_add_f32_e32 v120, v121, v120
	v_add_f32_e32 v116, v117, v116
	v_add_f32_e32 v124, v128, v124
	v_add_f32_e32 v116, v120, v116
	v_add_f32_e32 v117, v124, v116
	ds_swizzle_b32 v118, v117 offset:swizzle(SWAP,16)
	v_and_b32_e32 v152, 64, v236
	v_xor_b32_e32 v151, 32, v236
	v_add_u32_e32 v152, 64, v152
	v_cmp_lt_i32_e32 vcc, v151, v152
	s_lshl_b32 s9, s83, 2
	s_or_b32 s24, s24, s9
	v_cndmask_b32_e32 v116, v236, v151, vcc
	s_lshl_b64 s[0:1], s[0:1], 8
	v_lshlrev_b32_e32 v116, 2, v116
	s_waitcnt lgkmcnt(0)
	v_add_f32_e32 v117, v117, v118
	s_add_u32 s0, s0, s14
	ds_bpermute_b32 v118, v116, v117
	s_addc_u32 s1, s1, s15
	s_ashr_i32 s25, s24, 31
	v_or_b32_e32 v143, s0, v142
	v_mov_b32_e32 v142, s1
	s_lshl_b64 s[0:1], s[24:25], 2
	v_and_b32_e32 v119, 48, v141
	s_add_u32 s0, s73, s0
	v_cmp_eq_u32_e64 s[16:17], 0, v119
	s_addc_u32 s1, s74, s1
	s_and_saveexec_b64 s[14:15], s[16:17]
	s_cbranch_execz .LBB0_3053
	v_mov_b32_e32 v141, v2
	v_lshl_add_u64 v[120:121], s[22:23], 0, v[140:141]
	global_load_dword v119, v[120:121], off
	s_waitcnt lgkmcnt(0)
	v_add_f32_e32 v117, v117, v118
	s_waitcnt vmcnt(0)
	v_add_f32_e32 v117, v117, v119
	v_fmamk_f32 v117, v117, 0x3c2aaaab, v231
	v_cmp_gt_f32_e32 vcc, s11, v117
	v_mul_f32_e32 v118, 0x4b800000, v117
	s_nop 0
	v_cndmask_b32_e32 v117, v117, v118, vcc
	v_rsq_f32_e32 v117, v117
	s_nop 0
	v_mul_f32_e32 v118, 0x45800000, v117
	v_cndmask_b32_e32 v117, v117, v118, vcc
	v_mad_u64_u32 v[118:119], s[22:23], v143, 48, s[0:1]
	v_mov_b32_e32 v120, v119
	v_mad_u64_u32 v[120:121], s[22:23], v142, 48, v[120:121]
	v_mov_b32_e32 v119, v120
	global_store_dword v[118:119], v117, off

.LBB0_3088:
	s_add_u32 s16, s14, s45
	s_addc_u32 s17, s15, s46
	s_add_u32 s20, s16, 0xf0c5f100
	s_addc_u32 s21, s17, -1
	v_add_u32_e32 v148, s84, v1
	v_add_u32_e32 v164, s85, v1
	s_add_u32 s16, s14, 0x100
	ds_read_b128 v[136:139], v148
	ds_read_b128 v[140:143], v148 offset:1024
	ds_read_b128 v[144:147], v148 offset:2048
	ds_read_b128 v[148:151], v148 offset:3072
	ds_read_b128 v[152:155], v164
	ds_read_b128 v[156:159], v164 offset:1024
	ds_read_b128 v[160:163], v164 offset:2048
	ds_read_b128 v[164:167], v164 offset:3072
	s_addc_u32 s17, s15, 0
	s_cmp_eq_u32 s47, 40
	s_cselect_b32 s20, s6, s20
	s_cselect_b32 s21, s7, s21
	s_cselect_b32 s26, s0, s16
	s_cselect_b32 s27, s1, s17
	s_add_u32 s24, s20, 0x80
	s_addc_u32 s25, s21, 0
	s_add_u32 s22, s26, 0x80
	s_addc_u32 s23, s27, 0
	s_add_u32 s14, s14, 0xb0080
	s_addc_u32 s15, s15, 0
	ds_read_b128 v[168:171], v3
	ds_read_b128 v[172:175], v3 offset:1024
	ds_read_b128 v[176:179], v3 offset:2048
	ds_read_b128 v[180:183], v3 offset:3072
	ds_read_b128 v[184:187], v3 offset:4096
	ds_read_b128 v[188:191], v3 offset:5120
	ds_read_b128 v[192:195], v3 offset:6144
	ds_read_b128 v[210:213], v3 offset:7168
	s_add_i32 m0, s41, 0xc000
	s_nop 0
	global_load_lds_dwordx4 v132, s[14:15]
	s_add_i32 m0, s41, 0xe000
	s_nop 0
	global_load_lds_dwordx4 v134, s[14:15]
	s_waitcnt vmcnt(8)
	s_waitcnt lgkmcnt(0)
	s_barrier
	s_setprio 1
	s_waitcnt lgkmcnt(0)
	v_mfma_f32_16x16x32_bf16 v[128:131], v[136:139], v[168:171], v[128:131]
	v_mfma_f32_16x16x32_bf16 v[124:127], v[144:147], v[168:171], v[124:127]
	v_mfma_f32_16x16x32_bf16 v[112:115], v[136:139], v[176:179], v[112:115]
	v_mfma_f32_16x16x32_bf16 v[108:111], v[144:147], v[176:179], v[108:111]
	v_mfma_f32_16x16x32_bf16 v[96:99], v[136:139], v[184:187], v[96:99]
	v_mfma_f32_16x16x32_bf16 v[92:95], v[144:147], v[184:187], v[92:95]
	v_mfma_f32_16x16x32_bf16 v[80:83], v[136:139], v[192:195], v[80:83]
	v_mfma_f32_16x16x32_bf16 v[76:79], v[144:147], v[192:195], v[76:79]
	v_mfma_f32_16x16x32_bf16 v[128:131], v[140:143], v[172:175], v[128:131]
	v_mfma_f32_16x16x32_bf16 v[124:127], v[148:151], v[172:175], v[124:127]
	v_mfma_f32_16x16x32_bf16 v[112:115], v[140:143], v[180:183], v[112:115]
	v_mfma_f32_16x16x32_bf16 v[108:111], v[148:151], v[180:183], v[108:111]
	v_mfma_f32_16x16x32_bf16 v[96:99], v[140:143], v[188:191], v[96:99]
	v_mfma_f32_16x16x32_bf16 v[92:95], v[148:151], v[188:191], v[92:95]
	v_mfma_f32_16x16x32_bf16 v[80:83], v[140:143], v[210:213], v[80:83]
	v_mfma_f32_16x16x32_bf16 v[76:79], v[148:151], v[210:213], v[76:79]
	s_setprio 0
	s_setprio 1
	v_mfma_f32_16x16x32_bf16 v[120:123], v[152:155], v[168:171], v[120:123]
	v_mfma_f32_16x16x32_bf16 v[116:119], v[160:163], v[168:171], v[116:119]
	v_mfma_f32_16x16x32_bf16 v[104:107], v[152:155], v[176:179], v[104:107]
	v_mfma_f32_16x16x32_bf16 v[100:103], v[160:163], v[176:179], v[100:103]
	v_mfma_f32_16x16x32_bf16 v[88:91], v[152:155], v[184:187], v[88:91]
	v_mfma_f32_16x16x32_bf16 v[84:87], v[160:163], v[184:187], v[84:87]
	v_mfma_f32_16x16x32_bf16 v[72:75], v[152:155], v[192:195], v[72:75]
	v_mfma_f32_16x16x32_bf16 v[68:71], v[160:163], v[192:195], v[68:71]
	v_mfma_f32_16x16x32_bf16 v[120:123], v[156:159], v[172:175], v[120:123]
	v_mfma_f32_16x16x32_bf16 v[116:119], v[164:167], v[172:175], v[116:119]
	v_mfma_f32_16x16x32_bf16 v[104:107], v[156:159], v[180:183], v[104:107]
	v_mfma_f32_16x16x32_bf16 v[100:103], v[164:167], v[180:183], v[100:103]
	v_mfma_f32_16x16x32_bf16 v[88:91], v[156:159], v[188:191], v[88:91]
	v_mfma_f32_16x16x32_bf16 v[84:87], v[164:167], v[188:191], v[84:87]
	v_mfma_f32_16x16x32_bf16 v[72:75], v[156:159], v[210:213], v[72:75]
	v_mfma_f32_16x16x32_bf16 v[68:71], v[164:167], v[210:213], v[68:71]
	s_setprio 0
	s_barrier
	s_mov_b64 s[14:15], s[20:21]
	s_add_i32 s48, s84, s29
	ds_read_b128 v[168:171], v3 offset:16384
	ds_read_b128 v[172:175], v3 offset:17408
	ds_read_b128 v[176:179], v3 offset:18432
	ds_read_b128 v[180:183], v3 offset:19456
	ds_read_b128 v[184:187], v3 offset:20480
	ds_read_b128 v[188:191], v3 offset:21504
	ds_read_b128 v[192:195], v3 offset:22528
	ds_read_b128 v[210:213], v3 offset:23552
	s_mov_b32 m0, s48
	s_nop 0
	global_load_lds_dwordx4 v132, s[14:15]
	s_add_i32 m0, s48, 0x2000
	s_nop 0
	global_load_lds_dwordx4 v134, s[14:15]
	s_add_u32 s14, s20, 0xb0000
	s_addc_u32 s15, s21, 0
	s_add_i32 s48, s85, s29
	s_mov_b32 m0, s48
	s_nop 0
	global_load_lds_dwordx4 v132, s[14:15]
	s_add_i32 m0, s48, 0x2000
	s_nop 0
	global_load_lds_dwordx4 v134, s[14:15]
	s_mov_b64 s[14:15], s[26:27]
	s_mov_b32 m0, s41
	s_nop 0
	global_load_lds_dwordx4 v132, s[14:15]
	s_mov_b32 m0, s42
	s_nop 0
	global_load_lds_dwordx4 v134, s[14:15]
	s_waitcnt vmcnt(8)
	s_waitcnt lgkmcnt(0)
	s_barrier
	s_setprio 1
	s_waitcnt lgkmcnt(0)
	v_mfma_f32_16x16x32_bf16 v[64:67], v[136:139], v[168:171], v[64:67]
	v_mfma_f32_16x16x32_bf16 v[60:63], v[144:147], v[168:171], v[60:63]
	v_mfma_f32_16x16x32_bf16 v[48:51], v[136:139], v[176:179], v[48:51]
	v_mfma_f32_16x16x32_bf16 v[44:47], v[144:147], v[176:179], v[44:47]
	v_mfma_f32_16x16x32_bf16 v[32:35], v[136:139], v[184:187], v[32:35]
	v_mfma_f32_16x16x32_bf16 v[28:31], v[144:147], v[184:187], v[28:31]
	v_mfma_f32_16x16x32_bf16 v[16:19], v[136:139], v[192:195], v[16:19]
	v_mfma_f32_16x16x32_bf16 v[12:15], v[144:147], v[192:195], v[12:15]
	v_mfma_f32_16x16x32_bf16 v[64:67], v[140:143], v[172:175], v[64:67]
	v_mfma_f32_16x16x32_bf16 v[60:63], v[148:151], v[172:175], v[60:63]
	v_mfma_f32_16x16x32_bf16 v[48:51], v[140:143], v[180:183], v[48:51]
	v_mfma_f32_16x16x32_bf16 v[44:47], v[148:151], v[180:183], v[44:47]
	v_mfma_f32_16x16x32_bf16 v[32:35], v[140:143], v[188:191], v[32:35]
	v_mfma_f32_16x16x32_bf16 v[28:31], v[148:151], v[188:191], v[28:31]
	v_mfma_f32_16x16x32_bf16 v[16:19], v[140:143], v[210:213], v[16:19]
	v_mfma_f32_16x16x32_bf16 v[12:15], v[148:151], v[210:213], v[12:15]
	s_setprio 0
	s_setprio 1
	v_mfma_f32_16x16x32_bf16 v[56:59], v[152:155], v[168:171], v[56:59]
	v_mfma_f32_16x16x32_bf16 v[52:55], v[160:163], v[168:171], v[52:55]
	v_mfma_f32_16x16x32_bf16 v[40:43], v[152:155], v[176:179], v[40:43]
	v_mfma_f32_16x16x32_bf16 v[36:39], v[160:163], v[176:179], v[36:39]
	v_mfma_f32_16x16x32_bf16 v[24:27], v[152:155], v[184:187], v[24:27]
	v_mfma_f32_16x16x32_bf16 v[20:23], v[160:163], v[184:187], v[20:23]
	v_mfma_f32_16x16x32_bf16 v[8:11], v[152:155], v[192:195], v[8:11]
	v_mfma_f32_16x16x32_bf16 v[4:7], v[160:163], v[192:195], v[4:7]
	v_mfma_f32_16x16x32_bf16 v[56:59], v[156:159], v[172:175], v[56:59]
	v_mfma_f32_16x16x32_bf16 v[52:55], v[164:167], v[172:175], v[52:55]
	v_mfma_f32_16x16x32_bf16 v[40:43], v[156:159], v[180:183], v[40:43]
	v_mfma_f32_16x16x32_bf16 v[36:39], v[164:167], v[180:183], v[36:39]
	v_mfma_f32_16x16x32_bf16 v[24:27], v[156:159], v[188:191], v[24:27]
	v_mfma_f32_16x16x32_bf16 v[20:23], v[164:167], v[188:191], v[20:23]
	v_mfma_f32_16x16x32_bf16 v[8:11], v[156:159], v[210:213], v[8:11]
	v_mfma_f32_16x16x32_bf16 v[4:7], v[164:167], v[210:213], v[4:7]
	s_setprio 0
	s_barrier
	v_add_u32_e32 v148, s88, v1
	v_add_u32_e32 v164, s89, v1
	ds_read_b128 v[136:139], v148
	ds_read_b128 v[140:143], v148 offset:1024
	ds_read_b128 v[144:147], v148 offset:2048
	ds_read_b128 v[148:151], v148 offset:3072
	ds_read_b128 v[152:155], v164
	ds_read_b128 v[156:159], v164 offset:1024
	ds_read_b128 v[160:163], v164 offset:2048
	ds_read_b128 v[164:167], v164 offset:3072
	s_add_u32 s14, s26, 0xb0000
	s_addc_u32 s15, s27, 0
	s_mov_b32 m0, s43
	ds_read_b128 v[168:171], v3 offset:32768
	ds_read_b128 v[172:175], v3 offset:33792
	ds_read_b128 v[176:179], v3 offset:34816
	ds_read_b128 v[180:183], v3 offset:35840
	ds_read_b128 v[184:187], v3 offset:36864
	ds_read_b128 v[188:191], v3 offset:37888
	ds_read_b128 v[192:195], v3 offset:38912
	ds_read_b128 v[210:213], v3 offset:39936
	s_nop 0
	global_load_lds_dwordx4 v132, s[14:15]
	s_mov_b32 m0, s44
	s_nop 0
	global_load_lds_dwordx4 v134, s[14:15]
	s_waitcnt vmcnt(8)
	s_waitcnt lgkmcnt(0)
	s_barrier
	s_setprio 1
	s_waitcnt lgkmcnt(0)
	v_mfma_f32_16x16x32_bf16 v[128:131], v[136:139], v[168:171], v[128:131]
	v_mfma_f32_16x16x32_bf16 v[124:127], v[144:147], v[168:171], v[124:127]
	v_mfma_f32_16x16x32_bf16 v[112:115], v[136:139], v[176:179], v[112:115]
	v_mfma_f32_16x16x32_bf16 v[108:111], v[144:147], v[176:179], v[108:111]
	v_mfma_f32_16x16x32_bf16 v[96:99], v[136:139], v[184:187], v[96:99]
	v_mfma_f32_16x16x32_bf16 v[92:95], v[144:147], v[184:187], v[92:95]
	v_mfma_f32_16x16x32_bf16 v[80:83], v[136:139], v[192:195], v[80:83]
	v_mfma_f32_16x16x32_bf16 v[76:79], v[144:147], v[192:195], v[76:79]
	v_mfma_f32_16x16x32_bf16 v[128:131], v[140:143], v[172:175], v[128:131]
	v_mfma_f32_16x16x32_bf16 v[124:127], v[148:151], v[172:175], v[124:127]
	v_mfma_f32_16x16x32_bf16 v[112:115], v[140:143], v[180:183], v[112:115]
	v_mfma_f32_16x16x32_bf16 v[108:111], v[148:151], v[180:183], v[108:111]
	v_mfma_f32_16x16x32_bf16 v[96:99], v[140:143], v[188:191], v[96:99]
	v_mfma_f32_16x16x32_bf16 v[92:95], v[148:151], v[188:191], v[92:95]
	v_mfma_f32_16x16x32_bf16 v[80:83], v[140:143], v[210:213], v[80:83]
	v_mfma_f32_16x16x32_bf16 v[76:79], v[148:151], v[210:213], v[76:79]
	s_setprio 0
	s_setprio 1
	v_mfma_f32_16x16x32_bf16 v[120:123], v[152:155], v[168:171], v[120:123]
	v_mfma_f32_16x16x32_bf16 v[116:119], v[160:163], v[168:171], v[116:119]
	v_mfma_f32_16x16x32_bf16 v[104:107], v[152:155], v[176:179], v[104:107]
	v_mfma_f32_16x16x32_bf16 v[100:103], v[160:163], v[176:179], v[100:103]
	v_mfma_f32_16x16x32_bf16 v[88:91], v[152:155], v[184:187], v[88:91]
	v_mfma_f32_16x16x32_bf16 v[84:87], v[160:163], v[184:187], v[84:87]
	v_mfma_f32_16x16x32_bf16 v[72:75], v[152:155], v[192:195], v[72:75]
	v_mfma_f32_16x16x32_bf16 v[68:71], v[160:163], v[192:195], v[68:71]
	v_mfma_f32_16x16x32_bf16 v[120:123], v[156:159], v[172:175], v[120:123]
	v_mfma_f32_16x16x32_bf16 v[116:119], v[164:167], v[172:175], v[116:119]
	v_mfma_f32_16x16x32_bf16 v[104:107], v[156:159], v[180:183], v[104:107]
	v_mfma_f32_16x16x32_bf16 v[100:103], v[164:167], v[180:183], v[100:103]
	v_mfma_f32_16x16x32_bf16 v[88:91], v[156:159], v[188:191], v[88:91]
	v_mfma_f32_16x16x32_bf16 v[84:87], v[164:167], v[188:191], v[84:87]
	v_mfma_f32_16x16x32_bf16 v[72:75], v[156:159], v[210:213], v[72:75]
	v_mfma_f32_16x16x32_bf16 v[68:71], v[164:167], v[210:213], v[68:71]
	s_setprio 0
	s_barrier
	s_add_i32 s14, s88, s29
	ds_read_b128 v[168:171], v3 offset:49152
	ds_read_b128 v[172:175], v3 offset:50176
	ds_read_b128 v[176:179], v3 offset:51200
	ds_read_b128 v[180:183], v3 offset:52224
	ds_read_b128 v[184:187], v3 offset:53248
	ds_read_b128 v[188:191], v3 offset:54272
	ds_read_b128 v[192:195], v3 offset:55296
	ds_read_b128 v[210:213], v3 offset:56320
	s_mov_b32 m0, s14
	s_nop 0
	global_load_lds_dwordx4 v132, s[24:25]
	s_add_i32 m0, s14, 0x2000
	s_add_u32 s14, s20, 0xb0080
	s_addc_u32 s15, s21, 0
	s_add_i32 s20, s89, s29
	global_load_lds_dwordx4 v134, s[24:25]
	s_mov_b32 m0, s20
	s_nop 0
	global_load_lds_dwordx4 v132, s[14:15]
	s_add_i32 m0, s20, 0x2000
	s_nop 0
	global_load_lds_dwordx4 v134, s[14:15]
	s_mov_b32 m0, s38
	s_nop 0
	global_load_lds_dwordx4 v132, s[22:23]
	s_mov_b32 m0, s39
	s_nop 0
	global_load_lds_dwordx4 v134, s[22:23]
	s_waitcnt vmcnt(8)
	s_waitcnt lgkmcnt(0)
	s_barrier
	s_setprio 1
	s_waitcnt lgkmcnt(0)
	v_mfma_f32_16x16x32_bf16 v[64:67], v[136:139], v[168:171], v[64:67]
	v_mfma_f32_16x16x32_bf16 v[60:63], v[144:147], v[168:171], v[60:63]
	v_mfma_f32_16x16x32_bf16 v[48:51], v[136:139], v[176:179], v[48:51]
	v_mfma_f32_16x16x32_bf16 v[44:47], v[144:147], v[176:179], v[44:47]
	v_mfma_f32_16x16x32_bf16 v[32:35], v[136:139], v[184:187], v[32:35]
	v_mfma_f32_16x16x32_bf16 v[28:31], v[144:147], v[184:187], v[28:31]
	v_mfma_f32_16x16x32_bf16 v[16:19], v[136:139], v[192:195], v[16:19]
	v_mfma_f32_16x16x32_bf16 v[12:15], v[144:147], v[192:195], v[12:15]
	v_mfma_f32_16x16x32_bf16 v[64:67], v[140:143], v[172:175], v[64:67]
	v_mfma_f32_16x16x32_bf16 v[60:63], v[148:151], v[172:175], v[60:63]
	v_mfma_f32_16x16x32_bf16 v[48:51], v[140:143], v[180:183], v[48:51]
	v_mfma_f32_16x16x32_bf16 v[44:47], v[148:151], v[180:183], v[44:47]
	v_mfma_f32_16x16x32_bf16 v[32:35], v[140:143], v[188:191], v[32:35]
	v_mfma_f32_16x16x32_bf16 v[28:31], v[148:151], v[188:191], v[28:31]
	v_mfma_f32_16x16x32_bf16 v[16:19], v[140:143], v[210:213], v[16:19]
	v_mfma_f32_16x16x32_bf16 v[12:15], v[148:151], v[210:213], v[12:15]
	s_setprio 0
	s_setprio 1
	v_mfma_f32_16x16x32_bf16 v[56:59], v[152:155], v[168:171], v[56:59]
	v_mfma_f32_16x16x32_bf16 v[52:55], v[160:163], v[168:171], v[52:55]
	v_mfma_f32_16x16x32_bf16 v[40:43], v[152:155], v[176:179], v[40:43]
	v_mfma_f32_16x16x32_bf16 v[36:39], v[160:163], v[176:179], v[36:39]
	v_mfma_f32_16x16x32_bf16 v[24:27], v[152:155], v[184:187], v[24:27]
	v_mfma_f32_16x16x32_bf16 v[20:23], v[160:163], v[184:187], v[20:23]
	v_mfma_f32_16x16x32_bf16 v[8:11], v[152:155], v[192:195], v[8:11]
	v_mfma_f32_16x16x32_bf16 v[4:7], v[160:163], v[192:195], v[4:7]
	v_mfma_f32_16x16x32_bf16 v[56:59], v[156:159], v[172:175], v[56:59]
	v_mfma_f32_16x16x32_bf16 v[52:55], v[164:167], v[172:175], v[52:55]
	v_mfma_f32_16x16x32_bf16 v[40:43], v[156:159], v[180:183], v[40:43]
	v_mfma_f32_16x16x32_bf16 v[36:39], v[164:167], v[180:183], v[36:39]
	v_mfma_f32_16x16x32_bf16 v[24:27], v[156:159], v[188:191], v[24:27]
	v_mfma_f32_16x16x32_bf16 v[20:23], v[164:167], v[188:191], v[20:23]
	v_mfma_f32_16x16x32_bf16 v[8:11], v[156:159], v[210:213], v[8:11]
	v_mfma_f32_16x16x32_bf16 v[4:7], v[164:167], v[210:213], v[4:7]
	s_setprio 0
	s_barrier
	s_add_i32 s47, s47, 2
	s_cmp_gt_u32 s47, 41
	s_mov_b64 s[14:15], s[16:17]
	s_cbranch_scc0 .LBB0_3088
	s_cmpk_lt_u32 s28, 0x100
	s_cbranch_scc0 .LBB0_3091
	s_barrier

.LBB0_3199:
	v_add_u32_e32 v144, s84, v1
	v_add_u32_e32 v160, s85, v1
	ds_read_b128 v[132:135], v144
	ds_read_b128 v[136:139], v144 offset:1024
	ds_read_b128 v[140:143], v144 offset:2048
	ds_read_b128 v[144:147], v144 offset:3072
	ds_read_b128 v[148:151], v160
	ds_read_b128 v[152:155], v160 offset:1024
	ds_read_b128 v[156:159], v160 offset:2048
	ds_read_b128 v[160:163], v160 offset:3072
	s_add_u32 s8, s0, 0x100
	s_addc_u32 s9, s1, 0
	s_cmp_eq_u32 s64, 40
	s_cselect_b32 s40, s34, s8
	s_cselect_b32 s41, s35, s9
	s_cselect_b32 s38, s36, s62
	s_cselect_b32 s39, s37, s63
	s_add_u32 s16, s40, 0x80
	s_addc_u32 s17, s41, 0
	s_add_u32 s0, s0, 0xb0080
	s_addc_u32 s1, s1, 0
	ds_read_b128 v[164:167], v3
	ds_read_b128 v[168:171], v3 offset:1024
	ds_read_b128 v[172:175], v3 offset:2048
	ds_read_b128 v[176:179], v3 offset:3072
	ds_read_b128 v[180:183], v3 offset:4096
	ds_read_b128 v[184:187], v3 offset:5120
	ds_read_b128 v[192:195], v3 offset:6144
	ds_read_b128 v[210:213], v3 offset:7168
	s_add_i32 m0, s47, 0xc000
	s_nop 0
	global_load_lds_dwordx4 v190, s[0:1]
	s_add_i32 m0, s47, 0xe000
	s_nop 0
	global_load_lds_dwordx4 v188, s[0:1]
	s_waitcnt vmcnt(8)
	s_waitcnt lgkmcnt(0)
	s_barrier
	s_setprio 1
	s_waitcnt lgkmcnt(0)
	v_mfma_f32_16x16x32_bf16 v[128:131], v[132:135], v[164:167], v[128:131]
	v_mfma_f32_16x16x32_bf16 v[124:127], v[140:143], v[164:167], v[124:127]
	v_mfma_f32_16x16x32_bf16 v[112:115], v[132:135], v[172:175], v[112:115]
	v_mfma_f32_16x16x32_bf16 v[108:111], v[140:143], v[172:175], v[108:111]
	v_mfma_f32_16x16x32_bf16 v[96:99], v[132:135], v[180:183], v[96:99]
	v_mfma_f32_16x16x32_bf16 v[92:95], v[140:143], v[180:183], v[92:95]
	v_mfma_f32_16x16x32_bf16 v[80:83], v[132:135], v[192:195], v[80:83]
	v_mfma_f32_16x16x32_bf16 v[76:79], v[140:143], v[192:195], v[76:79]
	v_mfma_f32_16x16x32_bf16 v[128:131], v[136:139], v[168:171], v[128:131]
	v_mfma_f32_16x16x32_bf16 v[124:127], v[144:147], v[168:171], v[124:127]
	v_mfma_f32_16x16x32_bf16 v[112:115], v[136:139], v[176:179], v[112:115]
	v_mfma_f32_16x16x32_bf16 v[108:111], v[144:147], v[176:179], v[108:111]
	v_mfma_f32_16x16x32_bf16 v[96:99], v[136:139], v[184:187], v[96:99]
	v_mfma_f32_16x16x32_bf16 v[92:95], v[144:147], v[184:187], v[92:95]
	v_mfma_f32_16x16x32_bf16 v[80:83], v[136:139], v[210:213], v[80:83]
	v_mfma_f32_16x16x32_bf16 v[76:79], v[144:147], v[210:213], v[76:79]
	s_setprio 0
	s_setprio 1
	v_mfma_f32_16x16x32_bf16 v[120:123], v[148:151], v[164:167], v[120:123]
	v_mfma_f32_16x16x32_bf16 v[116:119], v[156:159], v[164:167], v[116:119]
	v_mfma_f32_16x16x32_bf16 v[104:107], v[148:151], v[172:175], v[104:107]
	v_mfma_f32_16x16x32_bf16 v[100:103], v[156:159], v[172:175], v[100:103]
	v_mfma_f32_16x16x32_bf16 v[88:91], v[148:151], v[180:183], v[88:91]
	v_mfma_f32_16x16x32_bf16 v[84:87], v[156:159], v[180:183], v[84:87]
	v_mfma_f32_16x16x32_bf16 v[72:75], v[148:151], v[192:195], v[72:75]
	v_mfma_f32_16x16x32_bf16 v[68:71], v[156:159], v[192:195], v[68:71]
	v_mfma_f32_16x16x32_bf16 v[120:123], v[152:155], v[168:171], v[120:123]
	v_mfma_f32_16x16x32_bf16 v[116:119], v[160:163], v[168:171], v[116:119]
	v_mfma_f32_16x16x32_bf16 v[104:107], v[152:155], v[176:179], v[104:107]
	v_mfma_f32_16x16x32_bf16 v[100:103], v[160:163], v[176:179], v[100:103]
	v_mfma_f32_16x16x32_bf16 v[88:91], v[152:155], v[184:187], v[88:91]
	v_mfma_f32_16x16x32_bf16 v[84:87], v[160:163], v[184:187], v[84:87]
	v_mfma_f32_16x16x32_bf16 v[72:75], v[152:155], v[210:213], v[72:75]
	v_mfma_f32_16x16x32_bf16 v[68:71], v[160:163], v[210:213], v[68:71]
	s_setprio 0
	s_barrier
	s_mov_b64 s[0:1], s[38:39]
	s_add_i32 s65, s84, s44
	ds_read_b128 v[164:167], v3 offset:16384
	ds_read_b128 v[168:171], v3 offset:17408
	ds_read_b128 v[172:175], v3 offset:18432
	ds_read_b128 v[176:179], v3 offset:19456
	ds_read_b128 v[180:183], v3 offset:20480
	ds_read_b128 v[184:187], v3 offset:21504
	ds_read_b128 v[192:195], v3 offset:22528
	ds_read_b128 v[210:213], v3 offset:23552
	s_mov_b32 m0, s65
	s_nop 0
	global_load_lds_dwordx4 v190, s[0:1]
	s_add_i32 m0, s65, 0x2000
	s_nop 0
	global_load_lds_dwordx4 v188, s[0:1]
	s_add_u32 s0, s38, 0xb0000
	s_addc_u32 s1, s39, 0
	s_add_i32 s65, s85, s44
	s_mov_b32 m0, s65
	s_nop 0
	global_load_lds_dwordx4 v190, s[0:1]
	s_add_i32 m0, s65, 0x2000
	s_nop 0
	global_load_lds_dwordx4 v188, s[0:1]
	s_mov_b64 s[0:1], s[40:41]
	s_mov_b32 m0, s47
	s_nop 0
	global_load_lds_dwordx4 v190, s[0:1]
	s_mov_b32 m0, s48
	s_nop 0
	global_load_lds_dwordx4 v188, s[0:1]
	s_waitcnt vmcnt(8)
	s_waitcnt lgkmcnt(0)
	s_barrier
	s_setprio 1
	s_waitcnt lgkmcnt(0)
	v_mfma_f32_16x16x32_bf16 v[64:67], v[132:135], v[164:167], v[64:67]
	v_mfma_f32_16x16x32_bf16 v[60:63], v[140:143], v[164:167], v[60:63]
	v_mfma_f32_16x16x32_bf16 v[48:51], v[132:135], v[172:175], v[48:51]
	v_mfma_f32_16x16x32_bf16 v[44:47], v[140:143], v[172:175], v[44:47]
	v_mfma_f32_16x16x32_bf16 v[32:35], v[132:135], v[180:183], v[32:35]
	v_mfma_f32_16x16x32_bf16 v[28:31], v[140:143], v[180:183], v[28:31]
	v_mfma_f32_16x16x32_bf16 v[16:19], v[132:135], v[192:195], v[16:19]
	v_mfma_f32_16x16x32_bf16 v[12:15], v[140:143], v[192:195], v[12:15]
	v_mfma_f32_16x16x32_bf16 v[64:67], v[136:139], v[168:171], v[64:67]
	v_mfma_f32_16x16x32_bf16 v[60:63], v[144:147], v[168:171], v[60:63]
	v_mfma_f32_16x16x32_bf16 v[48:51], v[136:139], v[176:179], v[48:51]
	v_mfma_f32_16x16x32_bf16 v[44:47], v[144:147], v[176:179], v[44:47]
	v_mfma_f32_16x16x32_bf16 v[32:35], v[136:139], v[184:187], v[32:35]
	v_mfma_f32_16x16x32_bf16 v[28:31], v[144:147], v[184:187], v[28:31]
	v_mfma_f32_16x16x32_bf16 v[16:19], v[136:139], v[210:213], v[16:19]
	v_mfma_f32_16x16x32_bf16 v[12:15], v[144:147], v[210:213], v[12:15]
	s_setprio 0
	s_setprio 1
	v_mfma_f32_16x16x32_bf16 v[56:59], v[148:151], v[164:167], v[56:59]
	v_mfma_f32_16x16x32_bf16 v[52:55], v[156:159], v[164:167], v[52:55]
	v_mfma_f32_16x16x32_bf16 v[40:43], v[148:151], v[172:175], v[40:43]
	v_mfma_f32_16x16x32_bf16 v[36:39], v[156:159], v[172:175], v[36:39]
	v_mfma_f32_16x16x32_bf16 v[24:27], v[148:151], v[180:183], v[24:27]
	v_mfma_f32_16x16x32_bf16 v[20:23], v[156:159], v[180:183], v[20:23]
	v_mfma_f32_16x16x32_bf16 v[8:11], v[148:151], v[192:195], v[8:11]
	v_mfma_f32_16x16x32_bf16 v[4:7], v[156:159], v[192:195], v[4:7]
	v_mfma_f32_16x16x32_bf16 v[56:59], v[152:155], v[168:171], v[56:59]
	v_mfma_f32_16x16x32_bf16 v[52:55], v[160:163], v[168:171], v[52:55]
	v_mfma_f32_16x16x32_bf16 v[40:43], v[152:155], v[176:179], v[40:43]
	v_mfma_f32_16x16x32_bf16 v[36:39], v[160:163], v[176:179], v[36:39]
	v_mfma_f32_16x16x32_bf16 v[24:27], v[152:155], v[184:187], v[24:27]
	v_mfma_f32_16x16x32_bf16 v[20:23], v[160:163], v[184:187], v[20:23]
	v_mfma_f32_16x16x32_bf16 v[8:11], v[152:155], v[210:213], v[8:11]
	v_mfma_f32_16x16x32_bf16 v[4:7], v[160:163], v[210:213], v[4:7]
	s_setprio 0
	s_barrier
	v_add_u32_e32 v144, s88, v1
	v_add_u32_e32 v160, s89, v1
	ds_read_b128 v[132:135], v144
	ds_read_b128 v[136:139], v144 offset:1024
	ds_read_b128 v[140:143], v144 offset:2048
	ds_read_b128 v[144:147], v144 offset:3072
	ds_read_b128 v[148:151], v160
	ds_read_b128 v[152:155], v160 offset:1024
	ds_read_b128 v[156:159], v160 offset:2048
	ds_read_b128 v[160:163], v160 offset:3072
	s_add_u32 s0, s40, 0xb0000
	s_addc_u32 s1, s41, 0
	s_mov_b32 m0, s49
	ds_read_b128 v[164:167], v3 offset:32768
	ds_read_b128 v[168:171], v3 offset:33792
	ds_read_b128 v[172:175], v3 offset:34816
	ds_read_b128 v[176:179], v3 offset:35840
	ds_read_b128 v[180:183], v3 offset:36864
	ds_read_b128 v[184:187], v3 offset:37888
	ds_read_b128 v[192:195], v3 offset:38912
	ds_read_b128 v[210:213], v3 offset:39936
	s_nop 0
	global_load_lds_dwordx4 v190, s[0:1]
	s_mov_b32 m0, s50
	s_nop 0
	global_load_lds_dwordx4 v188, s[0:1]
	s_waitcnt vmcnt(8)
	s_waitcnt lgkmcnt(0)
	s_barrier
	s_setprio 1
	s_waitcnt lgkmcnt(0)
	v_mfma_f32_16x16x32_bf16 v[128:131], v[132:135], v[164:167], v[128:131]
	v_mfma_f32_16x16x32_bf16 v[124:127], v[140:143], v[164:167], v[124:127]
	v_mfma_f32_16x16x32_bf16 v[112:115], v[132:135], v[172:175], v[112:115]
	v_mfma_f32_16x16x32_bf16 v[108:111], v[140:143], v[172:175], v[108:111]
	v_mfma_f32_16x16x32_bf16 v[96:99], v[132:135], v[180:183], v[96:99]
	v_mfma_f32_16x16x32_bf16 v[92:95], v[140:143], v[180:183], v[92:95]
	v_mfma_f32_16x16x32_bf16 v[80:83], v[132:135], v[192:195], v[80:83]
	v_mfma_f32_16x16x32_bf16 v[76:79], v[140:143], v[192:195], v[76:79]
	v_mfma_f32_16x16x32_bf16 v[128:131], v[136:139], v[168:171], v[128:131]
	v_mfma_f32_16x16x32_bf16 v[124:127], v[144:147], v[168:171], v[124:127]
	v_mfma_f32_16x16x32_bf16 v[112:115], v[136:139], v[176:179], v[112:115]
	v_mfma_f32_16x16x32_bf16 v[108:111], v[144:147], v[176:179], v[108:111]
	v_mfma_f32_16x16x32_bf16 v[96:99], v[136:139], v[184:187], v[96:99]
	v_mfma_f32_16x16x32_bf16 v[92:95], v[144:147], v[184:187], v[92:95]
	v_mfma_f32_16x16x32_bf16 v[80:83], v[136:139], v[210:213], v[80:83]
	v_mfma_f32_16x16x32_bf16 v[76:79], v[144:147], v[210:213], v[76:79]
	s_setprio 0
	s_setprio 1
	v_mfma_f32_16x16x32_bf16 v[120:123], v[148:151], v[164:167], v[120:123]
	v_mfma_f32_16x16x32_bf16 v[116:119], v[156:159], v[164:167], v[116:119]
	v_mfma_f32_16x16x32_bf16 v[104:107], v[148:151], v[172:175], v[104:107]
	v_mfma_f32_16x16x32_bf16 v[100:103], v[156:159], v[172:175], v[100:103]
	v_mfma_f32_16x16x32_bf16 v[88:91], v[148:151], v[180:183], v[88:91]
	v_mfma_f32_16x16x32_bf16 v[84:87], v[156:159], v[180:183], v[84:87]
	v_mfma_f32_16x16x32_bf16 v[72:75], v[148:151], v[192:195], v[72:75]
	v_mfma_f32_16x16x32_bf16 v[68:71], v[156:159], v[192:195], v[68:71]
	v_mfma_f32_16x16x32_bf16 v[120:123], v[152:155], v[168:171], v[120:123]
	v_mfma_f32_16x16x32_bf16 v[116:119], v[160:163], v[168:171], v[116:119]
	v_mfma_f32_16x16x32_bf16 v[104:107], v[152:155], v[176:179], v[104:107]
	v_mfma_f32_16x16x32_bf16 v[100:103], v[160:163], v[176:179], v[100:103]
	v_mfma_f32_16x16x32_bf16 v[88:91], v[152:155], v[184:187], v[88:91]
	v_mfma_f32_16x16x32_bf16 v[84:87], v[160:163], v[184:187], v[84:87]
	v_mfma_f32_16x16x32_bf16 v[72:75], v[152:155], v[210:213], v[72:75]
	v_mfma_f32_16x16x32_bf16 v[68:71], v[160:163], v[210:213], v[68:71]
	s_setprio 0
	s_barrier
	s_add_u32 s0, s38, 0x80
	s_addc_u32 s1, s39, 0
	s_add_i32 s40, s88, s44
	ds_read_b128 v[164:167], v3 offset:49152
	ds_read_b128 v[168:171], v3 offset:50176
	ds_read_b128 v[172:175], v3 offset:51200
	ds_read_b128 v[176:179], v3 offset:52224
	ds_read_b128 v[180:183], v3 offset:53248
	ds_read_b128 v[184:187], v3 offset:54272
	ds_read_b128 v[192:195], v3 offset:55296
	ds_read_b128 v[210:213], v3 offset:56320
	s_mov_b32 m0, s40
	s_nop 0
	global_load_lds_dwordx4 v190, s[0:1]
	s_add_i32 m0, s40, 0x2000
	s_nop 0
	global_load_lds_dwordx4 v188, s[0:1]
	s_add_u32 s0, s38, 0xb0080
	s_addc_u32 s1, s39, 0
	s_add_i32 s38, s89, s44
	s_mov_b32 m0, s38
	s_nop 0
	global_load_lds_dwordx4 v190, s[0:1]
	s_add_i32 m0, s38, 0x2000
	s_nop 0
	global_load_lds_dwordx4 v188, s[0:1]
	s_mov_b32 m0, s51
	s_nop 0
	global_load_lds_dwordx4 v190, s[16:17]
	s_mov_b32 m0, s52
	s_nop 0
	global_load_lds_dwordx4 v188, s[16:17]
	s_waitcnt vmcnt(8)
	s_waitcnt lgkmcnt(0)
	s_barrier
	s_setprio 1
	s_waitcnt lgkmcnt(0)
	v_mfma_f32_16x16x32_bf16 v[64:67], v[132:135], v[164:167], v[64:67]
	v_mfma_f32_16x16x32_bf16 v[60:63], v[140:143], v[164:167], v[60:63]
	v_mfma_f32_16x16x32_bf16 v[48:51], v[132:135], v[172:175], v[48:51]
	v_mfma_f32_16x16x32_bf16 v[44:47], v[140:143], v[172:175], v[44:47]
	v_mfma_f32_16x16x32_bf16 v[32:35], v[132:135], v[180:183], v[32:35]
	v_mfma_f32_16x16x32_bf16 v[28:31], v[140:143], v[180:183], v[28:31]
	v_mfma_f32_16x16x32_bf16 v[16:19], v[132:135], v[192:195], v[16:19]
	v_mfma_f32_16x16x32_bf16 v[12:15], v[140:143], v[192:195], v[12:15]
	v_mfma_f32_16x16x32_bf16 v[64:67], v[136:139], v[168:171], v[64:67]
	v_mfma_f32_16x16x32_bf16 v[60:63], v[144:147], v[168:171], v[60:63]
	v_mfma_f32_16x16x32_bf16 v[48:51], v[136:139], v[176:179], v[48:51]
	v_mfma_f32_16x16x32_bf16 v[44:47], v[144:147], v[176:179], v[44:47]
	v_mfma_f32_16x16x32_bf16 v[32:35], v[136:139], v[184:187], v[32:35]
	v_mfma_f32_16x16x32_bf16 v[28:31], v[144:147], v[184:187], v[28:31]
	v_mfma_f32_16x16x32_bf16 v[16:19], v[136:139], v[210:213], v[16:19]
	v_mfma_f32_16x16x32_bf16 v[12:15], v[144:147], v[210:213], v[12:15]
	s_setprio 0
	s_setprio 1
	v_mfma_f32_16x16x32_bf16 v[56:59], v[148:151], v[164:167], v[56:59]
	v_mfma_f32_16x16x32_bf16 v[52:55], v[156:159], v[164:167], v[52:55]
	v_mfma_f32_16x16x32_bf16 v[40:43], v[148:151], v[172:175], v[40:43]
	v_mfma_f32_16x16x32_bf16 v[36:39], v[156:159], v[172:175], v[36:39]
	v_mfma_f32_16x16x32_bf16 v[24:27], v[148:151], v[180:183], v[24:27]
	v_mfma_f32_16x16x32_bf16 v[20:23], v[156:159], v[180:183], v[20:23]
	v_mfma_f32_16x16x32_bf16 v[8:11], v[148:151], v[192:195], v[8:11]
	v_mfma_f32_16x16x32_bf16 v[4:7], v[156:159], v[192:195], v[4:7]
	v_mfma_f32_16x16x32_bf16 v[56:59], v[152:155], v[168:171], v[56:59]
	v_mfma_f32_16x16x32_bf16 v[52:55], v[160:163], v[168:171], v[52:55]
	v_mfma_f32_16x16x32_bf16 v[40:43], v[152:155], v[176:179], v[40:43]
	v_mfma_f32_16x16x32_bf16 v[36:39], v[160:163], v[176:179], v[36:39]
	v_mfma_f32_16x16x32_bf16 v[24:27], v[152:155], v[184:187], v[24:27]
	v_mfma_f32_16x16x32_bf16 v[20:23], v[160:163], v[184:187], v[20:23]
	v_mfma_f32_16x16x32_bf16 v[8:11], v[152:155], v[210:213], v[8:11]
	v_mfma_f32_16x16x32_bf16 v[4:7], v[160:163], v[210:213], v[4:7]
	s_setprio 0
	s_barrier
	s_add_i32 s64, s64, 2
	s_add_u32 s62, s62, 0x100
	s_addc_u32 s63, s63, 0
	s_cmp_gt_u32 s64, 41
	s_mov_b64 s[0:1], s[8:9]
	s_cbranch_scc0 .LBB0_3199
	s_and_b64 vcc, exec, s[26:27]
	s_cbranch_vccz .LBB0_3202
	s_barrier
